# v17 + GEMM unit boundary: first K-loop body of every unit peeled with vmcnt(8+S) in its first two super-phases (S = epilogue VMEM ops), prologue wait vmcnt(0)
# baseline (speedup 1.0000x reference)
; #define PG8_STAGE(bufoff, gbase, voff) do { _Pragma("unroll") for (int _i = 0; _i < 2; ++_i) \
;         __builtin_amdgcn_global_load_lds((const unsigned*)((const char*)(gbase) + (voff)[_i]), (PG8_LAS unsigned*)(lds + (bufoff) + ldsw + _i * 8192), 16, 0, 0); } while (0)
; #define PG8_WAIT_V(n) asm volatile("s_waitcnt vmcnt(" #n ")" ::: "memory")
; #define PG8_BAR __builtin_amdgcn_s_barrier()
; template <class Epi, class Sched, bool ALIGN_EPI = false, bool SP2 = false>
; __device__ __forceinline__ void gemm_phase(PG8_LAS unsigned char* lds, const Gemm g, const Sched& S, const Epi& E) {
;     const int tid = threadIdx.x, wid = __builtin_amdgcn_readfirstlane(tid >> 6), lane = tid & 63, wr = wid >> 2, wc = wid & 3, fr = lane & 15, fq = lane >> 4;
;     const int K = g.K, nt = K / BK;
;     unsigned voffA[2], voffB[2];
; #pragma unroll
;     for (int i = 0; i < 2; ++i) { int R, C; stage_rc(tid * 16 + i * 8192, R, C); const int Rb = Epi::PERM ? ((R & ~31) + perm32(R & 31)) : R;
;         voffA[i] = (unsigned)(R * g.lda + C) * 2u; voffB[i] = (unsigned)(Rb * g.ldb + C) * 2u; }
;     const size_t kstep = (size_t)(BK * 2);
;     const size_t hstepA = (size_t)HALF * g.lda * 2, hstepB = (size_t)HALF * g.ldb * 2;
;     const size_t tstepA = 2 * hstepA, tstepB = 2 * hstepB;
;     const unsigned ldsw = (unsigned)wid * 1024u;
;     const int aoff = lds_byte(wr * 64 + fr, fq * 8), boff = lds_byte(wc * 32 + fr, fq * 8);
;     ...
;         PG8_WAIT_V(2); PG8_BAR;
;         PG8_STAGE(PG8_SB(1, 0), cB + kstep, voffB); PG8_STAGE(PG8_SA(1, 0), cA + kstep, voffA); PG8_STAGE(PG8_SB(1, 1), cB + hstepB + kstep, voffB);
;         PG8_WAIT_V(6); PG8_BAR;
.LBB0_796:
	s_lshl_b32 s10, s10, 5
	s_and_b32 s16, s10, 0x60
	s_mov_b64 s[10:11], 0x80
	s_add_i32 m0, s27, 0x18000
	v_lshl_add_u64 v[8:9], v[8:9], 0, s[10:11]
	s_lshl_b32 s13, s12, 13
	s_lshl_b32 s17, s16, 7
	s_waitcnt vmcnt(2)
	s_barrier
	global_load_lds_dwordx4 v[8:9], off
	v_lshl_add_u64 v[4:5], v[4:5], 0, s[10:11]
	s_add_i32 m0, s27, 0x1a000
	s_add_i32 s51, s27, 0x8000
	s_add_i32 s52, s27, 0xa000
	global_load_lds_dwordx4 v[4:5], off
	v_lshl_add_u64 v[2:3], v[2:3], 0, s[10:11]
	s_mov_b32 m0, s51
	s_add_u32 s14, s40, 0x80080
	global_load_lds_dwordx4 v[2:3], off
	v_lshl_add_u64 v[2:3], v[6:7], 0, s[10:11]
	s_mov_b32 m0, s52
	s_addc_u32 s15, s41, 0
	global_load_lds_dwordx4 v[2:3], off
	s_add_i32 m0, s27, 0x1c000
	v_lshl_add_u64 v[2:3], s[14:15], 0, v[134:135]
	global_load_lds_dwordx4 v[2:3], off
	v_lshl_add_u64 v[2:3], s[14:15], 0, v[130:131]
	s_add_i32 m0, s27, 0x1e000
	s_sext_i32_i8 s60, s4
	global_load_lds_dwordx4 v[2:3], off
	v_and_b32_e32 v2, 15, v0
	v_lshlrev_b32_e32 v3, 1, v13
	v_lshlrev_b32_e32 v4, 2, v0
	v_lshlrev_b32_e32 v5, 6, v0
	s_movk_i32 s4, 0x3c0
	v_lshl_or_b32 v1, s12, 6, v2
	v_lshl_or_b32 v2, v2, 6, v3
	v_and_b32_e32 v4, 32, v4
	v_and_or_b32 v3, v5, s4, v3
	v_bitop3_b32 v146, s17, v3, v4 bitop3:0xf6
	v_lshlrev_b32_e32 v3, 9, v0
	v_bitop3_b32 v2, v2, s13, v4 bitop3:0xde
	v_and_b32_e32 v3, 0x30000, v3
	v_lshlrev_b32_e32 v4, 12, v14
	v_or3_b32 v3, v11, v3, v4
	v_add_u32_e32 v138, v3, v12
	v_lshlrev_b32_e32 v3, 5, v10
	s_waitcnt vmcnt(0)
	s_cmpk_lt_u32 s5, 0x100
	v_and_b32_e32 v3, 0x70000, v3
	s_cselect_b64 s[12:13], -1, 0
	v_or3_b32 v3, v11, v3, v4
	s_add_i32 s54, 0, 0x10000
	s_add_i32 s55, 0, 0x14000
	s_waitcnt lgkmcnt(0)
	s_ashr_i32 s53, s33, 31
	v_or_b32_e32 v147, s16, v13
	v_mov_b32_e32 v139, v135
	v_add_u32_e32 v140, v3, v12
	v_mov_b32_e32 v141, v135
	v_mov_b64_e32 v[142:143], 0x500
	v_mov_b64_e32 v[144:145], 0x4ff
	v_add_u32_e32 v148, s54, v146
	v_add_u32_e32 v149, s55, v146
	v_add_u32_e32 v150, 0, v2
	s_mov_b32 s56, 0x80000
	s_mov_b64 s[14:15], 0x90000
	s_mov_b32 s57, 0x90000
	s_mov_b64 s[16:17], 0xa0000
	s_mov_b32 s58, 0xa0000
	s_mov_b64 s[24:25], 0xb0000
	s_mov_b32 s59, 0xb0000
	s_barrier
	s_branch .LBB0_799

; #define PG8_STAGE(bufoff, gbase, voff) do { _Pragma("unroll") for (int _i = 0; _i < 2; ++_i) \
;         __builtin_amdgcn_global_load_lds((const unsigned*)((const char*)(gbase) + (voff)[_i]), (PG8_LAS unsigned*)(lds + (bufoff) + ldsw + _i * 8192), 16, 0, 0); } while (0)
; #define PG8_LDA(dst, b, h) do { _Pragma("unroll") for (int m = 0; m < 4; ++m) _Pragma("unroll") for (int k = 0; k < 2; ++k) dst[m][k] = *(const PG8_LAS bf16x8*)(lds + PG8_SA(b, h) + aoff + m * 2048 + k * 1024); } while (0)
; #define PG8_LDB(dst, b, h) do { _Pragma("unroll") for (int n = 0; n < 2; ++n) _Pragma("unroll") for (int k = 0; k < 2; ++k) dst[n][k] = *(const PG8_LAS bf16x8*)(lds + PG8_SB(b, h) + boff + n * 2048 + k * 1024); } while (0)
; #define PG8_WAIT_V(n) asm volatile("s_waitcnt vmcnt(" #n ")" ::: "memory")
; #define PG8_WAIT_L(n) asm volatile("s_waitcnt lgkmcnt(" #n ")" ::: "memory")
; #define PG8_BAR __builtin_amdgcn_s_barrier()
; template <class Epi, class Sched, bool ALIGN_EPI = false, bool SP2 = false>
; __device__ __forceinline__ void gemm_phase(PG8_LAS unsigned char* lds, const Gemm g, const Sched& S, const Epi& E) {
;     ...
;         const bool has_next = S.next(ui + 1, nxt);
;         const char* nA = has_next ? (const char*)g.A + (size_t)nxt.pm * tstepA : cA; const char* nB = has_next ? (const char*)g.Bt + (size_t)nxt.pn * tstepB : cB;
;         for (int t = 0; t < nt; t += 2) {
;             const bool last = (t == nt - 2);
;             const char* a1 = cA + (size_t)(t + 1) * kstep;
;             const char* a2 = last ? nA : cA + (size_t)(t + 2) * kstep; const char* b2 = last ? nB : cB + (size_t)(t + 2) * kstep;
;             const char* a3 = a2 + kstep; const char* b3 = b2 + kstep;
;             if (last && has_next) S.a_ready(nxt);
;             if constexpr (SP2) {
;             PG8_LDB(B0, 0, 0); PG8_LDB(B1, 0, 1); PG8_SCHED; PG8_LDA(At, 0, 0); PG8_STAGE(PG8_SA(1, 1), a1 + hstepA, voffA);
;             PG8_WAIT_V(8); PG8_WAIT_L(0); PG8_BAR; PG8_MMA(0, 0, At, B0); PG8_MMA(0, 1, At, B1); PG8_BAR; PG8_SCHED;
;     ...
; #pragma unroll
;         for (int a = 0; a < 2; ++a)
; #pragma unroll
;             for (int b = 0; b < 2; ++b)
; #pragma unroll
;                 for (int m = 0; m < 4; ++m)
; #pragma unroll
;                     for (int n = 0; n < 2; ++n) acc[a][b][m][n] = (f32x4){0.f, 0.f, 0.f, 0.f};
;         cur = nxt; cA = nA; cB = nB; ++ui;
.LBB0_801:
	s_ashr_i32 s31, s30, 31
	s_lshl_b64 s[34:35], s[30:31], 20
	s_add_u32 s34, s6, s34
	s_addc_u32 s35, s7, s35
	s_and_b64 s[36:37], s[4:5], exec
	s_cselect_b32 s31, s35, s39
	s_cselect_b32 s61, s34, s38
	s_ashr_i32 s29, s28, 31
	s_lshl_b64 s[36:37], s[28:29], 20
	s_add_u32 s36, s88, s36
	s_addc_u32 s37, s89, s37
	s_and_b64 s[42:43], s[4:5], exec
	s_cselect_b32 s29, s37, s41
	s_cselect_b32 s62, s36, s40
	s_add_u32 s38, s38, 0x80080
	s_addc_u32 s39, s39, 0
	s_add_u32 s63, s40, 0x100
	v_mov_b32_e32 v2, 0
	s_addc_u32 s64, s41, 0
	s_mov_b32 s65, -2
	v_mov_b32_e32 v3, v2
	v_mov_b32_e32 v4, v2
	v_mov_b32_e32 v5, v2
	v_mov_b32_e32 v6, v2
	v_mov_b32_e32 v7, v2
	v_mov_b32_e32 v8, v2
	v_mov_b32_e32 v9, v2
	v_mov_b32_e32 v10, v2
	v_mov_b32_e32 v11, v2
	v_mov_b32_e32 v12, v2
	v_mov_b32_e32 v13, v2
	v_mov_b32_e32 v14, v2
	v_mov_b32_e32 v15, v2
	v_mov_b32_e32 v16, v2
	v_mov_b32_e32 v17, v2
	v_mov_b32_e32 v26, v2
	v_mov_b32_e32 v27, v2
	v_mov_b32_e32 v28, v2
	v_mov_b32_e32 v29, v2
	v_mov_b32_e32 v30, v2
	v_mov_b32_e32 v31, v2
	v_mov_b32_e32 v32, v2
	v_mov_b32_e32 v33, v2
	v_mov_b32_e32 v42, v2
	v_mov_b32_e32 v43, v2
	v_mov_b32_e32 v44, v2
	v_mov_b32_e32 v45, v2
	v_mov_b32_e32 v46, v2
	v_mov_b32_e32 v47, v2
	v_mov_b32_e32 v48, v2
	v_mov_b32_e32 v49, v2
	v_mov_b32_e32 v18, v2
	v_mov_b32_e32 v19, v2
	v_mov_b32_e32 v20, v2
	v_mov_b32_e32 v21, v2
	v_mov_b32_e32 v22, v2
	v_mov_b32_e32 v23, v2
	v_mov_b32_e32 v24, v2
	v_mov_b32_e32 v25, v2
	v_mov_b32_e32 v34, v2
	v_mov_b32_e32 v35, v2
	v_mov_b32_e32 v36, v2
	v_mov_b32_e32 v37, v2
	v_mov_b32_e32 v38, v2
	v_mov_b32_e32 v39, v2
	v_mov_b32_e32 v40, v2
	v_mov_b32_e32 v41, v2
	v_mov_b32_e32 v50, v2
	v_mov_b32_e32 v51, v2
	v_mov_b32_e32 v52, v2
	v_mov_b32_e32 v53, v2
	v_mov_b32_e32 v54, v2
	v_mov_b32_e32 v55, v2
	v_mov_b32_e32 v56, v2
	v_mov_b32_e32 v57, v2
	v_mov_b32_e32 v58, v2
	v_mov_b32_e32 v59, v2
	v_mov_b32_e32 v60, v2
	v_mov_b32_e32 v61, v2
	v_mov_b32_e32 v62, v2
	v_mov_b32_e32 v63, v2
	v_mov_b32_e32 v64, v2
	v_mov_b32_e32 v65, v2
	v_mov_b32_e32 v66, v2
	v_mov_b32_e32 v67, v2
	v_mov_b32_e32 v68, v2
	v_mov_b32_e32 v69, v2
	v_mov_b32_e32 v70, v2
	v_mov_b32_e32 v71, v2
	v_mov_b32_e32 v72, v2
	v_mov_b32_e32 v73, v2
	v_mov_b32_e32 v74, v2
	v_mov_b32_e32 v75, v2
	v_mov_b32_e32 v76, v2
	v_mov_b32_e32 v77, v2
	v_mov_b32_e32 v78, v2
	v_mov_b32_e32 v79, v2
	v_mov_b32_e32 v80, v2
	v_mov_b32_e32 v81, v2
	v_mov_b32_e32 v90, v2
	v_mov_b32_e32 v91, v2
	v_mov_b32_e32 v92, v2
	v_mov_b32_e32 v93, v2
	v_mov_b32_e32 v94, v2
	v_mov_b32_e32 v95, v2
	v_mov_b32_e32 v96, v2
	v_mov_b32_e32 v97, v2
	v_mov_b32_e32 v106, v2
	v_mov_b32_e32 v107, v2
	v_mov_b32_e32 v108, v2
	v_mov_b32_e32 v109, v2
	v_mov_b32_e32 v110, v2
	v_mov_b32_e32 v111, v2
	v_mov_b32_e32 v112, v2
	v_mov_b32_e32 v113, v2
	v_mov_b32_e32 v82, v2
	v_mov_b32_e32 v83, v2
	v_mov_b32_e32 v84, v2
	v_mov_b32_e32 v85, v2
	v_mov_b32_e32 v86, v2
	v_mov_b32_e32 v87, v2
	v_mov_b32_e32 v88, v2
	v_mov_b32_e32 v89, v2
	v_mov_b32_e32 v98, v2
	v_mov_b32_e32 v99, v2
	v_mov_b32_e32 v100, v2
	v_mov_b32_e32 v101, v2
	v_mov_b32_e32 v102, v2
	v_mov_b32_e32 v103, v2
	v_mov_b32_e32 v104, v2
	v_mov_b32_e32 v105, v2
	v_mov_b32_e32 v114, v2
	v_mov_b32_e32 v115, v2
	v_mov_b32_e32 v116, v2
	v_mov_b32_e32 v117, v2
	v_mov_b32_e32 v118, v2
	v_mov_b32_e32 v119, v2
	v_mov_b32_e32 v120, v2
	v_mov_b32_e32 v121, v2
	v_mov_b32_e32 v122, v2
	v_mov_b32_e32 v123, v2
	v_mov_b32_e32 v124, v2
	v_mov_b32_e32 v125, v2
	v_mov_b32_e32 v126, v2
	v_mov_b32_e32 v127, v2
	v_mov_b32_e32 v128, v2
	v_mov_b32_e32 v129, v2
	ds_read_b128 v[152:155], v148
	ds_read_b128 v[156:159], v148 offset:1024
	ds_read_b128 v[160:163], v148 offset:2048
	ds_read_b128 v[164:167], v148 offset:3072
	ds_read_b128 v[168:171], v149
	ds_read_b128 v[172:175], v149 offset:1024
	ds_read_b128 v[176:179], v149 offset:2048
	ds_read_b128 v[180:183], v149 offset:3072
	s_add_u32 s40, s38, 0xfff80080
	s_addc_u32 s41, s39, -1
	s_cmp_eq_u32 s65, 28
	s_cselect_b32 s43, s31, s41
	s_cselect_b32 s42, s61, s40
	s_cselect_b32 s41, s29, s64
	s_cselect_b32 s40, s62, s63
	v_lshl_add_u64 v[218:219], s[38:39], 0, v[138:139]
	s_add_i32 m0, s27, 0xc000
	ds_read_b128 v[184:187], v150
	ds_read_b128 v[188:191], v150 offset:1024
	ds_read_b128 v[192:195], v150 offset:2048
	ds_read_b128 v[196:199], v150 offset:3072
	ds_read_b128 v[200:203], v150 offset:4096
	ds_read_b128 v[204:207], v150 offset:5120
	ds_read_b128 v[210:213], v150 offset:6144
	ds_read_b128 v[214:217], v150 offset:7168
	global_load_lds_dwordx4 v[218:219], off
	v_lshl_add_u64 v[218:219], s[38:39], 0, v[140:141]
	s_add_i32 m0, s27, 0xe000
	s_nop 0
	global_load_lds_dwordx4 v[218:219], off
	s_waitcnt vmcnt(24)
	s_waitcnt lgkmcnt(0)
	s_barrier
; #define PG8_STAGE(bufoff, gbase, voff) do { _Pragma("unroll") for (int _i = 0; _i < 2; ++_i) \
;         __builtin_amdgcn_global_load_lds((const unsigned*)((const char*)(gbase) + (voff)[_i]), (PG8_LAS unsigned*)(lds + (bufoff) + ldsw + _i * 8192), 16, 0, 0); } while (0)
; #define PG8_LDA(dst, b, h) do { _Pragma("unroll") for (int m = 0; m < 4; ++m) _Pragma("unroll") for (int k = 0; k < 2; ++k) dst[m][k] = *(const PG8_LAS bf16x8*)(lds + PG8_SA(b, h) + aoff + m * 2048 + k * 1024); } while (0)
; #define PG8_MMA(ai, bj, At, Bt) do { __builtin_amdgcn_s_setprio(1); _Pragma("unroll") for (int m = 0; m < 4; ++m) _Pragma("unroll") for (int n = 0; n < 2; ++n) _Pragma("unroll") for (int k = 0; k < 2; ++k) \
;         acc[ai][bj][m][n] = __builtin_amdgcn_mfma_f32_16x16x32_bf16(Bt[n][k], At[m][k], acc[ai][bj][m][n], 0, 0, 0); __builtin_amdgcn_s_setprio(0); } while (0)
; #define PG8_WAIT_V(n) asm volatile("s_waitcnt vmcnt(" #n ")" ::: "memory")
; #define PG8_WAIT_L(n) asm volatile("s_waitcnt lgkmcnt(" #n ")" ::: "memory")
; #define PG8_BAR __builtin_amdgcn_s_barrier()
; #define PG8_SCHED __builtin_amdgcn_sched_barrier(0)
; template <class Epi, class Sched, bool ALIGN_EPI = false, bool SP2 = false>
; __device__ __forceinline__ void gemm_phase(PG8_LAS unsigned char* lds, const Gemm g, const Sched& S, const Epi& E) {
;     ...
;             PG8_WAIT_V(8); PG8_WAIT_L(0); PG8_BAR; PG8_MMA(0, 0, At, B0); PG8_MMA(0, 1, At, B1); PG8_BAR; PG8_SCHED;
;             PG8_LDA(At, 0, 1); PG8_STAGE(PG8_SB(0, 0), b2, voffB); PG8_STAGE(PG8_SB(0, 1), b2 + hstepB, voffB); PG8_STAGE(PG8_SA(0, 0), a2, voffA);
;             PG8_WAIT_V(8); PG8_WAIT_L(0); PG8_BAR; PG8_MMA(1, 0, At, B0); PG8_MMA(1, 1, At, B1); PG8_BAR; PG8_SCHED;
	s_setprio 1
	s_waitcnt lgkmcnt(0)
	v_mfma_f32_16x16x32_bf16 v[126:129], v[152:155], v[184:187], v[126:129]
	v_mfma_f32_16x16x32_bf16 v[122:125], v[160:163], v[184:187], v[122:125]
	v_mfma_f32_16x16x32_bf16 v[118:121], v[152:155], v[192:195], v[118:121]
	v_mfma_f32_16x16x32_bf16 v[114:117], v[160:163], v[192:195], v[114:117]
	v_mfma_f32_16x16x32_bf16 v[102:105], v[152:155], v[200:203], v[102:105]
	v_mfma_f32_16x16x32_bf16 v[98:101], v[160:163], v[200:203], v[98:101]
	v_mfma_f32_16x16x32_bf16 v[86:89], v[152:155], v[210:213], v[86:89]
	v_mfma_f32_16x16x32_bf16 v[82:85], v[160:163], v[210:213], v[82:85]
	v_mfma_f32_16x16x32_bf16 v[126:129], v[156:159], v[188:191], v[126:129]
	v_mfma_f32_16x16x32_bf16 v[122:125], v[164:167], v[188:191], v[122:125]
	v_mfma_f32_16x16x32_bf16 v[118:121], v[156:159], v[196:199], v[118:121]
	v_mfma_f32_16x16x32_bf16 v[114:117], v[164:167], v[196:199], v[114:117]
	v_mfma_f32_16x16x32_bf16 v[102:105], v[156:159], v[204:207], v[102:105]
	v_mfma_f32_16x16x32_bf16 v[98:101], v[164:167], v[204:207], v[98:101]
	v_mfma_f32_16x16x32_bf16 v[86:89], v[156:159], v[214:217], v[86:89]
	v_mfma_f32_16x16x32_bf16 v[82:85], v[164:167], v[214:217], v[82:85]
	s_setprio 0
	s_setprio 1
	v_mfma_f32_16x16x32_bf16 v[110:113], v[168:171], v[184:187], v[110:113]
	v_mfma_f32_16x16x32_bf16 v[106:109], v[176:179], v[184:187], v[106:109]
	v_mfma_f32_16x16x32_bf16 v[94:97], v[168:171], v[192:195], v[94:97]
	v_mfma_f32_16x16x32_bf16 v[90:93], v[176:179], v[192:195], v[90:93]
	v_mfma_f32_16x16x32_bf16 v[78:81], v[168:171], v[200:203], v[78:81]
	v_mfma_f32_16x16x32_bf16 v[74:77], v[176:179], v[200:203], v[74:77]
	v_mfma_f32_16x16x32_bf16 v[70:73], v[168:171], v[210:213], v[70:73]
	v_mfma_f32_16x16x32_bf16 v[66:69], v[176:179], v[210:213], v[66:69]
	v_mfma_f32_16x16x32_bf16 v[110:113], v[172:175], v[188:191], v[110:113]
	v_mfma_f32_16x16x32_bf16 v[106:109], v[180:183], v[188:191], v[106:109]
	v_mfma_f32_16x16x32_bf16 v[94:97], v[172:175], v[196:199], v[94:97]
	v_mfma_f32_16x16x32_bf16 v[90:93], v[180:183], v[196:199], v[90:93]
	v_mfma_f32_16x16x32_bf16 v[78:81], v[172:175], v[204:207], v[78:81]
	v_mfma_f32_16x16x32_bf16 v[74:77], v[180:183], v[204:207], v[74:77]
	v_mfma_f32_16x16x32_bf16 v[70:73], v[172:175], v[214:217], v[70:73]
	v_mfma_f32_16x16x32_bf16 v[66:69], v[180:183], v[214:217], v[66:69]
	s_setprio 0
	s_barrier
	s_add_i32 s66, s54, s44
	v_lshl_add_u64 v[218:219], s[40:41], 0, v[134:135]
	s_mov_b32 m0, s66
	ds_read_b128 v[184:187], v150 offset:16384
	ds_read_b128 v[188:191], v150 offset:17408
	ds_read_b128 v[192:195], v150 offset:18432
	ds_read_b128 v[196:199], v150 offset:19456
	ds_read_b128 v[200:203], v150 offset:20480
	ds_read_b128 v[204:207], v150 offset:21504
	ds_read_b128 v[210:213], v150 offset:22528
	ds_read_b128 v[214:217], v150 offset:23552
	global_load_lds_dwordx4 v[218:219], off
	s_add_i32 m0, s66, 0x2000
	s_add_u32 s66, s40, 0x80000
	v_lshl_add_u64 v[220:221], s[40:41], 0, v[130:131]
	s_addc_u32 s67, s41, 0
	s_add_i32 s68, s55, s44
	global_load_lds_dwordx4 v[220:221], off
	v_lshl_add_u64 v[222:223], s[66:67], 0, v[134:135]
	s_mov_b32 m0, s68
	v_lshl_add_u64 v[224:225], s[42:43], 0, v[132:133]
	global_load_lds_dwordx4 v[222:223], off
	v_lshl_add_u64 v[222:223], s[66:67], 0, v[130:131]
	s_add_i32 m0, s68, 0x2000
	s_nop 0
	global_load_lds_dwordx4 v[222:223], off
	v_lshl_add_u64 v[222:223], s[42:43], 0, v[136:137]
	s_mov_b32 m0, s27
	s_nop 0
	global_load_lds_dwordx4 v[222:223], off
	s_mov_b32 m0, s47
	s_nop 0
	global_load_lds_dwordx4 v[224:225], off
	s_waitcnt vmcnt(24)
	s_waitcnt lgkmcnt(0)
	s_barrier
	s_setprio 1
	s_waitcnt lgkmcnt(0)
	v_mfma_f32_16x16x32_bf16 v[62:65], v[152:155], v[184:187], v[62:65]
	v_mfma_f32_16x16x32_bf16 v[58:61], v[160:163], v[184:187], v[58:61]
	v_mfma_f32_16x16x32_bf16 v[54:57], v[152:155], v[192:195], v[54:57]
	v_mfma_f32_16x16x32_bf16 v[50:53], v[160:163], v[192:195], v[50:53]
	v_mfma_f32_16x16x32_bf16 v[38:41], v[152:155], v[200:203], v[38:41]
	v_mfma_f32_16x16x32_bf16 v[34:37], v[160:163], v[200:203], v[34:37]
	v_mfma_f32_16x16x32_bf16 v[22:25], v[152:155], v[210:213], v[22:25]
	v_mfma_f32_16x16x32_bf16 v[18:21], v[160:163], v[210:213], v[18:21]
	v_mfma_f32_16x16x32_bf16 v[62:65], v[156:159], v[188:191], v[62:65]
	v_mfma_f32_16x16x32_bf16 v[58:61], v[164:167], v[188:191], v[58:61]
	v_mfma_f32_16x16x32_bf16 v[54:57], v[156:159], v[196:199], v[54:57]
	v_mfma_f32_16x16x32_bf16 v[50:53], v[164:167], v[196:199], v[50:53]
	v_mfma_f32_16x16x32_bf16 v[38:41], v[156:159], v[204:207], v[38:41]
	v_mfma_f32_16x16x32_bf16 v[34:37], v[164:167], v[204:207], v[34:37]
	v_mfma_f32_16x16x32_bf16 v[22:25], v[156:159], v[214:217], v[22:25]
	v_mfma_f32_16x16x32_bf16 v[18:21], v[164:167], v[214:217], v[18:21]
	s_setprio 0
	s_setprio 1
	v_mfma_f32_16x16x32_bf16 v[46:49], v[168:171], v[184:187], v[46:49]
	v_mfma_f32_16x16x32_bf16 v[42:45], v[176:179], v[184:187], v[42:45]
	v_mfma_f32_16x16x32_bf16 v[30:33], v[168:171], v[192:195], v[30:33]
	v_mfma_f32_16x16x32_bf16 v[26:29], v[176:179], v[192:195], v[26:29]
	v_mfma_f32_16x16x32_bf16 v[14:17], v[168:171], v[200:203], v[14:17]
	v_mfma_f32_16x16x32_bf16 v[10:13], v[176:179], v[200:203], v[10:13]
	v_mfma_f32_16x16x32_bf16 v[6:9], v[168:171], v[210:213], v[6:9]
	v_mfma_f32_16x16x32_bf16 v[2:5], v[176:179], v[210:213], v[2:5]
	v_mfma_f32_16x16x32_bf16 v[46:49], v[172:175], v[188:191], v[46:49]
	v_mfma_f32_16x16x32_bf16 v[42:45], v[180:183], v[188:191], v[42:45]
	v_mfma_f32_16x16x32_bf16 v[30:33], v[172:175], v[196:199], v[30:33]
	v_mfma_f32_16x16x32_bf16 v[26:29], v[180:183], v[196:199], v[26:29]
	v_mfma_f32_16x16x32_bf16 v[14:17], v[172:175], v[204:207], v[14:17]
	v_mfma_f32_16x16x32_bf16 v[10:13], v[180:183], v[204:207], v[10:13]
	v_mfma_f32_16x16x32_bf16 v[6:9], v[172:175], v[214:217], v[6:9]
	v_mfma_f32_16x16x32_bf16 v[2:5], v[180:183], v[214:217], v[2:5]
	s_setprio 0
	s_barrier
; #define PG8_STAGE(bufoff, gbase, voff) do { _Pragma("unroll") for (int _i = 0; _i < 2; ++_i) \
;         __builtin_amdgcn_global_load_lds((const unsigned*)((const char*)(gbase) + (voff)[_i]), (PG8_LAS unsigned*)(lds + (bufoff) + ldsw + _i * 8192), 16, 0, 0); } while (0)
; #define PG8_LDA(dst, b, h) do { _Pragma("unroll") for (int m = 0; m < 4; ++m) _Pragma("unroll") for (int k = 0; k < 2; ++k) dst[m][k] = *(const PG8_LAS bf16x8*)(lds + PG8_SA(b, h) + aoff + m * 2048 + k * 1024); } while (0)
; #define PG8_LDB(dst, b, h) do { _Pragma("unroll") for (int n = 0; n < 2; ++n) _Pragma("unroll") for (int k = 0; k < 2; ++k) dst[n][k] = *(const PG8_LAS bf16x8*)(lds + PG8_SB(b, h) + boff + n * 2048 + k * 1024); } while (0)
; #define PG8_MMA(ai, bj, At, Bt) do { __builtin_amdgcn_s_setprio(1); _Pragma("unroll") for (int m = 0; m < 4; ++m) _Pragma("unroll") for (int n = 0; n < 2; ++n) _Pragma("unroll") for (int k = 0; k < 2; ++k) \
;         acc[ai][bj][m][n] = __builtin_amdgcn_mfma_f32_16x16x32_bf16(Bt[n][k], At[m][k], acc[ai][bj][m][n], 0, 0, 0); __builtin_amdgcn_s_setprio(0); } while (0)
; #define PG8_WAIT_V(n) asm volatile("s_waitcnt vmcnt(" #n ")" ::: "memory")
; #define PG8_WAIT_L(n) asm volatile("s_waitcnt lgkmcnt(" #n ")" ::: "memory")
; #define PG8_BAR __builtin_amdgcn_s_barrier()
; #define PG8_SCHED __builtin_amdgcn_sched_barrier(0)
; template <class Epi, class Sched, bool ALIGN_EPI = false, bool SP2 = false>
; __device__ __forceinline__ void gemm_phase(PG8_LAS unsigned char* lds, const Gemm g, const Sched& S, const Epi& E) {
;     ...
;             PG8_LDB(B0, 1, 0); PG8_LDB(B1, 1, 1); PG8_SCHED; PG8_LDA(At, 1, 0); PG8_STAGE(PG8_SA(0, 1), a2 + hstepA, voffA);
;             PG8_WAIT_V(8); PG8_WAIT_L(0); PG8_BAR; PG8_MMA(0, 0, At, B0); PG8_MMA(0, 1, At, B1); PG8_BAR; PG8_SCHED;
	s_add_i32 s66, 0, 0x18000
	v_add_u32_e32 v151, s66, v146
	s_add_i32 s67, 0, 0x1c000
	ds_read_b128 v[152:155], v151
	ds_read_b128 v[156:159], v151 offset:1024
	ds_read_b128 v[160:163], v151 offset:2048
	ds_read_b128 v[164:167], v151 offset:3072
	v_add_u32_e32 v151, s67, v146
	ds_read_b128 v[168:171], v151
	ds_read_b128 v[172:175], v151 offset:1024
	ds_read_b128 v[176:179], v151 offset:2048
	ds_read_b128 v[180:183], v151 offset:3072
	s_add_u32 s42, s42, 0x80000
	s_addc_u32 s43, s43, 0
	s_mov_b32 m0, s48
	v_lshl_add_u64 v[226:227], s[42:43], 0, v[136:137]
	ds_read_b128 v[184:187], v150 offset:32768
	ds_read_b128 v[188:191], v150 offset:33792
	ds_read_b128 v[192:195], v150 offset:34816
	ds_read_b128 v[196:199], v150 offset:35840
	ds_read_b128 v[200:203], v150 offset:36864
	ds_read_b128 v[204:207], v150 offset:37888
	ds_read_b128 v[210:213], v150 offset:38912
	ds_read_b128 v[214:217], v150 offset:39936
	global_load_lds_dwordx4 v[226:227], off
	v_lshl_add_u64 v[226:227], s[42:43], 0, v[132:133]
	s_mov_b32 m0, s49
	s_nop 0
	global_load_lds_dwordx4 v[226:227], off
	s_waitcnt vmcnt(8)
	s_waitcnt lgkmcnt(0)
	s_barrier
	s_setprio 1
	s_waitcnt lgkmcnt(0)
	v_mfma_f32_16x16x32_bf16 v[126:129], v[152:155], v[184:187], v[126:129]
	v_mfma_f32_16x16x32_bf16 v[122:125], v[160:163], v[184:187], v[122:125]
	v_mfma_f32_16x16x32_bf16 v[118:121], v[152:155], v[192:195], v[118:121]
	v_mfma_f32_16x16x32_bf16 v[114:117], v[160:163], v[192:195], v[114:117]
	v_mfma_f32_16x16x32_bf16 v[102:105], v[152:155], v[200:203], v[102:105]
	v_mfma_f32_16x16x32_bf16 v[98:101], v[160:163], v[200:203], v[98:101]
	v_mfma_f32_16x16x32_bf16 v[86:89], v[152:155], v[210:213], v[86:89]
	v_mfma_f32_16x16x32_bf16 v[82:85], v[160:163], v[210:213], v[82:85]
	v_mfma_f32_16x16x32_bf16 v[126:129], v[156:159], v[188:191], v[126:129]
	v_mfma_f32_16x16x32_bf16 v[122:125], v[164:167], v[188:191], v[122:125]
	v_mfma_f32_16x16x32_bf16 v[118:121], v[156:159], v[196:199], v[118:121]
	v_mfma_f32_16x16x32_bf16 v[114:117], v[164:167], v[196:199], v[114:117]
	v_mfma_f32_16x16x32_bf16 v[102:105], v[156:159], v[204:207], v[102:105]
	v_mfma_f32_16x16x32_bf16 v[98:101], v[164:167], v[204:207], v[98:101]
	v_mfma_f32_16x16x32_bf16 v[86:89], v[156:159], v[214:217], v[86:89]
	v_mfma_f32_16x16x32_bf16 v[82:85], v[164:167], v[214:217], v[82:85]
	s_setprio 0
	s_setprio 1
	v_mfma_f32_16x16x32_bf16 v[110:113], v[168:171], v[184:187], v[110:113]
	v_mfma_f32_16x16x32_bf16 v[106:109], v[176:179], v[184:187], v[106:109]
	v_mfma_f32_16x16x32_bf16 v[94:97], v[168:171], v[192:195], v[94:97]
	v_mfma_f32_16x16x32_bf16 v[90:93], v[176:179], v[192:195], v[90:93]
	v_mfma_f32_16x16x32_bf16 v[78:81], v[168:171], v[200:203], v[78:81]
	v_mfma_f32_16x16x32_bf16 v[74:77], v[176:179], v[200:203], v[74:77]
	v_mfma_f32_16x16x32_bf16 v[70:73], v[168:171], v[210:213], v[70:73]
	v_mfma_f32_16x16x32_bf16 v[66:69], v[176:179], v[210:213], v[66:69]
	v_mfma_f32_16x16x32_bf16 v[110:113], v[172:175], v[188:191], v[110:113]
	v_mfma_f32_16x16x32_bf16 v[106:109], v[180:183], v[188:191], v[106:109]
	v_mfma_f32_16x16x32_bf16 v[94:97], v[172:175], v[196:199], v[94:97]
	v_mfma_f32_16x16x32_bf16 v[90:93], v[180:183], v[196:199], v[90:93]
	v_mfma_f32_16x16x32_bf16 v[78:81], v[172:175], v[204:207], v[78:81]
	v_mfma_f32_16x16x32_bf16 v[74:77], v[180:183], v[204:207], v[74:77]
	v_mfma_f32_16x16x32_bf16 v[70:73], v[172:175], v[214:217], v[70:73]
	v_mfma_f32_16x16x32_bf16 v[66:69], v[180:183], v[214:217], v[66:69]
	s_setprio 0
	s_barrier
; #define PG8_STAGE(bufoff, gbase, voff) do { _Pragma("unroll") for (int _i = 0; _i < 2; ++_i) \
;         __builtin_amdgcn_global_load_lds((const unsigned*)((const char*)(gbase) + (voff)[_i]), (PG8_LAS unsigned*)(lds + (bufoff) + ldsw + _i * 8192), 16, 0, 0); } while (0)
; #define PG8_LDA(dst, b, h) do { _Pragma("unroll") for (int m = 0; m < 4; ++m) _Pragma("unroll") for (int k = 0; k < 2; ++k) dst[m][k] = *(const PG8_LAS bf16x8*)(lds + PG8_SA(b, h) + aoff + m * 2048 + k * 1024); } while (0)
; #define PG8_MMA(ai, bj, At, Bt) do { __builtin_amdgcn_s_setprio(1); _Pragma("unroll") for (int m = 0; m < 4; ++m) _Pragma("unroll") for (int n = 0; n < 2; ++n) _Pragma("unroll") for (int k = 0; k < 2; ++k) \
;         acc[ai][bj][m][n] = __builtin_amdgcn_mfma_f32_16x16x32_bf16(Bt[n][k], At[m][k], acc[ai][bj][m][n], 0, 0, 0); __builtin_amdgcn_s_setprio(0); } while (0)
; #define PG8_WAIT_V(n) asm volatile("s_waitcnt vmcnt(" #n ")" ::: "memory")
; #define PG8_WAIT_L(n) asm volatile("s_waitcnt lgkmcnt(" #n ")" ::: "memory")
; #define PG8_BAR __builtin_amdgcn_s_barrier()
; #define PG8_SCHED __builtin_amdgcn_sched_barrier(0)
; template <class Epi, class Sched, bool ALIGN_EPI = false, bool SP2 = false>
; __device__ __forceinline__ void gemm_phase(PG8_LAS unsigned char* lds, const Gemm g, const Sched& S, const Epi& E) {
;     ...
;         for (int t = 0; t < nt; t += 2) {
;             const bool last = (t == nt - 2);
;             const char* a1 = cA + (size_t)(t + 1) * kstep;
;             const char* a2 = last ? nA : cA + (size_t)(t + 2) * kstep; const char* b2 = last ? nB : cB + (size_t)(t + 2) * kstep;
;             const char* a3 = a2 + kstep; const char* b3 = b2 + kstep;
;     ...
;             PG8_LDA(At, 1, 1); PG8_STAGE(PG8_SB(1, 0), b3, voffB); PG8_STAGE(PG8_SB(1, 1), b3 + hstepB, voffB); PG8_STAGE(PG8_SA(1, 0), a3, voffA);
;             PG8_WAIT_V(8); PG8_WAIT_L(0); PG8_BAR; PG8_MMA(1, 0, At, B0); PG8_MMA(1, 1, At, B1); PG8_BAR; PG8_SCHED;
	s_add_i32 s42, s66, s44
	v_lshl_add_u64 v[218:219], v[218:219], 0, s[10:11]
	s_mov_b32 m0, s42
	ds_read_b128 v[184:187], v150 offset:49152
	ds_read_b128 v[188:191], v150 offset:50176
	ds_read_b128 v[192:195], v150 offset:51200
	ds_read_b128 v[196:199], v150 offset:52224
	ds_read_b128 v[200:203], v150 offset:53248
	ds_read_b128 v[204:207], v150 offset:54272
	ds_read_b128 v[210:213], v150 offset:55296
	ds_read_b128 v[214:217], v150 offset:56320
	global_load_lds_dwordx4 v[218:219], off
	s_add_i32 m0, s42, 0x2000
	s_add_u32 s40, s40, 0x80080
	v_lshl_add_u64 v[218:219], v[220:221], 0, s[10:11]
	s_addc_u32 s41, s41, 0
	s_add_i32 s42, s67, s44
	global_load_lds_dwordx4 v[218:219], off
	v_lshl_add_u64 v[218:219], s[40:41], 0, v[134:135]
	s_mov_b32 m0, s42
	s_nop 0
	global_load_lds_dwordx4 v[218:219], off
	v_lshl_add_u64 v[218:219], s[40:41], 0, v[130:131]
	s_add_i32 m0, s42, 0x2000
	s_nop 0
	global_load_lds_dwordx4 v[218:219], off
	v_lshl_add_u64 v[218:219], v[222:223], 0, s[10:11]
	s_mov_b32 m0, s51
	s_nop 0
	global_load_lds_dwordx4 v[218:219], off
	v_lshl_add_u64 v[218:219], v[224:225], 0, s[10:11]
	s_mov_b32 m0, s52
	s_nop 0
	global_load_lds_dwordx4 v[218:219], off
	s_waitcnt vmcnt(8)
	s_waitcnt lgkmcnt(0)
	s_barrier
	s_setprio 1
	s_waitcnt lgkmcnt(0)
	v_mfma_f32_16x16x32_bf16 v[62:65], v[152:155], v[184:187], v[62:65]
	v_mfma_f32_16x16x32_bf16 v[58:61], v[160:163], v[184:187], v[58:61]
	v_mfma_f32_16x16x32_bf16 v[54:57], v[152:155], v[192:195], v[54:57]
	v_mfma_f32_16x16x32_bf16 v[50:53], v[160:163], v[192:195], v[50:53]
	v_mfma_f32_16x16x32_bf16 v[38:41], v[152:155], v[200:203], v[38:41]
	v_mfma_f32_16x16x32_bf16 v[34:37], v[160:163], v[200:203], v[34:37]
	v_mfma_f32_16x16x32_bf16 v[22:25], v[152:155], v[210:213], v[22:25]
	v_mfma_f32_16x16x32_bf16 v[18:21], v[160:163], v[210:213], v[18:21]
	v_mfma_f32_16x16x32_bf16 v[62:65], v[156:159], v[188:191], v[62:65]
	v_mfma_f32_16x16x32_bf16 v[58:61], v[164:167], v[188:191], v[58:61]
	v_mfma_f32_16x16x32_bf16 v[54:57], v[156:159], v[196:199], v[54:57]
	v_mfma_f32_16x16x32_bf16 v[50:53], v[164:167], v[196:199], v[50:53]
	v_mfma_f32_16x16x32_bf16 v[38:41], v[156:159], v[204:207], v[38:41]
	v_mfma_f32_16x16x32_bf16 v[34:37], v[164:167], v[204:207], v[34:37]
	v_mfma_f32_16x16x32_bf16 v[22:25], v[156:159], v[214:217], v[22:25]
	v_mfma_f32_16x16x32_bf16 v[18:21], v[164:167], v[214:217], v[18:21]
	s_setprio 0
	s_setprio 1
	v_mfma_f32_16x16x32_bf16 v[46:49], v[168:171], v[184:187], v[46:49]
	v_mfma_f32_16x16x32_bf16 v[42:45], v[176:179], v[184:187], v[42:45]
	v_mfma_f32_16x16x32_bf16 v[30:33], v[168:171], v[192:195], v[30:33]
	v_mfma_f32_16x16x32_bf16 v[26:29], v[176:179], v[192:195], v[26:29]
	v_mfma_f32_16x16x32_bf16 v[14:17], v[168:171], v[200:203], v[14:17]
	v_mfma_f32_16x16x32_bf16 v[10:13], v[176:179], v[200:203], v[10:13]
	v_mfma_f32_16x16x32_bf16 v[6:9], v[168:171], v[210:213], v[6:9]
	v_mfma_f32_16x16x32_bf16 v[2:5], v[176:179], v[210:213], v[2:5]
	v_mfma_f32_16x16x32_bf16 v[46:49], v[172:175], v[188:191], v[46:49]
	v_mfma_f32_16x16x32_bf16 v[42:45], v[180:183], v[188:191], v[42:45]
	v_mfma_f32_16x16x32_bf16 v[30:33], v[172:175], v[196:199], v[30:33]
	v_mfma_f32_16x16x32_bf16 v[26:29], v[180:183], v[196:199], v[26:29]
	v_mfma_f32_16x16x32_bf16 v[14:17], v[172:175], v[204:207], v[14:17]
	v_mfma_f32_16x16x32_bf16 v[10:13], v[180:183], v[204:207], v[10:13]
	v_mfma_f32_16x16x32_bf16 v[6:9], v[172:175], v[214:217], v[6:9]
	v_mfma_f32_16x16x32_bf16 v[2:5], v[180:183], v[214:217], v[2:5]
	s_setprio 0
	s_barrier
	s_add_i32 s65, s65, 2
	s_add_u32 s38, s38, 0x100
	s_addc_u32 s39, s39, 0
	s_add_u32 s63, s63, 0x100
	s_addc_u32 s64, s64, 0
	s_cmp_gt_u32 s65, 29
	s_cbranch_scc1 .Lpeel_exit_6
	.p2align 6

; #define PG8_BAR __builtin_amdgcn_s_barrier()
; template <class Epi, class Sched, bool ALIGN_EPI = false, bool SP2 = false>
; __device__ __forceinline__ void gemm_phase(PG8_LAS unsigned char* lds, const Gemm g, const Sched& S, const Epi& E) {
;     ...
;         if constexpr (ALIGN_EPI) { if (wr == 0) PG8_BAR; }
;         if constexpr (!Epi::AFTER_DRAIN) { E(acc, cur, wr, wc, fr, fq); S.done(cur); }
.Lpeel_exit_6:
	s_and_b64 vcc, exec, s[12:13]
	s_cbranch_vccz .LBB0_805
	s_barrier

; #define PG8_STAGE(bufoff, gbase, voff) do { _Pragma("unroll") for (int _i = 0; _i < 2; ++_i) \
;         __builtin_amdgcn_global_load_lds((const unsigned*)((const char*)(gbase) + (voff)[_i]), (PG8_LAS unsigned*)(lds + (bufoff) + ldsw + _i * 8192), 16, 0, 0); } while (0)
; #define PG8_WAIT_V(n) asm volatile("s_waitcnt vmcnt(" #n ")" ::: "memory")
; #define PG8_BAR __builtin_amdgcn_s_barrier()
; template <class Epi, class Sched, bool ALIGN_EPI = false, bool SP2 = false>
; __device__ __forceinline__ void gemm_phase(PG8_LAS unsigned char* lds, const Gemm g, const Sched& S, const Epi& E) {
;     const int tid = threadIdx.x, wid = __builtin_amdgcn_readfirstlane(tid >> 6), lane = tid & 63, wr = wid >> 2, wc = wid & 3, fr = lane & 15, fq = lane >> 4;
;     const int K = g.K, nt = K / BK;
;     unsigned voffA[2], voffB[2];
; #pragma unroll
;     for (int i = 0; i < 2; ++i) { int R, C; stage_rc(tid * 16 + i * 8192, R, C); const int Rb = Epi::PERM ? ((R & ~31) + perm32(R & 31)) : R;
;         voffA[i] = (unsigned)(R * g.lda + C) * 2u; voffB[i] = (unsigned)(Rb * g.ldb + C) * 2u; }
;     const size_t kstep = (size_t)(BK * 2);
;     const size_t hstepA = (size_t)HALF * g.lda * 2, hstepB = (size_t)HALF * g.ldb * 2;
;     const size_t tstepA = 2 * hstepA, tstepB = 2 * hstepB;
;     const unsigned ldsw = (unsigned)wid * 1024u;
;     const int aoff = lds_byte(wr * 64 + fr, fq * 8), boff = lds_byte(wc * 32 + fr, fq * 8);
;     ...
;         PG8_WAIT_V(2); PG8_BAR;
;         PG8_STAGE(PG8_SB(1, 0), cB + kstep, voffB); PG8_STAGE(PG8_SA(1, 0), cA + kstep, voffA); PG8_STAGE(PG8_SB(1, 1), cB + hstepB + kstep, voffB);
;         PG8_WAIT_V(6); PG8_BAR;
.LBB0_934:
	s_lshl_b32 s2, s2, 5
	s_and_b32 s12, s2, 0x60
	s_mov_b64 s[2:3], 0x80
	s_add_i32 m0, s25, 0x18000
	v_lshl_add_u64 v[8:9], v[8:9], 0, s[2:3]
	s_lshl_b32 s9, s8, 13
	s_lshl_b32 s13, s12, 7
	s_waitcnt vmcnt(2)
	s_barrier
	global_load_lds_dwordx4 v[8:9], off
	v_lshl_add_u64 v[6:7], v[6:7], 0, s[2:3]
	s_add_i32 m0, s25, 0x1a000
	s_add_i32 s41, s25, 0x8000
	s_add_i32 s42, s25, 0xa000
	global_load_lds_dwordx4 v[6:7], off
	v_lshl_add_u64 v[2:3], v[2:3], 0, s[2:3]
	s_mov_b32 m0, s41
	s_add_u32 s10, s28, 0x80080
	global_load_lds_dwordx4 v[2:3], off
	v_lshl_add_u64 v[2:3], v[4:5], 0, s[2:3]
	s_mov_b32 m0, s42
	s_addc_u32 s11, s29, 0
	global_load_lds_dwordx4 v[2:3], off
	s_add_i32 m0, s25, 0x1c000
	v_lshl_add_u64 v[2:3], s[10:11], 0, v[134:135]
	global_load_lds_dwordx4 v[2:3], off
	v_lshl_add_u64 v[2:3], s[10:11], 0, v[130:131]
	s_add_i32 m0, s25, 0x1e000
	s_sext_i32_i16 s47, s4
	global_load_lds_dwordx4 v[2:3], off
	v_and_b32_e32 v2, 15, v0
	v_lshlrev_b32_e32 v3, 1, v13
	v_lshlrev_b32_e32 v4, 2, v0
	v_lshlrev_b32_e32 v5, 6, v0
	s_movk_i32 s4, 0x3c0
	v_lshl_or_b32 v1, s8, 6, v2
	v_lshl_or_b32 v2, v2, 6, v3
	v_and_b32_e32 v4, 32, v4
	v_and_or_b32 v3, v5, s4, v3
	v_bitop3_b32 v148, s13, v3, v4 bitop3:0xf6
	v_lshlrev_b32_e32 v3, 9, v0
	v_bitop3_b32 v2, v2, s9, v4 bitop3:0xde
	v_and_b32_e32 v3, 0x30000, v3
	v_lshlrev_b32_e32 v4, 12, v14
	v_or3_b32 v3, v11, v3, v4
	v_add_u32_e32 v138, v3, v12
	v_lshlrev_b32_e32 v3, 5, v10
	s_waitcnt vmcnt(0)
	s_cmpk_lt_u32 s5, 0x100
	v_and_b32_e32 v3, 0x70000, v3
	s_cselect_b64 s[8:9], -1, 0
	v_or3_b32 v3, v11, v3, v4
	s_add_i32 s44, 0, 0x10000
	s_add_i32 s45, 0, 0x14000
	s_waitcnt lgkmcnt(0)
	s_ashr_i32 s43, s33, 31
	v_or_b32_e32 v149, s12, v13
	v_mov_b32_e32 v139, v135
	v_add_u32_e32 v140, v3, v12
	v_mov_b32_e32 v141, v135
	v_mov_b64_e32 v[142:143], 0x1b80
	v_mov_b64_e32 v[144:145], 0x1b7f
	v_add_u32_e32 v150, s44, v148
	v_add_u32_e32 v151, s45, v148
	v_add_u32_e32 v152, 0, v2
	s_movk_i32 s46, 0x2c00
	s_barrier
	s_branch .LBB0_937

; #define PG8_STAGE(bufoff, gbase, voff) do { _Pragma("unroll") for (int _i = 0; _i < 2; ++_i) \
;         __builtin_amdgcn_global_load_lds((const unsigned*)((const char*)(gbase) + (voff)[_i]), (PG8_LAS unsigned*)(lds + (bufoff) + ldsw + _i * 8192), 16, 0, 0); } while (0)
; #define PG8_LDA(dst, b, h) do { _Pragma("unroll") for (int m = 0; m < 4; ++m) _Pragma("unroll") for (int k = 0; k < 2; ++k) dst[m][k] = *(const PG8_LAS bf16x8*)(lds + PG8_SA(b, h) + aoff + m * 2048 + k * 1024); } while (0)
; #define PG8_LDB(dst, b, h) do { _Pragma("unroll") for (int n = 0; n < 2; ++n) _Pragma("unroll") for (int k = 0; k < 2; ++k) dst[n][k] = *(const PG8_LAS bf16x8*)(lds + PG8_SB(b, h) + boff + n * 2048 + k * 1024); } while (0)
; #define PG8_WAIT_V(n) asm volatile("s_waitcnt vmcnt(" #n ")" ::: "memory")
; #define PG8_WAIT_L(n) asm volatile("s_waitcnt lgkmcnt(" #n ")" ::: "memory")
; #define PG8_BAR __builtin_amdgcn_s_barrier()
; template <class Epi, class Sched, bool ALIGN_EPI = false, bool SP2 = false>
; __device__ __forceinline__ void gemm_phase(PG8_LAS unsigned char* lds, const Gemm g, const Sched& S, const Epi& E) {
;     ...
;         const bool has_next = S.next(ui + 1, nxt);
;         const char* nA = has_next ? (const char*)g.A + (size_t)nxt.pm * tstepA : cA; const char* nB = has_next ? (const char*)g.Bt + (size_t)nxt.pn * tstepB : cB;
;         for (int t = 0; t < nt; t += 2) {
;             const bool last = (t == nt - 2);
;             const char* a1 = cA + (size_t)(t + 1) * kstep;
;             const char* a2 = last ? nA : cA + (size_t)(t + 2) * kstep; const char* b2 = last ? nB : cB + (size_t)(t + 2) * kstep;
;             const char* a3 = a2 + kstep; const char* b3 = b2 + kstep;
;             if (last && has_next) S.a_ready(nxt);
;             if constexpr (SP2) {
;             PG8_LDB(B0, 0, 0); PG8_LDB(B1, 0, 1); PG8_SCHED; PG8_LDA(At, 0, 0); PG8_STAGE(PG8_SA(1, 1), a1 + hstepA, voffA);
;             PG8_WAIT_V(8); PG8_WAIT_L(0); PG8_BAR; PG8_MMA(0, 0, At, B0); PG8_MMA(0, 1, At, B1); PG8_BAR; PG8_SCHED;
;     ...
; #pragma unroll
;         for (int a = 0; a < 2; ++a)
; #pragma unroll
;             for (int b = 0; b < 2; ++b)
; #pragma unroll
;                 for (int m = 0; m < 4; ++m)
; #pragma unroll
;                     for (int n = 0; n < 2; ++n) acc[a][b][m][n] = (f32x4){0.f, 0.f, 0.f, 0.f};
;         cur = nxt; cA = nA; cB = nB; ++ui;
.LBB0_939:
	s_ashr_i32 s13, s12, 31
	s_lshl_b64 s[14:15], s[12:13], 20
	s_add_u32 s14, s86, s14
	s_addc_u32 s15, s87, s15
	s_and_b64 s[16:17], s[4:5], exec
	s_cselect_b32 s13, s15, s27
	s_cselect_b32 s48, s14, s26
	s_ashr_i32 s11, s10, 31
	s_lshl_b64 s[16:17], s[10:11], 20
	v_readlane_b32 s30, v254, 0
	v_readlane_b32 s31, v254, 1
	s_add_u32 s16, s30, s16
	s_addc_u32 s17, s31, s17
	s_and_b64 s[30:31], s[4:5], exec
	s_cselect_b32 s11, s17, s29
	s_cselect_b32 s49, s16, s28
	s_add_u32 s26, s26, 0x80080
	s_addc_u32 s27, s27, 0
	s_add_u32 s50, s28, 0x100
	v_mov_b32_e32 v2, 0
	s_addc_u32 s51, s29, 0
	s_mov_b32 s52, -2
	v_mov_b32_e32 v3, v2
	v_mov_b32_e32 v4, v2
	v_mov_b32_e32 v5, v2
	v_mov_b32_e32 v6, v2
	v_mov_b32_e32 v7, v2
	v_mov_b32_e32 v8, v2
	v_mov_b32_e32 v9, v2
	v_mov_b32_e32 v18, v2
	v_mov_b32_e32 v19, v2
	v_mov_b32_e32 v20, v2
	v_mov_b32_e32 v21, v2
	v_mov_b32_e32 v22, v2
	v_mov_b32_e32 v23, v2
	v_mov_b32_e32 v24, v2
	v_mov_b32_e32 v25, v2
	v_mov_b32_e32 v34, v2
	v_mov_b32_e32 v35, v2
	v_mov_b32_e32 v36, v2
	v_mov_b32_e32 v37, v2
	v_mov_b32_e32 v38, v2
	v_mov_b32_e32 v39, v2
	v_mov_b32_e32 v40, v2
	v_mov_b32_e32 v41, v2
	v_mov_b32_e32 v50, v2
	v_mov_b32_e32 v51, v2
	v_mov_b32_e32 v52, v2
	v_mov_b32_e32 v53, v2
	v_mov_b32_e32 v54, v2
	v_mov_b32_e32 v55, v2
	v_mov_b32_e32 v56, v2
	v_mov_b32_e32 v57, v2
	v_mov_b32_e32 v10, v2
	v_mov_b32_e32 v11, v2
	v_mov_b32_e32 v12, v2
	v_mov_b32_e32 v13, v2
	v_mov_b32_e32 v14, v2
	v_mov_b32_e32 v15, v2
	v_mov_b32_e32 v16, v2
	v_mov_b32_e32 v17, v2
	v_mov_b32_e32 v26, v2
	v_mov_b32_e32 v27, v2
	v_mov_b32_e32 v28, v2
	v_mov_b32_e32 v29, v2
	v_mov_b32_e32 v30, v2
	v_mov_b32_e32 v31, v2
	v_mov_b32_e32 v32, v2
	v_mov_b32_e32 v33, v2
	v_mov_b32_e32 v42, v2
	v_mov_b32_e32 v43, v2
	v_mov_b32_e32 v44, v2
	v_mov_b32_e32 v45, v2
	v_mov_b32_e32 v46, v2
	v_mov_b32_e32 v47, v2
	v_mov_b32_e32 v48, v2
	v_mov_b32_e32 v49, v2
	v_mov_b32_e32 v58, v2
	v_mov_b32_e32 v59, v2
	v_mov_b32_e32 v60, v2
	v_mov_b32_e32 v61, v2
	v_mov_b32_e32 v62, v2
	v_mov_b32_e32 v63, v2
	v_mov_b32_e32 v64, v2
	v_mov_b32_e32 v65, v2
	v_mov_b32_e32 v66, v2
	v_mov_b32_e32 v67, v2
	v_mov_b32_e32 v68, v2
	v_mov_b32_e32 v69, v2
	v_mov_b32_e32 v70, v2
	v_mov_b32_e32 v71, v2
	v_mov_b32_e32 v72, v2
	v_mov_b32_e32 v73, v2
	v_mov_b32_e32 v82, v2
	v_mov_b32_e32 v83, v2
	v_mov_b32_e32 v84, v2
	v_mov_b32_e32 v85, v2
	v_mov_b32_e32 v86, v2
	v_mov_b32_e32 v87, v2
	v_mov_b32_e32 v88, v2
	v_mov_b32_e32 v89, v2
	v_mov_b32_e32 v98, v2
	v_mov_b32_e32 v99, v2
	v_mov_b32_e32 v100, v2
	v_mov_b32_e32 v101, v2
	v_mov_b32_e32 v102, v2
	v_mov_b32_e32 v103, v2
	v_mov_b32_e32 v104, v2
	v_mov_b32_e32 v105, v2
	v_mov_b32_e32 v114, v2
	v_mov_b32_e32 v115, v2
	v_mov_b32_e32 v116, v2
	v_mov_b32_e32 v117, v2
	v_mov_b32_e32 v118, v2
	v_mov_b32_e32 v119, v2
	v_mov_b32_e32 v120, v2
	v_mov_b32_e32 v121, v2
	v_mov_b32_e32 v74, v2
	v_mov_b32_e32 v75, v2
	v_mov_b32_e32 v76, v2
	v_mov_b32_e32 v77, v2
	v_mov_b32_e32 v78, v2
	v_mov_b32_e32 v79, v2
	v_mov_b32_e32 v80, v2
	v_mov_b32_e32 v81, v2
	v_mov_b32_e32 v90, v2
	v_mov_b32_e32 v91, v2
	v_mov_b32_e32 v92, v2
	v_mov_b32_e32 v93, v2
	v_mov_b32_e32 v94, v2
	v_mov_b32_e32 v95, v2
	v_mov_b32_e32 v96, v2
	v_mov_b32_e32 v97, v2
	v_mov_b32_e32 v106, v2
	v_mov_b32_e32 v107, v2
	v_mov_b32_e32 v108, v2
	v_mov_b32_e32 v109, v2
	v_mov_b32_e32 v110, v2
	v_mov_b32_e32 v111, v2
	v_mov_b32_e32 v112, v2
	v_mov_b32_e32 v113, v2
	v_mov_b32_e32 v122, v2
	v_mov_b32_e32 v123, v2
	v_mov_b32_e32 v124, v2
	v_mov_b32_e32 v125, v2
	v_mov_b32_e32 v126, v2
	v_mov_b32_e32 v127, v2
	v_mov_b32_e32 v128, v2
	v_mov_b32_e32 v129, v2
	ds_read_b128 v[154:157], v150
	ds_read_b128 v[158:161], v150 offset:1024
	ds_read_b128 v[162:165], v150 offset:2048
	ds_read_b128 v[166:169], v150 offset:3072
	ds_read_b128 v[170:173], v151
	ds_read_b128 v[174:177], v151 offset:1024
	ds_read_b128 v[178:181], v151 offset:2048
	ds_read_b128 v[182:185], v151 offset:3072
	s_add_u32 s28, s26, 0xfff80080
	s_addc_u32 s29, s27, -1
	s_cmp_eq_u32 s52, 28
	s_cselect_b32 s31, s13, s29
	s_cselect_b32 s30, s48, s28
	s_cselect_b32 s29, s11, s51
	s_cselect_b32 s28, s49, s50
	v_lshl_add_u64 v[146:147], s[26:27], 0, v[138:139]
	s_add_i32 m0, s25, 0xc000
	ds_read_b128 v[186:189], v152
	ds_read_b128 v[190:193], v152 offset:1024
	ds_read_b128 v[194:197], v152 offset:2048
	ds_read_b128 v[198:201], v152 offset:3072
	ds_read_b128 v[202:205], v152 offset:4096
	ds_read_b128 v[210:213], v152 offset:5120
	ds_read_b128 v[214:217], v152 offset:6144
	ds_read_b128 v[218:221], v152 offset:7168
	global_load_lds_dwordx4 v[146:147], off
	v_lshl_add_u64 v[146:147], s[26:27], 0, v[140:141]
	s_add_i32 m0, s25, 0xe000
	s_nop 0
	global_load_lds_dwordx4 v[146:147], off
	s_waitcnt vmcnt(16)
	s_waitcnt lgkmcnt(0)
	s_barrier
; #define PG8_STAGE(bufoff, gbase, voff) do { _Pragma("unroll") for (int _i = 0; _i < 2; ++_i) \
;         __builtin_amdgcn_global_load_lds((const unsigned*)((const char*)(gbase) + (voff)[_i]), (PG8_LAS unsigned*)(lds + (bufoff) + ldsw + _i * 8192), 16, 0, 0); } while (0)
; #define PG8_LDA(dst, b, h) do { _Pragma("unroll") for (int m = 0; m < 4; ++m) _Pragma("unroll") for (int k = 0; k < 2; ++k) dst[m][k] = *(const PG8_LAS bf16x8*)(lds + PG8_SA(b, h) + aoff + m * 2048 + k * 1024); } while (0)
; #define PG8_MMA(ai, bj, At, Bt) do { __builtin_amdgcn_s_setprio(1); _Pragma("unroll") for (int m = 0; m < 4; ++m) _Pragma("unroll") for (int n = 0; n < 2; ++n) _Pragma("unroll") for (int k = 0; k < 2; ++k) \
;         acc[ai][bj][m][n] = __builtin_amdgcn_mfma_f32_16x16x32_bf16(Bt[n][k], At[m][k], acc[ai][bj][m][n], 0, 0, 0); __builtin_amdgcn_s_setprio(0); } while (0)
; #define PG8_WAIT_V(n) asm volatile("s_waitcnt vmcnt(" #n ")" ::: "memory")
; #define PG8_WAIT_L(n) asm volatile("s_waitcnt lgkmcnt(" #n ")" ::: "memory")
; #define PG8_BAR __builtin_amdgcn_s_barrier()
; #define PG8_SCHED __builtin_amdgcn_sched_barrier(0)
; template <class Epi, class Sched, bool ALIGN_EPI = false, bool SP2 = false>
; __device__ __forceinline__ void gemm_phase(PG8_LAS unsigned char* lds, const Gemm g, const Sched& S, const Epi& E) {
;     ...
;             PG8_WAIT_V(8); PG8_WAIT_L(0); PG8_BAR; PG8_MMA(0, 0, At, B0); PG8_MMA(0, 1, At, B1); PG8_BAR; PG8_SCHED;
;             PG8_LDA(At, 0, 1); PG8_STAGE(PG8_SB(0, 0), b2, voffB); PG8_STAGE(PG8_SB(0, 1), b2 + hstepB, voffB); PG8_STAGE(PG8_SA(0, 0), a2, voffA);
;             PG8_WAIT_V(8); PG8_WAIT_L(0); PG8_BAR; PG8_MMA(1, 0, At, B0); PG8_MMA(1, 1, At, B1); PG8_BAR; PG8_SCHED;
	s_setprio 1
	s_waitcnt lgkmcnt(0)
	v_mfma_f32_16x16x32_bf16 v[126:129], v[154:157], v[186:189], v[126:129]
	v_mfma_f32_16x16x32_bf16 v[122:125], v[162:165], v[186:189], v[122:125]
	v_mfma_f32_16x16x32_bf16 v[110:113], v[154:157], v[194:197], v[110:113]
	v_mfma_f32_16x16x32_bf16 v[106:109], v[162:165], v[194:197], v[106:109]
	v_mfma_f32_16x16x32_bf16 v[94:97], v[154:157], v[202:205], v[94:97]
	v_mfma_f32_16x16x32_bf16 v[90:93], v[162:165], v[202:205], v[90:93]
	v_mfma_f32_16x16x32_bf16 v[78:81], v[154:157], v[214:217], v[78:81]
	v_mfma_f32_16x16x32_bf16 v[74:77], v[162:165], v[214:217], v[74:77]
	v_mfma_f32_16x16x32_bf16 v[126:129], v[158:161], v[190:193], v[126:129]
	v_mfma_f32_16x16x32_bf16 v[122:125], v[166:169], v[190:193], v[122:125]
	v_mfma_f32_16x16x32_bf16 v[110:113], v[158:161], v[198:201], v[110:113]
	v_mfma_f32_16x16x32_bf16 v[106:109], v[166:169], v[198:201], v[106:109]
	v_mfma_f32_16x16x32_bf16 v[94:97], v[158:161], v[210:213], v[94:97]
	v_mfma_f32_16x16x32_bf16 v[90:93], v[166:169], v[210:213], v[90:93]
	v_mfma_f32_16x16x32_bf16 v[78:81], v[158:161], v[218:221], v[78:81]
	v_mfma_f32_16x16x32_bf16 v[74:77], v[166:169], v[218:221], v[74:77]
	s_setprio 0
	s_setprio 1
	v_mfma_f32_16x16x32_bf16 v[118:121], v[170:173], v[186:189], v[118:121]
	v_mfma_f32_16x16x32_bf16 v[114:117], v[178:181], v[186:189], v[114:117]
	v_mfma_f32_16x16x32_bf16 v[102:105], v[170:173], v[194:197], v[102:105]
	v_mfma_f32_16x16x32_bf16 v[98:101], v[178:181], v[194:197], v[98:101]
	v_mfma_f32_16x16x32_bf16 v[86:89], v[170:173], v[202:205], v[86:89]
	v_mfma_f32_16x16x32_bf16 v[82:85], v[178:181], v[202:205], v[82:85]
	v_mfma_f32_16x16x32_bf16 v[70:73], v[170:173], v[214:217], v[70:73]
	v_mfma_f32_16x16x32_bf16 v[66:69], v[178:181], v[214:217], v[66:69]
	v_mfma_f32_16x16x32_bf16 v[118:121], v[174:177], v[190:193], v[118:121]
	v_mfma_f32_16x16x32_bf16 v[114:117], v[182:185], v[190:193], v[114:117]
	v_mfma_f32_16x16x32_bf16 v[102:105], v[174:177], v[198:201], v[102:105]
	v_mfma_f32_16x16x32_bf16 v[98:101], v[182:185], v[198:201], v[98:101]
	v_mfma_f32_16x16x32_bf16 v[86:89], v[174:177], v[210:213], v[86:89]
	v_mfma_f32_16x16x32_bf16 v[82:85], v[182:185], v[210:213], v[82:85]
	v_mfma_f32_16x16x32_bf16 v[70:73], v[174:177], v[218:221], v[70:73]
	v_mfma_f32_16x16x32_bf16 v[66:69], v[182:185], v[218:221], v[66:69]
	s_setprio 0
	s_barrier
	s_add_i32 s53, s44, s34
	v_lshl_add_u64 v[146:147], s[28:29], 0, v[134:135]
	s_mov_b32 m0, s53
	ds_read_b128 v[186:189], v152 offset:16384
	ds_read_b128 v[190:193], v152 offset:17408
	ds_read_b128 v[194:197], v152 offset:18432
	ds_read_b128 v[198:201], v152 offset:19456
	ds_read_b128 v[202:205], v152 offset:20480
	ds_read_b128 v[210:213], v152 offset:21504
	ds_read_b128 v[214:217], v152 offset:22528
	ds_read_b128 v[218:221], v152 offset:23552
	global_load_lds_dwordx4 v[146:147], off
	s_add_i32 m0, s53, 0x2000
	s_add_u32 s54, s28, 0x80000
	v_lshl_add_u64 v[206:207], s[28:29], 0, v[130:131]
	s_addc_u32 s55, s29, 0
	s_add_i32 s53, s45, s34
	global_load_lds_dwordx4 v[206:207], off
	v_lshl_add_u64 v[222:223], s[54:55], 0, v[134:135]
	s_mov_b32 m0, s53
	v_lshl_add_u64 v[224:225], s[30:31], 0, v[132:133]
	global_load_lds_dwordx4 v[222:223], off
	v_lshl_add_u64 v[222:223], s[54:55], 0, v[130:131]
	s_add_i32 m0, s53, 0x2000
	s_nop 0
	global_load_lds_dwordx4 v[222:223], off
	v_lshl_add_u64 v[222:223], s[30:31], 0, v[136:137]
	s_mov_b32 m0, s25
	s_nop 0
	global_load_lds_dwordx4 v[222:223], off
	s_mov_b32 m0, s37
	s_nop 0
	global_load_lds_dwordx4 v[224:225], off
	s_waitcnt vmcnt(16)
	s_waitcnt lgkmcnt(0)
	s_barrier
	s_setprio 1
	s_waitcnt lgkmcnt(0)
	v_mfma_f32_16x16x32_bf16 v[62:65], v[154:157], v[186:189], v[62:65]
	v_mfma_f32_16x16x32_bf16 v[58:61], v[162:165], v[186:189], v[58:61]
	v_mfma_f32_16x16x32_bf16 v[46:49], v[154:157], v[194:197], v[46:49]
	v_mfma_f32_16x16x32_bf16 v[42:45], v[162:165], v[194:197], v[42:45]
	v_mfma_f32_16x16x32_bf16 v[30:33], v[154:157], v[202:205], v[30:33]
	v_mfma_f32_16x16x32_bf16 v[26:29], v[162:165], v[202:205], v[26:29]
	v_mfma_f32_16x16x32_bf16 v[14:17], v[154:157], v[214:217], v[14:17]
	v_mfma_f32_16x16x32_bf16 v[10:13], v[162:165], v[214:217], v[10:13]
	v_mfma_f32_16x16x32_bf16 v[62:65], v[158:161], v[190:193], v[62:65]
	v_mfma_f32_16x16x32_bf16 v[58:61], v[166:169], v[190:193], v[58:61]
	v_mfma_f32_16x16x32_bf16 v[46:49], v[158:161], v[198:201], v[46:49]
	v_mfma_f32_16x16x32_bf16 v[42:45], v[166:169], v[198:201], v[42:45]
	v_mfma_f32_16x16x32_bf16 v[30:33], v[158:161], v[210:213], v[30:33]
	v_mfma_f32_16x16x32_bf16 v[26:29], v[166:169], v[210:213], v[26:29]
	v_mfma_f32_16x16x32_bf16 v[14:17], v[158:161], v[218:221], v[14:17]
	v_mfma_f32_16x16x32_bf16 v[10:13], v[166:169], v[218:221], v[10:13]
	s_setprio 0
	s_setprio 1
	v_mfma_f32_16x16x32_bf16 v[54:57], v[170:173], v[186:189], v[54:57]
	v_mfma_f32_16x16x32_bf16 v[50:53], v[178:181], v[186:189], v[50:53]
	v_mfma_f32_16x16x32_bf16 v[38:41], v[170:173], v[194:197], v[38:41]
	v_mfma_f32_16x16x32_bf16 v[34:37], v[178:181], v[194:197], v[34:37]
	v_mfma_f32_16x16x32_bf16 v[22:25], v[170:173], v[202:205], v[22:25]
	v_mfma_f32_16x16x32_bf16 v[18:21], v[178:181], v[202:205], v[18:21]
	v_mfma_f32_16x16x32_bf16 v[6:9], v[170:173], v[214:217], v[6:9]
	v_mfma_f32_16x16x32_bf16 v[2:5], v[178:181], v[214:217], v[2:5]
	v_mfma_f32_16x16x32_bf16 v[54:57], v[174:177], v[190:193], v[54:57]
	v_mfma_f32_16x16x32_bf16 v[50:53], v[182:185], v[190:193], v[50:53]
	v_mfma_f32_16x16x32_bf16 v[38:41], v[174:177], v[198:201], v[38:41]
	v_mfma_f32_16x16x32_bf16 v[34:37], v[182:185], v[198:201], v[34:37]
	v_mfma_f32_16x16x32_bf16 v[22:25], v[174:177], v[210:213], v[22:25]
	v_mfma_f32_16x16x32_bf16 v[18:21], v[182:185], v[210:213], v[18:21]
	v_mfma_f32_16x16x32_bf16 v[6:9], v[174:177], v[218:221], v[6:9]
	v_mfma_f32_16x16x32_bf16 v[2:5], v[182:185], v[218:221], v[2:5]
	s_setprio 0
	s_barrier
; #define PG8_STAGE(bufoff, gbase, voff) do { _Pragma("unroll") for (int _i = 0; _i < 2; ++_i) \
;         __builtin_amdgcn_global_load_lds((const unsigned*)((const char*)(gbase) + (voff)[_i]), (PG8_LAS unsigned*)(lds + (bufoff) + ldsw + _i * 8192), 16, 0, 0); } while (0)
; #define PG8_LDA(dst, b, h) do { _Pragma("unroll") for (int m = 0; m < 4; ++m) _Pragma("unroll") for (int k = 0; k < 2; ++k) dst[m][k] = *(const PG8_LAS bf16x8*)(lds + PG8_SA(b, h) + aoff + m * 2048 + k * 1024); } while (0)
; #define PG8_LDB(dst, b, h) do { _Pragma("unroll") for (int n = 0; n < 2; ++n) _Pragma("unroll") for (int k = 0; k < 2; ++k) dst[n][k] = *(const PG8_LAS bf16x8*)(lds + PG8_SB(b, h) + boff + n * 2048 + k * 1024); } while (0)
; #define PG8_MMA(ai, bj, At, Bt) do { __builtin_amdgcn_s_setprio(1); _Pragma("unroll") for (int m = 0; m < 4; ++m) _Pragma("unroll") for (int n = 0; n < 2; ++n) _Pragma("unroll") for (int k = 0; k < 2; ++k) \
;         acc[ai][bj][m][n] = __builtin_amdgcn_mfma_f32_16x16x32_bf16(Bt[n][k], At[m][k], acc[ai][bj][m][n], 0, 0, 0); __builtin_amdgcn_s_setprio(0); } while (0)
; #define PG8_WAIT_V(n) asm volatile("s_waitcnt vmcnt(" #n ")" ::: "memory")
; #define PG8_WAIT_L(n) asm volatile("s_waitcnt lgkmcnt(" #n ")" ::: "memory")
; #define PG8_BAR __builtin_amdgcn_s_barrier()
; #define PG8_SCHED __builtin_amdgcn_sched_barrier(0)
; template <class Epi, class Sched, bool ALIGN_EPI = false, bool SP2 = false>
; __device__ __forceinline__ void gemm_phase(PG8_LAS unsigned char* lds, const Gemm g, const Sched& S, const Epi& E) {
;     ...
;             PG8_LDB(B0, 1, 0); PG8_LDB(B1, 1, 1); PG8_SCHED; PG8_LDA(At, 1, 0); PG8_STAGE(PG8_SA(0, 1), a2 + hstepA, voffA);
;             PG8_WAIT_V(8); PG8_WAIT_L(0); PG8_BAR; PG8_MMA(0, 0, At, B0); PG8_MMA(0, 1, At, B1); PG8_BAR; PG8_SCHED;
	s_add_i32 s53, 0, 0x18000
	v_add_u32_e32 v153, s53, v148
	s_add_i32 s54, 0, 0x1c000
	ds_read_b128 v[154:157], v153
	ds_read_b128 v[158:161], v153 offset:1024
	ds_read_b128 v[162:165], v153 offset:2048
	ds_read_b128 v[166:169], v153 offset:3072
	v_add_u32_e32 v153, s54, v148
	ds_read_b128 v[170:173], v153
	ds_read_b128 v[174:177], v153 offset:1024
	ds_read_b128 v[178:181], v153 offset:2048
	ds_read_b128 v[182:185], v153 offset:3072
	s_add_u32 s30, s30, 0x80000
	s_addc_u32 s31, s31, 0
	s_mov_b32 m0, s38
	v_lshl_add_u64 v[226:227], s[30:31], 0, v[136:137]
	ds_read_b128 v[186:189], v152 offset:32768
	ds_read_b128 v[190:193], v152 offset:33792
	ds_read_b128 v[194:197], v152 offset:34816
	ds_read_b128 v[198:201], v152 offset:35840
	ds_read_b128 v[202:205], v152 offset:36864
	ds_read_b128 v[210:213], v152 offset:37888
	ds_read_b128 v[214:217], v152 offset:38912
	ds_read_b128 v[218:221], v152 offset:39936
	global_load_lds_dwordx4 v[226:227], off
	v_lshl_add_u64 v[226:227], s[30:31], 0, v[132:133]
	s_mov_b32 m0, s39
	s_nop 0
	global_load_lds_dwordx4 v[226:227], off
	s_waitcnt vmcnt(8)
	s_waitcnt lgkmcnt(0)
	s_barrier
	s_setprio 1
	s_waitcnt lgkmcnt(0)
	v_mfma_f32_16x16x32_bf16 v[126:129], v[154:157], v[186:189], v[126:129]
	v_mfma_f32_16x16x32_bf16 v[122:125], v[162:165], v[186:189], v[122:125]
	v_mfma_f32_16x16x32_bf16 v[110:113], v[154:157], v[194:197], v[110:113]
	v_mfma_f32_16x16x32_bf16 v[106:109], v[162:165], v[194:197], v[106:109]
	v_mfma_f32_16x16x32_bf16 v[94:97], v[154:157], v[202:205], v[94:97]
	v_mfma_f32_16x16x32_bf16 v[90:93], v[162:165], v[202:205], v[90:93]
	v_mfma_f32_16x16x32_bf16 v[78:81], v[154:157], v[214:217], v[78:81]
	v_mfma_f32_16x16x32_bf16 v[74:77], v[162:165], v[214:217], v[74:77]
	v_mfma_f32_16x16x32_bf16 v[126:129], v[158:161], v[190:193], v[126:129]
	v_mfma_f32_16x16x32_bf16 v[122:125], v[166:169], v[190:193], v[122:125]
	v_mfma_f32_16x16x32_bf16 v[110:113], v[158:161], v[198:201], v[110:113]
	v_mfma_f32_16x16x32_bf16 v[106:109], v[166:169], v[198:201], v[106:109]
	v_mfma_f32_16x16x32_bf16 v[94:97], v[158:161], v[210:213], v[94:97]
	v_mfma_f32_16x16x32_bf16 v[90:93], v[166:169], v[210:213], v[90:93]
	v_mfma_f32_16x16x32_bf16 v[78:81], v[158:161], v[218:221], v[78:81]
	v_mfma_f32_16x16x32_bf16 v[74:77], v[166:169], v[218:221], v[74:77]
	s_setprio 0
	s_setprio 1
	v_mfma_f32_16x16x32_bf16 v[118:121], v[170:173], v[186:189], v[118:121]
	v_mfma_f32_16x16x32_bf16 v[114:117], v[178:181], v[186:189], v[114:117]
	v_mfma_f32_16x16x32_bf16 v[102:105], v[170:173], v[194:197], v[102:105]
	v_mfma_f32_16x16x32_bf16 v[98:101], v[178:181], v[194:197], v[98:101]
	v_mfma_f32_16x16x32_bf16 v[86:89], v[170:173], v[202:205], v[86:89]
	v_mfma_f32_16x16x32_bf16 v[82:85], v[178:181], v[202:205], v[82:85]
	v_mfma_f32_16x16x32_bf16 v[70:73], v[170:173], v[214:217], v[70:73]
	v_mfma_f32_16x16x32_bf16 v[66:69], v[178:181], v[214:217], v[66:69]
	v_mfma_f32_16x16x32_bf16 v[118:121], v[174:177], v[190:193], v[118:121]
	v_mfma_f32_16x16x32_bf16 v[114:117], v[182:185], v[190:193], v[114:117]
	v_mfma_f32_16x16x32_bf16 v[102:105], v[174:177], v[198:201], v[102:105]
	v_mfma_f32_16x16x32_bf16 v[98:101], v[182:185], v[198:201], v[98:101]
	v_mfma_f32_16x16x32_bf16 v[86:89], v[174:177], v[210:213], v[86:89]
	v_mfma_f32_16x16x32_bf16 v[82:85], v[182:185], v[210:213], v[82:85]
	v_mfma_f32_16x16x32_bf16 v[70:73], v[174:177], v[218:221], v[70:73]
	v_mfma_f32_16x16x32_bf16 v[66:69], v[182:185], v[218:221], v[66:69]
	s_setprio 0
	s_barrier
; #define PG8_STAGE(bufoff, gbase, voff) do { _Pragma("unroll") for (int _i = 0; _i < 2; ++_i) \
;         __builtin_amdgcn_global_load_lds((const unsigned*)((const char*)(gbase) + (voff)[_i]), (PG8_LAS unsigned*)(lds + (bufoff) + ldsw + _i * 8192), 16, 0, 0); } while (0)
; #define PG8_LDA(dst, b, h) do { _Pragma("unroll") for (int m = 0; m < 4; ++m) _Pragma("unroll") for (int k = 0; k < 2; ++k) dst[m][k] = *(const PG8_LAS bf16x8*)(lds + PG8_SA(b, h) + aoff + m * 2048 + k * 1024); } while (0)
; #define PG8_MMA(ai, bj, At, Bt) do { __builtin_amdgcn_s_setprio(1); _Pragma("unroll") for (int m = 0; m < 4; ++m) _Pragma("unroll") for (int n = 0; n < 2; ++n) _Pragma("unroll") for (int k = 0; k < 2; ++k) \
;         acc[ai][bj][m][n] = __builtin_amdgcn_mfma_f32_16x16x32_bf16(Bt[n][k], At[m][k], acc[ai][bj][m][n], 0, 0, 0); __builtin_amdgcn_s_setprio(0); } while (0)
; #define PG8_WAIT_V(n) asm volatile("s_waitcnt vmcnt(" #n ")" ::: "memory")
; #define PG8_WAIT_L(n) asm volatile("s_waitcnt lgkmcnt(" #n ")" ::: "memory")
; #define PG8_BAR __builtin_amdgcn_s_barrier()
; #define PG8_SCHED __builtin_amdgcn_sched_barrier(0)
; template <class Epi, class Sched, bool ALIGN_EPI = false, bool SP2 = false>
; __device__ __forceinline__ void gemm_phase(PG8_LAS unsigned char* lds, const Gemm g, const Sched& S, const Epi& E) {
;     ...
;         for (int t = 0; t < nt; t += 2) {
;             const bool last = (t == nt - 2);
;             const char* a1 = cA + (size_t)(t + 1) * kstep;
;             const char* a2 = last ? nA : cA + (size_t)(t + 2) * kstep; const char* b2 = last ? nB : cB + (size_t)(t + 2) * kstep;
;             const char* a3 = a2 + kstep; const char* b3 = b2 + kstep;
;     ...
;             PG8_LDA(At, 1, 1); PG8_STAGE(PG8_SB(1, 0), b3, voffB); PG8_STAGE(PG8_SB(1, 1), b3 + hstepB, voffB); PG8_STAGE(PG8_SA(1, 0), a3, voffA);
;             PG8_WAIT_V(8); PG8_WAIT_L(0); PG8_BAR; PG8_MMA(1, 0, At, B0); PG8_MMA(1, 1, At, B1); PG8_BAR; PG8_SCHED;
	s_add_i32 s30, s53, s34
	v_lshl_add_u64 v[146:147], v[146:147], 0, s[2:3]
	s_mov_b32 m0, s30
	ds_read_b128 v[186:189], v152 offset:49152
	ds_read_b128 v[190:193], v152 offset:50176
	ds_read_b128 v[194:197], v152 offset:51200
	ds_read_b128 v[198:201], v152 offset:52224
	ds_read_b128 v[202:205], v152 offset:53248
	ds_read_b128 v[210:213], v152 offset:54272
	ds_read_b128 v[214:217], v152 offset:55296
	ds_read_b128 v[218:221], v152 offset:56320
	global_load_lds_dwordx4 v[146:147], off
	s_add_i32 m0, s30, 0x2000
	s_add_u32 s28, s28, 0x80080
	v_lshl_add_u64 v[146:147], v[206:207], 0, s[2:3]
	s_addc_u32 s29, s29, 0
	s_add_i32 s30, s54, s34
	global_load_lds_dwordx4 v[146:147], off
	v_lshl_add_u64 v[146:147], s[28:29], 0, v[134:135]
	s_mov_b32 m0, s30
	s_nop 0
	global_load_lds_dwordx4 v[146:147], off
	v_lshl_add_u64 v[146:147], s[28:29], 0, v[130:131]
	s_add_i32 m0, s30, 0x2000
	s_nop 0
	global_load_lds_dwordx4 v[146:147], off
	v_lshl_add_u64 v[146:147], v[222:223], 0, s[2:3]
	s_mov_b32 m0, s41
	s_nop 0
	global_load_lds_dwordx4 v[146:147], off
	v_lshl_add_u64 v[146:147], v[224:225], 0, s[2:3]
	s_mov_b32 m0, s42
	s_nop 0
	global_load_lds_dwordx4 v[146:147], off
	s_waitcnt vmcnt(8)
	s_waitcnt lgkmcnt(0)
	s_barrier
	s_setprio 1
	s_waitcnt lgkmcnt(0)
	v_mfma_f32_16x16x32_bf16 v[62:65], v[154:157], v[186:189], v[62:65]
	v_mfma_f32_16x16x32_bf16 v[58:61], v[162:165], v[186:189], v[58:61]
	v_mfma_f32_16x16x32_bf16 v[46:49], v[154:157], v[194:197], v[46:49]
	v_mfma_f32_16x16x32_bf16 v[42:45], v[162:165], v[194:197], v[42:45]
	v_mfma_f32_16x16x32_bf16 v[30:33], v[154:157], v[202:205], v[30:33]
	v_mfma_f32_16x16x32_bf16 v[26:29], v[162:165], v[202:205], v[26:29]
	v_mfma_f32_16x16x32_bf16 v[14:17], v[154:157], v[214:217], v[14:17]
	v_mfma_f32_16x16x32_bf16 v[10:13], v[162:165], v[214:217], v[10:13]
	v_mfma_f32_16x16x32_bf16 v[62:65], v[158:161], v[190:193], v[62:65]
	v_mfma_f32_16x16x32_bf16 v[58:61], v[166:169], v[190:193], v[58:61]
	v_mfma_f32_16x16x32_bf16 v[46:49], v[158:161], v[198:201], v[46:49]
	v_mfma_f32_16x16x32_bf16 v[42:45], v[166:169], v[198:201], v[42:45]
	v_mfma_f32_16x16x32_bf16 v[30:33], v[158:161], v[210:213], v[30:33]
	v_mfma_f32_16x16x32_bf16 v[26:29], v[166:169], v[210:213], v[26:29]
	v_mfma_f32_16x16x32_bf16 v[14:17], v[158:161], v[218:221], v[14:17]
	v_mfma_f32_16x16x32_bf16 v[10:13], v[166:169], v[218:221], v[10:13]
	s_setprio 0
	s_setprio 1
	v_mfma_f32_16x16x32_bf16 v[54:57], v[170:173], v[186:189], v[54:57]
	v_mfma_f32_16x16x32_bf16 v[50:53], v[178:181], v[186:189], v[50:53]
	v_mfma_f32_16x16x32_bf16 v[38:41], v[170:173], v[194:197], v[38:41]
	v_mfma_f32_16x16x32_bf16 v[34:37], v[178:181], v[194:197], v[34:37]
	v_mfma_f32_16x16x32_bf16 v[22:25], v[170:173], v[202:205], v[22:25]
	v_mfma_f32_16x16x32_bf16 v[18:21], v[178:181], v[202:205], v[18:21]
	v_mfma_f32_16x16x32_bf16 v[6:9], v[170:173], v[214:217], v[6:9]
	v_mfma_f32_16x16x32_bf16 v[2:5], v[178:181], v[214:217], v[2:5]
	v_mfma_f32_16x16x32_bf16 v[54:57], v[174:177], v[190:193], v[54:57]
	v_mfma_f32_16x16x32_bf16 v[50:53], v[182:185], v[190:193], v[50:53]
	v_mfma_f32_16x16x32_bf16 v[38:41], v[174:177], v[198:201], v[38:41]
	v_mfma_f32_16x16x32_bf16 v[34:37], v[182:185], v[198:201], v[34:37]
	v_mfma_f32_16x16x32_bf16 v[22:25], v[174:177], v[210:213], v[22:25]
	v_mfma_f32_16x16x32_bf16 v[18:21], v[182:185], v[210:213], v[18:21]
	v_mfma_f32_16x16x32_bf16 v[6:9], v[174:177], v[218:221], v[6:9]
	v_mfma_f32_16x16x32_bf16 v[2:5], v[182:185], v[218:221], v[2:5]
	s_setprio 0
	s_barrier
	s_add_i32 s52, s52, 2
	s_add_u32 s26, s26, 0x100
	s_addc_u32 s27, s27, 0
	s_add_u32 s50, s50, 0x100
	s_addc_u32 s51, s51, 0
	s_cmp_gt_u32 s52, 29
	s_cbranch_scc1 .Lpeel_exit_8
	.p2align 6

; #define PG8_BAR __builtin_amdgcn_s_barrier()
; template <class Epi, class Sched, bool ALIGN_EPI = false, bool SP2 = false>
; __device__ __forceinline__ void gemm_phase(PG8_LAS unsigned char* lds, const Gemm g, const Sched& S, const Epi& E) {
;     ...
;         if constexpr (ALIGN_EPI) { if (wr == 0) PG8_BAR; }
;         if constexpr (!Epi::AFTER_DRAIN) { E(acc, cur, wr, wc, fr, fq); S.done(cur); }
.Lpeel_exit_8:
	s_and_b64 vcc, exec, s[8:9]
	s_cbranch_vccz .LBB0_943
	s_barrier

; #define PG8_STAGE(bufoff, gbase, voff) do { _Pragma("unroll") for (int _i = 0; _i < 2; ++_i) \
;         __builtin_amdgcn_global_load_lds((const unsigned*)((const char*)(gbase) + (voff)[_i]), (PG8_LAS unsigned*)(lds + (bufoff) + ldsw + _i * 8192), 16, 0, 0); } while (0)
; #define PG8_WAIT_V(n) asm volatile("s_waitcnt vmcnt(" #n ")" ::: "memory")
; #define PG8_BAR __builtin_amdgcn_s_barrier()
; template <class Epi, class Sched, bool ALIGN_EPI = false, bool SP2 = false>
; __device__ __forceinline__ void gemm_phase(PG8_LAS unsigned char* lds, const Gemm g, const Sched& S, const Epi& E) {
;     const int tid = threadIdx.x, wid = __builtin_amdgcn_readfirstlane(tid >> 6), lane = tid & 63, wr = wid >> 2, wc = wid & 3, fr = lane & 15, fq = lane >> 4;
;     const int K = g.K, nt = K / BK;
;     unsigned voffA[2], voffB[2];
; #pragma unroll
;     for (int i = 0; i < 2; ++i) { int R, C; stage_rc(tid * 16 + i * 8192, R, C); const int Rb = Epi::PERM ? ((R & ~31) + perm32(R & 31)) : R;
;         voffA[i] = (unsigned)(R * g.lda + C) * 2u; voffB[i] = (unsigned)(Rb * g.ldb + C) * 2u; }
;     const size_t kstep = (size_t)(BK * 2);
;     const size_t hstepA = (size_t)HALF * g.lda * 2, hstepB = (size_t)HALF * g.ldb * 2;
;     const size_t tstepA = 2 * hstepA, tstepB = 2 * hstepB;
;     const unsigned ldsw = (unsigned)wid * 1024u;
;     const int aoff = lds_byte(wr * 64 + fr, fq * 8), boff = lds_byte(wc * 32 + fr, fq * 8);
;     ...
;         PG8_WAIT_V(2); PG8_BAR;
;         PG8_STAGE(PG8_SB(1, 0), cB + kstep, voffB); PG8_STAGE(PG8_SA(1, 0), cA + kstep, voffA); PG8_STAGE(PG8_SB(1, 1), cB + hstepB + kstep, voffB);
;         PG8_WAIT_V(6); PG8_BAR;
.LBB0_1023:
	s_lshl_b32 s6, s6, 5
	s_mov_b64 s[8:9], 0x80
	s_and_b32 s6, s6, 0x60
	s_add_i32 m0, s39, 0x18000
	v_lshl_add_u64 v[8:9], v[8:9], 0, s[8:9]
	s_lshl_b32 s12, s5, 13
	s_lshl_b32 s13, s6, 7
	s_waitcnt vmcnt(2)
	s_barrier
	global_load_lds_dwordx4 v[8:9], off
	v_lshl_add_u64 v[6:7], v[6:7], 0, s[8:9]
	s_add_i32 m0, s39, 0x1a000
	s_add_i32 s44, s39, 0x8000
	s_add_i32 s45, s39, 0xa000
	global_load_lds_dwordx4 v[6:7], off
	v_lshl_add_u64 v[2:3], v[2:3], 0, s[8:9]
	s_mov_b32 m0, s44
	s_add_u32 s10, s30, 0x160080
	global_load_lds_dwordx4 v[2:3], off
	v_lshl_add_u64 v[2:3], v[4:5], 0, s[8:9]
	s_mov_b32 m0, s45
	s_addc_u32 s11, s31, 0
	global_load_lds_dwordx4 v[2:3], off
	s_add_i32 m0, s39, 0x1c000
	v_lshl_add_u64 v[2:3], s[10:11], 0, v[134:135]
	global_load_lds_dwordx4 v[2:3], off
	v_lshl_add_u64 v[2:3], s[10:11], 0, v[130:131]
	s_add_i32 m0, s39, 0x1e000
	v_lshlrev_b32_e32 v4, 2, v0
	global_load_lds_dwordx4 v[2:3], off
	v_and_b32_e32 v2, 15, v0
	v_lshl_or_b32 v1, s5, 6, v2
	v_lshlrev_b32_e32 v3, 1, v10
	v_lshlrev_b32_e32 v5, 6, v0
	s_movk_i32 s5, 0x3c0
	v_lshl_or_b32 v2, v2, 6, v3
	v_and_b32_e32 v4, 32, v4
	v_and_or_b32 v3, v5, s5, v3
	v_bitop3_b32 v146, s13, v3, v4 bitop3:0xf6
	s_waitcnt vmcnt(0)
	s_cmpk_lt_u32 s4, 0x100
	v_add_u16_e32 v3, v11, v12
	v_bitop3_b32 v2, v2, s12, v4 bitop3:0xde
	s_cselect_b64 s[10:11], -1, 0
	v_lshrrev_b16_e32 v3, 1, v3
	s_add_i32 s47, 0, 0x10000
	s_add_i32 s48, 0, 0x14000
	s_sext_i32_i8 s56, s7
	s_waitcnt lgkmcnt(0)
	s_ashr_i32 s46, s33, 31
	v_or_b32_e32 v147, s6, v10
	v_add_lshl_u32 v138, v14, v3, 1
	v_mov_b32_e32 v139, v135
	v_add_lshl_u32 v140, v13, v3, 1
	v_mov_b32_e32 v141, v135
	v_mov_b64_e32 v[142:143], 0x500
	v_mov_b64_e32 v[144:145], 0x4ff
	v_add_u32_e32 v148, s47, v146
	v_add_u32_e32 v149, s48, v146
	v_add_u32_e32 v150, 0, v2
	s_mov_b64 s[12:13], 0x80000
	s_mov_b32 s49, 0x80000
	s_mov_b64 s[14:15], 0x90000
	s_mov_b32 s50, 0x90000
	s_mov_b64 s[16:17], 0xa0000
	s_mov_b32 s51, 0xa0000
	s_mov_b64 s[24:25], 0xb0000
	s_mov_b32 s52, 0xb0000
	s_barrier
	s_branch .LBB0_1026

; #define PG8_STAGE(bufoff, gbase, voff) do { _Pragma("unroll") for (int _i = 0; _i < 2; ++_i) \
;         __builtin_amdgcn_global_load_lds((const unsigned*)((const char*)(gbase) + (voff)[_i]), (PG8_LAS unsigned*)(lds + (bufoff) + ldsw + _i * 8192), 16, 0, 0); } while (0)
; #define PG8_LDA(dst, b, h) do { _Pragma("unroll") for (int m = 0; m < 4; ++m) _Pragma("unroll") for (int k = 0; k < 2; ++k) dst[m][k] = *(const PG8_LAS bf16x8*)(lds + PG8_SA(b, h) + aoff + m * 2048 + k * 1024); } while (0)
; #define PG8_LDB(dst, b, h) do { _Pragma("unroll") for (int n = 0; n < 2; ++n) _Pragma("unroll") for (int k = 0; k < 2; ++k) dst[n][k] = *(const PG8_LAS bf16x8*)(lds + PG8_SB(b, h) + boff + n * 2048 + k * 1024); } while (0)
; #define PG8_WAIT_V(n) asm volatile("s_waitcnt vmcnt(" #n ")" ::: "memory")
; #define PG8_WAIT_L(n) asm volatile("s_waitcnt lgkmcnt(" #n ")" ::: "memory")
; #define PG8_BAR __builtin_amdgcn_s_barrier()
; template <class Epi, class Sched, bool ALIGN_EPI = false, bool SP2 = false>
; __device__ __forceinline__ void gemm_phase(PG8_LAS unsigned char* lds, const Gemm g, const Sched& S, const Epi& E) {
;     ...
;         const bool has_next = S.next(ui + 1, nxt);
;         const char* nA = has_next ? (const char*)g.A + (size_t)nxt.pm * tstepA : cA; const char* nB = has_next ? (const char*)g.Bt + (size_t)nxt.pn * tstepB : cB;
;         for (int t = 0; t < nt; t += 2) {
;             const bool last = (t == nt - 2);
;             const char* a1 = cA + (size_t)(t + 1) * kstep;
;             const char* a2 = last ? nA : cA + (size_t)(t + 2) * kstep; const char* b2 = last ? nB : cB + (size_t)(t + 2) * kstep;
;             const char* a3 = a2 + kstep; const char* b3 = b2 + kstep;
;             if (last && has_next) S.a_ready(nxt);
;             if constexpr (SP2) {
;             PG8_LDB(B0, 0, 0); PG8_LDB(B1, 0, 1); PG8_SCHED; PG8_LDA(At, 0, 0); PG8_STAGE(PG8_SA(1, 1), a1 + hstepA, voffA);
;             PG8_WAIT_V(8); PG8_WAIT_L(0); PG8_BAR; PG8_MMA(0, 0, At, B0); PG8_MMA(0, 1, At, B1); PG8_BAR; PG8_SCHED;
;     ...
; #pragma unroll
;         for (int a = 0; a < 2; ++a)
; #pragma unroll
;             for (int b = 0; b < 2; ++b)
; #pragma unroll
;                 for (int m = 0; m < 4; ++m)
; #pragma unroll
;                     for (int n = 0; n < 2; ++n) acc[a][b][m][n] = (f32x4){0.f, 0.f, 0.f, 0.f};
;         cur = nxt; cA = nA; cB = nB; ++ui;
.LBB0_1032:
	s_add_u32 s28, s28, 0x160080
	s_addc_u32 s29, s29, 0
	s_add_u32 s57, s30, 0x100
	v_mov_b32_e32 v2, 0
	s_addc_u32 s58, s31, 0
	s_mov_b32 s59, -2
	v_mov_b32_e32 v3, v2
	v_mov_b32_e32 v4, v2
	v_mov_b32_e32 v5, v2
	v_mov_b32_e32 v6, v2
	v_mov_b32_e32 v7, v2
	v_mov_b32_e32 v8, v2
	v_mov_b32_e32 v9, v2
	v_mov_b32_e32 v10, v2
	v_mov_b32_e32 v11, v2
	v_mov_b32_e32 v12, v2
	v_mov_b32_e32 v13, v2
	v_mov_b32_e32 v14, v2
	v_mov_b32_e32 v15, v2
	v_mov_b32_e32 v16, v2
	v_mov_b32_e32 v17, v2
	v_mov_b32_e32 v26, v2
	v_mov_b32_e32 v27, v2
	v_mov_b32_e32 v28, v2
	v_mov_b32_e32 v29, v2
	v_mov_b32_e32 v30, v2
	v_mov_b32_e32 v31, v2
	v_mov_b32_e32 v32, v2
	v_mov_b32_e32 v33, v2
	v_mov_b32_e32 v42, v2
	v_mov_b32_e32 v43, v2
	v_mov_b32_e32 v44, v2
	v_mov_b32_e32 v45, v2
	v_mov_b32_e32 v46, v2
	v_mov_b32_e32 v47, v2
	v_mov_b32_e32 v48, v2
	v_mov_b32_e32 v49, v2
	v_mov_b32_e32 v18, v2
	v_mov_b32_e32 v19, v2
	v_mov_b32_e32 v20, v2
	v_mov_b32_e32 v21, v2
	v_mov_b32_e32 v22, v2
	v_mov_b32_e32 v23, v2
	v_mov_b32_e32 v24, v2
	v_mov_b32_e32 v25, v2
	v_mov_b32_e32 v34, v2
	v_mov_b32_e32 v35, v2
	v_mov_b32_e32 v36, v2
	v_mov_b32_e32 v37, v2
	v_mov_b32_e32 v38, v2
	v_mov_b32_e32 v39, v2
	v_mov_b32_e32 v40, v2
	v_mov_b32_e32 v41, v2
	v_mov_b32_e32 v50, v2
	v_mov_b32_e32 v51, v2
	v_mov_b32_e32 v52, v2
	v_mov_b32_e32 v53, v2
	v_mov_b32_e32 v54, v2
	v_mov_b32_e32 v55, v2
	v_mov_b32_e32 v56, v2
	v_mov_b32_e32 v57, v2
	v_mov_b32_e32 v58, v2
	v_mov_b32_e32 v59, v2
	v_mov_b32_e32 v60, v2
	v_mov_b32_e32 v61, v2
	v_mov_b32_e32 v62, v2
	v_mov_b32_e32 v63, v2
	v_mov_b32_e32 v64, v2
	v_mov_b32_e32 v65, v2
	v_mov_b32_e32 v66, v2
	v_mov_b32_e32 v67, v2
	v_mov_b32_e32 v68, v2
	v_mov_b32_e32 v69, v2
	v_mov_b32_e32 v70, v2
	v_mov_b32_e32 v71, v2
	v_mov_b32_e32 v72, v2
	v_mov_b32_e32 v73, v2
	v_mov_b32_e32 v74, v2
	v_mov_b32_e32 v75, v2
	v_mov_b32_e32 v76, v2
	v_mov_b32_e32 v77, v2
	v_mov_b32_e32 v78, v2
	v_mov_b32_e32 v79, v2
	v_mov_b32_e32 v80, v2
	v_mov_b32_e32 v81, v2
	v_mov_b32_e32 v90, v2
	v_mov_b32_e32 v91, v2
	v_mov_b32_e32 v92, v2
	v_mov_b32_e32 v93, v2
	v_mov_b32_e32 v94, v2
	v_mov_b32_e32 v95, v2
	v_mov_b32_e32 v96, v2
	v_mov_b32_e32 v97, v2
	v_mov_b32_e32 v106, v2
	v_mov_b32_e32 v107, v2
	v_mov_b32_e32 v108, v2
	v_mov_b32_e32 v109, v2
	v_mov_b32_e32 v110, v2
	v_mov_b32_e32 v111, v2
	v_mov_b32_e32 v112, v2
	v_mov_b32_e32 v113, v2
	v_mov_b32_e32 v82, v2
	v_mov_b32_e32 v83, v2
	v_mov_b32_e32 v84, v2
	v_mov_b32_e32 v85, v2
	v_mov_b32_e32 v86, v2
	v_mov_b32_e32 v87, v2
	v_mov_b32_e32 v88, v2
	v_mov_b32_e32 v89, v2
	v_mov_b32_e32 v98, v2
	v_mov_b32_e32 v99, v2
	v_mov_b32_e32 v100, v2
	v_mov_b32_e32 v101, v2
	v_mov_b32_e32 v102, v2
	v_mov_b32_e32 v103, v2
	v_mov_b32_e32 v104, v2
	v_mov_b32_e32 v105, v2
	v_mov_b32_e32 v114, v2
	v_mov_b32_e32 v115, v2
	v_mov_b32_e32 v116, v2
	v_mov_b32_e32 v117, v2
	v_mov_b32_e32 v118, v2
	v_mov_b32_e32 v119, v2
	v_mov_b32_e32 v120, v2
	v_mov_b32_e32 v121, v2
	v_mov_b32_e32 v122, v2
	v_mov_b32_e32 v123, v2
	v_mov_b32_e32 v124, v2
	v_mov_b32_e32 v125, v2
	v_mov_b32_e32 v126, v2
	v_mov_b32_e32 v127, v2
	v_mov_b32_e32 v128, v2
	v_mov_b32_e32 v129, v2
	ds_read_b128 v[152:155], v148
	ds_read_b128 v[156:159], v148 offset:1024
	ds_read_b128 v[160:163], v148 offset:2048
	ds_read_b128 v[164:167], v148 offset:3072
	ds_read_b128 v[168:171], v149
	ds_read_b128 v[172:175], v149 offset:1024
	ds_read_b128 v[176:179], v149 offset:2048
	ds_read_b128 v[180:183], v149 offset:3072
	s_add_u32 s30, s28, 0xffea0080
	s_addc_u32 s31, s29, -1
	s_cmpk_eq_i32 s59, 0x54
	s_cselect_b32 s35, s7, s31
	s_cselect_b32 s34, s6, s30
	s_cselect_b32 s31, s27, s58
	s_cselect_b32 s30, s26, s57
	v_lshl_add_u64 v[218:219], s[28:29], 0, v[138:139]
	s_add_i32 m0, s39, 0xc000
	ds_read_b128 v[184:187], v150
	ds_read_b128 v[188:191], v150 offset:1024
	ds_read_b128 v[192:195], v150 offset:2048
	ds_read_b128 v[196:199], v150 offset:3072
	ds_read_b128 v[200:203], v150 offset:4096
	ds_read_b128 v[204:207], v150 offset:5120
	ds_read_b128 v[210:213], v150 offset:6144
	ds_read_b128 v[214:217], v150 offset:7168
	global_load_lds_dwordx4 v[218:219], off
	v_lshl_add_u64 v[218:219], s[28:29], 0, v[140:141]
	s_add_i32 m0, s39, 0xe000
	s_nop 0
	global_load_lds_dwordx4 v[218:219], off
	s_waitcnt vmcnt(24)
	s_waitcnt lgkmcnt(0)
	s_barrier
	s_setprio 1
	s_waitcnt lgkmcnt(0)
	v_mfma_f32_16x16x32_bf16 v[126:129], v[152:155], v[184:187], v[126:129]
	v_mfma_f32_16x16x32_bf16 v[122:125], v[160:163], v[184:187], v[122:125]
	v_mfma_f32_16x16x32_bf16 v[118:121], v[152:155], v[192:195], v[118:121]
	v_mfma_f32_16x16x32_bf16 v[114:117], v[160:163], v[192:195], v[114:117]
	v_mfma_f32_16x16x32_bf16 v[102:105], v[152:155], v[200:203], v[102:105]
	v_mfma_f32_16x16x32_bf16 v[98:101], v[160:163], v[200:203], v[98:101]
	v_mfma_f32_16x16x32_bf16 v[86:89], v[152:155], v[210:213], v[86:89]
	v_mfma_f32_16x16x32_bf16 v[82:85], v[160:163], v[210:213], v[82:85]
	v_mfma_f32_16x16x32_bf16 v[126:129], v[156:159], v[188:191], v[126:129]
	v_mfma_f32_16x16x32_bf16 v[122:125], v[164:167], v[188:191], v[122:125]
	v_mfma_f32_16x16x32_bf16 v[118:121], v[156:159], v[196:199], v[118:121]
	v_mfma_f32_16x16x32_bf16 v[114:117], v[164:167], v[196:199], v[114:117]
	v_mfma_f32_16x16x32_bf16 v[102:105], v[156:159], v[204:207], v[102:105]
	v_mfma_f32_16x16x32_bf16 v[98:101], v[164:167], v[204:207], v[98:101]
	v_mfma_f32_16x16x32_bf16 v[86:89], v[156:159], v[214:217], v[86:89]
	v_mfma_f32_16x16x32_bf16 v[82:85], v[164:167], v[214:217], v[82:85]
	s_setprio 0
	s_setprio 1
	v_mfma_f32_16x16x32_bf16 v[110:113], v[168:171], v[184:187], v[110:113]
	v_mfma_f32_16x16x32_bf16 v[106:109], v[176:179], v[184:187], v[106:109]
	v_mfma_f32_16x16x32_bf16 v[94:97], v[168:171], v[192:195], v[94:97]
	v_mfma_f32_16x16x32_bf16 v[90:93], v[176:179], v[192:195], v[90:93]
	v_mfma_f32_16x16x32_bf16 v[78:81], v[168:171], v[200:203], v[78:81]
	v_mfma_f32_16x16x32_bf16 v[74:77], v[176:179], v[200:203], v[74:77]
	v_mfma_f32_16x16x32_bf16 v[70:73], v[168:171], v[210:213], v[70:73]
	v_mfma_f32_16x16x32_bf16 v[66:69], v[176:179], v[210:213], v[66:69]
	v_mfma_f32_16x16x32_bf16 v[110:113], v[172:175], v[188:191], v[110:113]
	v_mfma_f32_16x16x32_bf16 v[106:109], v[180:183], v[188:191], v[106:109]
	v_mfma_f32_16x16x32_bf16 v[94:97], v[172:175], v[196:199], v[94:97]
	v_mfma_f32_16x16x32_bf16 v[90:93], v[180:183], v[196:199], v[90:93]
	v_mfma_f32_16x16x32_bf16 v[78:81], v[172:175], v[204:207], v[78:81]
	v_mfma_f32_16x16x32_bf16 v[74:77], v[180:183], v[204:207], v[74:77]
	v_mfma_f32_16x16x32_bf16 v[70:73], v[172:175], v[214:217], v[70:73]
	v_mfma_f32_16x16x32_bf16 v[66:69], v[180:183], v[214:217], v[66:69]
	s_setprio 0
	s_barrier
; #define PG8_STAGE(bufoff, gbase, voff) do { _Pragma("unroll") for (int _i = 0; _i < 2; ++_i) \
;         __builtin_amdgcn_global_load_lds((const unsigned*)((const char*)(gbase) + (voff)[_i]), (PG8_LAS unsigned*)(lds + (bufoff) + ldsw + _i * 8192), 16, 0, 0); } while (0)
; #define PG8_LDA(dst, b, h) do { _Pragma("unroll") for (int m = 0; m < 4; ++m) _Pragma("unroll") for (int k = 0; k < 2; ++k) dst[m][k] = *(const PG8_LAS bf16x8*)(lds + PG8_SA(b, h) + aoff + m * 2048 + k * 1024); } while (0)
; #define PG8_LDB(dst, b, h) do { _Pragma("unroll") for (int n = 0; n < 2; ++n) _Pragma("unroll") for (int k = 0; k < 2; ++k) dst[n][k] = *(const PG8_LAS bf16x8*)(lds + PG8_SB(b, h) + boff + n * 2048 + k * 1024); } while (0)
; #define PG8_MMA(ai, bj, At, Bt) do { __builtin_amdgcn_s_setprio(1); _Pragma("unroll") for (int m = 0; m < 4; ++m) _Pragma("unroll") for (int n = 0; n < 2; ++n) _Pragma("unroll") for (int k = 0; k < 2; ++k) \
;         acc[ai][bj][m][n] = __builtin_amdgcn_mfma_f32_16x16x32_bf16(Bt[n][k], At[m][k], acc[ai][bj][m][n], 0, 0, 0); __builtin_amdgcn_s_setprio(0); } while (0)
; #define PG8_WAIT_V(n) asm volatile("s_waitcnt vmcnt(" #n ")" ::: "memory")
; #define PG8_WAIT_L(n) asm volatile("s_waitcnt lgkmcnt(" #n ")" ::: "memory")
; #define PG8_BAR __builtin_amdgcn_s_barrier()
; #define PG8_SCHED __builtin_amdgcn_sched_barrier(0)
; template <class Epi, class Sched, bool ALIGN_EPI = false, bool SP2 = false>
; __device__ __forceinline__ void gemm_phase(PG8_LAS unsigned char* lds, const Gemm g, const Sched& S, const Epi& E) {
;     ...
;             PG8_LDA(At, 0, 1); PG8_STAGE(PG8_SB(0, 0), b2, voffB); PG8_STAGE(PG8_SB(0, 1), b2 + hstepB, voffB); PG8_STAGE(PG8_SA(0, 0), a2, voffA);
;             PG8_WAIT_V(8); PG8_WAIT_L(0); PG8_BAR; PG8_MMA(1, 0, At, B0); PG8_MMA(1, 1, At, B1); PG8_BAR; PG8_SCHED;
;             PG8_LDB(B0, 1, 0); PG8_LDB(B1, 1, 1); PG8_SCHED; PG8_LDA(At, 1, 0); PG8_STAGE(PG8_SA(0, 1), a2 + hstepA, voffA);
;             PG8_WAIT_V(8); PG8_WAIT_L(0); PG8_BAR; PG8_MMA(0, 0, At, B0); PG8_MMA(0, 1, At, B1); PG8_BAR; PG8_SCHED;
	s_add_i32 s60, s47, s36
	v_lshl_add_u64 v[218:219], s[30:31], 0, v[134:135]
	s_mov_b32 m0, s60
	ds_read_b128 v[184:187], v150 offset:16384
	ds_read_b128 v[188:191], v150 offset:17408
	ds_read_b128 v[192:195], v150 offset:18432
	ds_read_b128 v[196:199], v150 offset:19456
	ds_read_b128 v[200:203], v150 offset:20480
	ds_read_b128 v[204:207], v150 offset:21504
	ds_read_b128 v[210:213], v150 offset:22528
	ds_read_b128 v[214:217], v150 offset:23552
	global_load_lds_dwordx4 v[218:219], off
	s_add_i32 m0, s60, 0x2000
	s_add_u32 s60, s30, 0x160000
	v_lshl_add_u64 v[220:221], s[30:31], 0, v[130:131]
	s_addc_u32 s61, s31, 0
	s_add_i32 s62, s48, s36
	global_load_lds_dwordx4 v[220:221], off
	v_lshl_add_u64 v[222:223], s[60:61], 0, v[134:135]
	s_mov_b32 m0, s62
	v_lshl_add_u64 v[224:225], s[34:35], 0, v[132:133]
	global_load_lds_dwordx4 v[222:223], off
	v_lshl_add_u64 v[222:223], s[60:61], 0, v[130:131]
	s_add_i32 m0, s62, 0x2000
	s_nop 0
	global_load_lds_dwordx4 v[222:223], off
	v_lshl_add_u64 v[222:223], s[34:35], 0, v[136:137]
	s_mov_b32 m0, s39
	s_nop 0
	global_load_lds_dwordx4 v[222:223], off
	s_mov_b32 m0, s40
	s_nop 0
	global_load_lds_dwordx4 v[224:225], off
	s_waitcnt vmcnt(24)
	s_waitcnt lgkmcnt(0)
	s_barrier
	s_setprio 1
	s_waitcnt lgkmcnt(0)
	v_mfma_f32_16x16x32_bf16 v[62:65], v[152:155], v[184:187], v[62:65]
	v_mfma_f32_16x16x32_bf16 v[58:61], v[160:163], v[184:187], v[58:61]
	v_mfma_f32_16x16x32_bf16 v[54:57], v[152:155], v[192:195], v[54:57]
	v_mfma_f32_16x16x32_bf16 v[50:53], v[160:163], v[192:195], v[50:53]
	v_mfma_f32_16x16x32_bf16 v[38:41], v[152:155], v[200:203], v[38:41]
	v_mfma_f32_16x16x32_bf16 v[34:37], v[160:163], v[200:203], v[34:37]
	v_mfma_f32_16x16x32_bf16 v[22:25], v[152:155], v[210:213], v[22:25]
	v_mfma_f32_16x16x32_bf16 v[18:21], v[160:163], v[210:213], v[18:21]
	v_mfma_f32_16x16x32_bf16 v[62:65], v[156:159], v[188:191], v[62:65]
	v_mfma_f32_16x16x32_bf16 v[58:61], v[164:167], v[188:191], v[58:61]
	v_mfma_f32_16x16x32_bf16 v[54:57], v[156:159], v[196:199], v[54:57]
	v_mfma_f32_16x16x32_bf16 v[50:53], v[164:167], v[196:199], v[50:53]
	v_mfma_f32_16x16x32_bf16 v[38:41], v[156:159], v[204:207], v[38:41]
	v_mfma_f32_16x16x32_bf16 v[34:37], v[164:167], v[204:207], v[34:37]
	v_mfma_f32_16x16x32_bf16 v[22:25], v[156:159], v[214:217], v[22:25]
	v_mfma_f32_16x16x32_bf16 v[18:21], v[164:167], v[214:217], v[18:21]
	s_setprio 0
	s_setprio 1
	v_mfma_f32_16x16x32_bf16 v[46:49], v[168:171], v[184:187], v[46:49]
	v_mfma_f32_16x16x32_bf16 v[42:45], v[176:179], v[184:187], v[42:45]
	v_mfma_f32_16x16x32_bf16 v[30:33], v[168:171], v[192:195], v[30:33]
	v_mfma_f32_16x16x32_bf16 v[26:29], v[176:179], v[192:195], v[26:29]
	v_mfma_f32_16x16x32_bf16 v[14:17], v[168:171], v[200:203], v[14:17]
	v_mfma_f32_16x16x32_bf16 v[10:13], v[176:179], v[200:203], v[10:13]
	v_mfma_f32_16x16x32_bf16 v[6:9], v[168:171], v[210:213], v[6:9]
	v_mfma_f32_16x16x32_bf16 v[2:5], v[176:179], v[210:213], v[2:5]
	v_mfma_f32_16x16x32_bf16 v[46:49], v[172:175], v[188:191], v[46:49]
	v_mfma_f32_16x16x32_bf16 v[42:45], v[180:183], v[188:191], v[42:45]
	v_mfma_f32_16x16x32_bf16 v[30:33], v[172:175], v[196:199], v[30:33]
	v_mfma_f32_16x16x32_bf16 v[26:29], v[180:183], v[196:199], v[26:29]
	v_mfma_f32_16x16x32_bf16 v[14:17], v[172:175], v[204:207], v[14:17]
	v_mfma_f32_16x16x32_bf16 v[10:13], v[180:183], v[204:207], v[10:13]
	v_mfma_f32_16x16x32_bf16 v[6:9], v[172:175], v[214:217], v[6:9]
	v_mfma_f32_16x16x32_bf16 v[2:5], v[180:183], v[214:217], v[2:5]
	s_setprio 0
	s_barrier
	s_add_i32 s60, 0, 0x18000
	v_add_u32_e32 v151, s60, v146
	s_add_i32 s61, 0, 0x1c000
	ds_read_b128 v[152:155], v151
	ds_read_b128 v[156:159], v151 offset:1024
	ds_read_b128 v[160:163], v151 offset:2048
	ds_read_b128 v[164:167], v151 offset:3072
	v_add_u32_e32 v151, s61, v146
	ds_read_b128 v[168:171], v151
	ds_read_b128 v[172:175], v151 offset:1024
	ds_read_b128 v[176:179], v151 offset:2048
	ds_read_b128 v[180:183], v151 offset:3072
	s_add_u32 s34, s34, 0x160000
	s_addc_u32 s35, s35, 0
	s_mov_b32 m0, s41
	v_lshl_add_u64 v[226:227], s[34:35], 0, v[136:137]
	ds_read_b128 v[184:187], v150 offset:32768
	ds_read_b128 v[188:191], v150 offset:33792
	ds_read_b128 v[192:195], v150 offset:34816
	ds_read_b128 v[196:199], v150 offset:35840
	ds_read_b128 v[200:203], v150 offset:36864
	ds_read_b128 v[204:207], v150 offset:37888
	ds_read_b128 v[210:213], v150 offset:38912
	ds_read_b128 v[214:217], v150 offset:39936
	global_load_lds_dwordx4 v[226:227], off
	v_lshl_add_u64 v[226:227], s[34:35], 0, v[132:133]
	s_mov_b32 m0, s42
	s_nop 0
	global_load_lds_dwordx4 v[226:227], off
	s_waitcnt vmcnt(8)
	s_waitcnt lgkmcnt(0)
	s_barrier
; #define PG8_STAGE(bufoff, gbase, voff) do { _Pragma("unroll") for (int _i = 0; _i < 2; ++_i) \
;         __builtin_amdgcn_global_load_lds((const unsigned*)((const char*)(gbase) + (voff)[_i]), (PG8_LAS unsigned*)(lds + (bufoff) + ldsw + _i * 8192), 16, 0, 0); } while (0)
; #define PG8_LDA(dst, b, h) do { _Pragma("unroll") for (int m = 0; m < 4; ++m) _Pragma("unroll") for (int k = 0; k < 2; ++k) dst[m][k] = *(const PG8_LAS bf16x8*)(lds + PG8_SA(b, h) + aoff + m * 2048 + k * 1024); } while (0)
; #define PG8_MMA(ai, bj, At, Bt) do { __builtin_amdgcn_s_setprio(1); _Pragma("unroll") for (int m = 0; m < 4; ++m) _Pragma("unroll") for (int n = 0; n < 2; ++n) _Pragma("unroll") for (int k = 0; k < 2; ++k) \
;         acc[ai][bj][m][n] = __builtin_amdgcn_mfma_f32_16x16x32_bf16(Bt[n][k], At[m][k], acc[ai][bj][m][n], 0, 0, 0); __builtin_amdgcn_s_setprio(0); } while (0)
; #define PG8_WAIT_V(n) asm volatile("s_waitcnt vmcnt(" #n ")" ::: "memory")
; #define PG8_WAIT_L(n) asm volatile("s_waitcnt lgkmcnt(" #n ")" ::: "memory")
; #define PG8_BAR __builtin_amdgcn_s_barrier()
; #define PG8_SCHED __builtin_amdgcn_sched_barrier(0)
; template <class Epi, class Sched, bool ALIGN_EPI = false, bool SP2 = false>
; __device__ __forceinline__ void gemm_phase(PG8_LAS unsigned char* lds, const Gemm g, const Sched& S, const Epi& E) {
;     ...
;             PG8_WAIT_V(8); PG8_WAIT_L(0); PG8_BAR; PG8_MMA(0, 0, At, B0); PG8_MMA(0, 1, At, B1); PG8_BAR; PG8_SCHED;
;             PG8_LDA(At, 1, 1); PG8_STAGE(PG8_SB(1, 0), b3, voffB); PG8_STAGE(PG8_SB(1, 1), b3 + hstepB, voffB); PG8_STAGE(PG8_SA(1, 0), a3, voffA);
;             PG8_WAIT_V(8); PG8_WAIT_L(0); PG8_BAR; PG8_MMA(1, 0, At, B0); PG8_MMA(1, 1, At, B1); PG8_BAR; PG8_SCHED;
	s_setprio 1
	s_waitcnt lgkmcnt(0)
	v_mfma_f32_16x16x32_bf16 v[126:129], v[152:155], v[184:187], v[126:129]
	v_mfma_f32_16x16x32_bf16 v[122:125], v[160:163], v[184:187], v[122:125]
	v_mfma_f32_16x16x32_bf16 v[118:121], v[152:155], v[192:195], v[118:121]
	v_mfma_f32_16x16x32_bf16 v[114:117], v[160:163], v[192:195], v[114:117]
	v_mfma_f32_16x16x32_bf16 v[102:105], v[152:155], v[200:203], v[102:105]
	v_mfma_f32_16x16x32_bf16 v[98:101], v[160:163], v[200:203], v[98:101]
	v_mfma_f32_16x16x32_bf16 v[86:89], v[152:155], v[210:213], v[86:89]
	v_mfma_f32_16x16x32_bf16 v[82:85], v[160:163], v[210:213], v[82:85]
	v_mfma_f32_16x16x32_bf16 v[126:129], v[156:159], v[188:191], v[126:129]
	v_mfma_f32_16x16x32_bf16 v[122:125], v[164:167], v[188:191], v[122:125]
	v_mfma_f32_16x16x32_bf16 v[118:121], v[156:159], v[196:199], v[118:121]
	v_mfma_f32_16x16x32_bf16 v[114:117], v[164:167], v[196:199], v[114:117]
	v_mfma_f32_16x16x32_bf16 v[102:105], v[156:159], v[204:207], v[102:105]
	v_mfma_f32_16x16x32_bf16 v[98:101], v[164:167], v[204:207], v[98:101]
	v_mfma_f32_16x16x32_bf16 v[86:89], v[156:159], v[214:217], v[86:89]
	v_mfma_f32_16x16x32_bf16 v[82:85], v[164:167], v[214:217], v[82:85]
	s_setprio 0
	s_setprio 1
	v_mfma_f32_16x16x32_bf16 v[110:113], v[168:171], v[184:187], v[110:113]
	v_mfma_f32_16x16x32_bf16 v[106:109], v[176:179], v[184:187], v[106:109]
	v_mfma_f32_16x16x32_bf16 v[94:97], v[168:171], v[192:195], v[94:97]
	v_mfma_f32_16x16x32_bf16 v[90:93], v[176:179], v[192:195], v[90:93]
	v_mfma_f32_16x16x32_bf16 v[78:81], v[168:171], v[200:203], v[78:81]
	v_mfma_f32_16x16x32_bf16 v[74:77], v[176:179], v[200:203], v[74:77]
	v_mfma_f32_16x16x32_bf16 v[70:73], v[168:171], v[210:213], v[70:73]
	v_mfma_f32_16x16x32_bf16 v[66:69], v[176:179], v[210:213], v[66:69]
	v_mfma_f32_16x16x32_bf16 v[110:113], v[172:175], v[188:191], v[110:113]
	v_mfma_f32_16x16x32_bf16 v[106:109], v[180:183], v[188:191], v[106:109]
	v_mfma_f32_16x16x32_bf16 v[94:97], v[172:175], v[196:199], v[94:97]
	v_mfma_f32_16x16x32_bf16 v[90:93], v[180:183], v[196:199], v[90:93]
	v_mfma_f32_16x16x32_bf16 v[78:81], v[172:175], v[204:207], v[78:81]
	v_mfma_f32_16x16x32_bf16 v[74:77], v[180:183], v[204:207], v[74:77]
	v_mfma_f32_16x16x32_bf16 v[70:73], v[172:175], v[214:217], v[70:73]
	v_mfma_f32_16x16x32_bf16 v[66:69], v[180:183], v[214:217], v[66:69]
	s_setprio 0
	s_barrier
	s_add_i32 s34, s60, s36
	v_lshl_add_u64 v[218:219], v[218:219], 0, s[8:9]
	s_mov_b32 m0, s34
	ds_read_b128 v[184:187], v150 offset:49152
	ds_read_b128 v[188:191], v150 offset:50176
	ds_read_b128 v[192:195], v150 offset:51200
	ds_read_b128 v[196:199], v150 offset:52224
	ds_read_b128 v[200:203], v150 offset:53248
	ds_read_b128 v[204:207], v150 offset:54272
	ds_read_b128 v[210:213], v150 offset:55296
	ds_read_b128 v[214:217], v150 offset:56320
	global_load_lds_dwordx4 v[218:219], off
	s_add_i32 m0, s34, 0x2000
	s_add_u32 s30, s30, 0x160080
	v_lshl_add_u64 v[218:219], v[220:221], 0, s[8:9]
	s_addc_u32 s31, s31, 0
	s_add_i32 s34, s61, s36
	global_load_lds_dwordx4 v[218:219], off
	v_lshl_add_u64 v[218:219], s[30:31], 0, v[134:135]
	s_mov_b32 m0, s34
	s_nop 0
	global_load_lds_dwordx4 v[218:219], off
	v_lshl_add_u64 v[218:219], s[30:31], 0, v[130:131]
	s_add_i32 m0, s34, 0x2000
	s_nop 0
	global_load_lds_dwordx4 v[218:219], off
	v_lshl_add_u64 v[218:219], v[222:223], 0, s[8:9]
	s_mov_b32 m0, s44
	s_nop 0
	global_load_lds_dwordx4 v[218:219], off
	v_lshl_add_u64 v[218:219], v[224:225], 0, s[8:9]
	s_mov_b32 m0, s45
	s_nop 0
	global_load_lds_dwordx4 v[218:219], off
	s_waitcnt vmcnt(8)
	s_waitcnt lgkmcnt(0)
	s_barrier
	s_setprio 1
	s_waitcnt lgkmcnt(0)
	v_mfma_f32_16x16x32_bf16 v[62:65], v[152:155], v[184:187], v[62:65]
	v_mfma_f32_16x16x32_bf16 v[58:61], v[160:163], v[184:187], v[58:61]
	v_mfma_f32_16x16x32_bf16 v[54:57], v[152:155], v[192:195], v[54:57]
	v_mfma_f32_16x16x32_bf16 v[50:53], v[160:163], v[192:195], v[50:53]
	v_mfma_f32_16x16x32_bf16 v[38:41], v[152:155], v[200:203], v[38:41]
	v_mfma_f32_16x16x32_bf16 v[34:37], v[160:163], v[200:203], v[34:37]
	v_mfma_f32_16x16x32_bf16 v[22:25], v[152:155], v[210:213], v[22:25]
	v_mfma_f32_16x16x32_bf16 v[18:21], v[160:163], v[210:213], v[18:21]
	v_mfma_f32_16x16x32_bf16 v[62:65], v[156:159], v[188:191], v[62:65]
	v_mfma_f32_16x16x32_bf16 v[58:61], v[164:167], v[188:191], v[58:61]
	v_mfma_f32_16x16x32_bf16 v[54:57], v[156:159], v[196:199], v[54:57]
	v_mfma_f32_16x16x32_bf16 v[50:53], v[164:167], v[196:199], v[50:53]
	v_mfma_f32_16x16x32_bf16 v[38:41], v[156:159], v[204:207], v[38:41]
	v_mfma_f32_16x16x32_bf16 v[34:37], v[164:167], v[204:207], v[34:37]
	v_mfma_f32_16x16x32_bf16 v[22:25], v[156:159], v[214:217], v[22:25]
	v_mfma_f32_16x16x32_bf16 v[18:21], v[164:167], v[214:217], v[18:21]
	s_setprio 0
	s_setprio 1
	v_mfma_f32_16x16x32_bf16 v[46:49], v[168:171], v[184:187], v[46:49]
	v_mfma_f32_16x16x32_bf16 v[42:45], v[176:179], v[184:187], v[42:45]
	v_mfma_f32_16x16x32_bf16 v[30:33], v[168:171], v[192:195], v[30:33]
	v_mfma_f32_16x16x32_bf16 v[26:29], v[176:179], v[192:195], v[26:29]
	v_mfma_f32_16x16x32_bf16 v[14:17], v[168:171], v[200:203], v[14:17]
	v_mfma_f32_16x16x32_bf16 v[10:13], v[176:179], v[200:203], v[10:13]
	v_mfma_f32_16x16x32_bf16 v[6:9], v[168:171], v[210:213], v[6:9]
	v_mfma_f32_16x16x32_bf16 v[2:5], v[176:179], v[210:213], v[2:5]
	v_mfma_f32_16x16x32_bf16 v[46:49], v[172:175], v[188:191], v[46:49]
	v_mfma_f32_16x16x32_bf16 v[42:45], v[180:183], v[188:191], v[42:45]
	v_mfma_f32_16x16x32_bf16 v[30:33], v[172:175], v[196:199], v[30:33]
	v_mfma_f32_16x16x32_bf16 v[26:29], v[180:183], v[196:199], v[26:29]
	v_mfma_f32_16x16x32_bf16 v[14:17], v[172:175], v[204:207], v[14:17]
	v_mfma_f32_16x16x32_bf16 v[10:13], v[180:183], v[204:207], v[10:13]
	v_mfma_f32_16x16x32_bf16 v[6:9], v[172:175], v[214:217], v[6:9]
	v_mfma_f32_16x16x32_bf16 v[2:5], v[180:183], v[214:217], v[2:5]
	s_setprio 0
	s_barrier
	s_add_i32 s59, s59, 2
	s_add_u32 s28, s28, 0x100
	s_addc_u32 s29, s29, 0
	s_add_u32 s57, s57, 0x100
	s_addc_u32 s58, s58, 0
	s_cmpk_gt_u32 s59, 0x55
	s_cbranch_scc1 .Lpeel_exit_9
	.p2align 6

; #define PG8_BAR __builtin_amdgcn_s_barrier()
; template <class Epi, class Sched, bool ALIGN_EPI = false, bool SP2 = false>
; __device__ __forceinline__ void gemm_phase(PG8_LAS unsigned char* lds, const Gemm g, const Sched& S, const Epi& E) {
;     ...
;         if constexpr (ALIGN_EPI) { if (wr == 0) PG8_BAR; }
;         if constexpr (!Epi::AFTER_DRAIN) { E(acc, cur, wr, wc, fr, fq); S.done(cur); }
.Lpeel_exit_9:
	s_and_b64 vcc, exec, s[10:11]
	s_cbranch_vccz .LBB0_1036
	s_barrier

; #define PG8_STAGE(bufoff, gbase, voff) do { _Pragma("unroll") for (int _i = 0; _i < 2; ++_i) \
;         __builtin_amdgcn_global_load_lds((const unsigned*)((const char*)(gbase) + (voff)[_i]), (PG8_LAS unsigned*)(lds + (bufoff) + ldsw + _i * 8192), 16, 0, 0); } while (0)
; #define PG8_WAIT_V(n) asm volatile("s_waitcnt vmcnt(" #n ")" ::: "memory")
; #define PG8_BAR __builtin_amdgcn_s_barrier()
; template <class Epi, class Sched, bool ALIGN_EPI = false, bool SP2 = false>
; __device__ __forceinline__ void gemm_phase(PG8_LAS unsigned char* lds, const Gemm g, const Sched& S, const Epi& E) {
;     const int tid = threadIdx.x, wid = __builtin_amdgcn_readfirstlane(tid >> 6), lane = tid & 63, wr = wid >> 2, wc = wid & 3, fr = lane & 15, fq = lane >> 4;
;     const int K = g.K, nt = K / BK;
;     unsigned voffA[2], voffB[2];
; #pragma unroll
;     for (int i = 0; i < 2; ++i) { int R, C; stage_rc(tid * 16 + i * 8192, R, C); const int Rb = Epi::PERM ? ((R & ~31) + perm32(R & 31)) : R;
;         voffA[i] = (unsigned)(R * g.lda + C) * 2u; voffB[i] = (unsigned)(Rb * g.ldb + C) * 2u; }
;     const size_t kstep = (size_t)(BK * 2);
;     const size_t hstepA = (size_t)HALF * g.lda * 2, hstepB = (size_t)HALF * g.ldb * 2;
;     const size_t tstepA = 2 * hstepA, tstepB = 2 * hstepB;
;     const unsigned ldsw = (unsigned)wid * 1024u;
;     const int aoff = lds_byte(wr * 64 + fr, fq * 8), boff = lds_byte(wc * 32 + fr, fq * 8);
;     ...
;         PG8_WAIT_V(2); PG8_BAR;
;         PG8_STAGE(PG8_SB(1, 0), cB + kstep, voffB); PG8_STAGE(PG8_SA(1, 0), cA + kstep, voffA); PG8_STAGE(PG8_SB(1, 1), cB + hstepB + kstep, voffB);
;         PG8_WAIT_V(6); PG8_BAR;
.LBB0_1155:
	s_lshl_b32 s6, s6, 5
	s_mov_b64 s[12:13], 0x80
	s_and_b32 s16, s6, 0x60
	s_add_i32 m0, s42, 0x18000
	v_lshl_add_u64 v[8:9], v[8:9], 0, s[12:13]
	s_lshl_b32 s14, s5, 13
	s_lshl_b32 s15, s16, 7
	s_waitcnt vmcnt(2)
	s_barrier
	global_load_lds_dwordx4 v[8:9], off
	v_lshl_add_u64 v[4:5], v[4:5], 0, s[12:13]
	s_add_i32 m0, s42, 0x1a000
	s_add_i32 s48, s42, 0x8000
	s_add_i32 s49, s42, 0xa000
	global_load_lds_dwordx4 v[4:5], off
	v_lshl_add_u64 v[2:3], v[2:3], 0, s[12:13]
	s_mov_b32 m0, s48
	s_add_u32 s6, s36, 0x20080
	global_load_lds_dwordx4 v[2:3], off
	v_lshl_add_u64 v[2:3], v[6:7], 0, s[12:13]
	s_mov_b32 m0, s49
	s_addc_u32 s7, s37, 0
	global_load_lds_dwordx4 v[2:3], off
	s_add_i32 m0, s42, 0x1c000
	v_lshl_add_u64 v[2:3], s[6:7], 0, v[134:135]
	global_load_lds_dwordx4 v[2:3], off
	v_lshl_add_u64 v[2:3], s[6:7], 0, v[130:131]
	s_add_i32 m0, s42, 0x1e000
	v_lshlrev_b32_e32 v4, 2, v0
	global_load_lds_dwordx4 v[2:3], off
	v_and_b32_e32 v2, 15, v0
	v_and_b32_e32 v3, 48, v0
	v_lshl_or_b32 v1, s5, 6, v2
	v_lshl_or_b32 v2, v2, 6, v3
	v_and_b32_e32 v4, 32, v4
	v_bitop3_b32 v5, v2, s14, v4 bitop3:0xde
	v_lshlrev_b32_e32 v2, 6, v0
	s_movk_i32 s5, 0x3c0
	v_and_or_b32 v2, v2, s5, v3
	s_waitcnt vmcnt(0)
	s_cmpk_lt_u32 s4, 0x100
	v_bitop3_b32 v148, s15, v2, v4 bitop3:0xf6
	s_cselect_b64 s[14:15], -1, 0
	v_lshl_or_b32 v2, s16, 2, v3
	v_mov_b32_e32 v3, v135
	s_add_i32 s51, 0, 0x10000
	s_add_i32 s52, 0, 0x14000
	s_waitcnt lgkmcnt(0)
	s_ashr_i32 s50, s33, 31
	v_lshl_add_u64 v[138:139], s[0:1], 0, v[2:3]
	v_add3_u32 v140, v13, v10, v11
	v_mov_b32_e32 v141, v135
	v_add3_u32 v142, v12, v10, v11
	v_mov_b32_e32 v143, v135
	v_mov_b64_e32 v[144:145], 0x280
	v_mov_b64_e32 v[146:147], 0x27f
	v_add_u32_e32 v149, s51, v148
	v_add_u32_e32 v150, s52, v148
	v_add_u32_e32 v151, 0, v5
	s_mov_b32 s53, 0x20000
	s_mov_b64 s[16:17], 0x24000
	s_mov_b32 s54, 0x24000
	s_mov_b64 s[24:25], 0x28000
	s_mov_b32 s55, 0x28000
	s_mov_b64 s[26:27], 0x2c000
	s_barrier
	s_branch .LBB0_1158

; #define PG8_STAGE(bufoff, gbase, voff) do { _Pragma("unroll") for (int _i = 0; _i < 2; ++_i) \
;         __builtin_amdgcn_global_load_lds((const unsigned*)((const char*)(gbase) + (voff)[_i]), (PG8_LAS unsigned*)(lds + (bufoff) + ldsw + _i * 8192), 16, 0, 0); } while (0)
; #define PG8_LDA(dst, b, h) do { _Pragma("unroll") for (int m = 0; m < 4; ++m) _Pragma("unroll") for (int k = 0; k < 2; ++k) dst[m][k] = *(const PG8_LAS bf16x8*)(lds + PG8_SA(b, h) + aoff + m * 2048 + k * 1024); } while (0)
; #define PG8_LDB(dst, b, h) do { _Pragma("unroll") for (int n = 0; n < 2; ++n) _Pragma("unroll") for (int k = 0; k < 2; ++k) dst[n][k] = *(const PG8_LAS bf16x8*)(lds + PG8_SB(b, h) + boff + n * 2048 + k * 1024); } while (0)
; #define PG8_WAIT_V(n) asm volatile("s_waitcnt vmcnt(" #n ")" ::: "memory")
; #define PG8_WAIT_L(n) asm volatile("s_waitcnt lgkmcnt(" #n ")" ::: "memory")
; #define PG8_BAR __builtin_amdgcn_s_barrier()
; template <class Epi, class Sched, bool ALIGN_EPI = false, bool SP2 = false>
; __device__ __forceinline__ void gemm_phase(PG8_LAS unsigned char* lds, const Gemm g, const Sched& S, const Epi& E) {
;     ...
;         const bool has_next = S.next(ui + 1, nxt);
;         const char* nA = has_next ? (const char*)g.A + (size_t)nxt.pm * tstepA : cA; const char* nB = has_next ? (const char*)g.Bt + (size_t)nxt.pn * tstepB : cB;
;         for (int t = 0; t < nt; t += 2) {
;             const bool last = (t == nt - 2);
;             const char* a1 = cA + (size_t)(t + 1) * kstep;
;             const char* a2 = last ? nA : cA + (size_t)(t + 2) * kstep; const char* b2 = last ? nB : cB + (size_t)(t + 2) * kstep;
;             const char* a3 = a2 + kstep; const char* b3 = b2 + kstep;
;             if (last && has_next) S.a_ready(nxt);
;             if constexpr (SP2) {
;             PG8_LDB(B0, 0, 0); PG8_LDB(B1, 0, 1); PG8_SCHED; PG8_LDA(At, 0, 0); PG8_STAGE(PG8_SA(1, 1), a1 + hstepA, voffA);
;             PG8_WAIT_V(8); PG8_WAIT_L(0); PG8_BAR; PG8_MMA(0, 0, At, B0); PG8_MMA(0, 1, At, B1); PG8_BAR; PG8_SCHED;
;     ...
; #pragma unroll
;         for (int a = 0; a < 2; ++a)
; #pragma unroll
;             for (int b = 0; b < 2; ++b)
; #pragma unroll
;                 for (int m = 0; m < 4; ++m)
; #pragma unroll
;                     for (int n = 0; n < 2; ++n) acc[a][b][m][n] = (f32x4){0.f, 0.f, 0.f, 0.f};
;         cur = nxt; cA = nA; cB = nB; ++ui;
.LBB0_1162:
	s_ashr_i32 s29, s28, 31
	s_lshl_b64 s[34:35], s[28:29], 18
	s_add_u32 s34, s22, s34
	s_addc_u32 s35, s23, s35
	s_and_b64 s[6:7], s[6:7], exec
	s_cselect_b32 s29, s35, s37
	s_cselect_b32 s57, s34, s36
	s_add_u32 s6, s38, 0x30080
	s_addc_u32 s7, s39, 0
	s_add_u32 s58, s36, 0x100
	v_mov_b32_e32 v2, 0
	s_addc_u32 s59, s37, 0
	s_mov_b32 s60, -2
	v_mov_b32_e32 v3, v2
	v_mov_b32_e32 v4, v2
	v_mov_b32_e32 v5, v2
	v_mov_b32_e32 v6, v2
	v_mov_b32_e32 v7, v2
	v_mov_b32_e32 v8, v2
	v_mov_b32_e32 v9, v2
	v_mov_b32_e32 v10, v2
	v_mov_b32_e32 v11, v2
	v_mov_b32_e32 v12, v2
	v_mov_b32_e32 v13, v2
	v_mov_b32_e32 v14, v2
	v_mov_b32_e32 v15, v2
	v_mov_b32_e32 v16, v2
	v_mov_b32_e32 v17, v2
	v_mov_b32_e32 v22, v2
	v_mov_b32_e32 v23, v2
	v_mov_b32_e32 v24, v2
	v_mov_b32_e32 v25, v2
	v_mov_b32_e32 v30, v2
	v_mov_b32_e32 v31, v2
	v_mov_b32_e32 v32, v2
	v_mov_b32_e32 v33, v2
	v_mov_b32_e32 v38, v2
	v_mov_b32_e32 v39, v2
	v_mov_b32_e32 v40, v2
	v_mov_b32_e32 v41, v2
	v_mov_b32_e32 v46, v2
	v_mov_b32_e32 v47, v2
	v_mov_b32_e32 v48, v2
	v_mov_b32_e32 v49, v2
	v_mov_b32_e32 v18, v2
	v_mov_b32_e32 v19, v2
	v_mov_b32_e32 v20, v2
	v_mov_b32_e32 v21, v2
	v_mov_b32_e32 v26, v2
	v_mov_b32_e32 v27, v2
	v_mov_b32_e32 v28, v2
	v_mov_b32_e32 v29, v2
	v_mov_b32_e32 v34, v2
	v_mov_b32_e32 v35, v2
	v_mov_b32_e32 v36, v2
	v_mov_b32_e32 v37, v2
	v_mov_b32_e32 v42, v2
	v_mov_b32_e32 v43, v2
	v_mov_b32_e32 v44, v2
	v_mov_b32_e32 v45, v2
	v_mov_b32_e32 v50, v2
	v_mov_b32_e32 v51, v2
	v_mov_b32_e32 v52, v2
	v_mov_b32_e32 v53, v2
	v_mov_b32_e32 v54, v2
	v_mov_b32_e32 v55, v2
	v_mov_b32_e32 v56, v2
	v_mov_b32_e32 v57, v2
	v_mov_b32_e32 v58, v2
	v_mov_b32_e32 v59, v2
	v_mov_b32_e32 v60, v2
	v_mov_b32_e32 v61, v2
	v_mov_b32_e32 v62, v2
	v_mov_b32_e32 v63, v2
	v_mov_b32_e32 v64, v2
	v_mov_b32_e32 v65, v2
	v_mov_b32_e32 v66, v2
	v_mov_b32_e32 v67, v2
	v_mov_b32_e32 v68, v2
	v_mov_b32_e32 v69, v2
	v_mov_b32_e32 v70, v2
	v_mov_b32_e32 v71, v2
	v_mov_b32_e32 v72, v2
	v_mov_b32_e32 v73, v2
	v_mov_b32_e32 v74, v2
	v_mov_b32_e32 v75, v2
	v_mov_b32_e32 v76, v2
	v_mov_b32_e32 v77, v2
	v_mov_b32_e32 v78, v2
	v_mov_b32_e32 v79, v2
	v_mov_b32_e32 v80, v2
	v_mov_b32_e32 v81, v2
	v_mov_b32_e32 v86, v2
	v_mov_b32_e32 v87, v2
	v_mov_b32_e32 v88, v2
	v_mov_b32_e32 v89, v2
	v_mov_b32_e32 v94, v2
	v_mov_b32_e32 v95, v2
	v_mov_b32_e32 v96, v2
	v_mov_b32_e32 v97, v2
	v_mov_b32_e32 v102, v2
	v_mov_b32_e32 v103, v2
	v_mov_b32_e32 v104, v2
	v_mov_b32_e32 v105, v2
	v_mov_b32_e32 v110, v2
	v_mov_b32_e32 v111, v2
	v_mov_b32_e32 v112, v2
	v_mov_b32_e32 v113, v2
	v_mov_b32_e32 v82, v2
	v_mov_b32_e32 v83, v2
	v_mov_b32_e32 v84, v2
	v_mov_b32_e32 v85, v2
	v_mov_b32_e32 v90, v2
	v_mov_b32_e32 v91, v2
	v_mov_b32_e32 v92, v2
	v_mov_b32_e32 v93, v2
	v_mov_b32_e32 v98, v2
	v_mov_b32_e32 v99, v2
	v_mov_b32_e32 v100, v2
	v_mov_b32_e32 v101, v2
	v_mov_b32_e32 v106, v2
	v_mov_b32_e32 v107, v2
	v_mov_b32_e32 v108, v2
	v_mov_b32_e32 v109, v2
	v_mov_b32_e32 v114, v2
	v_mov_b32_e32 v115, v2
	v_mov_b32_e32 v116, v2
	v_mov_b32_e32 v117, v2
	v_mov_b32_e32 v118, v2
	v_mov_b32_e32 v119, v2
	v_mov_b32_e32 v120, v2
	v_mov_b32_e32 v121, v2
	v_mov_b32_e32 v122, v2
	v_mov_b32_e32 v123, v2
	v_mov_b32_e32 v124, v2
	v_mov_b32_e32 v125, v2
	v_mov_b32_e32 v126, v2
	v_mov_b32_e32 v127, v2
	v_mov_b32_e32 v128, v2
	v_mov_b32_e32 v129, v2
	ds_read_b128 v[152:155], v149
	ds_read_b128 v[156:159], v149 offset:1024
	ds_read_b128 v[160:163], v149 offset:2048
	ds_read_b128 v[164:167], v149 offset:3072
	ds_read_b128 v[168:171], v150
	ds_read_b128 v[172:175], v150 offset:1024
	ds_read_b128 v[176:179], v150 offset:2048
	ds_read_b128 v[180:183], v150 offset:3072
	s_add_u32 s36, s6, 0xfffd0080
	s_addc_u32 s37, s7, -1
	s_cmp_eq_u32 s60, 4
	s_cselect_b32 s39, s31, s37
	s_cselect_b32 s38, s30, s36
	s_cselect_b32 s37, s29, s59
	s_cselect_b32 s36, s57, s58
	v_lshl_add_u64 v[218:219], s[6:7], 0, v[140:141]
	s_add_i32 m0, s42, 0xc000
	ds_read_b128 v[184:187], v151
	ds_read_b128 v[188:191], v151 offset:1024
	ds_read_b128 v[192:195], v151 offset:2048
	ds_read_b128 v[196:199], v151 offset:3072
	ds_read_b128 v[200:203], v151 offset:4096
	ds_read_b128 v[204:207], v151 offset:5120
	ds_read_b128 v[210:213], v151 offset:6144
	ds_read_b128 v[214:217], v151 offset:7168
	global_load_lds_dwordx4 v[218:219], off
	v_lshl_add_u64 v[218:219], s[6:7], 0, v[142:143]
	s_add_i32 m0, s42, 0xe000
	s_nop 0
	global_load_lds_dwordx4 v[218:219], off
	s_waitcnt vmcnt(40)
	s_waitcnt lgkmcnt(0)
	s_barrier
	s_setprio 1
	s_waitcnt lgkmcnt(0)
	v_mfma_f32_16x16x32_bf16 v[126:129], v[152:155], v[184:187], v[126:129]
	v_mfma_f32_16x16x32_bf16 v[122:125], v[160:163], v[184:187], v[122:125]
	v_mfma_f32_16x16x32_bf16 v[118:121], v[152:155], v[192:195], v[118:121]
	v_mfma_f32_16x16x32_bf16 v[114:117], v[160:163], v[192:195], v[114:117]
	v_mfma_f32_16x16x32_bf16 v[106:109], v[152:155], v[200:203], v[106:109]
	v_mfma_f32_16x16x32_bf16 v[98:101], v[160:163], v[200:203], v[98:101]
	v_mfma_f32_16x16x32_bf16 v[90:93], v[152:155], v[210:213], v[90:93]
	v_mfma_f32_16x16x32_bf16 v[82:85], v[160:163], v[210:213], v[82:85]
	v_mfma_f32_16x16x32_bf16 v[126:129], v[156:159], v[188:191], v[126:129]
	v_mfma_f32_16x16x32_bf16 v[122:125], v[164:167], v[188:191], v[122:125]
	v_mfma_f32_16x16x32_bf16 v[118:121], v[156:159], v[196:199], v[118:121]
	v_mfma_f32_16x16x32_bf16 v[114:117], v[164:167], v[196:199], v[114:117]
	v_mfma_f32_16x16x32_bf16 v[106:109], v[156:159], v[204:207], v[106:109]
	v_mfma_f32_16x16x32_bf16 v[98:101], v[164:167], v[204:207], v[98:101]
	v_mfma_f32_16x16x32_bf16 v[90:93], v[156:159], v[214:217], v[90:93]
	v_mfma_f32_16x16x32_bf16 v[82:85], v[164:167], v[214:217], v[82:85]
	s_setprio 0
	s_setprio 1
	v_mfma_f32_16x16x32_bf16 v[110:113], v[168:171], v[184:187], v[110:113]
	v_mfma_f32_16x16x32_bf16 v[102:105], v[176:179], v[184:187], v[102:105]
	v_mfma_f32_16x16x32_bf16 v[94:97], v[168:171], v[192:195], v[94:97]
	v_mfma_f32_16x16x32_bf16 v[86:89], v[176:179], v[192:195], v[86:89]
	v_mfma_f32_16x16x32_bf16 v[78:81], v[168:171], v[200:203], v[78:81]
	v_mfma_f32_16x16x32_bf16 v[74:77], v[176:179], v[200:203], v[74:77]
	v_mfma_f32_16x16x32_bf16 v[70:73], v[168:171], v[210:213], v[70:73]
	v_mfma_f32_16x16x32_bf16 v[66:69], v[176:179], v[210:213], v[66:69]
	v_mfma_f32_16x16x32_bf16 v[110:113], v[172:175], v[188:191], v[110:113]
	v_mfma_f32_16x16x32_bf16 v[102:105], v[180:183], v[188:191], v[102:105]
	v_mfma_f32_16x16x32_bf16 v[94:97], v[172:175], v[196:199], v[94:97]
	v_mfma_f32_16x16x32_bf16 v[86:89], v[180:183], v[196:199], v[86:89]
	v_mfma_f32_16x16x32_bf16 v[78:81], v[172:175], v[204:207], v[78:81]
	v_mfma_f32_16x16x32_bf16 v[74:77], v[180:183], v[204:207], v[74:77]
	v_mfma_f32_16x16x32_bf16 v[70:73], v[172:175], v[214:217], v[70:73]
	v_mfma_f32_16x16x32_bf16 v[66:69], v[180:183], v[214:217], v[66:69]
	s_setprio 0
	s_barrier
; #define PG8_STAGE(bufoff, gbase, voff) do { _Pragma("unroll") for (int _i = 0; _i < 2; ++_i) \
;         __builtin_amdgcn_global_load_lds((const unsigned*)((const char*)(gbase) + (voff)[_i]), (PG8_LAS unsigned*)(lds + (bufoff) + ldsw + _i * 8192), 16, 0, 0); } while (0)
; #define PG8_LDA(dst, b, h) do { _Pragma("unroll") for (int m = 0; m < 4; ++m) _Pragma("unroll") for (int k = 0; k < 2; ++k) dst[m][k] = *(const PG8_LAS bf16x8*)(lds + PG8_SA(b, h) + aoff + m * 2048 + k * 1024); } while (0)
; #define PG8_LDB(dst, b, h) do { _Pragma("unroll") for (int n = 0; n < 2; ++n) _Pragma("unroll") for (int k = 0; k < 2; ++k) dst[n][k] = *(const PG8_LAS bf16x8*)(lds + PG8_SB(b, h) + boff + n * 2048 + k * 1024); } while (0)
; #define PG8_MMA(ai, bj, At, Bt) do { __builtin_amdgcn_s_setprio(1); _Pragma("unroll") for (int m = 0; m < 4; ++m) _Pragma("unroll") for (int n = 0; n < 2; ++n) _Pragma("unroll") for (int k = 0; k < 2; ++k) \
;         acc[ai][bj][m][n] = __builtin_amdgcn_mfma_f32_16x16x32_bf16(Bt[n][k], At[m][k], acc[ai][bj][m][n], 0, 0, 0); __builtin_amdgcn_s_setprio(0); } while (0)
; #define PG8_WAIT_V(n) asm volatile("s_waitcnt vmcnt(" #n ")" ::: "memory")
; #define PG8_WAIT_L(n) asm volatile("s_waitcnt lgkmcnt(" #n ")" ::: "memory")
; #define PG8_BAR __builtin_amdgcn_s_barrier()
; #define PG8_SCHED __builtin_amdgcn_sched_barrier(0)
; template <class Epi, class Sched, bool ALIGN_EPI = false, bool SP2 = false>
; __device__ __forceinline__ void gemm_phase(PG8_LAS unsigned char* lds, const Gemm g, const Sched& S, const Epi& E) {
;     ...
;             PG8_LDA(At, 0, 1); PG8_STAGE(PG8_SB(0, 0), b2, voffB); PG8_STAGE(PG8_SB(0, 1), b2 + hstepB, voffB); PG8_STAGE(PG8_SA(0, 0), a2, voffA);
;             PG8_WAIT_V(8); PG8_WAIT_L(0); PG8_BAR; PG8_MMA(1, 0, At, B0); PG8_MMA(1, 1, At, B1); PG8_BAR; PG8_SCHED;
;             PG8_LDB(B0, 1, 0); PG8_LDB(B1, 1, 1); PG8_SCHED; PG8_LDA(At, 1, 0); PG8_STAGE(PG8_SA(0, 1), a2 + hstepA, voffA);
;             PG8_WAIT_V(8); PG8_WAIT_L(0); PG8_BAR; PG8_MMA(0, 0, At, B0); PG8_MMA(0, 1, At, B1); PG8_BAR; PG8_SCHED;
	s_add_i32 s61, s51, s40
	v_lshl_add_u64 v[218:219], s[36:37], 0, v[134:135]
	s_mov_b32 m0, s61
	ds_read_b128 v[184:187], v151 offset:16384
	ds_read_b128 v[188:191], v151 offset:17408
	ds_read_b128 v[192:195], v151 offset:18432
	ds_read_b128 v[196:199], v151 offset:19456
	ds_read_b128 v[200:203], v151 offset:20480
	ds_read_b128 v[204:207], v151 offset:21504
	ds_read_b128 v[210:213], v151 offset:22528
	ds_read_b128 v[214:217], v151 offset:23552
	global_load_lds_dwordx4 v[218:219], off
	s_add_i32 m0, s61, 0x2000
	s_add_u32 s62, s36, 0x20000
	v_lshl_add_u64 v[220:221], s[36:37], 0, v[130:131]
	s_addc_u32 s63, s37, 0
	s_add_i32 s61, s52, s40
	global_load_lds_dwordx4 v[220:221], off
	v_lshl_add_u64 v[222:223], s[62:63], 0, v[134:135]
	s_mov_b32 m0, s61
	v_lshl_add_u64 v[224:225], s[38:39], 0, v[132:133]
	global_load_lds_dwordx4 v[222:223], off
	v_lshl_add_u64 v[222:223], s[62:63], 0, v[130:131]
	s_add_i32 m0, s61, 0x2000
	s_nop 0
	global_load_lds_dwordx4 v[222:223], off
	v_lshl_add_u64 v[222:223], s[38:39], 0, v[136:137]
	s_mov_b32 m0, s42
	s_nop 0
	global_load_lds_dwordx4 v[222:223], off
	s_mov_b32 m0, s43
	s_nop 0
	global_load_lds_dwordx4 v[224:225], off
	s_waitcnt vmcnt(40)
	s_waitcnt lgkmcnt(0)
	s_barrier
	s_setprio 1
	s_waitcnt lgkmcnt(0)
	v_mfma_f32_16x16x32_bf16 v[62:65], v[152:155], v[184:187], v[62:65]
	v_mfma_f32_16x16x32_bf16 v[58:61], v[160:163], v[184:187], v[58:61]
	v_mfma_f32_16x16x32_bf16 v[54:57], v[152:155], v[192:195], v[54:57]
	v_mfma_f32_16x16x32_bf16 v[50:53], v[160:163], v[192:195], v[50:53]
	v_mfma_f32_16x16x32_bf16 v[42:45], v[152:155], v[200:203], v[42:45]
	v_mfma_f32_16x16x32_bf16 v[34:37], v[160:163], v[200:203], v[34:37]
	v_mfma_f32_16x16x32_bf16 v[26:29], v[152:155], v[210:213], v[26:29]
	v_mfma_f32_16x16x32_bf16 v[18:21], v[160:163], v[210:213], v[18:21]
	v_mfma_f32_16x16x32_bf16 v[62:65], v[156:159], v[188:191], v[62:65]
	v_mfma_f32_16x16x32_bf16 v[58:61], v[164:167], v[188:191], v[58:61]
	v_mfma_f32_16x16x32_bf16 v[54:57], v[156:159], v[196:199], v[54:57]
	v_mfma_f32_16x16x32_bf16 v[50:53], v[164:167], v[196:199], v[50:53]
	v_mfma_f32_16x16x32_bf16 v[42:45], v[156:159], v[204:207], v[42:45]
	v_mfma_f32_16x16x32_bf16 v[34:37], v[164:167], v[204:207], v[34:37]
	v_mfma_f32_16x16x32_bf16 v[26:29], v[156:159], v[214:217], v[26:29]
	v_mfma_f32_16x16x32_bf16 v[18:21], v[164:167], v[214:217], v[18:21]
	s_setprio 0
	s_setprio 1
	v_mfma_f32_16x16x32_bf16 v[46:49], v[168:171], v[184:187], v[46:49]
	v_mfma_f32_16x16x32_bf16 v[38:41], v[176:179], v[184:187], v[38:41]
	v_mfma_f32_16x16x32_bf16 v[30:33], v[168:171], v[192:195], v[30:33]
	v_mfma_f32_16x16x32_bf16 v[22:25], v[176:179], v[192:195], v[22:25]
	v_mfma_f32_16x16x32_bf16 v[14:17], v[168:171], v[200:203], v[14:17]
	v_mfma_f32_16x16x32_bf16 v[10:13], v[176:179], v[200:203], v[10:13]
	v_mfma_f32_16x16x32_bf16 v[6:9], v[168:171], v[210:213], v[6:9]
	v_mfma_f32_16x16x32_bf16 v[2:5], v[176:179], v[210:213], v[2:5]
	v_mfma_f32_16x16x32_bf16 v[46:49], v[172:175], v[188:191], v[46:49]
	v_mfma_f32_16x16x32_bf16 v[38:41], v[180:183], v[188:191], v[38:41]
	v_mfma_f32_16x16x32_bf16 v[30:33], v[172:175], v[196:199], v[30:33]
	v_mfma_f32_16x16x32_bf16 v[22:25], v[180:183], v[196:199], v[22:25]
	v_mfma_f32_16x16x32_bf16 v[14:17], v[172:175], v[204:207], v[14:17]
	v_mfma_f32_16x16x32_bf16 v[10:13], v[180:183], v[204:207], v[10:13]
	v_mfma_f32_16x16x32_bf16 v[6:9], v[172:175], v[214:217], v[6:9]
	v_mfma_f32_16x16x32_bf16 v[2:5], v[180:183], v[214:217], v[2:5]
	s_setprio 0
	s_barrier
	s_add_i32 s61, 0, 0x18000
	s_add_i32 s62, 0, 0x1c000
	v_add_u32_e32 v164, s61, v148
	v_add_u32_e32 v180, s62, v148
	ds_read_b128 v[152:155], v164
	ds_read_b128 v[156:159], v164 offset:1024
	ds_read_b128 v[160:163], v164 offset:2048
	ds_read_b128 v[164:167], v164 offset:3072
	ds_read_b128 v[168:171], v180
	ds_read_b128 v[172:175], v180 offset:1024
	ds_read_b128 v[176:179], v180 offset:2048
	ds_read_b128 v[180:183], v180 offset:3072
	s_add_u32 s38, s38, 0x30000
	s_addc_u32 s39, s39, 0
	s_mov_b32 m0, s44
	v_lshl_add_u64 v[226:227], s[38:39], 0, v[136:137]
	ds_read_b128 v[184:187], v151 offset:32768
	ds_read_b128 v[188:191], v151 offset:33792
	ds_read_b128 v[192:195], v151 offset:34816
	ds_read_b128 v[196:199], v151 offset:35840
	ds_read_b128 v[200:203], v151 offset:36864
	ds_read_b128 v[204:207], v151 offset:37888
	ds_read_b128 v[210:213], v151 offset:38912
	ds_read_b128 v[214:217], v151 offset:39936
	global_load_lds_dwordx4 v[226:227], off
	v_lshl_add_u64 v[226:227], s[38:39], 0, v[132:133]
	s_mov_b32 m0, s45
	s_nop 0
	global_load_lds_dwordx4 v[226:227], off
	s_waitcnt vmcnt(8)
	s_waitcnt lgkmcnt(0)
	s_barrier
; #define PG8_STAGE(bufoff, gbase, voff) do { _Pragma("unroll") for (int _i = 0; _i < 2; ++_i) \
;         __builtin_amdgcn_global_load_lds((const unsigned*)((const char*)(gbase) + (voff)[_i]), (PG8_LAS unsigned*)(lds + (bufoff) + ldsw + _i * 8192), 16, 0, 0); } while (0)
; #define PG8_LDA(dst, b, h) do { _Pragma("unroll") for (int m = 0; m < 4; ++m) _Pragma("unroll") for (int k = 0; k < 2; ++k) dst[m][k] = *(const PG8_LAS bf16x8*)(lds + PG8_SA(b, h) + aoff + m * 2048 + k * 1024); } while (0)
; #define PG8_MMA(ai, bj, At, Bt) do { __builtin_amdgcn_s_setprio(1); _Pragma("unroll") for (int m = 0; m < 4; ++m) _Pragma("unroll") for (int n = 0; n < 2; ++n) _Pragma("unroll") for (int k = 0; k < 2; ++k) \
;         acc[ai][bj][m][n] = __builtin_amdgcn_mfma_f32_16x16x32_bf16(Bt[n][k], At[m][k], acc[ai][bj][m][n], 0, 0, 0); __builtin_amdgcn_s_setprio(0); } while (0)
; #define PG8_WAIT_V(n) asm volatile("s_waitcnt vmcnt(" #n ")" ::: "memory")
; #define PG8_WAIT_L(n) asm volatile("s_waitcnt lgkmcnt(" #n ")" ::: "memory")
; #define PG8_BAR __builtin_amdgcn_s_barrier()
; #define PG8_SCHED __builtin_amdgcn_sched_barrier(0)
; template <class Epi, class Sched, bool ALIGN_EPI = false, bool SP2 = false>
; __device__ __forceinline__ void gemm_phase(PG8_LAS unsigned char* lds, const Gemm g, const Sched& S, const Epi& E) {
;     ...
;             PG8_WAIT_V(8); PG8_WAIT_L(0); PG8_BAR; PG8_MMA(0, 0, At, B0); PG8_MMA(0, 1, At, B1); PG8_BAR; PG8_SCHED;
;             PG8_LDA(At, 1, 1); PG8_STAGE(PG8_SB(1, 0), b3, voffB); PG8_STAGE(PG8_SB(1, 1), b3 + hstepB, voffB); PG8_STAGE(PG8_SA(1, 0), a3, voffA);
;             PG8_WAIT_V(8); PG8_WAIT_L(0); PG8_BAR; PG8_MMA(1, 0, At, B0); PG8_MMA(1, 1, At, B1); PG8_BAR; PG8_SCHED;
	s_setprio 1
	s_waitcnt lgkmcnt(0)
	v_mfma_f32_16x16x32_bf16 v[126:129], v[152:155], v[184:187], v[126:129]
	v_mfma_f32_16x16x32_bf16 v[122:125], v[160:163], v[184:187], v[122:125]
	v_mfma_f32_16x16x32_bf16 v[118:121], v[152:155], v[192:195], v[118:121]
	v_mfma_f32_16x16x32_bf16 v[114:117], v[160:163], v[192:195], v[114:117]
	v_mfma_f32_16x16x32_bf16 v[106:109], v[152:155], v[200:203], v[106:109]
	v_mfma_f32_16x16x32_bf16 v[98:101], v[160:163], v[200:203], v[98:101]
	v_mfma_f32_16x16x32_bf16 v[90:93], v[152:155], v[210:213], v[90:93]
	v_mfma_f32_16x16x32_bf16 v[82:85], v[160:163], v[210:213], v[82:85]
	v_mfma_f32_16x16x32_bf16 v[126:129], v[156:159], v[188:191], v[126:129]
	v_mfma_f32_16x16x32_bf16 v[122:125], v[164:167], v[188:191], v[122:125]
	v_mfma_f32_16x16x32_bf16 v[118:121], v[156:159], v[196:199], v[118:121]
	v_mfma_f32_16x16x32_bf16 v[114:117], v[164:167], v[196:199], v[114:117]
	v_mfma_f32_16x16x32_bf16 v[106:109], v[156:159], v[204:207], v[106:109]
	v_mfma_f32_16x16x32_bf16 v[98:101], v[164:167], v[204:207], v[98:101]
	v_mfma_f32_16x16x32_bf16 v[90:93], v[156:159], v[214:217], v[90:93]
	v_mfma_f32_16x16x32_bf16 v[82:85], v[164:167], v[214:217], v[82:85]
	s_setprio 0
	s_setprio 1
	v_mfma_f32_16x16x32_bf16 v[110:113], v[168:171], v[184:187], v[110:113]
	v_mfma_f32_16x16x32_bf16 v[102:105], v[176:179], v[184:187], v[102:105]
	v_mfma_f32_16x16x32_bf16 v[94:97], v[168:171], v[192:195], v[94:97]
	v_mfma_f32_16x16x32_bf16 v[86:89], v[176:179], v[192:195], v[86:89]
	v_mfma_f32_16x16x32_bf16 v[78:81], v[168:171], v[200:203], v[78:81]
	v_mfma_f32_16x16x32_bf16 v[74:77], v[176:179], v[200:203], v[74:77]
	v_mfma_f32_16x16x32_bf16 v[70:73], v[168:171], v[210:213], v[70:73]
	v_mfma_f32_16x16x32_bf16 v[66:69], v[176:179], v[210:213], v[66:69]
	v_mfma_f32_16x16x32_bf16 v[110:113], v[172:175], v[188:191], v[110:113]
	v_mfma_f32_16x16x32_bf16 v[102:105], v[180:183], v[188:191], v[102:105]
	v_mfma_f32_16x16x32_bf16 v[94:97], v[172:175], v[196:199], v[94:97]
	v_mfma_f32_16x16x32_bf16 v[86:89], v[180:183], v[196:199], v[86:89]
	v_mfma_f32_16x16x32_bf16 v[78:81], v[172:175], v[204:207], v[78:81]
	v_mfma_f32_16x16x32_bf16 v[74:77], v[180:183], v[204:207], v[74:77]
	v_mfma_f32_16x16x32_bf16 v[70:73], v[172:175], v[214:217], v[70:73]
	v_mfma_f32_16x16x32_bf16 v[66:69], v[180:183], v[214:217], v[66:69]
	s_setprio 0
	s_barrier
	s_add_i32 s38, s61, s40
	v_lshl_add_u64 v[218:219], v[218:219], 0, s[12:13]
	s_mov_b32 m0, s38
	ds_read_b128 v[184:187], v151 offset:49152
	ds_read_b128 v[188:191], v151 offset:50176
	ds_read_b128 v[192:195], v151 offset:51200
	ds_read_b128 v[196:199], v151 offset:52224
	ds_read_b128 v[200:203], v151 offset:53248
	ds_read_b128 v[204:207], v151 offset:54272
	ds_read_b128 v[210:213], v151 offset:55296
	ds_read_b128 v[214:217], v151 offset:56320
	global_load_lds_dwordx4 v[218:219], off
	s_add_i32 m0, s38, 0x2000
	s_add_u32 s36, s36, 0x20080
	v_lshl_add_u64 v[218:219], v[220:221], 0, s[12:13]
	s_addc_u32 s37, s37, 0
	s_add_i32 s38, s62, s40
	global_load_lds_dwordx4 v[218:219], off
	v_lshl_add_u64 v[218:219], s[36:37], 0, v[134:135]
	s_mov_b32 m0, s38
	s_nop 0
	global_load_lds_dwordx4 v[218:219], off
	v_lshl_add_u64 v[218:219], s[36:37], 0, v[130:131]
	s_add_i32 m0, s38, 0x2000
	s_nop 0
	global_load_lds_dwordx4 v[218:219], off
	v_lshl_add_u64 v[218:219], v[222:223], 0, s[12:13]
	s_mov_b32 m0, s48
	s_nop 0
	global_load_lds_dwordx4 v[218:219], off
	v_lshl_add_u64 v[218:219], v[224:225], 0, s[12:13]
	s_mov_b32 m0, s49
	s_nop 0
	global_load_lds_dwordx4 v[218:219], off
	s_waitcnt vmcnt(8)
	s_waitcnt lgkmcnt(0)
	s_barrier
	s_setprio 1
	s_waitcnt lgkmcnt(0)
	v_mfma_f32_16x16x32_bf16 v[62:65], v[152:155], v[184:187], v[62:65]
	v_mfma_f32_16x16x32_bf16 v[58:61], v[160:163], v[184:187], v[58:61]
	v_mfma_f32_16x16x32_bf16 v[54:57], v[152:155], v[192:195], v[54:57]
	v_mfma_f32_16x16x32_bf16 v[50:53], v[160:163], v[192:195], v[50:53]
	v_mfma_f32_16x16x32_bf16 v[42:45], v[152:155], v[200:203], v[42:45]
	v_mfma_f32_16x16x32_bf16 v[34:37], v[160:163], v[200:203], v[34:37]
	v_mfma_f32_16x16x32_bf16 v[26:29], v[152:155], v[210:213], v[26:29]
	v_mfma_f32_16x16x32_bf16 v[18:21], v[160:163], v[210:213], v[18:21]
	v_mfma_f32_16x16x32_bf16 v[62:65], v[156:159], v[188:191], v[62:65]
	v_mfma_f32_16x16x32_bf16 v[58:61], v[164:167], v[188:191], v[58:61]
	v_mfma_f32_16x16x32_bf16 v[54:57], v[156:159], v[196:199], v[54:57]
	v_mfma_f32_16x16x32_bf16 v[50:53], v[164:167], v[196:199], v[50:53]
	v_mfma_f32_16x16x32_bf16 v[42:45], v[156:159], v[204:207], v[42:45]
	v_mfma_f32_16x16x32_bf16 v[34:37], v[164:167], v[204:207], v[34:37]
	v_mfma_f32_16x16x32_bf16 v[26:29], v[156:159], v[214:217], v[26:29]
	v_mfma_f32_16x16x32_bf16 v[18:21], v[164:167], v[214:217], v[18:21]
	s_setprio 0
	s_setprio 1
	v_mfma_f32_16x16x32_bf16 v[46:49], v[168:171], v[184:187], v[46:49]
	v_mfma_f32_16x16x32_bf16 v[38:41], v[176:179], v[184:187], v[38:41]
	v_mfma_f32_16x16x32_bf16 v[30:33], v[168:171], v[192:195], v[30:33]
	v_mfma_f32_16x16x32_bf16 v[22:25], v[176:179], v[192:195], v[22:25]
	v_mfma_f32_16x16x32_bf16 v[14:17], v[168:171], v[200:203], v[14:17]
	v_mfma_f32_16x16x32_bf16 v[10:13], v[176:179], v[200:203], v[10:13]
	v_mfma_f32_16x16x32_bf16 v[6:9], v[168:171], v[210:213], v[6:9]
	v_mfma_f32_16x16x32_bf16 v[2:5], v[176:179], v[210:213], v[2:5]
	v_mfma_f32_16x16x32_bf16 v[46:49], v[172:175], v[188:191], v[46:49]
	v_mfma_f32_16x16x32_bf16 v[38:41], v[180:183], v[188:191], v[38:41]
	v_mfma_f32_16x16x32_bf16 v[30:33], v[172:175], v[196:199], v[30:33]
	v_mfma_f32_16x16x32_bf16 v[22:25], v[180:183], v[196:199], v[22:25]
	v_mfma_f32_16x16x32_bf16 v[14:17], v[172:175], v[204:207], v[14:17]
	v_mfma_f32_16x16x32_bf16 v[10:13], v[180:183], v[204:207], v[10:13]
	v_mfma_f32_16x16x32_bf16 v[6:9], v[172:175], v[214:217], v[6:9]
	v_mfma_f32_16x16x32_bf16 v[2:5], v[180:183], v[214:217], v[2:5]
	s_setprio 0
	s_barrier
	s_add_i32 s60, s60, 2
	s_add_u32 s6, s6, 0x100
	s_addc_u32 s7, s7, 0
	s_add_u32 s58, s58, 0x100
	s_addc_u32 s59, s59, 0
	s_cmp_gt_u32 s60, 5
	s_cbranch_scc1 .Lpeel_exit_11
	.p2align 6

; #define PG8_BAR __builtin_amdgcn_s_barrier()
; template <class Epi, class Sched, bool ALIGN_EPI = false, bool SP2 = false>
; __device__ __forceinline__ void gemm_phase(PG8_LAS unsigned char* lds, const Gemm g, const Sched& S, const Epi& E) {
;     ...
;         if constexpr (ALIGN_EPI) { if (wr == 0) PG8_BAR; }
;         if constexpr (!Epi::AFTER_DRAIN) { E(acc, cur, wr, wc, fr, fq); S.done(cur); }
.Lpeel_exit_11:
	s_and_b64 vcc, exec, s[14:15]
	s_cbranch_vccz .LBB0_1166
	s_barrier

; #define PG8_STAGE(bufoff, gbase, voff) do { _Pragma("unroll") for (int _i = 0; _i < 2; ++_i) \
;         __builtin_amdgcn_global_load_lds((const unsigned*)((const char*)(gbase) + (voff)[_i]), (PG8_LAS unsigned*)(lds + (bufoff) + ldsw + _i * 8192), 16, 0, 0); } while (0)
; #define PG8_WAIT_V(n) asm volatile("s_waitcnt vmcnt(" #n ")" ::: "memory")
; #define PG8_BAR __builtin_amdgcn_s_barrier()
; template <class Epi, class Sched, bool ALIGN_EPI = false, bool SP2 = false>
; __device__ __forceinline__ void gemm_phase(PG8_LAS unsigned char* lds, const Gemm g, const Sched& S, const Epi& E) {
;     const int tid = threadIdx.x, wid = __builtin_amdgcn_readfirstlane(tid >> 6), lane = tid & 63, wr = wid >> 2, wc = wid & 3, fr = lane & 15, fq = lane >> 4;
;     const int K = g.K, nt = K / BK;
;     unsigned voffA[2], voffB[2];
; #pragma unroll
;     for (int i = 0; i < 2; ++i) { int R, C; stage_rc(tid * 16 + i * 8192, R, C); const int Rb = Epi::PERM ? ((R & ~31) + perm32(R & 31)) : R;
;         voffA[i] = (unsigned)(R * g.lda + C) * 2u; voffB[i] = (unsigned)(Rb * g.ldb + C) * 2u; }
;     const size_t kstep = (size_t)(BK * 2);
;     const size_t hstepA = (size_t)HALF * g.lda * 2, hstepB = (size_t)HALF * g.ldb * 2;
;     const size_t tstepA = 2 * hstepA, tstepB = 2 * hstepB;
;     const unsigned ldsw = (unsigned)wid * 1024u;
;     const int aoff = lds_byte(wr * 64 + fr, fq * 8), boff = lds_byte(wc * 32 + fr, fq * 8);
;     ...
;         PG8_WAIT_V(2); PG8_BAR;
;         PG8_STAGE(PG8_SB(1, 0), cB + kstep, voffB); PG8_STAGE(PG8_SA(1, 0), cA + kstep, voffA); PG8_STAGE(PG8_SB(1, 1), cB + hstepB + kstep, voffB);
;         PG8_WAIT_V(6); PG8_BAR;
.LBB0_1280:
	s_lshl_b32 s6, s6, 5
	s_mov_b64 s[12:13], 0x80
	s_and_b32 s16, s6, 0x60
	s_add_i32 m0, s25, 0x18000
	v_lshl_add_u64 v[8:9], v[8:9], 0, s[12:13]
	s_lshl_b32 s14, s4, 13
	s_lshl_b32 s15, s16, 7
	s_waitcnt vmcnt(2)
	s_barrier
	global_load_lds_dwordx4 v[8:9], off
	v_lshl_add_u64 v[6:7], v[6:7], 0, s[12:13]
	s_add_i32 m0, s25, 0x1a000
	s_add_i32 s30, s25, 0x8000
	s_add_i32 s31, s25, 0xa000
	global_load_lds_dwordx4 v[6:7], off
	v_lshl_add_u64 v[2:3], v[2:3], 0, s[12:13]
	s_mov_b32 m0, s30
	s_add_u32 s6, s2, 0x30080
	global_load_lds_dwordx4 v[2:3], off
	v_lshl_add_u64 v[2:3], v[4:5], 0, s[12:13]
	s_mov_b32 m0, s31
	s_addc_u32 s7, s3, 0
	global_load_lds_dwordx4 v[2:3], off
	s_add_i32 m0, s25, 0x1c000
	v_lshl_add_u64 v[2:3], s[6:7], 0, v[134:135]
	global_load_lds_dwordx4 v[2:3], off
	v_lshl_add_u64 v[2:3], s[6:7], 0, v[130:131]
	s_add_i32 m0, s25, 0x1e000
	v_lshlrev_b32_e32 v1, 1, v10
	global_load_lds_dwordx4 v[2:3], off
	v_and_b32_e32 v3, 15, v0
	v_lshlrev_b32_e32 v4, 2, v0
	v_lshl_or_b32 v2, v3, 6, v1
	v_and_b32_e32 v4, 32, v4
	v_bitop3_b32 v5, v2, s14, v4 bitop3:0xde
	v_lshlrev_b32_e32 v2, 6, v0
	s_movk_i32 s6, 0x3c0
	v_lshlrev_b32_e32 v3, 5, v3
	v_and_or_b32 v1, v2, s6, v1
	s_waitcnt vmcnt(0)
	s_cmpk_lt_u32 s5, 0x100
	v_lshl_or_b32 v148, s4, 11, v3
	v_add_u16_e32 v3, v11, v13
	v_bitop3_b32 v1, s15, v1, v4 bitop3:0xf6
	s_cselect_b64 s[14:15], -1, 0
	v_and_b32_e32 v2, 8, v12
	v_lshrrev_b16_e32 v3, 1, v3
	s_add_i32 s34, 0, 0x10000
	s_add_i32 s35, 0, 0x14000
	s_waitcnt lgkmcnt(0)
	s_ashr_i32 s33, s22, 31
	v_or_b32_e32 v149, s16, v10
	v_add_lshl_u32 v140, v15, v3, 1
	v_mov_b32_e32 v141, v139
	v_add_lshl_u32 v142, v14, v3, 1
	v_mov_b32_e32 v143, v139
	v_mov_b64_e32 v[144:145], 0x500
	v_mov_b64_e32 v[146:147], 0x4ff
	v_add_u32_e32 v150, s34, v1
	v_add_u32_e32 v151, s35, v1
	v_add_u32_e32 v152, 0, v5
	v_lshlrev_b32_e32 v138, 1, v2
	s_barrier
	s_branch .LBB0_1283

; #define PG8_STAGE(bufoff, gbase, voff) do { _Pragma("unroll") for (int _i = 0; _i < 2; ++_i) \
;         __builtin_amdgcn_global_load_lds((const unsigned*)((const char*)(gbase) + (voff)[_i]), (PG8_LAS unsigned*)(lds + (bufoff) + ldsw + _i * 8192), 16, 0, 0); } while (0)
; #define PG8_LDA(dst, b, h) do { _Pragma("unroll") for (int m = 0; m < 4; ++m) _Pragma("unroll") for (int k = 0; k < 2; ++k) dst[m][k] = *(const PG8_LAS bf16x8*)(lds + PG8_SA(b, h) + aoff + m * 2048 + k * 1024); } while (0)
; #define PG8_LDB(dst, b, h) do { _Pragma("unroll") for (int n = 0; n < 2; ++n) _Pragma("unroll") for (int k = 0; k < 2; ++k) dst[n][k] = *(const PG8_LAS bf16x8*)(lds + PG8_SB(b, h) + boff + n * 2048 + k * 1024); } while (0)
; #define PG8_WAIT_V(n) asm volatile("s_waitcnt vmcnt(" #n ")" ::: "memory")
; #define PG8_WAIT_L(n) asm volatile("s_waitcnt lgkmcnt(" #n ")" ::: "memory")
; #define PG8_BAR __builtin_amdgcn_s_barrier()
; template <class Epi, class Sched, bool ALIGN_EPI = false, bool SP2 = false>
; __device__ __forceinline__ void gemm_phase(PG8_LAS unsigned char* lds, const Gemm g, const Sched& S, const Epi& E) {
;     ...
;         const bool has_next = S.next(ui + 1, nxt);
;         const char* nA = has_next ? (const char*)g.A + (size_t)nxt.pm * tstepA : cA; const char* nB = has_next ? (const char*)g.Bt + (size_t)nxt.pn * tstepB : cB;
;         for (int t = 0; t < nt; t += 2) {
;             const bool last = (t == nt - 2);
;             const char* a1 = cA + (size_t)(t + 1) * kstep;
;             const char* a2 = last ? nA : cA + (size_t)(t + 2) * kstep; const char* b2 = last ? nB : cB + (size_t)(t + 2) * kstep;
;             const char* a3 = a2 + kstep; const char* b3 = b2 + kstep;
;             if (last && has_next) S.a_ready(nxt);
;             if constexpr (SP2) {
;             PG8_LDB(B0, 0, 0); PG8_LDB(B1, 0, 1); PG8_SCHED; PG8_LDA(At, 0, 0); PG8_STAGE(PG8_SA(1, 1), a1 + hstepA, voffA);
;             PG8_WAIT_V(8); PG8_WAIT_L(0); PG8_BAR; PG8_MMA(0, 0, At, B0); PG8_MMA(0, 1, At, B1); PG8_BAR; PG8_SCHED;
;     ...
; #pragma unroll
;         for (int a = 0; a < 2; ++a)
; #pragma unroll
;             for (int b = 0; b < 2; ++b)
; #pragma unroll
;                 for (int m = 0; m < 4; ++m)
; #pragma unroll
;                     for (int n = 0; n < 2; ++n) acc[a][b][m][n] = (f32x4){0.f, 0.f, 0.f, 0.f};
;         cur = nxt; cA = nA; cB = nB; ++ui;
.LBB0_1289:
	s_add_u32 s0, s0, 0x30080
	s_addc_u32 s1, s1, 0
	s_add_u32 s40, s2, 0x100
	v_mov_b32_e32 v2, 0
	s_addc_u32 s41, s3, 0
	s_mov_b32 s42, -2
	v_mov_b32_e32 v3, v2
	v_mov_b32_e32 v4, v2
	v_mov_b32_e32 v5, v2
	v_mov_b32_e32 v6, v2
	v_mov_b32_e32 v7, v2
	v_mov_b32_e32 v8, v2
	v_mov_b32_e32 v9, v2
	v_mov_b32_e32 v18, v2
	v_mov_b32_e32 v19, v2
	v_mov_b32_e32 v20, v2
	v_mov_b32_e32 v21, v2
	v_mov_b32_e32 v22, v2
	v_mov_b32_e32 v23, v2
	v_mov_b32_e32 v24, v2
	v_mov_b32_e32 v25, v2
	v_mov_b32_e32 v34, v2
	v_mov_b32_e32 v35, v2
	v_mov_b32_e32 v36, v2
	v_mov_b32_e32 v37, v2
	v_mov_b32_e32 v38, v2
	v_mov_b32_e32 v39, v2
	v_mov_b32_e32 v40, v2
	v_mov_b32_e32 v41, v2
	v_mov_b32_e32 v50, v2
	v_mov_b32_e32 v51, v2
	v_mov_b32_e32 v52, v2
	v_mov_b32_e32 v53, v2
	v_mov_b32_e32 v54, v2
	v_mov_b32_e32 v55, v2
	v_mov_b32_e32 v56, v2
	v_mov_b32_e32 v57, v2
	v_mov_b32_e32 v10, v2
	v_mov_b32_e32 v11, v2
	v_mov_b32_e32 v12, v2
	v_mov_b32_e32 v13, v2
	v_mov_b32_e32 v14, v2
	v_mov_b32_e32 v15, v2
	v_mov_b32_e32 v16, v2
	v_mov_b32_e32 v17, v2
	v_mov_b32_e32 v26, v2
	v_mov_b32_e32 v27, v2
	v_mov_b32_e32 v28, v2
	v_mov_b32_e32 v29, v2
	v_mov_b32_e32 v30, v2
	v_mov_b32_e32 v31, v2
	v_mov_b32_e32 v32, v2
	v_mov_b32_e32 v33, v2
	v_mov_b32_e32 v42, v2
	v_mov_b32_e32 v43, v2
	v_mov_b32_e32 v44, v2
	v_mov_b32_e32 v45, v2
	v_mov_b32_e32 v46, v2
	v_mov_b32_e32 v47, v2
	v_mov_b32_e32 v48, v2
	v_mov_b32_e32 v49, v2
	v_mov_b32_e32 v58, v2
	v_mov_b32_e32 v59, v2
	v_mov_b32_e32 v60, v2
	v_mov_b32_e32 v61, v2
	v_mov_b32_e32 v62, v2
	v_mov_b32_e32 v63, v2
	v_mov_b32_e32 v64, v2
	v_mov_b32_e32 v65, v2
	v_mov_b32_e32 v66, v2
	v_mov_b32_e32 v67, v2
	v_mov_b32_e32 v68, v2
	v_mov_b32_e32 v69, v2
	v_mov_b32_e32 v70, v2
	v_mov_b32_e32 v71, v2
	v_mov_b32_e32 v72, v2
	v_mov_b32_e32 v73, v2
	v_mov_b32_e32 v82, v2
	v_mov_b32_e32 v83, v2
	v_mov_b32_e32 v84, v2
	v_mov_b32_e32 v85, v2
	v_mov_b32_e32 v86, v2
	v_mov_b32_e32 v87, v2
	v_mov_b32_e32 v88, v2
	v_mov_b32_e32 v89, v2
	v_mov_b32_e32 v98, v2
	v_mov_b32_e32 v99, v2
	v_mov_b32_e32 v100, v2
	v_mov_b32_e32 v101, v2
	v_mov_b32_e32 v102, v2
	v_mov_b32_e32 v103, v2
	v_mov_b32_e32 v104, v2
	v_mov_b32_e32 v105, v2
	v_mov_b32_e32 v114, v2
	v_mov_b32_e32 v115, v2
	v_mov_b32_e32 v116, v2
	v_mov_b32_e32 v117, v2
	v_mov_b32_e32 v118, v2
	v_mov_b32_e32 v119, v2
	v_mov_b32_e32 v120, v2
	v_mov_b32_e32 v121, v2
	v_mov_b32_e32 v74, v2
	v_mov_b32_e32 v75, v2
	v_mov_b32_e32 v76, v2
	v_mov_b32_e32 v77, v2
	v_mov_b32_e32 v78, v2
	v_mov_b32_e32 v79, v2
	v_mov_b32_e32 v80, v2
	v_mov_b32_e32 v81, v2
	v_mov_b32_e32 v90, v2
	v_mov_b32_e32 v91, v2
	v_mov_b32_e32 v92, v2
	v_mov_b32_e32 v93, v2
	v_mov_b32_e32 v94, v2
	v_mov_b32_e32 v95, v2
	v_mov_b32_e32 v96, v2
	v_mov_b32_e32 v97, v2
	v_mov_b32_e32 v106, v2
	v_mov_b32_e32 v107, v2
	v_mov_b32_e32 v108, v2
	v_mov_b32_e32 v109, v2
	v_mov_b32_e32 v110, v2
	v_mov_b32_e32 v111, v2
	v_mov_b32_e32 v112, v2
	v_mov_b32_e32 v113, v2
	v_mov_b32_e32 v122, v2
	v_mov_b32_e32 v123, v2
	v_mov_b32_e32 v124, v2
	v_mov_b32_e32 v125, v2
	v_mov_b32_e32 v126, v2
	v_mov_b32_e32 v127, v2
	v_mov_b32_e32 v128, v2
	v_mov_b32_e32 v129, v2
	ds_read_b128 v[154:157], v150
	ds_read_b128 v[158:161], v150 offset:1024
	ds_read_b128 v[162:165], v150 offset:2048
	ds_read_b128 v[166:169], v150 offset:3072
	ds_read_b128 v[170:173], v151
	ds_read_b128 v[174:177], v151 offset:1024
	ds_read_b128 v[178:181], v151 offset:2048
	ds_read_b128 v[182:185], v151 offset:3072
	s_add_u32 s2, s0, 0xfffd0080
	s_addc_u32 s3, s1, -1
	s_cmp_eq_u32 s42, 8
	s_cselect_b32 s21, s7, s3
	s_cselect_b32 s20, s6, s2
	s_cselect_b32 s3, s17, s41
	s_cselect_b32 s2, s16, s40
	v_lshl_add_u64 v[206:207], s[0:1], 0, v[140:141]
	s_add_i32 m0, s25, 0xc000
	ds_read_b128 v[186:189], v152
	ds_read_b128 v[190:193], v152 offset:1024
	ds_read_b128 v[194:197], v152 offset:2048
	ds_read_b128 v[198:201], v152 offset:3072
	ds_read_b128 v[202:205], v152 offset:4096
	ds_read_b128 v[210:213], v152 offset:5120
	ds_read_b128 v[214:217], v152 offset:6144
	ds_read_b128 v[218:221], v152 offset:7168
	global_load_lds_dwordx4 v[206:207], off
	v_lshl_add_u64 v[206:207], s[0:1], 0, v[142:143]
	s_add_i32 m0, s25, 0xe000
	s_nop 0
	global_load_lds_dwordx4 v[206:207], off
	s_waitcnt vmcnt(24)
	s_waitcnt lgkmcnt(0)
	s_barrier
	s_setprio 1
	s_waitcnt lgkmcnt(0)
	v_mfma_f32_16x16x32_bf16 v[126:129], v[154:157], v[186:189], v[126:129]
	v_mfma_f32_16x16x32_bf16 v[122:125], v[162:165], v[186:189], v[122:125]
	v_mfma_f32_16x16x32_bf16 v[110:113], v[154:157], v[194:197], v[110:113]
	v_mfma_f32_16x16x32_bf16 v[106:109], v[162:165], v[194:197], v[106:109]
	v_mfma_f32_16x16x32_bf16 v[94:97], v[154:157], v[202:205], v[94:97]
	v_mfma_f32_16x16x32_bf16 v[90:93], v[162:165], v[202:205], v[90:93]
	v_mfma_f32_16x16x32_bf16 v[78:81], v[154:157], v[214:217], v[78:81]
	v_mfma_f32_16x16x32_bf16 v[74:77], v[162:165], v[214:217], v[74:77]
	v_mfma_f32_16x16x32_bf16 v[126:129], v[158:161], v[190:193], v[126:129]
	v_mfma_f32_16x16x32_bf16 v[122:125], v[166:169], v[190:193], v[122:125]
	v_mfma_f32_16x16x32_bf16 v[110:113], v[158:161], v[198:201], v[110:113]
	v_mfma_f32_16x16x32_bf16 v[106:109], v[166:169], v[198:201], v[106:109]
	v_mfma_f32_16x16x32_bf16 v[94:97], v[158:161], v[210:213], v[94:97]
	v_mfma_f32_16x16x32_bf16 v[90:93], v[166:169], v[210:213], v[90:93]
	v_mfma_f32_16x16x32_bf16 v[78:81], v[158:161], v[218:221], v[78:81]
	v_mfma_f32_16x16x32_bf16 v[74:77], v[166:169], v[218:221], v[74:77]
	s_setprio 0
	s_setprio 1
	v_mfma_f32_16x16x32_bf16 v[118:121], v[170:173], v[186:189], v[118:121]
	v_mfma_f32_16x16x32_bf16 v[114:117], v[178:181], v[186:189], v[114:117]
	v_mfma_f32_16x16x32_bf16 v[102:105], v[170:173], v[194:197], v[102:105]
	v_mfma_f32_16x16x32_bf16 v[98:101], v[178:181], v[194:197], v[98:101]
	v_mfma_f32_16x16x32_bf16 v[86:89], v[170:173], v[202:205], v[86:89]
	v_mfma_f32_16x16x32_bf16 v[82:85], v[178:181], v[202:205], v[82:85]
	v_mfma_f32_16x16x32_bf16 v[70:73], v[170:173], v[214:217], v[70:73]
	v_mfma_f32_16x16x32_bf16 v[66:69], v[178:181], v[214:217], v[66:69]
	v_mfma_f32_16x16x32_bf16 v[118:121], v[174:177], v[190:193], v[118:121]
	v_mfma_f32_16x16x32_bf16 v[114:117], v[182:185], v[190:193], v[114:117]
	v_mfma_f32_16x16x32_bf16 v[102:105], v[174:177], v[198:201], v[102:105]
	v_mfma_f32_16x16x32_bf16 v[98:101], v[182:185], v[198:201], v[98:101]
	v_mfma_f32_16x16x32_bf16 v[86:89], v[174:177], v[210:213], v[86:89]
	v_mfma_f32_16x16x32_bf16 v[82:85], v[182:185], v[210:213], v[82:85]
	v_mfma_f32_16x16x32_bf16 v[70:73], v[174:177], v[218:221], v[70:73]
	v_mfma_f32_16x16x32_bf16 v[66:69], v[182:185], v[218:221], v[66:69]
	s_setprio 0
	s_barrier
; #define PG8_STAGE(bufoff, gbase, voff) do { _Pragma("unroll") for (int _i = 0; _i < 2; ++_i) \
;         __builtin_amdgcn_global_load_lds((const unsigned*)((const char*)(gbase) + (voff)[_i]), (PG8_LAS unsigned*)(lds + (bufoff) + ldsw + _i * 8192), 16, 0, 0); } while (0)
; #define PG8_LDA(dst, b, h) do { _Pragma("unroll") for (int m = 0; m < 4; ++m) _Pragma("unroll") for (int k = 0; k < 2; ++k) dst[m][k] = *(const PG8_LAS bf16x8*)(lds + PG8_SA(b, h) + aoff + m * 2048 + k * 1024); } while (0)
; #define PG8_LDB(dst, b, h) do { _Pragma("unroll") for (int n = 0; n < 2; ++n) _Pragma("unroll") for (int k = 0; k < 2; ++k) dst[n][k] = *(const PG8_LAS bf16x8*)(lds + PG8_SB(b, h) + boff + n * 2048 + k * 1024); } while (0)
; #define PG8_MMA(ai, bj, At, Bt) do { __builtin_amdgcn_s_setprio(1); _Pragma("unroll") for (int m = 0; m < 4; ++m) _Pragma("unroll") for (int n = 0; n < 2; ++n) _Pragma("unroll") for (int k = 0; k < 2; ++k) \
;         acc[ai][bj][m][n] = __builtin_amdgcn_mfma_f32_16x16x32_bf16(Bt[n][k], At[m][k], acc[ai][bj][m][n], 0, 0, 0); __builtin_amdgcn_s_setprio(0); } while (0)
; #define PG8_WAIT_V(n) asm volatile("s_waitcnt vmcnt(" #n ")" ::: "memory")
; #define PG8_WAIT_L(n) asm volatile("s_waitcnt lgkmcnt(" #n ")" ::: "memory")
; #define PG8_BAR __builtin_amdgcn_s_barrier()
; #define PG8_SCHED __builtin_amdgcn_sched_barrier(0)
; template <class Epi, class Sched, bool ALIGN_EPI = false, bool SP2 = false>
; __device__ __forceinline__ void gemm_phase(PG8_LAS unsigned char* lds, const Gemm g, const Sched& S, const Epi& E) {
;     ...
;             PG8_LDA(At, 0, 1); PG8_STAGE(PG8_SB(0, 0), b2, voffB); PG8_STAGE(PG8_SB(0, 1), b2 + hstepB, voffB); PG8_STAGE(PG8_SA(0, 0), a2, voffA);
;             PG8_WAIT_V(8); PG8_WAIT_L(0); PG8_BAR; PG8_MMA(1, 0, At, B0); PG8_MMA(1, 1, At, B1); PG8_BAR; PG8_SCHED;
;             PG8_LDB(B0, 1, 0); PG8_LDB(B1, 1, 1); PG8_SCHED; PG8_LDA(At, 1, 0); PG8_STAGE(PG8_SA(0, 1), a2 + hstepA, voffA);
;             PG8_WAIT_V(8); PG8_WAIT_L(0); PG8_BAR; PG8_MMA(0, 0, At, B0); PG8_MMA(0, 1, At, B1); PG8_BAR; PG8_SCHED;
	s_add_i32 s43, s34, s23
	v_lshl_add_u64 v[206:207], s[2:3], 0, v[134:135]
	s_mov_b32 m0, s43
	ds_read_b128 v[186:189], v152 offset:16384
	ds_read_b128 v[190:193], v152 offset:17408
	ds_read_b128 v[194:197], v152 offset:18432
	ds_read_b128 v[198:201], v152 offset:19456
	ds_read_b128 v[202:205], v152 offset:20480
	ds_read_b128 v[210:213], v152 offset:21504
	ds_read_b128 v[214:217], v152 offset:22528
	ds_read_b128 v[218:221], v152 offset:23552
	global_load_lds_dwordx4 v[206:207], off
	s_add_i32 m0, s43, 0x2000
	s_add_u32 s44, s2, 0x30000
	v_lshl_add_u64 v[222:223], s[2:3], 0, v[130:131]
	s_addc_u32 s45, s3, 0
	s_add_i32 s43, s35, s23
	global_load_lds_dwordx4 v[222:223], off
	v_lshl_add_u64 v[224:225], s[44:45], 0, v[134:135]
	s_mov_b32 m0, s43
	v_lshl_add_u64 v[226:227], s[20:21], 0, v[132:133]
	global_load_lds_dwordx4 v[224:225], off
	v_lshl_add_u64 v[224:225], s[44:45], 0, v[130:131]
	s_add_i32 m0, s43, 0x2000
	s_nop 0
	global_load_lds_dwordx4 v[224:225], off
	v_lshl_add_u64 v[224:225], s[20:21], 0, v[136:137]
	s_mov_b32 m0, s25
	s_nop 0
	global_load_lds_dwordx4 v[224:225], off
	s_mov_b32 m0, s26
	s_nop 0
	global_load_lds_dwordx4 v[226:227], off
	s_waitcnt vmcnt(24)
	s_waitcnt lgkmcnt(0)
	s_barrier
	s_setprio 1
	s_waitcnt lgkmcnt(0)
	v_mfma_f32_16x16x32_bf16 v[62:65], v[154:157], v[186:189], v[62:65]
	v_mfma_f32_16x16x32_bf16 v[58:61], v[162:165], v[186:189], v[58:61]
	v_mfma_f32_16x16x32_bf16 v[46:49], v[154:157], v[194:197], v[46:49]
	v_mfma_f32_16x16x32_bf16 v[42:45], v[162:165], v[194:197], v[42:45]
	v_mfma_f32_16x16x32_bf16 v[30:33], v[154:157], v[202:205], v[30:33]
	v_mfma_f32_16x16x32_bf16 v[26:29], v[162:165], v[202:205], v[26:29]
	v_mfma_f32_16x16x32_bf16 v[14:17], v[154:157], v[214:217], v[14:17]
	v_mfma_f32_16x16x32_bf16 v[10:13], v[162:165], v[214:217], v[10:13]
	v_mfma_f32_16x16x32_bf16 v[62:65], v[158:161], v[190:193], v[62:65]
	v_mfma_f32_16x16x32_bf16 v[58:61], v[166:169], v[190:193], v[58:61]
	v_mfma_f32_16x16x32_bf16 v[46:49], v[158:161], v[198:201], v[46:49]
	v_mfma_f32_16x16x32_bf16 v[42:45], v[166:169], v[198:201], v[42:45]
	v_mfma_f32_16x16x32_bf16 v[30:33], v[158:161], v[210:213], v[30:33]
	v_mfma_f32_16x16x32_bf16 v[26:29], v[166:169], v[210:213], v[26:29]
	v_mfma_f32_16x16x32_bf16 v[14:17], v[158:161], v[218:221], v[14:17]
	v_mfma_f32_16x16x32_bf16 v[10:13], v[166:169], v[218:221], v[10:13]
	s_setprio 0
	s_setprio 1
	v_mfma_f32_16x16x32_bf16 v[54:57], v[170:173], v[186:189], v[54:57]
	v_mfma_f32_16x16x32_bf16 v[50:53], v[178:181], v[186:189], v[50:53]
	v_mfma_f32_16x16x32_bf16 v[38:41], v[170:173], v[194:197], v[38:41]
	v_mfma_f32_16x16x32_bf16 v[34:37], v[178:181], v[194:197], v[34:37]
	v_mfma_f32_16x16x32_bf16 v[22:25], v[170:173], v[202:205], v[22:25]
	v_mfma_f32_16x16x32_bf16 v[18:21], v[178:181], v[202:205], v[18:21]
	v_mfma_f32_16x16x32_bf16 v[6:9], v[170:173], v[214:217], v[6:9]
	v_mfma_f32_16x16x32_bf16 v[2:5], v[178:181], v[214:217], v[2:5]
	v_mfma_f32_16x16x32_bf16 v[54:57], v[174:177], v[190:193], v[54:57]
	v_mfma_f32_16x16x32_bf16 v[50:53], v[182:185], v[190:193], v[50:53]
	v_mfma_f32_16x16x32_bf16 v[38:41], v[174:177], v[198:201], v[38:41]
	v_mfma_f32_16x16x32_bf16 v[34:37], v[182:185], v[198:201], v[34:37]
	v_mfma_f32_16x16x32_bf16 v[22:25], v[174:177], v[210:213], v[22:25]
	v_mfma_f32_16x16x32_bf16 v[18:21], v[182:185], v[210:213], v[18:21]
	v_mfma_f32_16x16x32_bf16 v[6:9], v[174:177], v[218:221], v[6:9]
	v_mfma_f32_16x16x32_bf16 v[2:5], v[182:185], v[218:221], v[2:5]
	s_setprio 0
	s_barrier
	s_add_i32 s43, 0, 0x18000
	v_add_u32_e32 v153, s43, v1
	s_add_i32 s44, 0, 0x1c000
	ds_read_b128 v[154:157], v153
	ds_read_b128 v[158:161], v153 offset:1024
	ds_read_b128 v[162:165], v153 offset:2048
	ds_read_b128 v[166:169], v153 offset:3072
	v_add_u32_e32 v153, s44, v1
	ds_read_b128 v[170:173], v153
	ds_read_b128 v[174:177], v153 offset:1024
	ds_read_b128 v[178:181], v153 offset:2048
	ds_read_b128 v[182:185], v153 offset:3072
	s_add_u32 s20, s20, 0x30000
	s_addc_u32 s21, s21, 0
	s_mov_b32 m0, s27
	v_lshl_add_u64 v[228:229], s[20:21], 0, v[136:137]
	ds_read_b128 v[186:189], v152 offset:32768
	ds_read_b128 v[190:193], v152 offset:33792
	ds_read_b128 v[194:197], v152 offset:34816
	ds_read_b128 v[198:201], v152 offset:35840
	ds_read_b128 v[202:205], v152 offset:36864
	ds_read_b128 v[210:213], v152 offset:37888
	ds_read_b128 v[214:217], v152 offset:38912
	ds_read_b128 v[218:221], v152 offset:39936
	global_load_lds_dwordx4 v[228:229], off
	v_lshl_add_u64 v[228:229], s[20:21], 0, v[132:133]
	s_mov_b32 m0, s28
	s_nop 0
	global_load_lds_dwordx4 v[228:229], off
	s_waitcnt vmcnt(8)
	s_waitcnt lgkmcnt(0)
	s_barrier
; #define PG8_STAGE(bufoff, gbase, voff) do { _Pragma("unroll") for (int _i = 0; _i < 2; ++_i) \
;         __builtin_amdgcn_global_load_lds((const unsigned*)((const char*)(gbase) + (voff)[_i]), (PG8_LAS unsigned*)(lds + (bufoff) + ldsw + _i * 8192), 16, 0, 0); } while (0)
; #define PG8_LDA(dst, b, h) do { _Pragma("unroll") for (int m = 0; m < 4; ++m) _Pragma("unroll") for (int k = 0; k < 2; ++k) dst[m][k] = *(const PG8_LAS bf16x8*)(lds + PG8_SA(b, h) + aoff + m * 2048 + k * 1024); } while (0)
; #define PG8_MMA(ai, bj, At, Bt) do { __builtin_amdgcn_s_setprio(1); _Pragma("unroll") for (int m = 0; m < 4; ++m) _Pragma("unroll") for (int n = 0; n < 2; ++n) _Pragma("unroll") for (int k = 0; k < 2; ++k) \
;         acc[ai][bj][m][n] = __builtin_amdgcn_mfma_f32_16x16x32_bf16(Bt[n][k], At[m][k], acc[ai][bj][m][n], 0, 0, 0); __builtin_amdgcn_s_setprio(0); } while (0)
; #define PG8_WAIT_V(n) asm volatile("s_waitcnt vmcnt(" #n ")" ::: "memory")
; #define PG8_WAIT_L(n) asm volatile("s_waitcnt lgkmcnt(" #n ")" ::: "memory")
; #define PG8_BAR __builtin_amdgcn_s_barrier()
; #define PG8_SCHED __builtin_amdgcn_sched_barrier(0)
; template <class Epi, class Sched, bool ALIGN_EPI = false, bool SP2 = false>
; __device__ __forceinline__ void gemm_phase(PG8_LAS unsigned char* lds, const Gemm g, const Sched& S, const Epi& E) {
;     ...
;             PG8_WAIT_V(8); PG8_WAIT_L(0); PG8_BAR; PG8_MMA(0, 0, At, B0); PG8_MMA(0, 1, At, B1); PG8_BAR; PG8_SCHED;
;             PG8_LDA(At, 1, 1); PG8_STAGE(PG8_SB(1, 0), b3, voffB); PG8_STAGE(PG8_SB(1, 1), b3 + hstepB, voffB); PG8_STAGE(PG8_SA(1, 0), a3, voffA);
;             PG8_WAIT_V(8); PG8_WAIT_L(0); PG8_BAR; PG8_MMA(1, 0, At, B0); PG8_MMA(1, 1, At, B1); PG8_BAR; PG8_SCHED;
	s_setprio 1
	s_waitcnt lgkmcnt(0)
	v_mfma_f32_16x16x32_bf16 v[126:129], v[154:157], v[186:189], v[126:129]
	v_mfma_f32_16x16x32_bf16 v[122:125], v[162:165], v[186:189], v[122:125]
	v_mfma_f32_16x16x32_bf16 v[110:113], v[154:157], v[194:197], v[110:113]
	v_mfma_f32_16x16x32_bf16 v[106:109], v[162:165], v[194:197], v[106:109]
	v_mfma_f32_16x16x32_bf16 v[94:97], v[154:157], v[202:205], v[94:97]
	v_mfma_f32_16x16x32_bf16 v[90:93], v[162:165], v[202:205], v[90:93]
	v_mfma_f32_16x16x32_bf16 v[78:81], v[154:157], v[214:217], v[78:81]
	v_mfma_f32_16x16x32_bf16 v[74:77], v[162:165], v[214:217], v[74:77]
	v_mfma_f32_16x16x32_bf16 v[126:129], v[158:161], v[190:193], v[126:129]
	v_mfma_f32_16x16x32_bf16 v[122:125], v[166:169], v[190:193], v[122:125]
	v_mfma_f32_16x16x32_bf16 v[110:113], v[158:161], v[198:201], v[110:113]
	v_mfma_f32_16x16x32_bf16 v[106:109], v[166:169], v[198:201], v[106:109]
	v_mfma_f32_16x16x32_bf16 v[94:97], v[158:161], v[210:213], v[94:97]
	v_mfma_f32_16x16x32_bf16 v[90:93], v[166:169], v[210:213], v[90:93]
	v_mfma_f32_16x16x32_bf16 v[78:81], v[158:161], v[218:221], v[78:81]
	v_mfma_f32_16x16x32_bf16 v[74:77], v[166:169], v[218:221], v[74:77]
	s_setprio 0
	s_setprio 1
	v_mfma_f32_16x16x32_bf16 v[118:121], v[170:173], v[186:189], v[118:121]
	v_mfma_f32_16x16x32_bf16 v[114:117], v[178:181], v[186:189], v[114:117]
	v_mfma_f32_16x16x32_bf16 v[102:105], v[170:173], v[194:197], v[102:105]
	v_mfma_f32_16x16x32_bf16 v[98:101], v[178:181], v[194:197], v[98:101]
	v_mfma_f32_16x16x32_bf16 v[86:89], v[170:173], v[202:205], v[86:89]
	v_mfma_f32_16x16x32_bf16 v[82:85], v[178:181], v[202:205], v[82:85]
	v_mfma_f32_16x16x32_bf16 v[70:73], v[170:173], v[214:217], v[70:73]
	v_mfma_f32_16x16x32_bf16 v[66:69], v[178:181], v[214:217], v[66:69]
	v_mfma_f32_16x16x32_bf16 v[118:121], v[174:177], v[190:193], v[118:121]
	v_mfma_f32_16x16x32_bf16 v[114:117], v[182:185], v[190:193], v[114:117]
	v_mfma_f32_16x16x32_bf16 v[102:105], v[174:177], v[198:201], v[102:105]
	v_mfma_f32_16x16x32_bf16 v[98:101], v[182:185], v[198:201], v[98:101]
	v_mfma_f32_16x16x32_bf16 v[86:89], v[174:177], v[210:213], v[86:89]
	v_mfma_f32_16x16x32_bf16 v[82:85], v[182:185], v[210:213], v[82:85]
	v_mfma_f32_16x16x32_bf16 v[70:73], v[174:177], v[218:221], v[70:73]
	v_mfma_f32_16x16x32_bf16 v[66:69], v[182:185], v[218:221], v[66:69]
	s_setprio 0
	s_barrier
	s_add_i32 s20, s43, s23
	v_lshl_add_u64 v[206:207], v[206:207], 0, s[12:13]
	s_mov_b32 m0, s20
	ds_read_b128 v[186:189], v152 offset:49152
	ds_read_b128 v[190:193], v152 offset:50176
	ds_read_b128 v[194:197], v152 offset:51200
	ds_read_b128 v[198:201], v152 offset:52224
	ds_read_b128 v[202:205], v152 offset:53248
	ds_read_b128 v[210:213], v152 offset:54272
	ds_read_b128 v[214:217], v152 offset:55296
	ds_read_b128 v[218:221], v152 offset:56320
	global_load_lds_dwordx4 v[206:207], off
	s_add_i32 m0, s20, 0x2000
	s_add_u32 s2, s2, 0x30080
	v_lshl_add_u64 v[206:207], v[222:223], 0, s[12:13]
	s_addc_u32 s3, s3, 0
	s_add_i32 s20, s44, s23
	global_load_lds_dwordx4 v[206:207], off
	v_lshl_add_u64 v[206:207], s[2:3], 0, v[134:135]
	s_mov_b32 m0, s20
	s_nop 0
	global_load_lds_dwordx4 v[206:207], off
	v_lshl_add_u64 v[206:207], s[2:3], 0, v[130:131]
	s_add_i32 m0, s20, 0x2000
	s_nop 0
	global_load_lds_dwordx4 v[206:207], off
	v_lshl_add_u64 v[206:207], v[224:225], 0, s[12:13]
	s_mov_b32 m0, s30
	s_nop 0
	global_load_lds_dwordx4 v[206:207], off
	v_lshl_add_u64 v[206:207], v[226:227], 0, s[12:13]
	s_mov_b32 m0, s31
	s_nop 0
	global_load_lds_dwordx4 v[206:207], off
	s_waitcnt vmcnt(8)
	s_waitcnt lgkmcnt(0)
	s_barrier
	s_setprio 1
	s_waitcnt lgkmcnt(0)
	v_mfma_f32_16x16x32_bf16 v[62:65], v[154:157], v[186:189], v[62:65]
	v_mfma_f32_16x16x32_bf16 v[58:61], v[162:165], v[186:189], v[58:61]
	v_mfma_f32_16x16x32_bf16 v[46:49], v[154:157], v[194:197], v[46:49]
	v_mfma_f32_16x16x32_bf16 v[42:45], v[162:165], v[194:197], v[42:45]
	v_mfma_f32_16x16x32_bf16 v[30:33], v[154:157], v[202:205], v[30:33]
	v_mfma_f32_16x16x32_bf16 v[26:29], v[162:165], v[202:205], v[26:29]
	v_mfma_f32_16x16x32_bf16 v[14:17], v[154:157], v[214:217], v[14:17]
	v_mfma_f32_16x16x32_bf16 v[10:13], v[162:165], v[214:217], v[10:13]
	v_mfma_f32_16x16x32_bf16 v[62:65], v[158:161], v[190:193], v[62:65]
	v_mfma_f32_16x16x32_bf16 v[58:61], v[166:169], v[190:193], v[58:61]
	v_mfma_f32_16x16x32_bf16 v[46:49], v[158:161], v[198:201], v[46:49]
	v_mfma_f32_16x16x32_bf16 v[42:45], v[166:169], v[198:201], v[42:45]
	v_mfma_f32_16x16x32_bf16 v[30:33], v[158:161], v[210:213], v[30:33]
	v_mfma_f32_16x16x32_bf16 v[26:29], v[166:169], v[210:213], v[26:29]
	v_mfma_f32_16x16x32_bf16 v[14:17], v[158:161], v[218:221], v[14:17]
	v_mfma_f32_16x16x32_bf16 v[10:13], v[166:169], v[218:221], v[10:13]
	s_setprio 0
	s_setprio 1
	v_mfma_f32_16x16x32_bf16 v[54:57], v[170:173], v[186:189], v[54:57]
	v_mfma_f32_16x16x32_bf16 v[50:53], v[178:181], v[186:189], v[50:53]
	v_mfma_f32_16x16x32_bf16 v[38:41], v[170:173], v[194:197], v[38:41]
	v_mfma_f32_16x16x32_bf16 v[34:37], v[178:181], v[194:197], v[34:37]
	v_mfma_f32_16x16x32_bf16 v[22:25], v[170:173], v[202:205], v[22:25]
	v_mfma_f32_16x16x32_bf16 v[18:21], v[178:181], v[202:205], v[18:21]
	v_mfma_f32_16x16x32_bf16 v[6:9], v[170:173], v[214:217], v[6:9]
	v_mfma_f32_16x16x32_bf16 v[2:5], v[178:181], v[214:217], v[2:5]
	v_mfma_f32_16x16x32_bf16 v[54:57], v[174:177], v[190:193], v[54:57]
	v_mfma_f32_16x16x32_bf16 v[50:53], v[182:185], v[190:193], v[50:53]
	v_mfma_f32_16x16x32_bf16 v[38:41], v[174:177], v[198:201], v[38:41]
	v_mfma_f32_16x16x32_bf16 v[34:37], v[182:185], v[198:201], v[34:37]
	v_mfma_f32_16x16x32_bf16 v[22:25], v[174:177], v[210:213], v[22:25]
	v_mfma_f32_16x16x32_bf16 v[18:21], v[182:185], v[210:213], v[18:21]
	v_mfma_f32_16x16x32_bf16 v[6:9], v[174:177], v[218:221], v[6:9]
	v_mfma_f32_16x16x32_bf16 v[2:5], v[182:185], v[218:221], v[2:5]
	s_setprio 0
	s_barrier
	s_add_i32 s42, s42, 2
	s_add_u32 s0, s0, 0x100
	s_addc_u32 s1, s1, 0
	s_add_u32 s40, s40, 0x100
	s_addc_u32 s41, s41, 0
	s_cmp_gt_u32 s42, 9
	s_cbranch_scc1 .Lpeel_exit_13
	.p2align 6

; #define PG8_STAGE(bufoff, gbase, voff) do { _Pragma("unroll") for (int _i = 0; _i < 2; ++_i) \
;         __builtin_amdgcn_global_load_lds((const unsigned*)((const char*)(gbase) + (voff)[_i]), (PG8_LAS unsigned*)(lds + (bufoff) + ldsw + _i * 8192), 16, 0, 0); } while (0)
; #define PG8_WAIT_V(n) asm volatile("s_waitcnt vmcnt(" #n ")" ::: "memory")
; #define PG8_BAR __builtin_amdgcn_s_barrier()
; template <class Epi, class Sched, bool ALIGN_EPI = false, bool SP2 = false>
; __device__ __forceinline__ void gemm_phase(PG8_LAS unsigned char* lds, const Gemm g, const Sched& S, const Epi& E) {
;     const int tid = threadIdx.x, wid = __builtin_amdgcn_readfirstlane(tid >> 6), lane = tid & 63, wr = wid >> 2, wc = wid & 3, fr = lane & 15, fq = lane >> 4;
;     const int K = g.K, nt = K / BK;
;     unsigned voffA[2], voffB[2];
; #pragma unroll
;     for (int i = 0; i < 2; ++i) { int R, C; stage_rc(tid * 16 + i * 8192, R, C); const int Rb = Epi::PERM ? ((R & ~31) + perm32(R & 31)) : R;
;         voffA[i] = (unsigned)(R * g.lda + C) * 2u; voffB[i] = (unsigned)(Rb * g.ldb + C) * 2u; }
;     const size_t kstep = (size_t)(BK * 2);
;     const size_t hstepA = (size_t)HALF * g.lda * 2, hstepB = (size_t)HALF * g.ldb * 2;
;     const size_t tstepA = 2 * hstepA, tstepB = 2 * hstepB;
;     const unsigned ldsw = (unsigned)wid * 1024u;
;     const int aoff = lds_byte(wr * 64 + fr, fq * 8), boff = lds_byte(wc * 32 + fr, fq * 8);
;     ...
;         PG8_WAIT_V(2); PG8_BAR;
;         PG8_STAGE(PG8_SB(1, 0), cB + kstep, voffB); PG8_STAGE(PG8_SA(1, 0), cA + kstep, voffA); PG8_STAGE(PG8_SB(1, 1), cB + hstepB + kstep, voffB);
;         PG8_WAIT_V(6); PG8_BAR;
.LBB0_1351:
	s_lshl_b32 s1, s14, 5
	s_mov_b64 s[14:15], 0x80
	s_and_b32 s22, s1, 0x60
	s_add_i32 m0, s43, 0x18000
	v_lshl_add_u64 v[8:9], v[8:9], 0, s[14:15]
	s_lshl_b32 s17, s16, 13
	s_lshl_b32 s23, s22, 7
	s_waitcnt vmcnt(2)
	s_barrier
	global_load_lds_dwordx4 v[8:9], off
	v_lshl_add_u64 v[4:5], v[4:5], 0, s[14:15]
	s_add_i32 m0, s43, 0x1a000
	s_add_i32 s48, s43, 0x8000
	s_add_i32 s49, s43, 0xa000
	global_load_lds_dwordx4 v[4:5], off
	v_lshl_add_u64 v[2:3], v[2:3], 0, s[14:15]
	s_mov_b32 m0, s48
	s_add_u32 s20, s36, 0x80080
	global_load_lds_dwordx4 v[2:3], off
	v_lshl_add_u64 v[2:3], v[6:7], 0, s[14:15]
	s_mov_b32 m0, s49
	s_addc_u32 s21, s37, 0
	global_load_lds_dwordx4 v[2:3], off
	s_add_i32 m0, s43, 0x1c000
	v_lshl_add_u64 v[2:3], s[20:21], 0, v[150:151]
	global_load_lds_dwordx4 v[2:3], off
	v_lshl_add_u64 v[2:3], s[20:21], 0, v[146:147]
	s_add_i32 m0, s43, 0x1e000
	s_sext_i32_i8 s1, s4
	global_load_lds_dwordx4 v[2:3], off
	v_and_b32_e32 v2, 15, v0
	v_lshlrev_b32_e32 v3, 1, v13
	v_lshlrev_b32_e32 v4, 2, v0
	v_lshlrev_b32_e32 v5, 6, v0
	s_movk_i32 s4, 0x3c0
	v_lshl_or_b32 v1, s16, 6, v2
	v_lshl_or_b32 v2, v2, 6, v3
	v_and_b32_e32 v4, 32, v4
	v_and_or_b32 v3, v5, s4, v3
	v_bitop3_b32 v168, s23, v3, v4 bitop3:0xf6
	v_lshlrev_b32_e32 v3, 9, v0
	v_bitop3_b32 v2, v2, s17, v4 bitop3:0xde
	v_and_b32_e32 v3, 0x30000, v3
	v_lshlrev_b32_e32 v4, 12, v14
	v_or3_b32 v3, v11, v3, v4
	v_add_u32_e32 v154, v3, v12
	v_lshlrev_b32_e32 v3, 5, v10
	s_waitcnt vmcnt(0)
	s_cmpk_lt_u32 s5, 0x100
	v_and_b32_e32 v3, 0x70000, v3
	s_cselect_b64 s[16:17], -1, 0
	v_or3_b32 v3, v11, v3, v4
	s_add_i32 s51, 0, 0x10000
	s_add_i32 s52, 0, 0x14000
	s_waitcnt lgkmcnt(0)
	s_ashr_i32 s50, s33, 31
	v_or_b32_e32 v169, s22, v13
	v_mov_b32_e32 v155, v151
	v_add_u32_e32 v156, v3, v12
	v_mov_b32_e32 v157, v151
	v_mov_b64_e32 v[158:159], 0x500
	v_mov_b64_e32 v[160:161], 0x4ff
	v_add_u32_e32 v170, s51, v168
	v_add_u32_e32 v171, s52, v168
	v_add_u32_e32 v172, 0, v2
	s_mov_b64 s[20:21], 0x90000
	s_mov_b64 s[22:23], 0xa0000
	s_mov_b64 s[24:25], 0xb0000
	s_barrier
	s_branch .LBB0_1354

; #define PG8_STAGE(bufoff, gbase, voff) do { _Pragma("unroll") for (int _i = 0; _i < 2; ++_i) \
;         __builtin_amdgcn_global_load_lds((const unsigned*)((const char*)(gbase) + (voff)[_i]), (PG8_LAS unsigned*)(lds + (bufoff) + ldsw + _i * 8192), 16, 0, 0); } while (0)
; #define PG8_LDA(dst, b, h) do { _Pragma("unroll") for (int m = 0; m < 4; ++m) _Pragma("unroll") for (int k = 0; k < 2; ++k) dst[m][k] = *(const PG8_LAS bf16x8*)(lds + PG8_SA(b, h) + aoff + m * 2048 + k * 1024); } while (0)
; #define PG8_LDB(dst, b, h) do { _Pragma("unroll") for (int n = 0; n < 2; ++n) _Pragma("unroll") for (int k = 0; k < 2; ++k) dst[n][k] = *(const PG8_LAS bf16x8*)(lds + PG8_SB(b, h) + boff + n * 2048 + k * 1024); } while (0)
; #define PG8_WAIT_V(n) asm volatile("s_waitcnt vmcnt(" #n ")" ::: "memory")
; #define PG8_WAIT_L(n) asm volatile("s_waitcnt lgkmcnt(" #n ")" ::: "memory")
; #define PG8_BAR __builtin_amdgcn_s_barrier()
; template <class Epi, class Sched, bool ALIGN_EPI = false, bool SP2 = false>
; __device__ __forceinline__ void gemm_phase(PG8_LAS unsigned char* lds, const Gemm g, const Sched& S, const Epi& E) {
;     ...
;         const bool has_next = S.next(ui + 1, nxt);
;         const char* nA = has_next ? (const char*)g.A + (size_t)nxt.pm * tstepA : cA; const char* nB = has_next ? (const char*)g.Bt + (size_t)nxt.pn * tstepB : cB;
;         for (int t = 0; t < nt; t += 2) {
;             const bool last = (t == nt - 2);
;             const char* a1 = cA + (size_t)(t + 1) * kstep;
;             const char* a2 = last ? nA : cA + (size_t)(t + 2) * kstep; const char* b2 = last ? nB : cB + (size_t)(t + 2) * kstep;
;             const char* a3 = a2 + kstep; const char* b3 = b2 + kstep;
;             if (last && has_next) S.a_ready(nxt);
;             if constexpr (SP2) {
;             PG8_LDB(B0, 0, 0); PG8_LDB(B1, 0, 1); PG8_SCHED; PG8_LDA(At, 0, 0); PG8_STAGE(PG8_SA(1, 1), a1 + hstepA, voffA);
;             PG8_WAIT_V(8); PG8_WAIT_L(0); PG8_BAR; PG8_MMA(0, 0, At, B0); PG8_MMA(0, 1, At, B1); PG8_BAR; PG8_SCHED;
;     ...
; #pragma unroll
;         for (int a = 0; a < 2; ++a)
; #pragma unroll
;             for (int b = 0; b < 2; ++b)
; #pragma unroll
;                 for (int m = 0; m < 4; ++m)
; #pragma unroll
;                     for (int n = 0; n < 2; ++n) acc[a][b][m][n] = (f32x4){0.f, 0.f, 0.f, 0.f};
;         cur = nxt; cA = nA; cB = nB; ++ui;
.LBB0_1356:
	s_ashr_i32 s29, s28, 31
	s_lshl_b64 s[30:31], s[28:29], 20
	s_add_u32 s30, s86, s30
	s_addc_u32 s31, s87, s31
	s_and_b64 s[34:35], s[4:5], exec
	s_cselect_b32 s29, s31, s3
	s_cselect_b32 s53, s30, s2
	s_ashr_i32 s27, s26, 31
	s_lshl_b64 s[34:35], s[26:27], 20
	s_add_u32 s34, s88, s34
	s_addc_u32 s35, s89, s35
	s_and_b64 s[38:39], s[4:5], exec
	s_cselect_b32 s27, s35, s37
	s_cselect_b32 s54, s34, s36
	s_add_u32 s2, s2, 0x80080
	s_addc_u32 s3, s3, 0
	s_add_u32 s55, s36, 0x100
	v_mov_b32_e32 v2, 0
	s_addc_u32 s56, s37, 0
	s_mov_b32 s57, -2
	v_mov_b32_e32 v3, v2
	v_mov_b32_e32 v4, v2
	v_mov_b32_e32 v5, v2
	v_mov_b32_e32 v6, v2
	v_mov_b32_e32 v7, v2
	v_mov_b32_e32 v8, v2
	v_mov_b32_e32 v9, v2
	v_mov_b32_e32 v18, v2
	v_mov_b32_e32 v19, v2
	v_mov_b32_e32 v20, v2
	v_mov_b32_e32 v21, v2
	v_mov_b32_e32 v22, v2
	v_mov_b32_e32 v23, v2
	v_mov_b32_e32 v24, v2
	v_mov_b32_e32 v25, v2
	v_mov_b32_e32 v34, v2
	v_mov_b32_e32 v35, v2
	v_mov_b32_e32 v36, v2
	v_mov_b32_e32 v37, v2
	v_mov_b32_e32 v38, v2
	v_mov_b32_e32 v39, v2
	v_mov_b32_e32 v40, v2
	v_mov_b32_e32 v41, v2
	v_mov_b32_e32 v50, v2
	v_mov_b32_e32 v51, v2
	v_mov_b32_e32 v52, v2
	v_mov_b32_e32 v53, v2
	v_mov_b32_e32 v54, v2
	v_mov_b32_e32 v55, v2
	v_mov_b32_e32 v56, v2
	v_mov_b32_e32 v57, v2
	v_mov_b32_e32 v10, v2
	v_mov_b32_e32 v11, v2
	v_mov_b32_e32 v12, v2
	v_mov_b32_e32 v13, v2
	v_mov_b32_e32 v14, v2
	v_mov_b32_e32 v15, v2
	v_mov_b32_e32 v16, v2
	v_mov_b32_e32 v17, v2
	v_mov_b32_e32 v26, v2
	v_mov_b32_e32 v27, v2
	v_mov_b32_e32 v28, v2
	v_mov_b32_e32 v29, v2
	v_mov_b32_e32 v30, v2
	v_mov_b32_e32 v31, v2
	v_mov_b32_e32 v32, v2
	v_mov_b32_e32 v33, v2
	v_mov_b32_e32 v42, v2
	v_mov_b32_e32 v43, v2
	v_mov_b32_e32 v44, v2
	v_mov_b32_e32 v45, v2
	v_mov_b32_e32 v46, v2
	v_mov_b32_e32 v47, v2
	v_mov_b32_e32 v48, v2
	v_mov_b32_e32 v49, v2
	v_mov_b32_e32 v58, v2
	v_mov_b32_e32 v59, v2
	v_mov_b32_e32 v60, v2
	v_mov_b32_e32 v61, v2
	v_mov_b32_e32 v62, v2
	v_mov_b32_e32 v63, v2
	v_mov_b32_e32 v64, v2
	v_mov_b32_e32 v65, v2
	v_mov_b32_e32 v82, v2
	v_mov_b32_e32 v83, v2
	v_mov_b32_e32 v84, v2
	v_mov_b32_e32 v85, v2
	v_mov_b32_e32 v86, v2
	v_mov_b32_e32 v87, v2
	v_mov_b32_e32 v88, v2
	v_mov_b32_e32 v89, v2
	v_mov_b32_e32 v98, v2
	v_mov_b32_e32 v99, v2
	v_mov_b32_e32 v100, v2
	v_mov_b32_e32 v101, v2
	v_mov_b32_e32 v102, v2
	v_mov_b32_e32 v103, v2
	v_mov_b32_e32 v104, v2
	v_mov_b32_e32 v105, v2
	v_mov_b32_e32 v114, v2
	v_mov_b32_e32 v115, v2
	v_mov_b32_e32 v116, v2
	v_mov_b32_e32 v117, v2
	v_mov_b32_e32 v118, v2
	v_mov_b32_e32 v119, v2
	v_mov_b32_e32 v120, v2
	v_mov_b32_e32 v121, v2
	v_mov_b32_e32 v130, v2
	v_mov_b32_e32 v131, v2
	v_mov_b32_e32 v132, v2
	v_mov_b32_e32 v133, v2
	v_mov_b32_e32 v134, v2
	v_mov_b32_e32 v135, v2
	v_mov_b32_e32 v136, v2
	v_mov_b32_e32 v137, v2
	v_mov_b32_e32 v90, v2
	v_mov_b32_e32 v91, v2
	v_mov_b32_e32 v92, v2
	v_mov_b32_e32 v93, v2
	v_mov_b32_e32 v94, v2
	v_mov_b32_e32 v95, v2
	v_mov_b32_e32 v96, v2
	v_mov_b32_e32 v97, v2
	v_mov_b32_e32 v106, v2
	v_mov_b32_e32 v107, v2
	v_mov_b32_e32 v108, v2
	v_mov_b32_e32 v109, v2
	v_mov_b32_e32 v110, v2
	v_mov_b32_e32 v111, v2
	v_mov_b32_e32 v112, v2
	v_mov_b32_e32 v113, v2
	v_mov_b32_e32 v122, v2
	v_mov_b32_e32 v123, v2
	v_mov_b32_e32 v124, v2
	v_mov_b32_e32 v125, v2
	v_mov_b32_e32 v126, v2
	v_mov_b32_e32 v127, v2
	v_mov_b32_e32 v128, v2
	v_mov_b32_e32 v129, v2
	v_mov_b32_e32 v138, v2
	v_mov_b32_e32 v139, v2
	v_mov_b32_e32 v140, v2
	v_mov_b32_e32 v141, v2
	v_mov_b32_e32 v142, v2
	v_mov_b32_e32 v143, v2
	v_mov_b32_e32 v144, v2
	v_mov_b32_e32 v145, v2
	ds_read_b128 v[66:69], v170
	ds_read_b128 v[70:73], v170 offset:1024
	ds_read_b128 v[74:77], v170 offset:2048
	ds_read_b128 v[78:81], v170 offset:3072
	ds_read_b128 v[162:165], v171
	ds_read_b128 v[174:177], v171 offset:1024
	ds_read_b128 v[178:181], v171 offset:2048
	ds_read_b128 v[182:185], v171 offset:3072
	s_add_u32 s36, s2, 0xfff80080
	s_addc_u32 s37, s3, -1
	s_cmp_eq_u32 s57, 28
	s_cselect_b32 s39, s29, s37
	s_cselect_b32 s38, s53, s36
	s_cselect_b32 s37, s27, s56
	s_cselect_b32 s36, s54, s55
	v_lshl_add_u64 v[166:167], s[2:3], 0, v[154:155]
	s_add_i32 m0, s43, 0xc000
	ds_read_b128 v[186:189], v172
	ds_read_b128 v[190:193], v172 offset:1024
	ds_read_b128 v[194:197], v172 offset:2048
	ds_read_b128 v[198:201], v172 offset:3072
	ds_read_b128 v[202:205], v172 offset:4096
	ds_read_b128 v[210:213], v172 offset:5120
	ds_read_b128 v[214:217], v172 offset:6144
	ds_read_b128 v[218:221], v172 offset:7168
	global_load_lds_dwordx4 v[166:167], off
	v_lshl_add_u64 v[166:167], s[2:3], 0, v[156:157]
	s_add_i32 m0, s43, 0xe000
	s_nop 0
	global_load_lds_dwordx4 v[166:167], off
	s_waitcnt vmcnt(44)
	s_waitcnt lgkmcnt(0)
	s_barrier
; #define PG8_STAGE(bufoff, gbase, voff) do { _Pragma("unroll") for (int _i = 0; _i < 2; ++_i) \
;         __builtin_amdgcn_global_load_lds((const unsigned*)((const char*)(gbase) + (voff)[_i]), (PG8_LAS unsigned*)(lds + (bufoff) + ldsw + _i * 8192), 16, 0, 0); } while (0)
; #define PG8_LDA(dst, b, h) do { _Pragma("unroll") for (int m = 0; m < 4; ++m) _Pragma("unroll") for (int k = 0; k < 2; ++k) dst[m][k] = *(const PG8_LAS bf16x8*)(lds + PG8_SA(b, h) + aoff + m * 2048 + k * 1024); } while (0)
; #define PG8_MMA(ai, bj, At, Bt) do { __builtin_amdgcn_s_setprio(1); _Pragma("unroll") for (int m = 0; m < 4; ++m) _Pragma("unroll") for (int n = 0; n < 2; ++n) _Pragma("unroll") for (int k = 0; k < 2; ++k) \
;         acc[ai][bj][m][n] = __builtin_amdgcn_mfma_f32_16x16x32_bf16(Bt[n][k], At[m][k], acc[ai][bj][m][n], 0, 0, 0); __builtin_amdgcn_s_setprio(0); } while (0)
; #define PG8_WAIT_V(n) asm volatile("s_waitcnt vmcnt(" #n ")" ::: "memory")
; #define PG8_WAIT_L(n) asm volatile("s_waitcnt lgkmcnt(" #n ")" ::: "memory")
; #define PG8_BAR __builtin_amdgcn_s_barrier()
; #define PG8_SCHED __builtin_amdgcn_sched_barrier(0)
; template <class Epi, class Sched, bool ALIGN_EPI = false, bool SP2 = false>
; __device__ __forceinline__ void gemm_phase(PG8_LAS unsigned char* lds, const Gemm g, const Sched& S, const Epi& E) {
;     ...
;             PG8_WAIT_V(8); PG8_WAIT_L(0); PG8_BAR; PG8_MMA(0, 0, At, B0); PG8_MMA(0, 1, At, B1); PG8_BAR; PG8_SCHED;
;             PG8_LDA(At, 0, 1); PG8_STAGE(PG8_SB(0, 0), b2, voffB); PG8_STAGE(PG8_SB(0, 1), b2 + hstepB, voffB); PG8_STAGE(PG8_SA(0, 0), a2, voffA);
;             PG8_WAIT_V(8); PG8_WAIT_L(0); PG8_BAR; PG8_MMA(1, 0, At, B0); PG8_MMA(1, 1, At, B1); PG8_BAR; PG8_SCHED;
	s_setprio 1
	s_waitcnt lgkmcnt(0)
	v_mfma_f32_16x16x32_bf16 v[142:145], v[66:69], v[186:189], v[142:145]
	v_mfma_f32_16x16x32_bf16 v[138:141], v[74:77], v[186:189], v[138:141]
	v_mfma_f32_16x16x32_bf16 v[126:129], v[66:69], v[194:197], v[126:129]
	v_mfma_f32_16x16x32_bf16 v[122:125], v[74:77], v[194:197], v[122:125]
	v_mfma_f32_16x16x32_bf16 v[110:113], v[66:69], v[202:205], v[110:113]
	v_mfma_f32_16x16x32_bf16 v[106:109], v[74:77], v[202:205], v[106:109]
	v_mfma_f32_16x16x32_bf16 v[94:97], v[66:69], v[214:217], v[94:97]
	v_mfma_f32_16x16x32_bf16 v[90:93], v[74:77], v[214:217], v[90:93]
	v_mfma_f32_16x16x32_bf16 v[142:145], v[70:73], v[190:193], v[142:145]
	v_mfma_f32_16x16x32_bf16 v[138:141], v[78:81], v[190:193], v[138:141]
	v_mfma_f32_16x16x32_bf16 v[126:129], v[70:73], v[198:201], v[126:129]
	v_mfma_f32_16x16x32_bf16 v[122:125], v[78:81], v[198:201], v[122:125]
	v_mfma_f32_16x16x32_bf16 v[110:113], v[70:73], v[210:213], v[110:113]
	v_mfma_f32_16x16x32_bf16 v[106:109], v[78:81], v[210:213], v[106:109]
	v_mfma_f32_16x16x32_bf16 v[94:97], v[70:73], v[218:221], v[94:97]
	v_mfma_f32_16x16x32_bf16 v[90:93], v[78:81], v[218:221], v[90:93]
	s_setprio 0
	s_setprio 1
	v_mfma_f32_16x16x32_bf16 v[134:137], v[162:165], v[186:189], v[134:137]
	v_mfma_f32_16x16x32_bf16 v[130:133], v[178:181], v[186:189], v[130:133]
	v_mfma_f32_16x16x32_bf16 v[118:121], v[162:165], v[194:197], v[118:121]
	v_mfma_f32_16x16x32_bf16 v[114:117], v[178:181], v[194:197], v[114:117]
	v_mfma_f32_16x16x32_bf16 v[102:105], v[162:165], v[202:205], v[102:105]
	v_mfma_f32_16x16x32_bf16 v[98:101], v[178:181], v[202:205], v[98:101]
	v_mfma_f32_16x16x32_bf16 v[86:89], v[162:165], v[214:217], v[86:89]
	v_mfma_f32_16x16x32_bf16 v[82:85], v[178:181], v[214:217], v[82:85]
	v_mfma_f32_16x16x32_bf16 v[134:137], v[174:177], v[190:193], v[134:137]
	v_mfma_f32_16x16x32_bf16 v[130:133], v[182:185], v[190:193], v[130:133]
	v_mfma_f32_16x16x32_bf16 v[118:121], v[174:177], v[198:201], v[118:121]
	v_mfma_f32_16x16x32_bf16 v[114:117], v[182:185], v[198:201], v[114:117]
	v_mfma_f32_16x16x32_bf16 v[102:105], v[174:177], v[210:213], v[102:105]
	v_mfma_f32_16x16x32_bf16 v[98:101], v[182:185], v[210:213], v[98:101]
	v_mfma_f32_16x16x32_bf16 v[86:89], v[174:177], v[218:221], v[86:89]
	v_mfma_f32_16x16x32_bf16 v[82:85], v[182:185], v[218:221], v[82:85]
	s_setprio 0
	s_barrier
	s_add_i32 s58, s51, s40
	v_lshl_add_u64 v[166:167], s[36:37], 0, v[150:151]
	s_mov_b32 m0, s58
	ds_read_b128 v[186:189], v172 offset:16384
	ds_read_b128 v[190:193], v172 offset:17408
	ds_read_b128 v[194:197], v172 offset:18432
	ds_read_b128 v[198:201], v172 offset:19456
	ds_read_b128 v[202:205], v172 offset:20480
	ds_read_b128 v[210:213], v172 offset:21504
	ds_read_b128 v[214:217], v172 offset:22528
	ds_read_b128 v[218:221], v172 offset:23552
	global_load_lds_dwordx4 v[166:167], off
	s_add_i32 m0, s58, 0x2000
	s_add_u32 s58, s36, 0x80000
	v_lshl_add_u64 v[206:207], s[36:37], 0, v[146:147]
	s_addc_u32 s59, s37, 0
	s_add_i32 s60, s52, s40
	global_load_lds_dwordx4 v[206:207], off
	v_lshl_add_u64 v[222:223], s[58:59], 0, v[150:151]
	s_mov_b32 m0, s60
	v_lshl_add_u64 v[224:225], s[38:39], 0, v[148:149]
	global_load_lds_dwordx4 v[222:223], off
	v_lshl_add_u64 v[222:223], s[58:59], 0, v[146:147]
	s_add_i32 m0, s60, 0x2000
	s_nop 0
	global_load_lds_dwordx4 v[222:223], off
	v_lshl_add_u64 v[222:223], s[38:39], 0, v[152:153]
	s_mov_b32 m0, s43
	s_nop 0
	global_load_lds_dwordx4 v[222:223], off
	s_mov_b32 m0, s44
	s_nop 0
	global_load_lds_dwordx4 v[224:225], off
	s_waitcnt vmcnt(44)
	s_waitcnt lgkmcnt(0)
	s_barrier
	s_setprio 1
	s_waitcnt lgkmcnt(0)
	v_mfma_f32_16x16x32_bf16 v[62:65], v[66:69], v[186:189], v[62:65]
	v_mfma_f32_16x16x32_bf16 v[58:61], v[74:77], v[186:189], v[58:61]
	v_mfma_f32_16x16x32_bf16 v[46:49], v[66:69], v[194:197], v[46:49]
	v_mfma_f32_16x16x32_bf16 v[42:45], v[74:77], v[194:197], v[42:45]
	v_mfma_f32_16x16x32_bf16 v[30:33], v[66:69], v[202:205], v[30:33]
	v_mfma_f32_16x16x32_bf16 v[26:29], v[74:77], v[202:205], v[26:29]
	v_mfma_f32_16x16x32_bf16 v[14:17], v[66:69], v[214:217], v[14:17]
	v_mfma_f32_16x16x32_bf16 v[10:13], v[74:77], v[214:217], v[10:13]
	v_mfma_f32_16x16x32_bf16 v[62:65], v[70:73], v[190:193], v[62:65]
	v_mfma_f32_16x16x32_bf16 v[58:61], v[78:81], v[190:193], v[58:61]
	v_mfma_f32_16x16x32_bf16 v[46:49], v[70:73], v[198:201], v[46:49]
	v_mfma_f32_16x16x32_bf16 v[42:45], v[78:81], v[198:201], v[42:45]
	v_mfma_f32_16x16x32_bf16 v[30:33], v[70:73], v[210:213], v[30:33]
	v_mfma_f32_16x16x32_bf16 v[26:29], v[78:81], v[210:213], v[26:29]
	v_mfma_f32_16x16x32_bf16 v[14:17], v[70:73], v[218:221], v[14:17]
	v_mfma_f32_16x16x32_bf16 v[10:13], v[78:81], v[218:221], v[10:13]
	s_setprio 0
	s_setprio 1
	v_mfma_f32_16x16x32_bf16 v[54:57], v[162:165], v[186:189], v[54:57]
	v_mfma_f32_16x16x32_bf16 v[50:53], v[178:181], v[186:189], v[50:53]
	v_mfma_f32_16x16x32_bf16 v[38:41], v[162:165], v[194:197], v[38:41]
	v_mfma_f32_16x16x32_bf16 v[34:37], v[178:181], v[194:197], v[34:37]
	v_mfma_f32_16x16x32_bf16 v[22:25], v[162:165], v[202:205], v[22:25]
	v_mfma_f32_16x16x32_bf16 v[18:21], v[178:181], v[202:205], v[18:21]
	v_mfma_f32_16x16x32_bf16 v[6:9], v[162:165], v[214:217], v[6:9]
	v_mfma_f32_16x16x32_bf16 v[2:5], v[178:181], v[214:217], v[2:5]
	v_mfma_f32_16x16x32_bf16 v[54:57], v[174:177], v[190:193], v[54:57]
	v_mfma_f32_16x16x32_bf16 v[50:53], v[182:185], v[190:193], v[50:53]
	v_mfma_f32_16x16x32_bf16 v[38:41], v[174:177], v[198:201], v[38:41]
	v_mfma_f32_16x16x32_bf16 v[34:37], v[182:185], v[198:201], v[34:37]
	v_mfma_f32_16x16x32_bf16 v[22:25], v[174:177], v[210:213], v[22:25]
	v_mfma_f32_16x16x32_bf16 v[18:21], v[182:185], v[210:213], v[18:21]
	v_mfma_f32_16x16x32_bf16 v[6:9], v[174:177], v[218:221], v[6:9]
	v_mfma_f32_16x16x32_bf16 v[2:5], v[182:185], v[218:221], v[2:5]
	s_setprio 0
	s_barrier
; #define PG8_STAGE(bufoff, gbase, voff) do { _Pragma("unroll") for (int _i = 0; _i < 2; ++_i) \
;         __builtin_amdgcn_global_load_lds((const unsigned*)((const char*)(gbase) + (voff)[_i]), (PG8_LAS unsigned*)(lds + (bufoff) + ldsw + _i * 8192), 16, 0, 0); } while (0)
; #define PG8_LDA(dst, b, h) do { _Pragma("unroll") for (int m = 0; m < 4; ++m) _Pragma("unroll") for (int k = 0; k < 2; ++k) dst[m][k] = *(const PG8_LAS bf16x8*)(lds + PG8_SA(b, h) + aoff + m * 2048 + k * 1024); } while (0)
; #define PG8_LDB(dst, b, h) do { _Pragma("unroll") for (int n = 0; n < 2; ++n) _Pragma("unroll") for (int k = 0; k < 2; ++k) dst[n][k] = *(const PG8_LAS bf16x8*)(lds + PG8_SB(b, h) + boff + n * 2048 + k * 1024); } while (0)
; #define PG8_MMA(ai, bj, At, Bt) do { __builtin_amdgcn_s_setprio(1); _Pragma("unroll") for (int m = 0; m < 4; ++m) _Pragma("unroll") for (int n = 0; n < 2; ++n) _Pragma("unroll") for (int k = 0; k < 2; ++k) \
;         acc[ai][bj][m][n] = __builtin_amdgcn_mfma_f32_16x16x32_bf16(Bt[n][k], At[m][k], acc[ai][bj][m][n], 0, 0, 0); __builtin_amdgcn_s_setprio(0); } while (0)
; #define PG8_WAIT_V(n) asm volatile("s_waitcnt vmcnt(" #n ")" ::: "memory")
; #define PG8_WAIT_L(n) asm volatile("s_waitcnt lgkmcnt(" #n ")" ::: "memory")
; #define PG8_BAR __builtin_amdgcn_s_barrier()
; #define PG8_SCHED __builtin_amdgcn_sched_barrier(0)
; template <class Epi, class Sched, bool ALIGN_EPI = false, bool SP2 = false>
; __device__ __forceinline__ void gemm_phase(PG8_LAS unsigned char* lds, const Gemm g, const Sched& S, const Epi& E) {
;     ...
;             PG8_LDB(B0, 1, 0); PG8_LDB(B1, 1, 1); PG8_SCHED; PG8_LDA(At, 1, 0); PG8_STAGE(PG8_SA(0, 1), a2 + hstepA, voffA);
;             PG8_WAIT_V(8); PG8_WAIT_L(0); PG8_BAR; PG8_MMA(0, 0, At, B0); PG8_MMA(0, 1, At, B1); PG8_BAR; PG8_SCHED;
	s_add_i32 s58, 0, 0x18000
	s_add_i32 s59, 0, 0x1c000
	v_add_u32_e32 v78, s58, v168
	v_add_u32_e32 v173, s59, v168
	ds_read_b128 v[66:69], v78
	ds_read_b128 v[70:73], v78 offset:1024
	ds_read_b128 v[74:77], v78 offset:2048
	ds_read_b128 v[78:81], v78 offset:3072
	ds_read_b128 v[162:165], v173
	ds_read_b128 v[174:177], v173 offset:1024
	ds_read_b128 v[178:181], v173 offset:2048
	ds_read_b128 v[182:185], v173 offset:3072
	s_add_u32 s38, s38, 0x80000
	s_addc_u32 s39, s39, 0
	s_mov_b32 m0, s45
	v_lshl_add_u64 v[226:227], s[38:39], 0, v[152:153]
	ds_read_b128 v[186:189], v172 offset:32768
	ds_read_b128 v[190:193], v172 offset:33792
	ds_read_b128 v[194:197], v172 offset:34816
	ds_read_b128 v[198:201], v172 offset:35840
	ds_read_b128 v[202:205], v172 offset:36864
	ds_read_b128 v[210:213], v172 offset:37888
	ds_read_b128 v[214:217], v172 offset:38912
	ds_read_b128 v[218:221], v172 offset:39936
	global_load_lds_dwordx4 v[226:227], off
	v_lshl_add_u64 v[226:227], s[38:39], 0, v[148:149]
	s_mov_b32 m0, s46
	s_nop 0
	global_load_lds_dwordx4 v[226:227], off
	s_waitcnt vmcnt(8)
	s_waitcnt lgkmcnt(0)
	s_barrier
	s_setprio 1
	s_waitcnt lgkmcnt(0)
	v_mfma_f32_16x16x32_bf16 v[142:145], v[66:69], v[186:189], v[142:145]
	v_mfma_f32_16x16x32_bf16 v[138:141], v[74:77], v[186:189], v[138:141]
	v_mfma_f32_16x16x32_bf16 v[126:129], v[66:69], v[194:197], v[126:129]
	v_mfma_f32_16x16x32_bf16 v[122:125], v[74:77], v[194:197], v[122:125]
	v_mfma_f32_16x16x32_bf16 v[110:113], v[66:69], v[202:205], v[110:113]
	v_mfma_f32_16x16x32_bf16 v[106:109], v[74:77], v[202:205], v[106:109]
	v_mfma_f32_16x16x32_bf16 v[94:97], v[66:69], v[214:217], v[94:97]
	v_mfma_f32_16x16x32_bf16 v[90:93], v[74:77], v[214:217], v[90:93]
	v_mfma_f32_16x16x32_bf16 v[142:145], v[70:73], v[190:193], v[142:145]
	v_mfma_f32_16x16x32_bf16 v[138:141], v[78:81], v[190:193], v[138:141]
	v_mfma_f32_16x16x32_bf16 v[126:129], v[70:73], v[198:201], v[126:129]
	v_mfma_f32_16x16x32_bf16 v[122:125], v[78:81], v[198:201], v[122:125]
	v_mfma_f32_16x16x32_bf16 v[110:113], v[70:73], v[210:213], v[110:113]
	v_mfma_f32_16x16x32_bf16 v[106:109], v[78:81], v[210:213], v[106:109]
	v_mfma_f32_16x16x32_bf16 v[94:97], v[70:73], v[218:221], v[94:97]
	v_mfma_f32_16x16x32_bf16 v[90:93], v[78:81], v[218:221], v[90:93]
	s_setprio 0
	s_setprio 1
	v_mfma_f32_16x16x32_bf16 v[134:137], v[162:165], v[186:189], v[134:137]
	v_mfma_f32_16x16x32_bf16 v[130:133], v[178:181], v[186:189], v[130:133]
	v_mfma_f32_16x16x32_bf16 v[118:121], v[162:165], v[194:197], v[118:121]
	v_mfma_f32_16x16x32_bf16 v[114:117], v[178:181], v[194:197], v[114:117]
	v_mfma_f32_16x16x32_bf16 v[102:105], v[162:165], v[202:205], v[102:105]
	v_mfma_f32_16x16x32_bf16 v[98:101], v[178:181], v[202:205], v[98:101]
	v_mfma_f32_16x16x32_bf16 v[86:89], v[162:165], v[214:217], v[86:89]
	v_mfma_f32_16x16x32_bf16 v[82:85], v[178:181], v[214:217], v[82:85]
	v_mfma_f32_16x16x32_bf16 v[134:137], v[174:177], v[190:193], v[134:137]
	v_mfma_f32_16x16x32_bf16 v[130:133], v[182:185], v[190:193], v[130:133]
	v_mfma_f32_16x16x32_bf16 v[118:121], v[174:177], v[198:201], v[118:121]
	v_mfma_f32_16x16x32_bf16 v[114:117], v[182:185], v[198:201], v[114:117]
	v_mfma_f32_16x16x32_bf16 v[102:105], v[174:177], v[210:213], v[102:105]
	v_mfma_f32_16x16x32_bf16 v[98:101], v[182:185], v[210:213], v[98:101]
	v_mfma_f32_16x16x32_bf16 v[86:89], v[174:177], v[218:221], v[86:89]
	v_mfma_f32_16x16x32_bf16 v[82:85], v[182:185], v[218:221], v[82:85]
	s_setprio 0
	s_barrier
; #define PG8_STAGE(bufoff, gbase, voff) do { _Pragma("unroll") for (int _i = 0; _i < 2; ++_i) \
;         __builtin_amdgcn_global_load_lds((const unsigned*)((const char*)(gbase) + (voff)[_i]), (PG8_LAS unsigned*)(lds + (bufoff) + ldsw + _i * 8192), 16, 0, 0); } while (0)
; #define PG8_LDA(dst, b, h) do { _Pragma("unroll") for (int m = 0; m < 4; ++m) _Pragma("unroll") for (int k = 0; k < 2; ++k) dst[m][k] = *(const PG8_LAS bf16x8*)(lds + PG8_SA(b, h) + aoff + m * 2048 + k * 1024); } while (0)
; #define PG8_MMA(ai, bj, At, Bt) do { __builtin_amdgcn_s_setprio(1); _Pragma("unroll") for (int m = 0; m < 4; ++m) _Pragma("unroll") for (int n = 0; n < 2; ++n) _Pragma("unroll") for (int k = 0; k < 2; ++k) \
;         acc[ai][bj][m][n] = __builtin_amdgcn_mfma_f32_16x16x32_bf16(Bt[n][k], At[m][k], acc[ai][bj][m][n], 0, 0, 0); __builtin_amdgcn_s_setprio(0); } while (0)
; #define PG8_WAIT_V(n) asm volatile("s_waitcnt vmcnt(" #n ")" ::: "memory")
; #define PG8_WAIT_L(n) asm volatile("s_waitcnt lgkmcnt(" #n ")" ::: "memory")
; #define PG8_BAR __builtin_amdgcn_s_barrier()
; #define PG8_SCHED __builtin_amdgcn_sched_barrier(0)
; template <class Epi, class Sched, bool ALIGN_EPI = false, bool SP2 = false>
; __device__ __forceinline__ void gemm_phase(PG8_LAS unsigned char* lds, const Gemm g, const Sched& S, const Epi& E) {
;     ...
;         for (int t = 0; t < nt; t += 2) {
;             const bool last = (t == nt - 2);
;             const char* a1 = cA + (size_t)(t + 1) * kstep;
;             const char* a2 = last ? nA : cA + (size_t)(t + 2) * kstep; const char* b2 = last ? nB : cB + (size_t)(t + 2) * kstep;
;     ...
;             PG8_LDA(At, 1, 1); PG8_STAGE(PG8_SB(1, 0), b3, voffB); PG8_STAGE(PG8_SB(1, 1), b3 + hstepB, voffB); PG8_STAGE(PG8_SA(1, 0), a3, voffA);
;             PG8_WAIT_V(8); PG8_WAIT_L(0); PG8_BAR; PG8_MMA(1, 0, At, B0); PG8_MMA(1, 1, At, B1); PG8_BAR; PG8_SCHED;
	s_add_i32 s38, s58, s40
	v_lshl_add_u64 v[166:167], v[166:167], 0, s[14:15]
	s_mov_b32 m0, s38
	ds_read_b128 v[186:189], v172 offset:49152
	ds_read_b128 v[190:193], v172 offset:50176
	ds_read_b128 v[194:197], v172 offset:51200
	ds_read_b128 v[198:201], v172 offset:52224
	ds_read_b128 v[202:205], v172 offset:53248
	ds_read_b128 v[210:213], v172 offset:54272
	ds_read_b128 v[214:217], v172 offset:55296
	ds_read_b128 v[218:221], v172 offset:56320
	global_load_lds_dwordx4 v[166:167], off
	s_add_i32 m0, s38, 0x2000
	s_add_u32 s36, s36, 0x80080
	v_lshl_add_u64 v[166:167], v[206:207], 0, s[14:15]
	s_addc_u32 s37, s37, 0
	s_add_i32 s38, s59, s40
	global_load_lds_dwordx4 v[166:167], off
	v_lshl_add_u64 v[166:167], s[36:37], 0, v[150:151]
	s_mov_b32 m0, s38
	s_nop 0
	global_load_lds_dwordx4 v[166:167], off
	v_lshl_add_u64 v[166:167], s[36:37], 0, v[146:147]
	s_add_i32 m0, s38, 0x2000
	s_nop 0
	global_load_lds_dwordx4 v[166:167], off
	v_lshl_add_u64 v[166:167], v[222:223], 0, s[14:15]
	s_mov_b32 m0, s48
	s_nop 0
	global_load_lds_dwordx4 v[166:167], off
	v_lshl_add_u64 v[166:167], v[224:225], 0, s[14:15]
	s_mov_b32 m0, s49
	s_nop 0
	global_load_lds_dwordx4 v[166:167], off
	s_waitcnt vmcnt(8)
	s_waitcnt lgkmcnt(0)
	s_barrier
	s_setprio 1
	s_waitcnt lgkmcnt(0)
	v_mfma_f32_16x16x32_bf16 v[62:65], v[66:69], v[186:189], v[62:65]
	v_mfma_f32_16x16x32_bf16 v[58:61], v[74:77], v[186:189], v[58:61]
	v_mfma_f32_16x16x32_bf16 v[46:49], v[66:69], v[194:197], v[46:49]
	v_mfma_f32_16x16x32_bf16 v[42:45], v[74:77], v[194:197], v[42:45]
	v_mfma_f32_16x16x32_bf16 v[30:33], v[66:69], v[202:205], v[30:33]
	v_mfma_f32_16x16x32_bf16 v[26:29], v[74:77], v[202:205], v[26:29]
	v_mfma_f32_16x16x32_bf16 v[14:17], v[66:69], v[214:217], v[14:17]
	v_mfma_f32_16x16x32_bf16 v[10:13], v[74:77], v[214:217], v[10:13]
	v_mfma_f32_16x16x32_bf16 v[62:65], v[70:73], v[190:193], v[62:65]
	v_mfma_f32_16x16x32_bf16 v[58:61], v[78:81], v[190:193], v[58:61]
	v_mfma_f32_16x16x32_bf16 v[46:49], v[70:73], v[198:201], v[46:49]
	v_mfma_f32_16x16x32_bf16 v[42:45], v[78:81], v[198:201], v[42:45]
	v_mfma_f32_16x16x32_bf16 v[30:33], v[70:73], v[210:213], v[30:33]
	v_mfma_f32_16x16x32_bf16 v[26:29], v[78:81], v[210:213], v[26:29]
	v_mfma_f32_16x16x32_bf16 v[14:17], v[70:73], v[218:221], v[14:17]
	v_mfma_f32_16x16x32_bf16 v[10:13], v[78:81], v[218:221], v[10:13]
	s_setprio 0
	s_setprio 1
	v_mfma_f32_16x16x32_bf16 v[54:57], v[162:165], v[186:189], v[54:57]
	v_mfma_f32_16x16x32_bf16 v[50:53], v[178:181], v[186:189], v[50:53]
	v_mfma_f32_16x16x32_bf16 v[38:41], v[162:165], v[194:197], v[38:41]
	v_mfma_f32_16x16x32_bf16 v[34:37], v[178:181], v[194:197], v[34:37]
	v_mfma_f32_16x16x32_bf16 v[22:25], v[162:165], v[202:205], v[22:25]
	v_mfma_f32_16x16x32_bf16 v[18:21], v[178:181], v[202:205], v[18:21]
	v_mfma_f32_16x16x32_bf16 v[6:9], v[162:165], v[214:217], v[6:9]
	v_mfma_f32_16x16x32_bf16 v[2:5], v[178:181], v[214:217], v[2:5]
	v_mfma_f32_16x16x32_bf16 v[54:57], v[174:177], v[190:193], v[54:57]
	v_mfma_f32_16x16x32_bf16 v[50:53], v[182:185], v[190:193], v[50:53]
	v_mfma_f32_16x16x32_bf16 v[38:41], v[174:177], v[198:201], v[38:41]
	v_mfma_f32_16x16x32_bf16 v[34:37], v[182:185], v[198:201], v[34:37]
	v_mfma_f32_16x16x32_bf16 v[22:25], v[174:177], v[210:213], v[22:25]
	v_mfma_f32_16x16x32_bf16 v[18:21], v[182:185], v[210:213], v[18:21]
	v_mfma_f32_16x16x32_bf16 v[6:9], v[174:177], v[218:221], v[6:9]
	v_mfma_f32_16x16x32_bf16 v[2:5], v[182:185], v[218:221], v[2:5]
	s_setprio 0
	s_barrier
	s_add_i32 s57, s57, 2
	s_add_u32 s2, s2, 0x100
	s_addc_u32 s3, s3, 0
	s_add_u32 s55, s55, 0x100
	s_addc_u32 s56, s56, 0
	s_cmp_gt_u32 s57, 29
	s_cbranch_scc1 .Lpeel_exit_14
	.p2align 6

; #define PG8_BAR __builtin_amdgcn_s_barrier()
; template <class Epi, class Sched, bool ALIGN_EPI = false, bool SP2 = false>
; __device__ __forceinline__ void gemm_phase(PG8_LAS unsigned char* lds, const Gemm g, const Sched& S, const Epi& E) {
;     ...
;         if constexpr (ALIGN_EPI) { if (wr == 0) PG8_BAR; }
.Lpeel_exit_14:
	s_and_b64 vcc, exec, s[16:17]
	s_cbranch_vccz .LBB0_1360
	s_barrier

; #define PG8_STAGE(bufoff, gbase, voff) do { _Pragma("unroll") for (int _i = 0; _i < 2; ++_i) \
;         __builtin_amdgcn_global_load_lds((const unsigned*)((const char*)(gbase) + (voff)[_i]), (PG8_LAS unsigned*)(lds + (bufoff) + ldsw + _i * 8192), 16, 0, 0); } while (0)
; #define PG8_WAIT_V(n) asm volatile("s_waitcnt vmcnt(" #n ")" ::: "memory")
; #define PG8_BAR __builtin_amdgcn_s_barrier()
; template <class Epi, class Sched, bool ALIGN_EPI = false, bool SP2 = false>
; __device__ __forceinline__ void gemm_phase(PG8_LAS unsigned char* lds, const Gemm g, const Sched& S, const Epi& E) {
;     const int tid = threadIdx.x, wid = __builtin_amdgcn_readfirstlane(tid >> 6), lane = tid & 63, wr = wid >> 2, wc = wid & 3, fr = lane & 15, fq = lane >> 4;
;     const int K = g.K, nt = K / BK;
;     unsigned voffA[2], voffB[2];
; #pragma unroll
;     for (int i = 0; i < 2; ++i) { int R, C; stage_rc(tid * 16 + i * 8192, R, C); const int Rb = Epi::PERM ? ((R & ~31) + perm32(R & 31)) : R;
;         voffA[i] = (unsigned)(R * g.lda + C) * 2u; voffB[i] = (unsigned)(Rb * g.ldb + C) * 2u; }
;     const size_t kstep = (size_t)(BK * 2);
;     const size_t hstepA = (size_t)HALF * g.lda * 2, hstepB = (size_t)HALF * g.ldb * 2;
;     const size_t tstepA = 2 * hstepA, tstepB = 2 * hstepB;
;     const unsigned ldsw = (unsigned)wid * 1024u;
;     const int aoff = lds_byte(wr * 64 + fr, fq * 8), boff = lds_byte(wc * 32 + fr, fq * 8);
;     ...
;         PG8_WAIT_V(2); PG8_BAR;
;         PG8_STAGE(PG8_SB(1, 0), cB + kstep, voffB); PG8_STAGE(PG8_SA(1, 0), cA + kstep, voffA); PG8_STAGE(PG8_SB(1, 1), cB + hstepB + kstep, voffB);
;         PG8_WAIT_V(6); PG8_BAR;
.LBB0_1481:
	s_lshl_b32 s2, s2, 5
	s_and_b32 s12, s2, 0x60
	s_mov_b64 s[2:3], 0x80
	s_add_i32 m0, s21, 0x18000
	v_lshl_add_u64 v[8:9], v[8:9], 0, s[2:3]
	s_lshl_b32 s9, s8, 13
	s_lshl_b32 s13, s12, 7
	s_waitcnt vmcnt(2)
	s_barrier
	global_load_lds_dwordx4 v[8:9], off
	v_lshl_add_u64 v[6:7], v[6:7], 0, s[2:3]
	s_add_i32 m0, s21, 0x1a000
	s_add_i32 s39, s21, 0x8000
	s_add_i32 s40, s21, 0xa000
	global_load_lds_dwordx4 v[6:7], off
	v_lshl_add_u64 v[2:3], v[2:3], 0, s[2:3]
	s_mov_b32 m0, s39
	s_add_u32 s10, s24, 0x80080
	global_load_lds_dwordx4 v[2:3], off
	v_lshl_add_u64 v[2:3], v[4:5], 0, s[2:3]
	s_mov_b32 m0, s40
	s_addc_u32 s11, s25, 0
	global_load_lds_dwordx4 v[2:3], off
	s_add_i32 m0, s21, 0x1c000
	v_lshl_add_u64 v[2:3], s[10:11], 0, v[134:135]
	global_load_lds_dwordx4 v[2:3], off
	v_lshl_add_u64 v[2:3], s[10:11], 0, v[130:131]
	s_add_i32 m0, s21, 0x1e000
	s_sext_i32_i16 s45, s4
	global_load_lds_dwordx4 v[2:3], off
	v_and_b32_e32 v2, 15, v0
	v_lshlrev_b32_e32 v3, 1, v13
	v_lshlrev_b32_e32 v4, 2, v0
	v_lshlrev_b32_e32 v5, 6, v0
	s_movk_i32 s4, 0x3c0
	v_lshl_or_b32 v1, s8, 6, v2
	v_lshl_or_b32 v2, v2, 6, v3
	v_and_b32_e32 v4, 32, v4
	v_and_or_b32 v3, v5, s4, v3
	v_bitop3_b32 v148, s13, v3, v4 bitop3:0xf6
	v_lshlrev_b32_e32 v3, 9, v0
	v_bitop3_b32 v2, v2, s9, v4 bitop3:0xde
	v_and_b32_e32 v3, 0x30000, v3
	v_lshlrev_b32_e32 v4, 12, v14
	v_or3_b32 v3, v11, v3, v4
	v_add_u32_e32 v138, v3, v12
	v_lshlrev_b32_e32 v3, 5, v10
	s_waitcnt vmcnt(0)
	s_cmpk_lt_u32 s5, 0x100
	v_and_b32_e32 v3, 0x70000, v3
	s_cselect_b64 s[8:9], -1, 0
	v_or3_b32 v3, v11, v3, v4
	s_add_i32 s42, 0, 0x10000
	s_add_i32 s43, 0, 0x14000
	s_ashr_i32 s41, s28, 31
	v_or_b32_e32 v149, s12, v13
	v_mov_b32_e32 v139, v135
	v_add_u32_e32 v140, v3, v12
	v_mov_b32_e32 v141, v135
	v_mov_b64_e32 v[142:143], 0x1b80
	v_mov_b64_e32 v[144:145], 0x1b7f
	v_add_u32_e32 v150, s42, v148
	v_add_u32_e32 v151, s43, v148
	v_add_u32_e32 v152, 0, v2
	s_movk_i32 s44, 0x2c00
	s_barrier
	s_branch .LBB0_1484

; #define PG8_STAGE(bufoff, gbase, voff) do { _Pragma("unroll") for (int _i = 0; _i < 2; ++_i) \
;         __builtin_amdgcn_global_load_lds((const unsigned*)((const char*)(gbase) + (voff)[_i]), (PG8_LAS unsigned*)(lds + (bufoff) + ldsw + _i * 8192), 16, 0, 0); } while (0)
; #define PG8_LDA(dst, b, h) do { _Pragma("unroll") for (int m = 0; m < 4; ++m) _Pragma("unroll") for (int k = 0; k < 2; ++k) dst[m][k] = *(const PG8_LAS bf16x8*)(lds + PG8_SA(b, h) + aoff + m * 2048 + k * 1024); } while (0)
; #define PG8_LDB(dst, b, h) do { _Pragma("unroll") for (int n = 0; n < 2; ++n) _Pragma("unroll") for (int k = 0; k < 2; ++k) dst[n][k] = *(const PG8_LAS bf16x8*)(lds + PG8_SB(b, h) + boff + n * 2048 + k * 1024); } while (0)
; #define PG8_WAIT_V(n) asm volatile("s_waitcnt vmcnt(" #n ")" ::: "memory")
; #define PG8_WAIT_L(n) asm volatile("s_waitcnt lgkmcnt(" #n ")" ::: "memory")
; #define PG8_BAR __builtin_amdgcn_s_barrier()
; #define PG8_SCHED __builtin_amdgcn_sched_barrier(0)
; template <class Epi, class Sched, bool ALIGN_EPI = false, bool SP2 = false>
; __device__ __forceinline__ void gemm_phase(PG8_LAS unsigned char* lds, const Gemm g, const Sched& S, const Epi& E) {
;     ...
;         const char* nA = has_next ? (const char*)g.A + (size_t)nxt.pm * tstepA : cA; const char* nB = has_next ? (const char*)g.Bt + (size_t)nxt.pn * tstepB : cB;
;         for (int t = 0; t < nt; t += 2) {
;             const bool last = (t == nt - 2);
;             const char* a1 = cA + (size_t)(t + 1) * kstep;
;             const char* a2 = last ? nA : cA + (size_t)(t + 2) * kstep; const char* b2 = last ? nB : cB + (size_t)(t + 2) * kstep;
;             const char* a3 = a2 + kstep; const char* b3 = b2 + kstep;
;             if (last && has_next) S.a_ready(nxt);
;             if constexpr (SP2) {
;             PG8_LDB(B0, 0, 0); PG8_LDB(B1, 0, 1); PG8_SCHED; PG8_LDA(At, 0, 0); PG8_STAGE(PG8_SA(1, 1), a1 + hstepA, voffA);
;             PG8_WAIT_V(8); PG8_WAIT_L(0); PG8_BAR; PG8_MMA(0, 0, At, B0); PG8_MMA(0, 1, At, B1); PG8_BAR; PG8_SCHED;
;     ...
; #pragma unroll
;         for (int a = 0; a < 2; ++a)
; #pragma unroll
;             for (int b = 0; b < 2; ++b)
; #pragma unroll
;                 for (int m = 0; m < 4; ++m)
; #pragma unroll
;                     for (int n = 0; n < 2; ++n) acc[a][b][m][n] = (f32x4){0.f, 0.f, 0.f, 0.f};
.LBB0_1486:
	s_ashr_i32 s13, s12, 31
	s_lshl_b64 s[14:15], s[12:13], 20
	s_add_u32 s14, s86, s14
	s_addc_u32 s15, s87, s15
	s_and_b64 s[16:17], s[4:5], exec
	s_cselect_b32 s13, s15, s23
	s_cselect_b32 s46, s14, s22
	s_ashr_i32 s11, s10, 31
	s_lshl_b64 s[16:17], s[10:11], 20
	s_add_u32 s16, s29, s16
	s_addc_u32 s17, s30, s17
	s_and_b64 s[26:27], s[4:5], exec
	s_cselect_b32 s11, s17, s25
	s_cselect_b32 s47, s16, s24
	s_add_u32 s22, s22, 0x80080
	s_addc_u32 s23, s23, 0
	s_add_u32 s48, s24, 0x100
	v_mov_b32_e32 v2, 0
	s_addc_u32 s49, s25, 0
	s_mov_b32 s50, -2
	v_mov_b32_e32 v3, v2
	v_mov_b32_e32 v4, v2
	v_mov_b32_e32 v5, v2
	v_mov_b32_e32 v6, v2
	v_mov_b32_e32 v7, v2
	v_mov_b32_e32 v8, v2
	v_mov_b32_e32 v9, v2
	v_mov_b32_e32 v18, v2
	v_mov_b32_e32 v19, v2
	v_mov_b32_e32 v20, v2
	v_mov_b32_e32 v21, v2
	v_mov_b32_e32 v22, v2
	v_mov_b32_e32 v23, v2
	v_mov_b32_e32 v24, v2
	v_mov_b32_e32 v25, v2
	v_mov_b32_e32 v34, v2
	v_mov_b32_e32 v35, v2
	v_mov_b32_e32 v36, v2
	v_mov_b32_e32 v37, v2
	v_mov_b32_e32 v38, v2
	v_mov_b32_e32 v39, v2
	v_mov_b32_e32 v40, v2
	v_mov_b32_e32 v41, v2
	v_mov_b32_e32 v50, v2
	v_mov_b32_e32 v51, v2
	v_mov_b32_e32 v52, v2
	v_mov_b32_e32 v53, v2
	v_mov_b32_e32 v54, v2
	v_mov_b32_e32 v55, v2
	v_mov_b32_e32 v56, v2
	v_mov_b32_e32 v57, v2
	v_mov_b32_e32 v10, v2
	v_mov_b32_e32 v11, v2
	v_mov_b32_e32 v12, v2
	v_mov_b32_e32 v13, v2
	v_mov_b32_e32 v14, v2
	v_mov_b32_e32 v15, v2
	v_mov_b32_e32 v16, v2
	v_mov_b32_e32 v17, v2
	v_mov_b32_e32 v26, v2
	v_mov_b32_e32 v27, v2
	v_mov_b32_e32 v28, v2
	v_mov_b32_e32 v29, v2
	v_mov_b32_e32 v30, v2
	v_mov_b32_e32 v31, v2
	v_mov_b32_e32 v32, v2
	v_mov_b32_e32 v33, v2
	v_mov_b32_e32 v42, v2
	v_mov_b32_e32 v43, v2
	v_mov_b32_e32 v44, v2
	v_mov_b32_e32 v45, v2
	v_mov_b32_e32 v46, v2
	v_mov_b32_e32 v47, v2
	v_mov_b32_e32 v48, v2
	v_mov_b32_e32 v49, v2
	v_mov_b32_e32 v58, v2
	v_mov_b32_e32 v59, v2
	v_mov_b32_e32 v60, v2
	v_mov_b32_e32 v61, v2
	v_mov_b32_e32 v62, v2
	v_mov_b32_e32 v63, v2
	v_mov_b32_e32 v64, v2
	v_mov_b32_e32 v65, v2
	v_mov_b32_e32 v66, v2
	v_mov_b32_e32 v67, v2
	v_mov_b32_e32 v68, v2
	v_mov_b32_e32 v69, v2
	v_mov_b32_e32 v70, v2
	v_mov_b32_e32 v71, v2
	v_mov_b32_e32 v72, v2
	v_mov_b32_e32 v73, v2
	v_mov_b32_e32 v82, v2
	v_mov_b32_e32 v83, v2
	v_mov_b32_e32 v84, v2
	v_mov_b32_e32 v85, v2
	v_mov_b32_e32 v86, v2
	v_mov_b32_e32 v87, v2
	v_mov_b32_e32 v88, v2
	v_mov_b32_e32 v89, v2
	v_mov_b32_e32 v98, v2
	v_mov_b32_e32 v99, v2
	v_mov_b32_e32 v100, v2
	v_mov_b32_e32 v101, v2
	v_mov_b32_e32 v102, v2
	v_mov_b32_e32 v103, v2
	v_mov_b32_e32 v104, v2
	v_mov_b32_e32 v105, v2
	v_mov_b32_e32 v114, v2
	v_mov_b32_e32 v115, v2
	v_mov_b32_e32 v116, v2
	v_mov_b32_e32 v117, v2
	v_mov_b32_e32 v118, v2
	v_mov_b32_e32 v119, v2
	v_mov_b32_e32 v120, v2
	v_mov_b32_e32 v121, v2
	v_mov_b32_e32 v74, v2
	v_mov_b32_e32 v75, v2
	v_mov_b32_e32 v76, v2
	v_mov_b32_e32 v77, v2
	v_mov_b32_e32 v78, v2
	v_mov_b32_e32 v79, v2
	v_mov_b32_e32 v80, v2
	v_mov_b32_e32 v81, v2
	v_mov_b32_e32 v90, v2
	v_mov_b32_e32 v91, v2
	v_mov_b32_e32 v92, v2
	v_mov_b32_e32 v93, v2
	v_mov_b32_e32 v94, v2
	v_mov_b32_e32 v95, v2
	v_mov_b32_e32 v96, v2
	v_mov_b32_e32 v97, v2
	v_mov_b32_e32 v106, v2
	v_mov_b32_e32 v107, v2
	v_mov_b32_e32 v108, v2
	v_mov_b32_e32 v109, v2
	v_mov_b32_e32 v110, v2
	v_mov_b32_e32 v111, v2
	v_mov_b32_e32 v112, v2
	v_mov_b32_e32 v113, v2
	v_mov_b32_e32 v122, v2
	v_mov_b32_e32 v123, v2
	v_mov_b32_e32 v124, v2
	v_mov_b32_e32 v125, v2
	v_mov_b32_e32 v126, v2
	v_mov_b32_e32 v127, v2
	v_mov_b32_e32 v128, v2
	v_mov_b32_e32 v129, v2
	ds_read_b128 v[154:157], v150
	ds_read_b128 v[158:161], v150 offset:1024
	ds_read_b128 v[162:165], v150 offset:2048
	ds_read_b128 v[166:169], v150 offset:3072
	ds_read_b128 v[170:173], v151
	ds_read_b128 v[174:177], v151 offset:1024
	ds_read_b128 v[178:181], v151 offset:2048
	ds_read_b128 v[182:185], v151 offset:3072
	s_add_u32 s24, s22, 0xfff80080
	s_addc_u32 s25, s23, -1
	s_cmp_eq_u32 s50, 28
	s_cselect_b32 s27, s13, s25
	s_cselect_b32 s26, s46, s24
	s_cselect_b32 s25, s11, s49
	s_cselect_b32 s24, s47, s48
	v_lshl_add_u64 v[146:147], s[22:23], 0, v[138:139]
	s_add_i32 m0, s21, 0xc000
	ds_read_b128 v[186:189], v152
	ds_read_b128 v[190:193], v152 offset:1024
	ds_read_b128 v[194:197], v152 offset:2048
	ds_read_b128 v[198:201], v152 offset:3072
	ds_read_b128 v[202:205], v152 offset:4096
	ds_read_b128 v[210:213], v152 offset:5120
	ds_read_b128 v[214:217], v152 offset:6144
	ds_read_b128 v[218:221], v152 offset:7168
	global_load_lds_dwordx4 v[146:147], off
	v_lshl_add_u64 v[146:147], s[22:23], 0, v[140:141]
	s_add_i32 m0, s21, 0xe000
	s_nop 0
	global_load_lds_dwordx4 v[146:147], off
	s_waitcnt vmcnt(16)
	s_waitcnt lgkmcnt(0)
	s_barrier
; #define PG8_STAGE(bufoff, gbase, voff) do { _Pragma("unroll") for (int _i = 0; _i < 2; ++_i) \
;         __builtin_amdgcn_global_load_lds((const unsigned*)((const char*)(gbase) + (voff)[_i]), (PG8_LAS unsigned*)(lds + (bufoff) + ldsw + _i * 8192), 16, 0, 0); } while (0)
; #define PG8_LDA(dst, b, h) do { _Pragma("unroll") for (int m = 0; m < 4; ++m) _Pragma("unroll") for (int k = 0; k < 2; ++k) dst[m][k] = *(const PG8_LAS bf16x8*)(lds + PG8_SA(b, h) + aoff + m * 2048 + k * 1024); } while (0)
; #define PG8_MMA(ai, bj, At, Bt) do { __builtin_amdgcn_s_setprio(1); _Pragma("unroll") for (int m = 0; m < 4; ++m) _Pragma("unroll") for (int n = 0; n < 2; ++n) _Pragma("unroll") for (int k = 0; k < 2; ++k) \
;         acc[ai][bj][m][n] = __builtin_amdgcn_mfma_f32_16x16x32_bf16(Bt[n][k], At[m][k], acc[ai][bj][m][n], 0, 0, 0); __builtin_amdgcn_s_setprio(0); } while (0)
; #define PG8_WAIT_V(n) asm volatile("s_waitcnt vmcnt(" #n ")" ::: "memory")
; #define PG8_WAIT_L(n) asm volatile("s_waitcnt lgkmcnt(" #n ")" ::: "memory")
; #define PG8_BAR __builtin_amdgcn_s_barrier()
; #define PG8_SCHED __builtin_amdgcn_sched_barrier(0)
; template <class Epi, class Sched, bool ALIGN_EPI = false, bool SP2 = false>
; __device__ __forceinline__ void gemm_phase(PG8_LAS unsigned char* lds, const Gemm g, const Sched& S, const Epi& E) {
;     ...
;             PG8_WAIT_V(8); PG8_WAIT_L(0); PG8_BAR; PG8_MMA(0, 0, At, B0); PG8_MMA(0, 1, At, B1); PG8_BAR; PG8_SCHED;
;             PG8_LDA(At, 0, 1); PG8_STAGE(PG8_SB(0, 0), b2, voffB); PG8_STAGE(PG8_SB(0, 1), b2 + hstepB, voffB); PG8_STAGE(PG8_SA(0, 0), a2, voffA);
;             PG8_WAIT_V(8); PG8_WAIT_L(0); PG8_BAR; PG8_MMA(1, 0, At, B0); PG8_MMA(1, 1, At, B1); PG8_BAR; PG8_SCHED;
	s_setprio 1
	s_waitcnt lgkmcnt(0)
	v_mfma_f32_16x16x32_bf16 v[126:129], v[154:157], v[186:189], v[126:129]
	v_mfma_f32_16x16x32_bf16 v[122:125], v[162:165], v[186:189], v[122:125]
	v_mfma_f32_16x16x32_bf16 v[110:113], v[154:157], v[194:197], v[110:113]
	v_mfma_f32_16x16x32_bf16 v[106:109], v[162:165], v[194:197], v[106:109]
	v_mfma_f32_16x16x32_bf16 v[94:97], v[154:157], v[202:205], v[94:97]
	v_mfma_f32_16x16x32_bf16 v[90:93], v[162:165], v[202:205], v[90:93]
	v_mfma_f32_16x16x32_bf16 v[78:81], v[154:157], v[214:217], v[78:81]
	v_mfma_f32_16x16x32_bf16 v[74:77], v[162:165], v[214:217], v[74:77]
	v_mfma_f32_16x16x32_bf16 v[126:129], v[158:161], v[190:193], v[126:129]
	v_mfma_f32_16x16x32_bf16 v[122:125], v[166:169], v[190:193], v[122:125]
	v_mfma_f32_16x16x32_bf16 v[110:113], v[158:161], v[198:201], v[110:113]
	v_mfma_f32_16x16x32_bf16 v[106:109], v[166:169], v[198:201], v[106:109]
	v_mfma_f32_16x16x32_bf16 v[94:97], v[158:161], v[210:213], v[94:97]
	v_mfma_f32_16x16x32_bf16 v[90:93], v[166:169], v[210:213], v[90:93]
	v_mfma_f32_16x16x32_bf16 v[78:81], v[158:161], v[218:221], v[78:81]
	v_mfma_f32_16x16x32_bf16 v[74:77], v[166:169], v[218:221], v[74:77]
	s_setprio 0
	s_setprio 1
	v_mfma_f32_16x16x32_bf16 v[118:121], v[170:173], v[186:189], v[118:121]
	v_mfma_f32_16x16x32_bf16 v[114:117], v[178:181], v[186:189], v[114:117]
	v_mfma_f32_16x16x32_bf16 v[102:105], v[170:173], v[194:197], v[102:105]
	v_mfma_f32_16x16x32_bf16 v[98:101], v[178:181], v[194:197], v[98:101]
	v_mfma_f32_16x16x32_bf16 v[86:89], v[170:173], v[202:205], v[86:89]
	v_mfma_f32_16x16x32_bf16 v[82:85], v[178:181], v[202:205], v[82:85]
	v_mfma_f32_16x16x32_bf16 v[70:73], v[170:173], v[214:217], v[70:73]
	v_mfma_f32_16x16x32_bf16 v[66:69], v[178:181], v[214:217], v[66:69]
	v_mfma_f32_16x16x32_bf16 v[118:121], v[174:177], v[190:193], v[118:121]
	v_mfma_f32_16x16x32_bf16 v[114:117], v[182:185], v[190:193], v[114:117]
	v_mfma_f32_16x16x32_bf16 v[102:105], v[174:177], v[198:201], v[102:105]
	v_mfma_f32_16x16x32_bf16 v[98:101], v[182:185], v[198:201], v[98:101]
	v_mfma_f32_16x16x32_bf16 v[86:89], v[174:177], v[210:213], v[86:89]
	v_mfma_f32_16x16x32_bf16 v[82:85], v[182:185], v[210:213], v[82:85]
	v_mfma_f32_16x16x32_bf16 v[70:73], v[174:177], v[218:221], v[70:73]
	v_mfma_f32_16x16x32_bf16 v[66:69], v[182:185], v[218:221], v[66:69]
	s_setprio 0
	s_barrier
	s_add_i32 s51, s42, s31
	v_lshl_add_u64 v[146:147], s[24:25], 0, v[134:135]
	s_mov_b32 m0, s51
	ds_read_b128 v[186:189], v152 offset:16384
	ds_read_b128 v[190:193], v152 offset:17408
	ds_read_b128 v[194:197], v152 offset:18432
	ds_read_b128 v[198:201], v152 offset:19456
	ds_read_b128 v[202:205], v152 offset:20480
	ds_read_b128 v[210:213], v152 offset:21504
	ds_read_b128 v[214:217], v152 offset:22528
	ds_read_b128 v[218:221], v152 offset:23552
	global_load_lds_dwordx4 v[146:147], off
	s_add_i32 m0, s51, 0x2000
	s_add_u32 s52, s24, 0x80000
	v_lshl_add_u64 v[206:207], s[24:25], 0, v[130:131]
	s_addc_u32 s53, s25, 0
	s_add_i32 s51, s43, s31
	global_load_lds_dwordx4 v[206:207], off
	v_lshl_add_u64 v[222:223], s[52:53], 0, v[134:135]
	s_mov_b32 m0, s51
	v_lshl_add_u64 v[224:225], s[26:27], 0, v[132:133]
	global_load_lds_dwordx4 v[222:223], off
	v_lshl_add_u64 v[222:223], s[52:53], 0, v[130:131]
	s_add_i32 m0, s51, 0x2000
	s_nop 0
	global_load_lds_dwordx4 v[222:223], off
	v_lshl_add_u64 v[222:223], s[26:27], 0, v[136:137]
	s_mov_b32 m0, s21
	s_nop 0
	global_load_lds_dwordx4 v[222:223], off
	s_mov_b32 m0, s35
	s_nop 0
	global_load_lds_dwordx4 v[224:225], off
	s_waitcnt vmcnt(16)
	s_waitcnt lgkmcnt(0)
	s_barrier
	s_setprio 1
	s_waitcnt lgkmcnt(0)
	v_mfma_f32_16x16x32_bf16 v[62:65], v[154:157], v[186:189], v[62:65]
	v_mfma_f32_16x16x32_bf16 v[58:61], v[162:165], v[186:189], v[58:61]
	v_mfma_f32_16x16x32_bf16 v[46:49], v[154:157], v[194:197], v[46:49]
	v_mfma_f32_16x16x32_bf16 v[42:45], v[162:165], v[194:197], v[42:45]
	v_mfma_f32_16x16x32_bf16 v[30:33], v[154:157], v[202:205], v[30:33]
	v_mfma_f32_16x16x32_bf16 v[26:29], v[162:165], v[202:205], v[26:29]
	v_mfma_f32_16x16x32_bf16 v[14:17], v[154:157], v[214:217], v[14:17]
	v_mfma_f32_16x16x32_bf16 v[10:13], v[162:165], v[214:217], v[10:13]
	v_mfma_f32_16x16x32_bf16 v[62:65], v[158:161], v[190:193], v[62:65]
	v_mfma_f32_16x16x32_bf16 v[58:61], v[166:169], v[190:193], v[58:61]
	v_mfma_f32_16x16x32_bf16 v[46:49], v[158:161], v[198:201], v[46:49]
	v_mfma_f32_16x16x32_bf16 v[42:45], v[166:169], v[198:201], v[42:45]
	v_mfma_f32_16x16x32_bf16 v[30:33], v[158:161], v[210:213], v[30:33]
	v_mfma_f32_16x16x32_bf16 v[26:29], v[166:169], v[210:213], v[26:29]
	v_mfma_f32_16x16x32_bf16 v[14:17], v[158:161], v[218:221], v[14:17]
	v_mfma_f32_16x16x32_bf16 v[10:13], v[166:169], v[218:221], v[10:13]
	s_setprio 0
	s_setprio 1
	v_mfma_f32_16x16x32_bf16 v[54:57], v[170:173], v[186:189], v[54:57]
	v_mfma_f32_16x16x32_bf16 v[50:53], v[178:181], v[186:189], v[50:53]
	v_mfma_f32_16x16x32_bf16 v[38:41], v[170:173], v[194:197], v[38:41]
	v_mfma_f32_16x16x32_bf16 v[34:37], v[178:181], v[194:197], v[34:37]
	v_mfma_f32_16x16x32_bf16 v[22:25], v[170:173], v[202:205], v[22:25]
	v_mfma_f32_16x16x32_bf16 v[18:21], v[178:181], v[202:205], v[18:21]
	v_mfma_f32_16x16x32_bf16 v[6:9], v[170:173], v[214:217], v[6:9]
	v_mfma_f32_16x16x32_bf16 v[2:5], v[178:181], v[214:217], v[2:5]
	v_mfma_f32_16x16x32_bf16 v[54:57], v[174:177], v[190:193], v[54:57]
	v_mfma_f32_16x16x32_bf16 v[50:53], v[182:185], v[190:193], v[50:53]
	v_mfma_f32_16x16x32_bf16 v[38:41], v[174:177], v[198:201], v[38:41]
	v_mfma_f32_16x16x32_bf16 v[34:37], v[182:185], v[198:201], v[34:37]
	v_mfma_f32_16x16x32_bf16 v[22:25], v[174:177], v[210:213], v[22:25]
	v_mfma_f32_16x16x32_bf16 v[18:21], v[182:185], v[210:213], v[18:21]
	v_mfma_f32_16x16x32_bf16 v[6:9], v[174:177], v[218:221], v[6:9]
	v_mfma_f32_16x16x32_bf16 v[2:5], v[182:185], v[218:221], v[2:5]
	s_setprio 0
	s_barrier
; #define PG8_STAGE(bufoff, gbase, voff) do { _Pragma("unroll") for (int _i = 0; _i < 2; ++_i) \
;         __builtin_amdgcn_global_load_lds((const unsigned*)((const char*)(gbase) + (voff)[_i]), (PG8_LAS unsigned*)(lds + (bufoff) + ldsw + _i * 8192), 16, 0, 0); } while (0)
; #define PG8_LDA(dst, b, h) do { _Pragma("unroll") for (int m = 0; m < 4; ++m) _Pragma("unroll") for (int k = 0; k < 2; ++k) dst[m][k] = *(const PG8_LAS bf16x8*)(lds + PG8_SA(b, h) + aoff + m * 2048 + k * 1024); } while (0)
; #define PG8_LDB(dst, b, h) do { _Pragma("unroll") for (int n = 0; n < 2; ++n) _Pragma("unroll") for (int k = 0; k < 2; ++k) dst[n][k] = *(const PG8_LAS bf16x8*)(lds + PG8_SB(b, h) + boff + n * 2048 + k * 1024); } while (0)
; #define PG8_MMA(ai, bj, At, Bt) do { __builtin_amdgcn_s_setprio(1); _Pragma("unroll") for (int m = 0; m < 4; ++m) _Pragma("unroll") for (int n = 0; n < 2; ++n) _Pragma("unroll") for (int k = 0; k < 2; ++k) \
;         acc[ai][bj][m][n] = __builtin_amdgcn_mfma_f32_16x16x32_bf16(Bt[n][k], At[m][k], acc[ai][bj][m][n], 0, 0, 0); __builtin_amdgcn_s_setprio(0); } while (0)
; #define PG8_WAIT_V(n) asm volatile("s_waitcnt vmcnt(" #n ")" ::: "memory")
; #define PG8_WAIT_L(n) asm volatile("s_waitcnt lgkmcnt(" #n ")" ::: "memory")
; #define PG8_BAR __builtin_amdgcn_s_barrier()
; #define PG8_SCHED __builtin_amdgcn_sched_barrier(0)
; template <class Epi, class Sched, bool ALIGN_EPI = false, bool SP2 = false>
; __device__ __forceinline__ void gemm_phase(PG8_LAS unsigned char* lds, const Gemm g, const Sched& S, const Epi& E) {
;     ...
;             PG8_LDB(B0, 1, 0); PG8_LDB(B1, 1, 1); PG8_SCHED; PG8_LDA(At, 1, 0); PG8_STAGE(PG8_SA(0, 1), a2 + hstepA, voffA);
;             PG8_WAIT_V(8); PG8_WAIT_L(0); PG8_BAR; PG8_MMA(0, 0, At, B0); PG8_MMA(0, 1, At, B1); PG8_BAR; PG8_SCHED;
	s_add_i32 s51, 0, 0x18000
	v_add_u32_e32 v153, s51, v148
	s_add_i32 s52, 0, 0x1c000
	ds_read_b128 v[154:157], v153
	ds_read_b128 v[158:161], v153 offset:1024
	ds_read_b128 v[162:165], v153 offset:2048
	ds_read_b128 v[166:169], v153 offset:3072
	v_add_u32_e32 v153, s52, v148
	ds_read_b128 v[170:173], v153
	ds_read_b128 v[174:177], v153 offset:1024
	ds_read_b128 v[178:181], v153 offset:2048
	ds_read_b128 v[182:185], v153 offset:3072
	s_add_u32 s26, s26, 0x80000
	s_addc_u32 s27, s27, 0
	s_mov_b32 m0, s36
	v_lshl_add_u64 v[226:227], s[26:27], 0, v[136:137]
	ds_read_b128 v[186:189], v152 offset:32768
	ds_read_b128 v[190:193], v152 offset:33792
	ds_read_b128 v[194:197], v152 offset:34816
	ds_read_b128 v[198:201], v152 offset:35840
	ds_read_b128 v[202:205], v152 offset:36864
	ds_read_b128 v[210:213], v152 offset:37888
	ds_read_b128 v[214:217], v152 offset:38912
	ds_read_b128 v[218:221], v152 offset:39936
	global_load_lds_dwordx4 v[226:227], off
	v_lshl_add_u64 v[226:227], s[26:27], 0, v[132:133]
	s_mov_b32 m0, s37
	s_nop 0
	global_load_lds_dwordx4 v[226:227], off
	s_waitcnt vmcnt(8)
	s_waitcnt lgkmcnt(0)
	s_barrier
	s_setprio 1
	s_waitcnt lgkmcnt(0)
	v_mfma_f32_16x16x32_bf16 v[126:129], v[154:157], v[186:189], v[126:129]
	v_mfma_f32_16x16x32_bf16 v[122:125], v[162:165], v[186:189], v[122:125]
	v_mfma_f32_16x16x32_bf16 v[110:113], v[154:157], v[194:197], v[110:113]
	v_mfma_f32_16x16x32_bf16 v[106:109], v[162:165], v[194:197], v[106:109]
	v_mfma_f32_16x16x32_bf16 v[94:97], v[154:157], v[202:205], v[94:97]
	v_mfma_f32_16x16x32_bf16 v[90:93], v[162:165], v[202:205], v[90:93]
	v_mfma_f32_16x16x32_bf16 v[78:81], v[154:157], v[214:217], v[78:81]
	v_mfma_f32_16x16x32_bf16 v[74:77], v[162:165], v[214:217], v[74:77]
	v_mfma_f32_16x16x32_bf16 v[126:129], v[158:161], v[190:193], v[126:129]
	v_mfma_f32_16x16x32_bf16 v[122:125], v[166:169], v[190:193], v[122:125]
	v_mfma_f32_16x16x32_bf16 v[110:113], v[158:161], v[198:201], v[110:113]
	v_mfma_f32_16x16x32_bf16 v[106:109], v[166:169], v[198:201], v[106:109]
	v_mfma_f32_16x16x32_bf16 v[94:97], v[158:161], v[210:213], v[94:97]
	v_mfma_f32_16x16x32_bf16 v[90:93], v[166:169], v[210:213], v[90:93]
	v_mfma_f32_16x16x32_bf16 v[78:81], v[158:161], v[218:221], v[78:81]
	v_mfma_f32_16x16x32_bf16 v[74:77], v[166:169], v[218:221], v[74:77]
	s_setprio 0
	s_setprio 1
	v_mfma_f32_16x16x32_bf16 v[118:121], v[170:173], v[186:189], v[118:121]
	v_mfma_f32_16x16x32_bf16 v[114:117], v[178:181], v[186:189], v[114:117]
	v_mfma_f32_16x16x32_bf16 v[102:105], v[170:173], v[194:197], v[102:105]
	v_mfma_f32_16x16x32_bf16 v[98:101], v[178:181], v[194:197], v[98:101]
	v_mfma_f32_16x16x32_bf16 v[86:89], v[170:173], v[202:205], v[86:89]
	v_mfma_f32_16x16x32_bf16 v[82:85], v[178:181], v[202:205], v[82:85]
	v_mfma_f32_16x16x32_bf16 v[70:73], v[170:173], v[214:217], v[70:73]
	v_mfma_f32_16x16x32_bf16 v[66:69], v[178:181], v[214:217], v[66:69]
	v_mfma_f32_16x16x32_bf16 v[118:121], v[174:177], v[190:193], v[118:121]
	v_mfma_f32_16x16x32_bf16 v[114:117], v[182:185], v[190:193], v[114:117]
	v_mfma_f32_16x16x32_bf16 v[102:105], v[174:177], v[198:201], v[102:105]
	v_mfma_f32_16x16x32_bf16 v[98:101], v[182:185], v[198:201], v[98:101]
	v_mfma_f32_16x16x32_bf16 v[86:89], v[174:177], v[210:213], v[86:89]
	v_mfma_f32_16x16x32_bf16 v[82:85], v[182:185], v[210:213], v[82:85]
	v_mfma_f32_16x16x32_bf16 v[70:73], v[174:177], v[218:221], v[70:73]
	v_mfma_f32_16x16x32_bf16 v[66:69], v[182:185], v[218:221], v[66:69]
	s_setprio 0
	s_barrier
; #define PG8_STAGE(bufoff, gbase, voff) do { _Pragma("unroll") for (int _i = 0; _i < 2; ++_i) \
;         __builtin_amdgcn_global_load_lds((const unsigned*)((const char*)(gbase) + (voff)[_i]), (PG8_LAS unsigned*)(lds + (bufoff) + ldsw + _i * 8192), 16, 0, 0); } while (0)
; #define PG8_LDA(dst, b, h) do { _Pragma("unroll") for (int m = 0; m < 4; ++m) _Pragma("unroll") for (int k = 0; k < 2; ++k) dst[m][k] = *(const PG8_LAS bf16x8*)(lds + PG8_SA(b, h) + aoff + m * 2048 + k * 1024); } while (0)
; #define PG8_MMA(ai, bj, At, Bt) do { __builtin_amdgcn_s_setprio(1); _Pragma("unroll") for (int m = 0; m < 4; ++m) _Pragma("unroll") for (int n = 0; n < 2; ++n) _Pragma("unroll") for (int k = 0; k < 2; ++k) \
;         acc[ai][bj][m][n] = __builtin_amdgcn_mfma_f32_16x16x32_bf16(Bt[n][k], At[m][k], acc[ai][bj][m][n], 0, 0, 0); __builtin_amdgcn_s_setprio(0); } while (0)
; #define PG8_WAIT_V(n) asm volatile("s_waitcnt vmcnt(" #n ")" ::: "memory")
; #define PG8_WAIT_L(n) asm volatile("s_waitcnt lgkmcnt(" #n ")" ::: "memory")
; #define PG8_BAR __builtin_amdgcn_s_barrier()
; #define PG8_SCHED __builtin_amdgcn_sched_barrier(0)
; template <class Epi, class Sched, bool ALIGN_EPI = false, bool SP2 = false>
; __device__ __forceinline__ void gemm_phase(PG8_LAS unsigned char* lds, const Gemm g, const Sched& S, const Epi& E) {
;     ...
;         for (int t = 0; t < nt; t += 2) {
;             const bool last = (t == nt - 2);
;             const char* a1 = cA + (size_t)(t + 1) * kstep;
;             const char* a2 = last ? nA : cA + (size_t)(t + 2) * kstep; const char* b2 = last ? nB : cB + (size_t)(t + 2) * kstep;
;     ...
;             PG8_LDA(At, 1, 1); PG8_STAGE(PG8_SB(1, 0), b3, voffB); PG8_STAGE(PG8_SB(1, 1), b3 + hstepB, voffB); PG8_STAGE(PG8_SA(1, 0), a3, voffA);
;             PG8_WAIT_V(8); PG8_WAIT_L(0); PG8_BAR; PG8_MMA(1, 0, At, B0); PG8_MMA(1, 1, At, B1); PG8_BAR; PG8_SCHED;
	s_add_i32 s26, s51, s31
	v_lshl_add_u64 v[146:147], v[146:147], 0, s[2:3]
	s_mov_b32 m0, s26
	ds_read_b128 v[186:189], v152 offset:49152
	ds_read_b128 v[190:193], v152 offset:50176
	ds_read_b128 v[194:197], v152 offset:51200
	ds_read_b128 v[198:201], v152 offset:52224
	ds_read_b128 v[202:205], v152 offset:53248
	ds_read_b128 v[210:213], v152 offset:54272
	ds_read_b128 v[214:217], v152 offset:55296
	ds_read_b128 v[218:221], v152 offset:56320
	global_load_lds_dwordx4 v[146:147], off
	s_add_i32 m0, s26, 0x2000
	s_add_u32 s24, s24, 0x80080
	v_lshl_add_u64 v[146:147], v[206:207], 0, s[2:3]
	s_addc_u32 s25, s25, 0
	s_add_i32 s26, s52, s31
	global_load_lds_dwordx4 v[146:147], off
	v_lshl_add_u64 v[146:147], s[24:25], 0, v[134:135]
	s_mov_b32 m0, s26
	s_nop 0
	global_load_lds_dwordx4 v[146:147], off
	v_lshl_add_u64 v[146:147], s[24:25], 0, v[130:131]
	s_add_i32 m0, s26, 0x2000
	s_nop 0
	global_load_lds_dwordx4 v[146:147], off
	v_lshl_add_u64 v[146:147], v[222:223], 0, s[2:3]
	s_mov_b32 m0, s39
	s_nop 0
	global_load_lds_dwordx4 v[146:147], off
	v_lshl_add_u64 v[146:147], v[224:225], 0, s[2:3]
	s_mov_b32 m0, s40
	s_nop 0
	global_load_lds_dwordx4 v[146:147], off
	s_waitcnt vmcnt(8)
	s_waitcnt lgkmcnt(0)
	s_barrier
	s_setprio 1
	s_waitcnt lgkmcnt(0)
	v_mfma_f32_16x16x32_bf16 v[62:65], v[154:157], v[186:189], v[62:65]
	v_mfma_f32_16x16x32_bf16 v[58:61], v[162:165], v[186:189], v[58:61]
	v_mfma_f32_16x16x32_bf16 v[46:49], v[154:157], v[194:197], v[46:49]
	v_mfma_f32_16x16x32_bf16 v[42:45], v[162:165], v[194:197], v[42:45]
	v_mfma_f32_16x16x32_bf16 v[30:33], v[154:157], v[202:205], v[30:33]
	v_mfma_f32_16x16x32_bf16 v[26:29], v[162:165], v[202:205], v[26:29]
	v_mfma_f32_16x16x32_bf16 v[14:17], v[154:157], v[214:217], v[14:17]
	v_mfma_f32_16x16x32_bf16 v[10:13], v[162:165], v[214:217], v[10:13]
	v_mfma_f32_16x16x32_bf16 v[62:65], v[158:161], v[190:193], v[62:65]
	v_mfma_f32_16x16x32_bf16 v[58:61], v[166:169], v[190:193], v[58:61]
	v_mfma_f32_16x16x32_bf16 v[46:49], v[158:161], v[198:201], v[46:49]
	v_mfma_f32_16x16x32_bf16 v[42:45], v[166:169], v[198:201], v[42:45]
	v_mfma_f32_16x16x32_bf16 v[30:33], v[158:161], v[210:213], v[30:33]
	v_mfma_f32_16x16x32_bf16 v[26:29], v[166:169], v[210:213], v[26:29]
	v_mfma_f32_16x16x32_bf16 v[14:17], v[158:161], v[218:221], v[14:17]
	v_mfma_f32_16x16x32_bf16 v[10:13], v[166:169], v[218:221], v[10:13]
	s_setprio 0
	s_setprio 1
	v_mfma_f32_16x16x32_bf16 v[54:57], v[170:173], v[186:189], v[54:57]
	v_mfma_f32_16x16x32_bf16 v[50:53], v[178:181], v[186:189], v[50:53]
	v_mfma_f32_16x16x32_bf16 v[38:41], v[170:173], v[194:197], v[38:41]
	v_mfma_f32_16x16x32_bf16 v[34:37], v[178:181], v[194:197], v[34:37]
	v_mfma_f32_16x16x32_bf16 v[22:25], v[170:173], v[202:205], v[22:25]
	v_mfma_f32_16x16x32_bf16 v[18:21], v[178:181], v[202:205], v[18:21]
	v_mfma_f32_16x16x32_bf16 v[6:9], v[170:173], v[214:217], v[6:9]
	v_mfma_f32_16x16x32_bf16 v[2:5], v[178:181], v[214:217], v[2:5]
	v_mfma_f32_16x16x32_bf16 v[54:57], v[174:177], v[190:193], v[54:57]
	v_mfma_f32_16x16x32_bf16 v[50:53], v[182:185], v[190:193], v[50:53]
	v_mfma_f32_16x16x32_bf16 v[38:41], v[174:177], v[198:201], v[38:41]
	v_mfma_f32_16x16x32_bf16 v[34:37], v[182:185], v[198:201], v[34:37]
	v_mfma_f32_16x16x32_bf16 v[22:25], v[174:177], v[210:213], v[22:25]
	v_mfma_f32_16x16x32_bf16 v[18:21], v[182:185], v[210:213], v[18:21]
	v_mfma_f32_16x16x32_bf16 v[6:9], v[174:177], v[218:221], v[6:9]
	v_mfma_f32_16x16x32_bf16 v[2:5], v[182:185], v[218:221], v[2:5]
	s_setprio 0
	s_barrier
	s_add_i32 s50, s50, 2
	s_add_u32 s22, s22, 0x100
	s_addc_u32 s23, s23, 0
	s_add_u32 s48, s48, 0x100
	s_addc_u32 s49, s49, 0
	s_cmp_gt_u32 s50, 29
	s_cbranch_scc1 .Lpeel_exit_16
	.p2align 6

; #define PG8_STAGE(bufoff, gbase, voff) do { _Pragma("unroll") for (int _i = 0; _i < 2; ++_i) \
;         __builtin_amdgcn_global_load_lds((const unsigned*)((const char*)(gbase) + (voff)[_i]), (PG8_LAS unsigned*)(lds + (bufoff) + ldsw + _i * 8192), 16, 0, 0); } while (0)
; #define PG8_WAIT_V(n) asm volatile("s_waitcnt vmcnt(" #n ")" ::: "memory")
; #define PG8_BAR __builtin_amdgcn_s_barrier()
; template <class Epi, class Sched, bool ALIGN_EPI = false, bool SP2 = false>
; __device__ __forceinline__ void gemm_phase(PG8_LAS unsigned char* lds, const Gemm g, const Sched& S, const Epi& E) {
;     const int tid = threadIdx.x, wid = __builtin_amdgcn_readfirstlane(tid >> 6), lane = tid & 63, wr = wid >> 2, wc = wid & 3, fr = lane & 15, fq = lane >> 4;
;     const int K = g.K, nt = K / BK;
;     unsigned voffA[2], voffB[2];
; #pragma unroll
;     for (int i = 0; i < 2; ++i) { int R, C; stage_rc(tid * 16 + i * 8192, R, C); const int Rb = Epi::PERM ? ((R & ~31) + perm32(R & 31)) : R;
;         voffA[i] = (unsigned)(R * g.lda + C) * 2u; voffB[i] = (unsigned)(Rb * g.ldb + C) * 2u; }
;     const size_t kstep = (size_t)(BK * 2);
;     const size_t hstepA = (size_t)HALF * g.lda * 2, hstepB = (size_t)HALF * g.ldb * 2;
;     const size_t tstepA = 2 * hstepA, tstepB = 2 * hstepB;
;     const unsigned ldsw = (unsigned)wid * 1024u;
;     const int aoff = lds_byte(wr * 64 + fr, fq * 8), boff = lds_byte(wc * 32 + fr, fq * 8);
;     ...
;         PG8_WAIT_V(2); PG8_BAR;
;         PG8_STAGE(PG8_SB(1, 0), cB + kstep, voffB); PG8_STAGE(PG8_SA(1, 0), cA + kstep, voffA); PG8_STAGE(PG8_SB(1, 1), cB + hstepB + kstep, voffB);
;         PG8_WAIT_V(6); PG8_BAR;
.LBB0_1698:
	s_lshl_b32 s6, s6, 5
	s_mov_b64 s[8:9], 0x80
	s_and_b32 s6, s6, 0x60
	s_add_i32 m0, s37, 0x18000
	v_lshl_add_u64 v[8:9], v[8:9], 0, s[8:9]
	s_lshl_b32 s12, s5, 13
	s_lshl_b32 s13, s6, 7
	s_waitcnt vmcnt(2)
	s_barrier
	global_load_lds_dwordx4 v[8:9], off
	v_lshl_add_u64 v[6:7], v[6:7], 0, s[8:9]
	s_add_i32 m0, s37, 0x1a000
	s_add_i32 s42, s37, 0x8000
	s_add_i32 s43, s37, 0xa000
	global_load_lds_dwordx4 v[6:7], off
	v_lshl_add_u64 v[2:3], v[2:3], 0, s[8:9]
	s_mov_b32 m0, s42
	s_add_u32 s10, s26, 0x160080
	global_load_lds_dwordx4 v[2:3], off
	v_lshl_add_u64 v[2:3], v[4:5], 0, s[8:9]
	s_mov_b32 m0, s43
	s_addc_u32 s11, s27, 0
	global_load_lds_dwordx4 v[2:3], off
	s_add_i32 m0, s37, 0x1c000
	v_lshl_add_u64 v[2:3], s[10:11], 0, v[134:135]
	global_load_lds_dwordx4 v[2:3], off
	v_lshl_add_u64 v[2:3], s[10:11], 0, v[130:131]
	s_add_i32 m0, s37, 0x1e000
	v_lshlrev_b32_e32 v4, 2, v0
	global_load_lds_dwordx4 v[2:3], off
	v_and_b32_e32 v2, 15, v0
	v_lshl_or_b32 v1, s5, 6, v2
	v_lshlrev_b32_e32 v3, 1, v10
	v_lshlrev_b32_e32 v5, 6, v0
	s_movk_i32 s5, 0x3c0
	v_lshl_or_b32 v2, v2, 6, v3
	v_and_b32_e32 v4, 32, v4
	v_and_or_b32 v3, v5, s5, v3
	v_bitop3_b32 v146, s13, v3, v4 bitop3:0xf6
	s_waitcnt vmcnt(0)
	s_cmpk_lt_u32 s4, 0x100
	v_add_u16_e32 v3, v11, v12
	v_bitop3_b32 v2, v2, s12, v4 bitop3:0xde
	s_cselect_b64 s[10:11], -1, 0
	v_lshrrev_b16_e32 v3, 1, v3
	s_add_i32 s45, 0, 0x10000
	s_add_i32 s46, 0, 0x14000
	s_sext_i32_i8 s54, s7
	s_ashr_i32 s44, s30, 31
	v_or_b32_e32 v147, s6, v10
	v_add_lshl_u32 v138, v14, v3, 1
	v_mov_b32_e32 v139, v135
	v_add_lshl_u32 v140, v13, v3, 1
	v_mov_b32_e32 v141, v135
	v_mov_b64_e32 v[142:143], 0x500
	v_mov_b64_e32 v[144:145], 0x4ff
	v_add_u32_e32 v148, s45, v146
	v_add_u32_e32 v149, s46, v146
	v_add_u32_e32 v150, 0, v2
	s_mov_b64 s[12:13], 0x80000
	s_mov_b32 s47, 0x80000
	s_mov_b64 s[14:15], 0x90000
	s_mov_b32 s48, 0x90000
	s_mov_b64 s[16:17], 0xa0000
	s_mov_b32 s49, 0xa0000
	s_mov_b64 s[20:21], 0xb0000
	s_mov_b32 s50, 0xb0000
	s_barrier
	s_branch .LBB0_1701

; #define PG8_STAGE(bufoff, gbase, voff) do { _Pragma("unroll") for (int _i = 0; _i < 2; ++_i) \
;         __builtin_amdgcn_global_load_lds((const unsigned*)((const char*)(gbase) + (voff)[_i]), (PG8_LAS unsigned*)(lds + (bufoff) + ldsw + _i * 8192), 16, 0, 0); } while (0)
; #define PG8_LDA(dst, b, h) do { _Pragma("unroll") for (int m = 0; m < 4; ++m) _Pragma("unroll") for (int k = 0; k < 2; ++k) dst[m][k] = *(const PG8_LAS bf16x8*)(lds + PG8_SA(b, h) + aoff + m * 2048 + k * 1024); } while (0)
; #define PG8_LDB(dst, b, h) do { _Pragma("unroll") for (int n = 0; n < 2; ++n) _Pragma("unroll") for (int k = 0; k < 2; ++k) dst[n][k] = *(const PG8_LAS bf16x8*)(lds + PG8_SB(b, h) + boff + n * 2048 + k * 1024); } while (0)
; #define PG8_WAIT_V(n) asm volatile("s_waitcnt vmcnt(" #n ")" ::: "memory")
; #define PG8_WAIT_L(n) asm volatile("s_waitcnt lgkmcnt(" #n ")" ::: "memory")
; template <class Epi, class Sched, bool ALIGN_EPI = false, bool SP2 = false>
; __device__ __forceinline__ void gemm_phase(PG8_LAS unsigned char* lds, const Gemm g, const Sched& S, const Epi& E) {
;     ...
;         const char* nA = has_next ? (const char*)g.A + (size_t)nxt.pm * tstepA : cA; const char* nB = has_next ? (const char*)g.Bt + (size_t)nxt.pn * tstepB : cB;
;         for (int t = 0; t < nt; t += 2) {
;             const bool last = (t == nt - 2);
;             const char* a1 = cA + (size_t)(t + 1) * kstep;
;             const char* a2 = last ? nA : cA + (size_t)(t + 2) * kstep; const char* b2 = last ? nB : cB + (size_t)(t + 2) * kstep;
;             const char* a3 = a2 + kstep; const char* b3 = b2 + kstep;
;             if (last && has_next) S.a_ready(nxt);
;             if constexpr (SP2) {
;             PG8_LDB(B0, 0, 0); PG8_LDB(B1, 0, 1); PG8_SCHED; PG8_LDA(At, 0, 0); PG8_STAGE(PG8_SA(1, 1), a1 + hstepA, voffA);
;             PG8_WAIT_V(8); PG8_WAIT_L(0); PG8_BAR; PG8_MMA(0, 0, At, B0); PG8_MMA(0, 1, At, B1); PG8_BAR; PG8_SCHED;
;             PG8_LDA(At, 0, 1); PG8_STAGE(PG8_SB(0, 0), b2, voffB); PG8_STAGE(PG8_SB(0, 1), b2 + hstepB, voffB); PG8_STAGE(PG8_SA(0, 0), a2, voffA);
;     ...
; #pragma unroll
;         for (int a = 0; a < 2; ++a)
; #pragma unroll
;             for (int b = 0; b < 2; ++b)
; #pragma unroll
;                 for (int m = 0; m < 4; ++m)
; #pragma unroll
;                     for (int n = 0; n < 2; ++n) acc[a][b][m][n] = (f32x4){0.f, 0.f, 0.f, 0.f};
.LBB0_1707:
	s_add_u32 s24, s24, 0x160080
	s_addc_u32 s25, s25, 0
	s_add_u32 s55, s26, 0x100
	v_mov_b32_e32 v2, 0
	s_addc_u32 s56, s27, 0
	s_mov_b32 s57, -2
	v_mov_b32_e32 v3, v2
	v_mov_b32_e32 v4, v2
	v_mov_b32_e32 v5, v2
	v_mov_b32_e32 v6, v2
	v_mov_b32_e32 v7, v2
	v_mov_b32_e32 v8, v2
	v_mov_b32_e32 v9, v2
	v_mov_b32_e32 v10, v2
	v_mov_b32_e32 v11, v2
	v_mov_b32_e32 v12, v2
	v_mov_b32_e32 v13, v2
	v_mov_b32_e32 v14, v2
	v_mov_b32_e32 v15, v2
	v_mov_b32_e32 v16, v2
	v_mov_b32_e32 v17, v2
	v_mov_b32_e32 v26, v2
	v_mov_b32_e32 v27, v2
	v_mov_b32_e32 v28, v2
	v_mov_b32_e32 v29, v2
	v_mov_b32_e32 v30, v2
	v_mov_b32_e32 v31, v2
	v_mov_b32_e32 v32, v2
	v_mov_b32_e32 v33, v2
	v_mov_b32_e32 v42, v2
	v_mov_b32_e32 v43, v2
	v_mov_b32_e32 v44, v2
	v_mov_b32_e32 v45, v2
	v_mov_b32_e32 v46, v2
	v_mov_b32_e32 v47, v2
	v_mov_b32_e32 v48, v2
	v_mov_b32_e32 v49, v2
	v_mov_b32_e32 v18, v2
	v_mov_b32_e32 v19, v2
	v_mov_b32_e32 v20, v2
	v_mov_b32_e32 v21, v2
	v_mov_b32_e32 v22, v2
	v_mov_b32_e32 v23, v2
	v_mov_b32_e32 v24, v2
	v_mov_b32_e32 v25, v2
	v_mov_b32_e32 v34, v2
	v_mov_b32_e32 v35, v2
	v_mov_b32_e32 v36, v2
	v_mov_b32_e32 v37, v2
	v_mov_b32_e32 v38, v2
	v_mov_b32_e32 v39, v2
	v_mov_b32_e32 v40, v2
	v_mov_b32_e32 v41, v2
	v_mov_b32_e32 v50, v2
	v_mov_b32_e32 v51, v2
	v_mov_b32_e32 v52, v2
	v_mov_b32_e32 v53, v2
	v_mov_b32_e32 v54, v2
	v_mov_b32_e32 v55, v2
	v_mov_b32_e32 v56, v2
	v_mov_b32_e32 v57, v2
	v_mov_b32_e32 v58, v2
	v_mov_b32_e32 v59, v2
	v_mov_b32_e32 v60, v2
	v_mov_b32_e32 v61, v2
	v_mov_b32_e32 v62, v2
	v_mov_b32_e32 v63, v2
	v_mov_b32_e32 v64, v2
	v_mov_b32_e32 v65, v2
	v_mov_b32_e32 v66, v2
	v_mov_b32_e32 v67, v2
	v_mov_b32_e32 v68, v2
	v_mov_b32_e32 v69, v2
	v_mov_b32_e32 v70, v2
	v_mov_b32_e32 v71, v2
	v_mov_b32_e32 v72, v2
	v_mov_b32_e32 v73, v2
	v_mov_b32_e32 v74, v2
	v_mov_b32_e32 v75, v2
	v_mov_b32_e32 v76, v2
	v_mov_b32_e32 v77, v2
	v_mov_b32_e32 v78, v2
	v_mov_b32_e32 v79, v2
	v_mov_b32_e32 v80, v2
	v_mov_b32_e32 v81, v2
	v_mov_b32_e32 v90, v2
	v_mov_b32_e32 v91, v2
	v_mov_b32_e32 v92, v2
	v_mov_b32_e32 v93, v2
	v_mov_b32_e32 v94, v2
	v_mov_b32_e32 v95, v2
	v_mov_b32_e32 v96, v2
	v_mov_b32_e32 v97, v2
	v_mov_b32_e32 v106, v2
	v_mov_b32_e32 v107, v2
	v_mov_b32_e32 v108, v2
	v_mov_b32_e32 v109, v2
	v_mov_b32_e32 v110, v2
	v_mov_b32_e32 v111, v2
	v_mov_b32_e32 v112, v2
	v_mov_b32_e32 v113, v2
	v_mov_b32_e32 v82, v2
	v_mov_b32_e32 v83, v2
	v_mov_b32_e32 v84, v2
	v_mov_b32_e32 v85, v2
	v_mov_b32_e32 v86, v2
	v_mov_b32_e32 v87, v2
	v_mov_b32_e32 v88, v2
	v_mov_b32_e32 v89, v2
	v_mov_b32_e32 v98, v2
	v_mov_b32_e32 v99, v2
	v_mov_b32_e32 v100, v2
	v_mov_b32_e32 v101, v2
	v_mov_b32_e32 v102, v2
	v_mov_b32_e32 v103, v2
	v_mov_b32_e32 v104, v2
	v_mov_b32_e32 v105, v2
	v_mov_b32_e32 v114, v2
	v_mov_b32_e32 v115, v2
	v_mov_b32_e32 v116, v2
	v_mov_b32_e32 v117, v2
	v_mov_b32_e32 v118, v2
	v_mov_b32_e32 v119, v2
	v_mov_b32_e32 v120, v2
	v_mov_b32_e32 v121, v2
	v_mov_b32_e32 v122, v2
	v_mov_b32_e32 v123, v2
	v_mov_b32_e32 v124, v2
	v_mov_b32_e32 v125, v2
	v_mov_b32_e32 v126, v2
	v_mov_b32_e32 v127, v2
	v_mov_b32_e32 v128, v2
	v_mov_b32_e32 v129, v2
	ds_read_b128 v[152:155], v148
	ds_read_b128 v[156:159], v148 offset:1024
	ds_read_b128 v[160:163], v148 offset:2048
	ds_read_b128 v[164:167], v148 offset:3072
	ds_read_b128 v[168:171], v149
	ds_read_b128 v[172:175], v149 offset:1024
	ds_read_b128 v[176:179], v149 offset:2048
	ds_read_b128 v[180:183], v149 offset:3072
	s_add_u32 s26, s24, 0xffea0080
	s_addc_u32 s27, s25, -1
	s_cmpk_eq_i32 s57, 0x54
	s_cselect_b32 s29, s7, s27
	s_cselect_b32 s28, s6, s26
	s_cselect_b32 s27, s23, s56
	s_cselect_b32 s26, s22, s55
	v_lshl_add_u64 v[218:219], s[24:25], 0, v[138:139]
	s_add_i32 m0, s37, 0xc000
	ds_read_b128 v[184:187], v150
	ds_read_b128 v[188:191], v150 offset:1024
	ds_read_b128 v[192:195], v150 offset:2048
	ds_read_b128 v[196:199], v150 offset:3072
	ds_read_b128 v[200:203], v150 offset:4096
	ds_read_b128 v[204:207], v150 offset:5120
	ds_read_b128 v[210:213], v150 offset:6144
	ds_read_b128 v[214:217], v150 offset:7168
	global_load_lds_dwordx4 v[218:219], off
	v_lshl_add_u64 v[218:219], s[24:25], 0, v[140:141]
	s_add_i32 m0, s37, 0xe000
	s_nop 0
	global_load_lds_dwordx4 v[218:219], off
	s_waitcnt vmcnt(24)
	s_waitcnt lgkmcnt(0)
	s_barrier
	s_setprio 1
	s_waitcnt lgkmcnt(0)
	v_mfma_f32_16x16x32_bf16 v[126:129], v[152:155], v[184:187], v[126:129]
	v_mfma_f32_16x16x32_bf16 v[122:125], v[160:163], v[184:187], v[122:125]
	v_mfma_f32_16x16x32_bf16 v[118:121], v[152:155], v[192:195], v[118:121]
	v_mfma_f32_16x16x32_bf16 v[114:117], v[160:163], v[192:195], v[114:117]
	v_mfma_f32_16x16x32_bf16 v[102:105], v[152:155], v[200:203], v[102:105]
	v_mfma_f32_16x16x32_bf16 v[98:101], v[160:163], v[200:203], v[98:101]
	v_mfma_f32_16x16x32_bf16 v[86:89], v[152:155], v[210:213], v[86:89]
	v_mfma_f32_16x16x32_bf16 v[82:85], v[160:163], v[210:213], v[82:85]
	v_mfma_f32_16x16x32_bf16 v[126:129], v[156:159], v[188:191], v[126:129]
	v_mfma_f32_16x16x32_bf16 v[122:125], v[164:167], v[188:191], v[122:125]
	v_mfma_f32_16x16x32_bf16 v[118:121], v[156:159], v[196:199], v[118:121]
	v_mfma_f32_16x16x32_bf16 v[114:117], v[164:167], v[196:199], v[114:117]
	v_mfma_f32_16x16x32_bf16 v[102:105], v[156:159], v[204:207], v[102:105]
	v_mfma_f32_16x16x32_bf16 v[98:101], v[164:167], v[204:207], v[98:101]
	v_mfma_f32_16x16x32_bf16 v[86:89], v[156:159], v[214:217], v[86:89]
	v_mfma_f32_16x16x32_bf16 v[82:85], v[164:167], v[214:217], v[82:85]
	s_setprio 0
	s_setprio 1
	v_mfma_f32_16x16x32_bf16 v[110:113], v[168:171], v[184:187], v[110:113]
	v_mfma_f32_16x16x32_bf16 v[106:109], v[176:179], v[184:187], v[106:109]
	v_mfma_f32_16x16x32_bf16 v[94:97], v[168:171], v[192:195], v[94:97]
	v_mfma_f32_16x16x32_bf16 v[90:93], v[176:179], v[192:195], v[90:93]
	v_mfma_f32_16x16x32_bf16 v[78:81], v[168:171], v[200:203], v[78:81]
	v_mfma_f32_16x16x32_bf16 v[74:77], v[176:179], v[200:203], v[74:77]
	v_mfma_f32_16x16x32_bf16 v[70:73], v[168:171], v[210:213], v[70:73]
	v_mfma_f32_16x16x32_bf16 v[66:69], v[176:179], v[210:213], v[66:69]
	v_mfma_f32_16x16x32_bf16 v[110:113], v[172:175], v[188:191], v[110:113]
	v_mfma_f32_16x16x32_bf16 v[106:109], v[180:183], v[188:191], v[106:109]
	v_mfma_f32_16x16x32_bf16 v[94:97], v[172:175], v[196:199], v[94:97]
	v_mfma_f32_16x16x32_bf16 v[90:93], v[180:183], v[196:199], v[90:93]
	v_mfma_f32_16x16x32_bf16 v[78:81], v[172:175], v[204:207], v[78:81]
	v_mfma_f32_16x16x32_bf16 v[74:77], v[180:183], v[204:207], v[74:77]
	v_mfma_f32_16x16x32_bf16 v[70:73], v[172:175], v[214:217], v[70:73]
	v_mfma_f32_16x16x32_bf16 v[66:69], v[180:183], v[214:217], v[66:69]
	s_setprio 0
	s_barrier
; #define PG8_STAGE(bufoff, gbase, voff) do { _Pragma("unroll") for (int _i = 0; _i < 2; ++_i) \
;         __builtin_amdgcn_global_load_lds((const unsigned*)((const char*)(gbase) + (voff)[_i]), (PG8_LAS unsigned*)(lds + (bufoff) + ldsw + _i * 8192), 16, 0, 0); } while (0)
; #define PG8_LDA(dst, b, h) do { _Pragma("unroll") for (int m = 0; m < 4; ++m) _Pragma("unroll") for (int k = 0; k < 2; ++k) dst[m][k] = *(const PG8_LAS bf16x8*)(lds + PG8_SA(b, h) + aoff + m * 2048 + k * 1024); } while (0)
; #define PG8_LDB(dst, b, h) do { _Pragma("unroll") for (int n = 0; n < 2; ++n) _Pragma("unroll") for (int k = 0; k < 2; ++k) dst[n][k] = *(const PG8_LAS bf16x8*)(lds + PG8_SB(b, h) + boff + n * 2048 + k * 1024); } while (0)
; #define PG8_MMA(ai, bj, At, Bt) do { __builtin_amdgcn_s_setprio(1); _Pragma("unroll") for (int m = 0; m < 4; ++m) _Pragma("unroll") for (int n = 0; n < 2; ++n) _Pragma("unroll") for (int k = 0; k < 2; ++k) \
;         acc[ai][bj][m][n] = __builtin_amdgcn_mfma_f32_16x16x32_bf16(Bt[n][k], At[m][k], acc[ai][bj][m][n], 0, 0, 0); __builtin_amdgcn_s_setprio(0); } while (0)
; #define PG8_WAIT_V(n) asm volatile("s_waitcnt vmcnt(" #n ")" ::: "memory")
; #define PG8_WAIT_L(n) asm volatile("s_waitcnt lgkmcnt(" #n ")" ::: "memory")
; #define PG8_BAR __builtin_amdgcn_s_barrier()
; #define PG8_SCHED __builtin_amdgcn_sched_barrier(0)
; template <class Epi, class Sched, bool ALIGN_EPI = false, bool SP2 = false>
; __device__ __forceinline__ void gemm_phase(PG8_LAS unsigned char* lds, const Gemm g, const Sched& S, const Epi& E) {
;     ...
;             PG8_LDA(At, 0, 1); PG8_STAGE(PG8_SB(0, 0), b2, voffB); PG8_STAGE(PG8_SB(0, 1), b2 + hstepB, voffB); PG8_STAGE(PG8_SA(0, 0), a2, voffA);
;             PG8_WAIT_V(8); PG8_WAIT_L(0); PG8_BAR; PG8_MMA(1, 0, At, B0); PG8_MMA(1, 1, At, B1); PG8_BAR; PG8_SCHED;
;             PG8_LDB(B0, 1, 0); PG8_LDB(B1, 1, 1); PG8_SCHED; PG8_LDA(At, 1, 0); PG8_STAGE(PG8_SA(0, 1), a2 + hstepA, voffA);
;             PG8_WAIT_V(8); PG8_WAIT_L(0); PG8_BAR; PG8_MMA(0, 0, At, B0); PG8_MMA(0, 1, At, B1); PG8_BAR; PG8_SCHED;
	s_add_i32 s58, s45, s34
	v_lshl_add_u64 v[218:219], s[26:27], 0, v[134:135]
	s_mov_b32 m0, s58
	ds_read_b128 v[184:187], v150 offset:16384
	ds_read_b128 v[188:191], v150 offset:17408
	ds_read_b128 v[192:195], v150 offset:18432
	ds_read_b128 v[196:199], v150 offset:19456
	ds_read_b128 v[200:203], v150 offset:20480
	ds_read_b128 v[204:207], v150 offset:21504
	ds_read_b128 v[210:213], v150 offset:22528
	ds_read_b128 v[214:217], v150 offset:23552
	global_load_lds_dwordx4 v[218:219], off
	s_add_i32 m0, s58, 0x2000
	s_add_u32 s58, s26, 0x160000
	v_lshl_add_u64 v[220:221], s[26:27], 0, v[130:131]
	s_addc_u32 s59, s27, 0
	s_add_i32 s60, s46, s34
	global_load_lds_dwordx4 v[220:221], off
	v_lshl_add_u64 v[222:223], s[58:59], 0, v[134:135]
	s_mov_b32 m0, s60
	v_lshl_add_u64 v[224:225], s[28:29], 0, v[132:133]
	global_load_lds_dwordx4 v[222:223], off
	v_lshl_add_u64 v[222:223], s[58:59], 0, v[130:131]
	s_add_i32 m0, s60, 0x2000
	s_nop 0
	global_load_lds_dwordx4 v[222:223], off
	v_lshl_add_u64 v[222:223], s[28:29], 0, v[136:137]
	s_mov_b32 m0, s37
	s_nop 0
	global_load_lds_dwordx4 v[222:223], off
	s_mov_b32 m0, s38
	s_nop 0
	global_load_lds_dwordx4 v[224:225], off
	s_waitcnt vmcnt(24)
	s_waitcnt lgkmcnt(0)
	s_barrier
	s_setprio 1
	s_waitcnt lgkmcnt(0)
	v_mfma_f32_16x16x32_bf16 v[62:65], v[152:155], v[184:187], v[62:65]
	v_mfma_f32_16x16x32_bf16 v[58:61], v[160:163], v[184:187], v[58:61]
	v_mfma_f32_16x16x32_bf16 v[54:57], v[152:155], v[192:195], v[54:57]
	v_mfma_f32_16x16x32_bf16 v[50:53], v[160:163], v[192:195], v[50:53]
	v_mfma_f32_16x16x32_bf16 v[38:41], v[152:155], v[200:203], v[38:41]
	v_mfma_f32_16x16x32_bf16 v[34:37], v[160:163], v[200:203], v[34:37]
	v_mfma_f32_16x16x32_bf16 v[22:25], v[152:155], v[210:213], v[22:25]
	v_mfma_f32_16x16x32_bf16 v[18:21], v[160:163], v[210:213], v[18:21]
	v_mfma_f32_16x16x32_bf16 v[62:65], v[156:159], v[188:191], v[62:65]
	v_mfma_f32_16x16x32_bf16 v[58:61], v[164:167], v[188:191], v[58:61]
	v_mfma_f32_16x16x32_bf16 v[54:57], v[156:159], v[196:199], v[54:57]
	v_mfma_f32_16x16x32_bf16 v[50:53], v[164:167], v[196:199], v[50:53]
	v_mfma_f32_16x16x32_bf16 v[38:41], v[156:159], v[204:207], v[38:41]
	v_mfma_f32_16x16x32_bf16 v[34:37], v[164:167], v[204:207], v[34:37]
	v_mfma_f32_16x16x32_bf16 v[22:25], v[156:159], v[214:217], v[22:25]
	v_mfma_f32_16x16x32_bf16 v[18:21], v[164:167], v[214:217], v[18:21]
	s_setprio 0
	s_setprio 1
	v_mfma_f32_16x16x32_bf16 v[46:49], v[168:171], v[184:187], v[46:49]
	v_mfma_f32_16x16x32_bf16 v[42:45], v[176:179], v[184:187], v[42:45]
	v_mfma_f32_16x16x32_bf16 v[30:33], v[168:171], v[192:195], v[30:33]
	v_mfma_f32_16x16x32_bf16 v[26:29], v[176:179], v[192:195], v[26:29]
	v_mfma_f32_16x16x32_bf16 v[14:17], v[168:171], v[200:203], v[14:17]
	v_mfma_f32_16x16x32_bf16 v[10:13], v[176:179], v[200:203], v[10:13]
	v_mfma_f32_16x16x32_bf16 v[6:9], v[168:171], v[210:213], v[6:9]
	v_mfma_f32_16x16x32_bf16 v[2:5], v[176:179], v[210:213], v[2:5]
	v_mfma_f32_16x16x32_bf16 v[46:49], v[172:175], v[188:191], v[46:49]
	v_mfma_f32_16x16x32_bf16 v[42:45], v[180:183], v[188:191], v[42:45]
	v_mfma_f32_16x16x32_bf16 v[30:33], v[172:175], v[196:199], v[30:33]
	v_mfma_f32_16x16x32_bf16 v[26:29], v[180:183], v[196:199], v[26:29]
	v_mfma_f32_16x16x32_bf16 v[14:17], v[172:175], v[204:207], v[14:17]
	v_mfma_f32_16x16x32_bf16 v[10:13], v[180:183], v[204:207], v[10:13]
	v_mfma_f32_16x16x32_bf16 v[6:9], v[172:175], v[214:217], v[6:9]
	v_mfma_f32_16x16x32_bf16 v[2:5], v[180:183], v[214:217], v[2:5]
	s_setprio 0
	s_barrier
	s_add_i32 s58, 0, 0x18000
	v_add_u32_e32 v151, s58, v146
	s_add_i32 s59, 0, 0x1c000
	ds_read_b128 v[152:155], v151
	ds_read_b128 v[156:159], v151 offset:1024
	ds_read_b128 v[160:163], v151 offset:2048
	ds_read_b128 v[164:167], v151 offset:3072
	v_add_u32_e32 v151, s59, v146
	ds_read_b128 v[168:171], v151
	ds_read_b128 v[172:175], v151 offset:1024
	ds_read_b128 v[176:179], v151 offset:2048
	ds_read_b128 v[180:183], v151 offset:3072
	s_add_u32 s28, s28, 0x160000
	s_addc_u32 s29, s29, 0
	s_mov_b32 m0, s39
	v_lshl_add_u64 v[226:227], s[28:29], 0, v[136:137]
	ds_read_b128 v[184:187], v150 offset:32768
	ds_read_b128 v[188:191], v150 offset:33792
	ds_read_b128 v[192:195], v150 offset:34816
	ds_read_b128 v[196:199], v150 offset:35840
	ds_read_b128 v[200:203], v150 offset:36864
	ds_read_b128 v[204:207], v150 offset:37888
	ds_read_b128 v[210:213], v150 offset:38912
	ds_read_b128 v[214:217], v150 offset:39936
	global_load_lds_dwordx4 v[226:227], off
	v_lshl_add_u64 v[226:227], s[28:29], 0, v[132:133]
	s_mov_b32 m0, s40
	s_nop 0
	global_load_lds_dwordx4 v[226:227], off
	s_waitcnt vmcnt(8)
	s_waitcnt lgkmcnt(0)
	s_barrier
; #define PG8_STAGE(bufoff, gbase, voff) do { _Pragma("unroll") for (int _i = 0; _i < 2; ++_i) \
;         __builtin_amdgcn_global_load_lds((const unsigned*)((const char*)(gbase) + (voff)[_i]), (PG8_LAS unsigned*)(lds + (bufoff) + ldsw + _i * 8192), 16, 0, 0); } while (0)
; #define PG8_LDA(dst, b, h) do { _Pragma("unroll") for (int m = 0; m < 4; ++m) _Pragma("unroll") for (int k = 0; k < 2; ++k) dst[m][k] = *(const PG8_LAS bf16x8*)(lds + PG8_SA(b, h) + aoff + m * 2048 + k * 1024); } while (0)
; #define PG8_MMA(ai, bj, At, Bt) do { __builtin_amdgcn_s_setprio(1); _Pragma("unroll") for (int m = 0; m < 4; ++m) _Pragma("unroll") for (int n = 0; n < 2; ++n) _Pragma("unroll") for (int k = 0; k < 2; ++k) \
;         acc[ai][bj][m][n] = __builtin_amdgcn_mfma_f32_16x16x32_bf16(Bt[n][k], At[m][k], acc[ai][bj][m][n], 0, 0, 0); __builtin_amdgcn_s_setprio(0); } while (0)
; #define PG8_WAIT_V(n) asm volatile("s_waitcnt vmcnt(" #n ")" ::: "memory")
; #define PG8_WAIT_L(n) asm volatile("s_waitcnt lgkmcnt(" #n ")" ::: "memory")
; #define PG8_BAR __builtin_amdgcn_s_barrier()
; #define PG8_SCHED __builtin_amdgcn_sched_barrier(0)
; template <class Epi, class Sched, bool ALIGN_EPI = false, bool SP2 = false>
; __device__ __forceinline__ void gemm_phase(PG8_LAS unsigned char* lds, const Gemm g, const Sched& S, const Epi& E) {
;     ...
;         for (int t = 0; t < nt; t += 2) {
;             const bool last = (t == nt - 2);
;             const char* a1 = cA + (size_t)(t + 1) * kstep;
;             const char* a2 = last ? nA : cA + (size_t)(t + 2) * kstep; const char* b2 = last ? nB : cB + (size_t)(t + 2) * kstep;
;     ...
;             PG8_WAIT_V(8); PG8_WAIT_L(0); PG8_BAR; PG8_MMA(0, 0, At, B0); PG8_MMA(0, 1, At, B1); PG8_BAR; PG8_SCHED;
;             PG8_LDA(At, 1, 1); PG8_STAGE(PG8_SB(1, 0), b3, voffB); PG8_STAGE(PG8_SB(1, 1), b3 + hstepB, voffB); PG8_STAGE(PG8_SA(1, 0), a3, voffA);
;             PG8_WAIT_V(8); PG8_WAIT_L(0); PG8_BAR; PG8_MMA(1, 0, At, B0); PG8_MMA(1, 1, At, B1); PG8_BAR; PG8_SCHED;
	s_setprio 1
	s_waitcnt lgkmcnt(0)
	v_mfma_f32_16x16x32_bf16 v[126:129], v[152:155], v[184:187], v[126:129]
	v_mfma_f32_16x16x32_bf16 v[122:125], v[160:163], v[184:187], v[122:125]
	v_mfma_f32_16x16x32_bf16 v[118:121], v[152:155], v[192:195], v[118:121]
	v_mfma_f32_16x16x32_bf16 v[114:117], v[160:163], v[192:195], v[114:117]
	v_mfma_f32_16x16x32_bf16 v[102:105], v[152:155], v[200:203], v[102:105]
	v_mfma_f32_16x16x32_bf16 v[98:101], v[160:163], v[200:203], v[98:101]
	v_mfma_f32_16x16x32_bf16 v[86:89], v[152:155], v[210:213], v[86:89]
	v_mfma_f32_16x16x32_bf16 v[82:85], v[160:163], v[210:213], v[82:85]
	v_mfma_f32_16x16x32_bf16 v[126:129], v[156:159], v[188:191], v[126:129]
	v_mfma_f32_16x16x32_bf16 v[122:125], v[164:167], v[188:191], v[122:125]
	v_mfma_f32_16x16x32_bf16 v[118:121], v[156:159], v[196:199], v[118:121]
	v_mfma_f32_16x16x32_bf16 v[114:117], v[164:167], v[196:199], v[114:117]
	v_mfma_f32_16x16x32_bf16 v[102:105], v[156:159], v[204:207], v[102:105]
	v_mfma_f32_16x16x32_bf16 v[98:101], v[164:167], v[204:207], v[98:101]
	v_mfma_f32_16x16x32_bf16 v[86:89], v[156:159], v[214:217], v[86:89]
	v_mfma_f32_16x16x32_bf16 v[82:85], v[164:167], v[214:217], v[82:85]
	s_setprio 0
	s_setprio 1
	v_mfma_f32_16x16x32_bf16 v[110:113], v[168:171], v[184:187], v[110:113]
	v_mfma_f32_16x16x32_bf16 v[106:109], v[176:179], v[184:187], v[106:109]
	v_mfma_f32_16x16x32_bf16 v[94:97], v[168:171], v[192:195], v[94:97]
	v_mfma_f32_16x16x32_bf16 v[90:93], v[176:179], v[192:195], v[90:93]
	v_mfma_f32_16x16x32_bf16 v[78:81], v[168:171], v[200:203], v[78:81]
	v_mfma_f32_16x16x32_bf16 v[74:77], v[176:179], v[200:203], v[74:77]
	v_mfma_f32_16x16x32_bf16 v[70:73], v[168:171], v[210:213], v[70:73]
	v_mfma_f32_16x16x32_bf16 v[66:69], v[176:179], v[210:213], v[66:69]
	v_mfma_f32_16x16x32_bf16 v[110:113], v[172:175], v[188:191], v[110:113]
	v_mfma_f32_16x16x32_bf16 v[106:109], v[180:183], v[188:191], v[106:109]
	v_mfma_f32_16x16x32_bf16 v[94:97], v[172:175], v[196:199], v[94:97]
	v_mfma_f32_16x16x32_bf16 v[90:93], v[180:183], v[196:199], v[90:93]
	v_mfma_f32_16x16x32_bf16 v[78:81], v[172:175], v[204:207], v[78:81]
	v_mfma_f32_16x16x32_bf16 v[74:77], v[180:183], v[204:207], v[74:77]
	v_mfma_f32_16x16x32_bf16 v[70:73], v[172:175], v[214:217], v[70:73]
	v_mfma_f32_16x16x32_bf16 v[66:69], v[180:183], v[214:217], v[66:69]
	s_setprio 0
	s_barrier
	s_add_i32 s28, s58, s34
	v_lshl_add_u64 v[218:219], v[218:219], 0, s[8:9]
	s_mov_b32 m0, s28
	ds_read_b128 v[184:187], v150 offset:49152
	ds_read_b128 v[188:191], v150 offset:50176
	ds_read_b128 v[192:195], v150 offset:51200
	ds_read_b128 v[196:199], v150 offset:52224
	ds_read_b128 v[200:203], v150 offset:53248
	ds_read_b128 v[204:207], v150 offset:54272
	ds_read_b128 v[210:213], v150 offset:55296
	ds_read_b128 v[214:217], v150 offset:56320
	global_load_lds_dwordx4 v[218:219], off
	s_add_i32 m0, s28, 0x2000
	s_add_u32 s26, s26, 0x160080
	v_lshl_add_u64 v[218:219], v[220:221], 0, s[8:9]
	s_addc_u32 s27, s27, 0
	s_add_i32 s28, s59, s34
	global_load_lds_dwordx4 v[218:219], off
	v_lshl_add_u64 v[218:219], s[26:27], 0, v[134:135]
	s_mov_b32 m0, s28
	s_nop 0
	global_load_lds_dwordx4 v[218:219], off
	v_lshl_add_u64 v[218:219], s[26:27], 0, v[130:131]
	s_add_i32 m0, s28, 0x2000
	s_nop 0
	global_load_lds_dwordx4 v[218:219], off
	v_lshl_add_u64 v[218:219], v[222:223], 0, s[8:9]
	s_mov_b32 m0, s42
	s_nop 0
	global_load_lds_dwordx4 v[218:219], off
	v_lshl_add_u64 v[218:219], v[224:225], 0, s[8:9]
	s_mov_b32 m0, s43
	s_nop 0
	global_load_lds_dwordx4 v[218:219], off
	s_waitcnt vmcnt(8)
	s_waitcnt lgkmcnt(0)
	s_barrier
	s_setprio 1
	s_waitcnt lgkmcnt(0)
	v_mfma_f32_16x16x32_bf16 v[62:65], v[152:155], v[184:187], v[62:65]
	v_mfma_f32_16x16x32_bf16 v[58:61], v[160:163], v[184:187], v[58:61]
	v_mfma_f32_16x16x32_bf16 v[54:57], v[152:155], v[192:195], v[54:57]
	v_mfma_f32_16x16x32_bf16 v[50:53], v[160:163], v[192:195], v[50:53]
	v_mfma_f32_16x16x32_bf16 v[38:41], v[152:155], v[200:203], v[38:41]
	v_mfma_f32_16x16x32_bf16 v[34:37], v[160:163], v[200:203], v[34:37]
	v_mfma_f32_16x16x32_bf16 v[22:25], v[152:155], v[210:213], v[22:25]
	v_mfma_f32_16x16x32_bf16 v[18:21], v[160:163], v[210:213], v[18:21]
	v_mfma_f32_16x16x32_bf16 v[62:65], v[156:159], v[188:191], v[62:65]
	v_mfma_f32_16x16x32_bf16 v[58:61], v[164:167], v[188:191], v[58:61]
	v_mfma_f32_16x16x32_bf16 v[54:57], v[156:159], v[196:199], v[54:57]
	v_mfma_f32_16x16x32_bf16 v[50:53], v[164:167], v[196:199], v[50:53]
	v_mfma_f32_16x16x32_bf16 v[38:41], v[156:159], v[204:207], v[38:41]
	v_mfma_f32_16x16x32_bf16 v[34:37], v[164:167], v[204:207], v[34:37]
	v_mfma_f32_16x16x32_bf16 v[22:25], v[156:159], v[214:217], v[22:25]
	v_mfma_f32_16x16x32_bf16 v[18:21], v[164:167], v[214:217], v[18:21]
	s_setprio 0
	s_setprio 1
	v_mfma_f32_16x16x32_bf16 v[46:49], v[168:171], v[184:187], v[46:49]
	v_mfma_f32_16x16x32_bf16 v[42:45], v[176:179], v[184:187], v[42:45]
	v_mfma_f32_16x16x32_bf16 v[30:33], v[168:171], v[192:195], v[30:33]
	v_mfma_f32_16x16x32_bf16 v[26:29], v[176:179], v[192:195], v[26:29]
	v_mfma_f32_16x16x32_bf16 v[14:17], v[168:171], v[200:203], v[14:17]
	v_mfma_f32_16x16x32_bf16 v[10:13], v[176:179], v[200:203], v[10:13]
	v_mfma_f32_16x16x32_bf16 v[6:9], v[168:171], v[210:213], v[6:9]
	v_mfma_f32_16x16x32_bf16 v[2:5], v[176:179], v[210:213], v[2:5]
	v_mfma_f32_16x16x32_bf16 v[46:49], v[172:175], v[188:191], v[46:49]
	v_mfma_f32_16x16x32_bf16 v[42:45], v[180:183], v[188:191], v[42:45]
	v_mfma_f32_16x16x32_bf16 v[30:33], v[172:175], v[196:199], v[30:33]
	v_mfma_f32_16x16x32_bf16 v[26:29], v[180:183], v[196:199], v[26:29]
	v_mfma_f32_16x16x32_bf16 v[14:17], v[172:175], v[204:207], v[14:17]
	v_mfma_f32_16x16x32_bf16 v[10:13], v[180:183], v[204:207], v[10:13]
	v_mfma_f32_16x16x32_bf16 v[6:9], v[172:175], v[214:217], v[6:9]
	v_mfma_f32_16x16x32_bf16 v[2:5], v[180:183], v[214:217], v[2:5]
	s_setprio 0
	s_barrier
	s_add_i32 s57, s57, 2
	s_add_u32 s24, s24, 0x100
	s_addc_u32 s25, s25, 0
	s_add_u32 s55, s55, 0x100
	s_addc_u32 s56, s56, 0
	s_cmpk_gt_u32 s57, 0x55
	s_cbranch_scc1 .Lpeel_exit_17
	.p2align 6

; #define PG8_STAGE(bufoff, gbase, voff) do { _Pragma("unroll") for (int _i = 0; _i < 2; ++_i) \
;         __builtin_amdgcn_global_load_lds((const unsigned*)((const char*)(gbase) + (voff)[_i]), (PG8_LAS unsigned*)(lds + (bufoff) + ldsw + _i * 8192), 16, 0, 0); } while (0)
; #define PG8_WAIT_V(n) asm volatile("s_waitcnt vmcnt(" #n ")" ::: "memory")
; #define PG8_BAR __builtin_amdgcn_s_barrier()
; template <class Epi, class Sched, bool ALIGN_EPI = false, bool SP2 = false>
; __device__ __forceinline__ void gemm_phase(PG8_LAS unsigned char* lds, const Gemm g, const Sched& S, const Epi& E) {
;     const int tid = threadIdx.x, wid = __builtin_amdgcn_readfirstlane(tid >> 6), lane = tid & 63, wr = wid >> 2, wc = wid & 3, fr = lane & 15, fq = lane >> 4;
;     const int K = g.K, nt = K / BK;
;     unsigned voffA[2], voffB[2];
; #pragma unroll
;     for (int i = 0; i < 2; ++i) { int R, C; stage_rc(tid * 16 + i * 8192, R, C); const int Rb = Epi::PERM ? ((R & ~31) + perm32(R & 31)) : R;
;         voffA[i] = (unsigned)(R * g.lda + C) * 2u; voffB[i] = (unsigned)(Rb * g.ldb + C) * 2u; }
;     const size_t kstep = (size_t)(BK * 2);
;     const size_t hstepA = (size_t)HALF * g.lda * 2, hstepB = (size_t)HALF * g.ldb * 2;
;     const size_t tstepA = 2 * hstepA, tstepB = 2 * hstepB;
;     const unsigned ldsw = (unsigned)wid * 1024u;
;     const int aoff = lds_byte(wr * 64 + fr, fq * 8), boff = lds_byte(wc * 32 + fr, fq * 8);
;     ...
;         PG8_WAIT_V(2); PG8_BAR;
;         PG8_STAGE(PG8_SB(1, 0), cB + kstep, voffB); PG8_STAGE(PG8_SA(1, 0), cA + kstep, voffA); PG8_STAGE(PG8_SB(1, 1), cB + hstepB + kstep, voffB);
;         PG8_WAIT_V(6); PG8_BAR;
.LBB0_2253:
	s_lshl_b32 s6, s6, 5
	s_and_b32 s12, s6, 0x60
	s_mov_b64 s[6:7], 0x80
	s_add_i32 m0, s19, 0x18000
	v_lshl_add_u64 v[8:9], v[8:9], 0, s[6:7]
	s_lshl_b32 s9, s8, 13
	s_lshl_b32 s13, s12, 7
	s_waitcnt vmcnt(2)
	s_barrier
	global_load_lds_dwordx4 v[8:9], off
	v_lshl_add_u64 v[6:7], v[6:7], 0, s[6:7]
	s_add_i32 m0, s19, 0x1a000
	s_add_i32 s43, s19, 0x8000
	s_add_i32 s44, s19, 0xa000
	global_load_lds_dwordx4 v[6:7], off
	v_lshl_add_u64 v[2:3], v[2:3], 0, s[6:7]
	s_mov_b32 m0, s43
	s_add_u32 s10, s30, 0x100080
	global_load_lds_dwordx4 v[2:3], off
	v_lshl_add_u64 v[2:3], v[4:5], 0, s[6:7]
	s_mov_b32 m0, s44
	s_addc_u32 s11, s31, 0
	global_load_lds_dwordx4 v[2:3], off
	s_add_i32 m0, s19, 0x1c000
	v_lshl_add_u64 v[2:3], s[10:11], 0, v[134:135]
	global_load_lds_dwordx4 v[2:3], off
	v_lshl_add_u64 v[2:3], s[10:11], 0, v[130:131]
	s_add_i32 m0, s19, 0x1e000
	s_sext_i32_i8 s52, s4
	global_load_lds_dwordx4 v[2:3], off
	v_and_b32_e32 v2, 15, v0
	v_lshlrev_b32_e32 v3, 1, v13
	v_lshlrev_b32_e32 v4, 2, v0
	v_lshlrev_b32_e32 v5, 6, v0
	s_movk_i32 s4, 0x3c0
	v_lshl_or_b32 v1, s8, 6, v2
	v_lshl_or_b32 v2, v2, 6, v3
	v_and_b32_e32 v4, 32, v4
	v_and_or_b32 v3, v5, s4, v3
	v_bitop3_b32 v146, s13, v3, v4 bitop3:0xf6
	v_lshlrev_b32_e32 v3, 10, v0
	v_bitop3_b32 v2, v2, s9, v4 bitop3:0xde
	v_and_b32_e32 v3, 0x60000, v3
	v_lshlrev_b32_e32 v4, 13, v14
	v_or3_b32 v3, v11, v3, v4
	v_add_u32_e32 v138, v3, v12
	v_lshlrev_b32_e32 v3, 6, v10
	s_waitcnt vmcnt(0)
	s_cmpk_lt_u32 s5, 0x100
	v_and_b32_e32 v3, 0xe0000, v3
	s_cselect_b64 s[8:9], -1, 0
	v_or3_b32 v3, v11, v3, v4
	s_add_i32 s46, 0, 0x10000
	s_add_i32 s47, 0, 0x14000
	s_waitcnt lgkmcnt(0)
	s_ashr_i32 s45, s33, 31
	v_or_b32_e32 v147, s12, v13
	v_mov_b32_e32 v139, v135
	v_add_u32_e32 v140, v3, v12
	v_mov_b32_e32 v141, v135
	v_mov_b64_e32 v[142:143], 0x500
	v_mov_b64_e32 v[144:145], 0x4ff
	v_add_u32_e32 v148, s46, v146
	v_add_u32_e32 v149, s47, v146
	v_add_u32_e32 v150, 0, v2
	s_mov_b64 s[10:11], 0x80000
	s_mov_b32 s48, 0x80000
	s_mov_b64 s[12:13], 0x90000
	s_mov_b32 s49, 0x90000
	s_mov_b64 s[14:15], 0xa0000
	s_mov_b32 s50, 0xa0000
	s_mov_b64 s[16:17], 0xb0000
	s_mov_b32 s51, 0xb0000
	s_barrier
	s_branch .LBB0_2256

; #define PG8_STAGE(bufoff, gbase, voff) do { _Pragma("unroll") for (int _i = 0; _i < 2; ++_i) \
;         __builtin_amdgcn_global_load_lds((const unsigned*)((const char*)(gbase) + (voff)[_i]), (PG8_LAS unsigned*)(lds + (bufoff) + ldsw + _i * 8192), 16, 0, 0); } while (0)
; #define PG8_LDA(dst, b, h) do { _Pragma("unroll") for (int m = 0; m < 4; ++m) _Pragma("unroll") for (int k = 0; k < 2; ++k) dst[m][k] = *(const PG8_LAS bf16x8*)(lds + PG8_SA(b, h) + aoff + m * 2048 + k * 1024); } while (0)
; #define PG8_LDB(dst, b, h) do { _Pragma("unroll") for (int n = 0; n < 2; ++n) _Pragma("unroll") for (int k = 0; k < 2; ++k) dst[n][k] = *(const PG8_LAS bf16x8*)(lds + PG8_SB(b, h) + boff + n * 2048 + k * 1024); } while (0)
; #define PG8_WAIT_V(n) asm volatile("s_waitcnt vmcnt(" #n ")" ::: "memory")
; #define PG8_WAIT_L(n) asm volatile("s_waitcnt lgkmcnt(" #n ")" ::: "memory")
; #define PG8_BAR __builtin_amdgcn_s_barrier()
; #define PG8_SCHED __builtin_amdgcn_sched_barrier(0)
; template <class Epi, class Sched, bool ALIGN_EPI = false, bool SP2 = false>
; __device__ __forceinline__ void gemm_phase(PG8_LAS unsigned char* lds, const Gemm g, const Sched& S, const Epi& E) {
;     ...
;         const char* nA = has_next ? (const char*)g.A + (size_t)nxt.pm * tstepA : cA; const char* nB = has_next ? (const char*)g.Bt + (size_t)nxt.pn * tstepB : cB;
;         for (int t = 0; t < nt; t += 2) {
;             const bool last = (t == nt - 2);
;             const char* a1 = cA + (size_t)(t + 1) * kstep;
;             const char* a2 = last ? nA : cA + (size_t)(t + 2) * kstep; const char* b2 = last ? nB : cB + (size_t)(t + 2) * kstep;
;             const char* a3 = a2 + kstep; const char* b3 = b2 + kstep;
;             if (last && has_next) S.a_ready(nxt);
;             if constexpr (SP2) {
;             PG8_LDB(B0, 0, 0); PG8_LDB(B1, 0, 1); PG8_SCHED; PG8_LDA(At, 0, 0); PG8_STAGE(PG8_SA(1, 1), a1 + hstepA, voffA);
;             PG8_WAIT_V(8); PG8_WAIT_L(0); PG8_BAR; PG8_MMA(0, 0, At, B0); PG8_MMA(0, 1, At, B1); PG8_BAR; PG8_SCHED;
;     ...
; #pragma unroll
;         for (int a = 0; a < 2; ++a)
; #pragma unroll
;             for (int b = 0; b < 2; ++b)
; #pragma unroll
;                 for (int m = 0; m < 4; ++m)
; #pragma unroll
;                     for (int n = 0; n < 2; ++n) acc[a][b][m][n] = (f32x4){0.f, 0.f, 0.f, 0.f};
.LBB0_2258:
	s_ashr_i32 s23, s22, 31
	s_lshl_b64 s[24:25], s[22:23], 21
	s_add_u32 s24, s86, s24
	s_addc_u32 s25, s87, s25
	s_and_b64 s[26:27], s[4:5], exec
	s_cselect_b32 s23, s25, s29
	s_cselect_b32 s53, s24, s28
	s_ashr_i32 s21, s20, 31
	s_lshl_b64 s[26:27], s[20:21], 21
	s_add_u32 s26, s88, s26
	s_addc_u32 s27, s89, s27
	s_and_b64 s[34:35], s[4:5], exec
	s_cselect_b32 s21, s27, s31
	s_cselect_b32 s54, s26, s30
	s_add_u32 s28, s28, 0x100080
	s_addc_u32 s29, s29, 0
	s_add_u32 s55, s30, 0x100
	v_mov_b32_e32 v2, 0
	s_addc_u32 s56, s31, 0
	s_mov_b32 s57, -2
	v_mov_b32_e32 v3, v2
	v_mov_b32_e32 v4, v2
	v_mov_b32_e32 v5, v2
	v_mov_b32_e32 v6, v2
	v_mov_b32_e32 v7, v2
	v_mov_b32_e32 v8, v2
	v_mov_b32_e32 v9, v2
	v_mov_b32_e32 v10, v2
	v_mov_b32_e32 v11, v2
	v_mov_b32_e32 v12, v2
	v_mov_b32_e32 v13, v2
	v_mov_b32_e32 v14, v2
	v_mov_b32_e32 v15, v2
	v_mov_b32_e32 v16, v2
	v_mov_b32_e32 v17, v2
	v_mov_b32_e32 v26, v2
	v_mov_b32_e32 v27, v2
	v_mov_b32_e32 v28, v2
	v_mov_b32_e32 v29, v2
	v_mov_b32_e32 v30, v2
	v_mov_b32_e32 v31, v2
	v_mov_b32_e32 v32, v2
	v_mov_b32_e32 v33, v2
	v_mov_b32_e32 v42, v2
	v_mov_b32_e32 v43, v2
	v_mov_b32_e32 v44, v2
	v_mov_b32_e32 v45, v2
	v_mov_b32_e32 v46, v2
	v_mov_b32_e32 v47, v2
	v_mov_b32_e32 v48, v2
	v_mov_b32_e32 v49, v2
	v_mov_b32_e32 v18, v2
	v_mov_b32_e32 v19, v2
	v_mov_b32_e32 v20, v2
	v_mov_b32_e32 v21, v2
	v_mov_b32_e32 v22, v2
	v_mov_b32_e32 v23, v2
	v_mov_b32_e32 v24, v2
	v_mov_b32_e32 v25, v2
	v_mov_b32_e32 v34, v2
	v_mov_b32_e32 v35, v2
	v_mov_b32_e32 v36, v2
	v_mov_b32_e32 v37, v2
	v_mov_b32_e32 v38, v2
	v_mov_b32_e32 v39, v2
	v_mov_b32_e32 v40, v2
	v_mov_b32_e32 v41, v2
	v_mov_b32_e32 v50, v2
	v_mov_b32_e32 v51, v2
	v_mov_b32_e32 v52, v2
	v_mov_b32_e32 v53, v2
	v_mov_b32_e32 v54, v2
	v_mov_b32_e32 v55, v2
	v_mov_b32_e32 v56, v2
	v_mov_b32_e32 v57, v2
	v_mov_b32_e32 v58, v2
	v_mov_b32_e32 v59, v2
	v_mov_b32_e32 v60, v2
	v_mov_b32_e32 v61, v2
	v_mov_b32_e32 v62, v2
	v_mov_b32_e32 v63, v2
	v_mov_b32_e32 v64, v2
	v_mov_b32_e32 v65, v2
	v_mov_b32_e32 v66, v2
	v_mov_b32_e32 v67, v2
	v_mov_b32_e32 v68, v2
	v_mov_b32_e32 v69, v2
	v_mov_b32_e32 v70, v2
	v_mov_b32_e32 v71, v2
	v_mov_b32_e32 v72, v2
	v_mov_b32_e32 v73, v2
	v_mov_b32_e32 v74, v2
	v_mov_b32_e32 v75, v2
	v_mov_b32_e32 v76, v2
	v_mov_b32_e32 v77, v2
	v_mov_b32_e32 v78, v2
	v_mov_b32_e32 v79, v2
	v_mov_b32_e32 v80, v2
	v_mov_b32_e32 v81, v2
	v_mov_b32_e32 v90, v2
	v_mov_b32_e32 v91, v2
	v_mov_b32_e32 v92, v2
	v_mov_b32_e32 v93, v2
	v_mov_b32_e32 v94, v2
	v_mov_b32_e32 v95, v2
	v_mov_b32_e32 v96, v2
	v_mov_b32_e32 v97, v2
	v_mov_b32_e32 v106, v2
	v_mov_b32_e32 v107, v2
	v_mov_b32_e32 v108, v2
	v_mov_b32_e32 v109, v2
	v_mov_b32_e32 v110, v2
	v_mov_b32_e32 v111, v2
	v_mov_b32_e32 v112, v2
	v_mov_b32_e32 v113, v2
	v_mov_b32_e32 v82, v2
	v_mov_b32_e32 v83, v2
	v_mov_b32_e32 v84, v2
	v_mov_b32_e32 v85, v2
	v_mov_b32_e32 v86, v2
	v_mov_b32_e32 v87, v2
	v_mov_b32_e32 v88, v2
	v_mov_b32_e32 v89, v2
	v_mov_b32_e32 v98, v2
	v_mov_b32_e32 v99, v2
	v_mov_b32_e32 v100, v2
	v_mov_b32_e32 v101, v2
	v_mov_b32_e32 v102, v2
	v_mov_b32_e32 v103, v2
	v_mov_b32_e32 v104, v2
	v_mov_b32_e32 v105, v2
	v_mov_b32_e32 v114, v2
	v_mov_b32_e32 v115, v2
	v_mov_b32_e32 v116, v2
	v_mov_b32_e32 v117, v2
	v_mov_b32_e32 v118, v2
	v_mov_b32_e32 v119, v2
	v_mov_b32_e32 v120, v2
	v_mov_b32_e32 v121, v2
	v_mov_b32_e32 v122, v2
	v_mov_b32_e32 v123, v2
	v_mov_b32_e32 v124, v2
	v_mov_b32_e32 v125, v2
	v_mov_b32_e32 v126, v2
	v_mov_b32_e32 v127, v2
	v_mov_b32_e32 v128, v2
	v_mov_b32_e32 v129, v2
	ds_read_b128 v[152:155], v148
	ds_read_b128 v[156:159], v148 offset:1024
	ds_read_b128 v[160:163], v148 offset:2048
	ds_read_b128 v[164:167], v148 offset:3072
	ds_read_b128 v[168:171], v149
	ds_read_b128 v[172:175], v149 offset:1024
	ds_read_b128 v[176:179], v149 offset:2048
	ds_read_b128 v[180:183], v149 offset:3072
	s_add_u32 s30, s28, 0xfff00080
	s_addc_u32 s31, s29, -1
	s_cmp_eq_u32 s57, 60
	s_cselect_b32 s35, s23, s31
	s_cselect_b32 s34, s53, s30
	s_cselect_b32 s31, s21, s56
	s_cselect_b32 s30, s54, s55
	v_lshl_add_u64 v[218:219], s[28:29], 0, v[138:139]
	s_add_i32 m0, s19, 0xc000
	ds_read_b128 v[184:187], v150
	ds_read_b128 v[188:191], v150 offset:1024
	ds_read_b128 v[192:195], v150 offset:2048
	ds_read_b128 v[196:199], v150 offset:3072
	ds_read_b128 v[200:203], v150 offset:4096
	ds_read_b128 v[204:207], v150 offset:5120
	ds_read_b128 v[210:213], v150 offset:6144
	ds_read_b128 v[214:217], v150 offset:7168
	global_load_lds_dwordx4 v[218:219], off
	v_lshl_add_u64 v[218:219], s[28:29], 0, v[140:141]
	s_add_i32 m0, s19, 0xe000
	s_nop 0
	global_load_lds_dwordx4 v[218:219], off
	s_waitcnt vmcnt(24)
	s_waitcnt lgkmcnt(0)
	s_barrier
; #define PG8_STAGE(bufoff, gbase, voff) do { _Pragma("unroll") for (int _i = 0; _i < 2; ++_i) \
;         __builtin_amdgcn_global_load_lds((const unsigned*)((const char*)(gbase) + (voff)[_i]), (PG8_LAS unsigned*)(lds + (bufoff) + ldsw + _i * 8192), 16, 0, 0); } while (0)
; #define PG8_LDA(dst, b, h) do { _Pragma("unroll") for (int m = 0; m < 4; ++m) _Pragma("unroll") for (int k = 0; k < 2; ++k) dst[m][k] = *(const PG8_LAS bf16x8*)(lds + PG8_SA(b, h) + aoff + m * 2048 + k * 1024); } while (0)
; #define PG8_MMA(ai, bj, At, Bt) do { __builtin_amdgcn_s_setprio(1); _Pragma("unroll") for (int m = 0; m < 4; ++m) _Pragma("unroll") for (int n = 0; n < 2; ++n) _Pragma("unroll") for (int k = 0; k < 2; ++k) \
;         acc[ai][bj][m][n] = __builtin_amdgcn_mfma_f32_16x16x32_bf16(Bt[n][k], At[m][k], acc[ai][bj][m][n], 0, 0, 0); __builtin_amdgcn_s_setprio(0); } while (0)
; #define PG8_WAIT_V(n) asm volatile("s_waitcnt vmcnt(" #n ")" ::: "memory")
; #define PG8_WAIT_L(n) asm volatile("s_waitcnt lgkmcnt(" #n ")" ::: "memory")
; #define PG8_BAR __builtin_amdgcn_s_barrier()
; #define PG8_SCHED __builtin_amdgcn_sched_barrier(0)
; template <class Epi, class Sched, bool ALIGN_EPI = false, bool SP2 = false>
; __device__ __forceinline__ void gemm_phase(PG8_LAS unsigned char* lds, const Gemm g, const Sched& S, const Epi& E) {
;     ...
;             PG8_WAIT_V(8); PG8_WAIT_L(0); PG8_BAR; PG8_MMA(0, 0, At, B0); PG8_MMA(0, 1, At, B1); PG8_BAR; PG8_SCHED;
;             PG8_LDA(At, 0, 1); PG8_STAGE(PG8_SB(0, 0), b2, voffB); PG8_STAGE(PG8_SB(0, 1), b2 + hstepB, voffB); PG8_STAGE(PG8_SA(0, 0), a2, voffA);
;             PG8_WAIT_V(8); PG8_WAIT_L(0); PG8_BAR; PG8_MMA(1, 0, At, B0); PG8_MMA(1, 1, At, B1); PG8_BAR; PG8_SCHED;
	s_setprio 1
	s_waitcnt lgkmcnt(0)
	v_mfma_f32_16x16x32_bf16 v[126:129], v[152:155], v[184:187], v[126:129]
	v_mfma_f32_16x16x32_bf16 v[122:125], v[160:163], v[184:187], v[122:125]
	v_mfma_f32_16x16x32_bf16 v[118:121], v[152:155], v[192:195], v[118:121]
	v_mfma_f32_16x16x32_bf16 v[114:117], v[160:163], v[192:195], v[114:117]
	v_mfma_f32_16x16x32_bf16 v[102:105], v[152:155], v[200:203], v[102:105]
	v_mfma_f32_16x16x32_bf16 v[98:101], v[160:163], v[200:203], v[98:101]
	v_mfma_f32_16x16x32_bf16 v[86:89], v[152:155], v[210:213], v[86:89]
	v_mfma_f32_16x16x32_bf16 v[82:85], v[160:163], v[210:213], v[82:85]
	v_mfma_f32_16x16x32_bf16 v[126:129], v[156:159], v[188:191], v[126:129]
	v_mfma_f32_16x16x32_bf16 v[122:125], v[164:167], v[188:191], v[122:125]
	v_mfma_f32_16x16x32_bf16 v[118:121], v[156:159], v[196:199], v[118:121]
	v_mfma_f32_16x16x32_bf16 v[114:117], v[164:167], v[196:199], v[114:117]
	v_mfma_f32_16x16x32_bf16 v[102:105], v[156:159], v[204:207], v[102:105]
	v_mfma_f32_16x16x32_bf16 v[98:101], v[164:167], v[204:207], v[98:101]
	v_mfma_f32_16x16x32_bf16 v[86:89], v[156:159], v[214:217], v[86:89]
	v_mfma_f32_16x16x32_bf16 v[82:85], v[164:167], v[214:217], v[82:85]
	s_setprio 0
	s_setprio 1
	v_mfma_f32_16x16x32_bf16 v[110:113], v[168:171], v[184:187], v[110:113]
	v_mfma_f32_16x16x32_bf16 v[106:109], v[176:179], v[184:187], v[106:109]
	v_mfma_f32_16x16x32_bf16 v[94:97], v[168:171], v[192:195], v[94:97]
	v_mfma_f32_16x16x32_bf16 v[90:93], v[176:179], v[192:195], v[90:93]
	v_mfma_f32_16x16x32_bf16 v[78:81], v[168:171], v[200:203], v[78:81]
	v_mfma_f32_16x16x32_bf16 v[74:77], v[176:179], v[200:203], v[74:77]
	v_mfma_f32_16x16x32_bf16 v[70:73], v[168:171], v[210:213], v[70:73]
	v_mfma_f32_16x16x32_bf16 v[66:69], v[176:179], v[210:213], v[66:69]
	v_mfma_f32_16x16x32_bf16 v[110:113], v[172:175], v[188:191], v[110:113]
	v_mfma_f32_16x16x32_bf16 v[106:109], v[180:183], v[188:191], v[106:109]
	v_mfma_f32_16x16x32_bf16 v[94:97], v[172:175], v[196:199], v[94:97]
	v_mfma_f32_16x16x32_bf16 v[90:93], v[180:183], v[196:199], v[90:93]
	v_mfma_f32_16x16x32_bf16 v[78:81], v[172:175], v[204:207], v[78:81]
	v_mfma_f32_16x16x32_bf16 v[74:77], v[180:183], v[204:207], v[74:77]
	v_mfma_f32_16x16x32_bf16 v[70:73], v[172:175], v[214:217], v[70:73]
	v_mfma_f32_16x16x32_bf16 v[66:69], v[180:183], v[214:217], v[66:69]
	s_setprio 0
	s_barrier
	s_add_i32 s58, s46, s36
	v_lshl_add_u64 v[218:219], s[30:31], 0, v[134:135]
	s_mov_b32 m0, s58
	ds_read_b128 v[184:187], v150 offset:16384
	ds_read_b128 v[188:191], v150 offset:17408
	ds_read_b128 v[192:195], v150 offset:18432
	ds_read_b128 v[196:199], v150 offset:19456
	ds_read_b128 v[200:203], v150 offset:20480
	ds_read_b128 v[204:207], v150 offset:21504
	ds_read_b128 v[210:213], v150 offset:22528
	ds_read_b128 v[214:217], v150 offset:23552
	global_load_lds_dwordx4 v[218:219], off
	s_add_i32 m0, s58, 0x2000
	s_add_u32 s58, s30, 0x100000
	v_lshl_add_u64 v[220:221], s[30:31], 0, v[130:131]
	s_addc_u32 s59, s31, 0
	s_add_i32 s60, s47, s36
	global_load_lds_dwordx4 v[220:221], off
	v_lshl_add_u64 v[222:223], s[58:59], 0, v[134:135]
	s_mov_b32 m0, s60
	v_lshl_add_u64 v[224:225], s[34:35], 0, v[132:133]
	global_load_lds_dwordx4 v[222:223], off
	v_lshl_add_u64 v[222:223], s[58:59], 0, v[130:131]
	s_add_i32 m0, s60, 0x2000
	s_nop 0
	global_load_lds_dwordx4 v[222:223], off
	v_lshl_add_u64 v[222:223], s[34:35], 0, v[136:137]
	s_mov_b32 m0, s19
	s_nop 0
	global_load_lds_dwordx4 v[222:223], off
	s_mov_b32 m0, s39
	s_nop 0
	global_load_lds_dwordx4 v[224:225], off
	s_waitcnt vmcnt(24)
	s_waitcnt lgkmcnt(0)
	s_barrier
	s_setprio 1
	s_waitcnt lgkmcnt(0)
	v_mfma_f32_16x16x32_bf16 v[62:65], v[152:155], v[184:187], v[62:65]
	v_mfma_f32_16x16x32_bf16 v[58:61], v[160:163], v[184:187], v[58:61]
	v_mfma_f32_16x16x32_bf16 v[54:57], v[152:155], v[192:195], v[54:57]
	v_mfma_f32_16x16x32_bf16 v[50:53], v[160:163], v[192:195], v[50:53]
	v_mfma_f32_16x16x32_bf16 v[38:41], v[152:155], v[200:203], v[38:41]
	v_mfma_f32_16x16x32_bf16 v[34:37], v[160:163], v[200:203], v[34:37]
	v_mfma_f32_16x16x32_bf16 v[22:25], v[152:155], v[210:213], v[22:25]
	v_mfma_f32_16x16x32_bf16 v[18:21], v[160:163], v[210:213], v[18:21]
	v_mfma_f32_16x16x32_bf16 v[62:65], v[156:159], v[188:191], v[62:65]
	v_mfma_f32_16x16x32_bf16 v[58:61], v[164:167], v[188:191], v[58:61]
	v_mfma_f32_16x16x32_bf16 v[54:57], v[156:159], v[196:199], v[54:57]
	v_mfma_f32_16x16x32_bf16 v[50:53], v[164:167], v[196:199], v[50:53]
	v_mfma_f32_16x16x32_bf16 v[38:41], v[156:159], v[204:207], v[38:41]
	v_mfma_f32_16x16x32_bf16 v[34:37], v[164:167], v[204:207], v[34:37]
	v_mfma_f32_16x16x32_bf16 v[22:25], v[156:159], v[214:217], v[22:25]
	v_mfma_f32_16x16x32_bf16 v[18:21], v[164:167], v[214:217], v[18:21]
	s_setprio 0
	s_setprio 1
	v_mfma_f32_16x16x32_bf16 v[46:49], v[168:171], v[184:187], v[46:49]
	v_mfma_f32_16x16x32_bf16 v[42:45], v[176:179], v[184:187], v[42:45]
	v_mfma_f32_16x16x32_bf16 v[30:33], v[168:171], v[192:195], v[30:33]
	v_mfma_f32_16x16x32_bf16 v[26:29], v[176:179], v[192:195], v[26:29]
	v_mfma_f32_16x16x32_bf16 v[14:17], v[168:171], v[200:203], v[14:17]
	v_mfma_f32_16x16x32_bf16 v[10:13], v[176:179], v[200:203], v[10:13]
	v_mfma_f32_16x16x32_bf16 v[6:9], v[168:171], v[210:213], v[6:9]
	v_mfma_f32_16x16x32_bf16 v[2:5], v[176:179], v[210:213], v[2:5]
	v_mfma_f32_16x16x32_bf16 v[46:49], v[172:175], v[188:191], v[46:49]
	v_mfma_f32_16x16x32_bf16 v[42:45], v[180:183], v[188:191], v[42:45]
	v_mfma_f32_16x16x32_bf16 v[30:33], v[172:175], v[196:199], v[30:33]
	v_mfma_f32_16x16x32_bf16 v[26:29], v[180:183], v[196:199], v[26:29]
	v_mfma_f32_16x16x32_bf16 v[14:17], v[172:175], v[204:207], v[14:17]
	v_mfma_f32_16x16x32_bf16 v[10:13], v[180:183], v[204:207], v[10:13]
	v_mfma_f32_16x16x32_bf16 v[6:9], v[172:175], v[214:217], v[6:9]
	v_mfma_f32_16x16x32_bf16 v[2:5], v[180:183], v[214:217], v[2:5]
	s_setprio 0
	s_barrier
; #define PG8_STAGE(bufoff, gbase, voff) do { _Pragma("unroll") for (int _i = 0; _i < 2; ++_i) \
;         __builtin_amdgcn_global_load_lds((const unsigned*)((const char*)(gbase) + (voff)[_i]), (PG8_LAS unsigned*)(lds + (bufoff) + ldsw + _i * 8192), 16, 0, 0); } while (0)
; #define PG8_LDA(dst, b, h) do { _Pragma("unroll") for (int m = 0; m < 4; ++m) _Pragma("unroll") for (int k = 0; k < 2; ++k) dst[m][k] = *(const PG8_LAS bf16x8*)(lds + PG8_SA(b, h) + aoff + m * 2048 + k * 1024); } while (0)
; #define PG8_LDB(dst, b, h) do { _Pragma("unroll") for (int n = 0; n < 2; ++n) _Pragma("unroll") for (int k = 0; k < 2; ++k) dst[n][k] = *(const PG8_LAS bf16x8*)(lds + PG8_SB(b, h) + boff + n * 2048 + k * 1024); } while (0)
; #define PG8_MMA(ai, bj, At, Bt) do { __builtin_amdgcn_s_setprio(1); _Pragma("unroll") for (int m = 0; m < 4; ++m) _Pragma("unroll") for (int n = 0; n < 2; ++n) _Pragma("unroll") for (int k = 0; k < 2; ++k) \
;         acc[ai][bj][m][n] = __builtin_amdgcn_mfma_f32_16x16x32_bf16(Bt[n][k], At[m][k], acc[ai][bj][m][n], 0, 0, 0); __builtin_amdgcn_s_setprio(0); } while (0)
; #define PG8_WAIT_V(n) asm volatile("s_waitcnt vmcnt(" #n ")" ::: "memory")
; #define PG8_WAIT_L(n) asm volatile("s_waitcnt lgkmcnt(" #n ")" ::: "memory")
; #define PG8_BAR __builtin_amdgcn_s_barrier()
; #define PG8_SCHED __builtin_amdgcn_sched_barrier(0)
; template <class Epi, class Sched, bool ALIGN_EPI = false, bool SP2 = false>
; __device__ __forceinline__ void gemm_phase(PG8_LAS unsigned char* lds, const Gemm g, const Sched& S, const Epi& E) {
;     ...
;             PG8_LDB(B0, 1, 0); PG8_LDB(B1, 1, 1); PG8_SCHED; PG8_LDA(At, 1, 0); PG8_STAGE(PG8_SA(0, 1), a2 + hstepA, voffA);
;             PG8_WAIT_V(8); PG8_WAIT_L(0); PG8_BAR; PG8_MMA(0, 0, At, B0); PG8_MMA(0, 1, At, B1); PG8_BAR; PG8_SCHED;
	s_add_i32 s58, 0, 0x18000
	v_add_u32_e32 v151, s58, v146
	s_add_i32 s59, 0, 0x1c000
	ds_read_b128 v[152:155], v151
	ds_read_b128 v[156:159], v151 offset:1024
	ds_read_b128 v[160:163], v151 offset:2048
	ds_read_b128 v[164:167], v151 offset:3072
	v_add_u32_e32 v151, s59, v146
	ds_read_b128 v[168:171], v151
	ds_read_b128 v[172:175], v151 offset:1024
	ds_read_b128 v[176:179], v151 offset:2048
	ds_read_b128 v[180:183], v151 offset:3072
	s_add_u32 s34, s34, 0x100000
	s_addc_u32 s35, s35, 0
	s_mov_b32 m0, s40
	v_lshl_add_u64 v[226:227], s[34:35], 0, v[136:137]
	ds_read_b128 v[184:187], v150 offset:32768
	ds_read_b128 v[188:191], v150 offset:33792
	ds_read_b128 v[192:195], v150 offset:34816
	ds_read_b128 v[196:199], v150 offset:35840
	ds_read_b128 v[200:203], v150 offset:36864
	ds_read_b128 v[204:207], v150 offset:37888
	ds_read_b128 v[210:213], v150 offset:38912
	ds_read_b128 v[214:217], v150 offset:39936
	global_load_lds_dwordx4 v[226:227], off
	v_lshl_add_u64 v[226:227], s[34:35], 0, v[132:133]
	s_mov_b32 m0, s41
	s_nop 0
	global_load_lds_dwordx4 v[226:227], off
	s_waitcnt vmcnt(8)
	s_waitcnt lgkmcnt(0)
	s_barrier
	s_setprio 1
	s_waitcnt lgkmcnt(0)
	v_mfma_f32_16x16x32_bf16 v[126:129], v[152:155], v[184:187], v[126:129]
	v_mfma_f32_16x16x32_bf16 v[122:125], v[160:163], v[184:187], v[122:125]
	v_mfma_f32_16x16x32_bf16 v[118:121], v[152:155], v[192:195], v[118:121]
	v_mfma_f32_16x16x32_bf16 v[114:117], v[160:163], v[192:195], v[114:117]
	v_mfma_f32_16x16x32_bf16 v[102:105], v[152:155], v[200:203], v[102:105]
	v_mfma_f32_16x16x32_bf16 v[98:101], v[160:163], v[200:203], v[98:101]
	v_mfma_f32_16x16x32_bf16 v[86:89], v[152:155], v[210:213], v[86:89]
	v_mfma_f32_16x16x32_bf16 v[82:85], v[160:163], v[210:213], v[82:85]
	v_mfma_f32_16x16x32_bf16 v[126:129], v[156:159], v[188:191], v[126:129]
	v_mfma_f32_16x16x32_bf16 v[122:125], v[164:167], v[188:191], v[122:125]
	v_mfma_f32_16x16x32_bf16 v[118:121], v[156:159], v[196:199], v[118:121]
	v_mfma_f32_16x16x32_bf16 v[114:117], v[164:167], v[196:199], v[114:117]
	v_mfma_f32_16x16x32_bf16 v[102:105], v[156:159], v[204:207], v[102:105]
	v_mfma_f32_16x16x32_bf16 v[98:101], v[164:167], v[204:207], v[98:101]
	v_mfma_f32_16x16x32_bf16 v[86:89], v[156:159], v[214:217], v[86:89]
	v_mfma_f32_16x16x32_bf16 v[82:85], v[164:167], v[214:217], v[82:85]
	s_setprio 0
	s_setprio 1
	v_mfma_f32_16x16x32_bf16 v[110:113], v[168:171], v[184:187], v[110:113]
	v_mfma_f32_16x16x32_bf16 v[106:109], v[176:179], v[184:187], v[106:109]
	v_mfma_f32_16x16x32_bf16 v[94:97], v[168:171], v[192:195], v[94:97]
	v_mfma_f32_16x16x32_bf16 v[90:93], v[176:179], v[192:195], v[90:93]
	v_mfma_f32_16x16x32_bf16 v[78:81], v[168:171], v[200:203], v[78:81]
	v_mfma_f32_16x16x32_bf16 v[74:77], v[176:179], v[200:203], v[74:77]
	v_mfma_f32_16x16x32_bf16 v[70:73], v[168:171], v[210:213], v[70:73]
	v_mfma_f32_16x16x32_bf16 v[66:69], v[176:179], v[210:213], v[66:69]
	v_mfma_f32_16x16x32_bf16 v[110:113], v[172:175], v[188:191], v[110:113]
	v_mfma_f32_16x16x32_bf16 v[106:109], v[180:183], v[188:191], v[106:109]
	v_mfma_f32_16x16x32_bf16 v[94:97], v[172:175], v[196:199], v[94:97]
	v_mfma_f32_16x16x32_bf16 v[90:93], v[180:183], v[196:199], v[90:93]
	v_mfma_f32_16x16x32_bf16 v[78:81], v[172:175], v[204:207], v[78:81]
	v_mfma_f32_16x16x32_bf16 v[74:77], v[180:183], v[204:207], v[74:77]
	v_mfma_f32_16x16x32_bf16 v[70:73], v[172:175], v[214:217], v[70:73]
	v_mfma_f32_16x16x32_bf16 v[66:69], v[180:183], v[214:217], v[66:69]
	s_setprio 0
	s_barrier
; #define PG8_STAGE(bufoff, gbase, voff) do { _Pragma("unroll") for (int _i = 0; _i < 2; ++_i) \
;         __builtin_amdgcn_global_load_lds((const unsigned*)((const char*)(gbase) + (voff)[_i]), (PG8_LAS unsigned*)(lds + (bufoff) + ldsw + _i * 8192), 16, 0, 0); } while (0)
; #define PG8_LDA(dst, b, h) do { _Pragma("unroll") for (int m = 0; m < 4; ++m) _Pragma("unroll") for (int k = 0; k < 2; ++k) dst[m][k] = *(const PG8_LAS bf16x8*)(lds + PG8_SA(b, h) + aoff + m * 2048 + k * 1024); } while (0)
; #define PG8_MMA(ai, bj, At, Bt) do { __builtin_amdgcn_s_setprio(1); _Pragma("unroll") for (int m = 0; m < 4; ++m) _Pragma("unroll") for (int n = 0; n < 2; ++n) _Pragma("unroll") for (int k = 0; k < 2; ++k) \
;         acc[ai][bj][m][n] = __builtin_amdgcn_mfma_f32_16x16x32_bf16(Bt[n][k], At[m][k], acc[ai][bj][m][n], 0, 0, 0); __builtin_amdgcn_s_setprio(0); } while (0)
; #define PG8_WAIT_V(n) asm volatile("s_waitcnt vmcnt(" #n ")" ::: "memory")
; #define PG8_WAIT_L(n) asm volatile("s_waitcnt lgkmcnt(" #n ")" ::: "memory")
; #define PG8_BAR __builtin_amdgcn_s_barrier()
; #define PG8_SCHED __builtin_amdgcn_sched_barrier(0)
; template <class Epi, class Sched, bool ALIGN_EPI = false, bool SP2 = false>
; __device__ __forceinline__ void gemm_phase(PG8_LAS unsigned char* lds, const Gemm g, const Sched& S, const Epi& E) {
;     ...
;         for (int t = 0; t < nt; t += 2) {
;             const bool last = (t == nt - 2);
;             const char* a1 = cA + (size_t)(t + 1) * kstep;
;             const char* a2 = last ? nA : cA + (size_t)(t + 2) * kstep; const char* b2 = last ? nB : cB + (size_t)(t + 2) * kstep;
;     ...
;             PG8_LDA(At, 1, 1); PG8_STAGE(PG8_SB(1, 0), b3, voffB); PG8_STAGE(PG8_SB(1, 1), b3 + hstepB, voffB); PG8_STAGE(PG8_SA(1, 0), a3, voffA);
;             PG8_WAIT_V(8); PG8_WAIT_L(0); PG8_BAR; PG8_MMA(1, 0, At, B0); PG8_MMA(1, 1, At, B1); PG8_BAR; PG8_SCHED;
	s_add_i32 s34, s58, s36
	v_lshl_add_u64 v[218:219], v[218:219], 0, s[6:7]
	s_mov_b32 m0, s34
	ds_read_b128 v[184:187], v150 offset:49152
	ds_read_b128 v[188:191], v150 offset:50176
	ds_read_b128 v[192:195], v150 offset:51200
	ds_read_b128 v[196:199], v150 offset:52224
	ds_read_b128 v[200:203], v150 offset:53248
	ds_read_b128 v[204:207], v150 offset:54272
	ds_read_b128 v[210:213], v150 offset:55296
	ds_read_b128 v[214:217], v150 offset:56320
	global_load_lds_dwordx4 v[218:219], off
	s_add_i32 m0, s34, 0x2000
	s_add_u32 s30, s30, 0x100080
	v_lshl_add_u64 v[218:219], v[220:221], 0, s[6:7]
	s_addc_u32 s31, s31, 0
	s_add_i32 s34, s59, s36
	global_load_lds_dwordx4 v[218:219], off
	v_lshl_add_u64 v[218:219], s[30:31], 0, v[134:135]
	s_mov_b32 m0, s34
	s_nop 0
	global_load_lds_dwordx4 v[218:219], off
	v_lshl_add_u64 v[218:219], s[30:31], 0, v[130:131]
	s_add_i32 m0, s34, 0x2000
	s_nop 0
	global_load_lds_dwordx4 v[218:219], off
	v_lshl_add_u64 v[218:219], v[222:223], 0, s[6:7]
	s_mov_b32 m0, s43
	s_nop 0
	global_load_lds_dwordx4 v[218:219], off
	v_lshl_add_u64 v[218:219], v[224:225], 0, s[6:7]
	s_mov_b32 m0, s44
	s_nop 0
	global_load_lds_dwordx4 v[218:219], off
	s_waitcnt vmcnt(8)
	s_waitcnt lgkmcnt(0)
	s_barrier
	s_setprio 1
	s_waitcnt lgkmcnt(0)
	v_mfma_f32_16x16x32_bf16 v[62:65], v[152:155], v[184:187], v[62:65]
	v_mfma_f32_16x16x32_bf16 v[58:61], v[160:163], v[184:187], v[58:61]
	v_mfma_f32_16x16x32_bf16 v[54:57], v[152:155], v[192:195], v[54:57]
	v_mfma_f32_16x16x32_bf16 v[50:53], v[160:163], v[192:195], v[50:53]
	v_mfma_f32_16x16x32_bf16 v[38:41], v[152:155], v[200:203], v[38:41]
	v_mfma_f32_16x16x32_bf16 v[34:37], v[160:163], v[200:203], v[34:37]
	v_mfma_f32_16x16x32_bf16 v[22:25], v[152:155], v[210:213], v[22:25]
	v_mfma_f32_16x16x32_bf16 v[18:21], v[160:163], v[210:213], v[18:21]
	v_mfma_f32_16x16x32_bf16 v[62:65], v[156:159], v[188:191], v[62:65]
	v_mfma_f32_16x16x32_bf16 v[58:61], v[164:167], v[188:191], v[58:61]
	v_mfma_f32_16x16x32_bf16 v[54:57], v[156:159], v[196:199], v[54:57]
	v_mfma_f32_16x16x32_bf16 v[50:53], v[164:167], v[196:199], v[50:53]
	v_mfma_f32_16x16x32_bf16 v[38:41], v[156:159], v[204:207], v[38:41]
	v_mfma_f32_16x16x32_bf16 v[34:37], v[164:167], v[204:207], v[34:37]
	v_mfma_f32_16x16x32_bf16 v[22:25], v[156:159], v[214:217], v[22:25]
	v_mfma_f32_16x16x32_bf16 v[18:21], v[164:167], v[214:217], v[18:21]
	s_setprio 0
	s_setprio 1
	v_mfma_f32_16x16x32_bf16 v[46:49], v[168:171], v[184:187], v[46:49]
	v_mfma_f32_16x16x32_bf16 v[42:45], v[176:179], v[184:187], v[42:45]
	v_mfma_f32_16x16x32_bf16 v[30:33], v[168:171], v[192:195], v[30:33]
	v_mfma_f32_16x16x32_bf16 v[26:29], v[176:179], v[192:195], v[26:29]
	v_mfma_f32_16x16x32_bf16 v[14:17], v[168:171], v[200:203], v[14:17]
	v_mfma_f32_16x16x32_bf16 v[10:13], v[176:179], v[200:203], v[10:13]
	v_mfma_f32_16x16x32_bf16 v[6:9], v[168:171], v[210:213], v[6:9]
	v_mfma_f32_16x16x32_bf16 v[2:5], v[176:179], v[210:213], v[2:5]
	v_mfma_f32_16x16x32_bf16 v[46:49], v[172:175], v[188:191], v[46:49]
	v_mfma_f32_16x16x32_bf16 v[42:45], v[180:183], v[188:191], v[42:45]
	v_mfma_f32_16x16x32_bf16 v[30:33], v[172:175], v[196:199], v[30:33]
	v_mfma_f32_16x16x32_bf16 v[26:29], v[180:183], v[196:199], v[26:29]
	v_mfma_f32_16x16x32_bf16 v[14:17], v[172:175], v[204:207], v[14:17]
	v_mfma_f32_16x16x32_bf16 v[10:13], v[180:183], v[204:207], v[10:13]
	v_mfma_f32_16x16x32_bf16 v[6:9], v[172:175], v[214:217], v[6:9]
	v_mfma_f32_16x16x32_bf16 v[2:5], v[180:183], v[214:217], v[2:5]
	s_setprio 0
	s_barrier
	s_add_i32 s57, s57, 2
	s_add_u32 s28, s28, 0x100
	s_addc_u32 s29, s29, 0
	s_add_u32 s55, s55, 0x100
	s_addc_u32 s56, s56, 0
	s_cmp_gt_u32 s57, 61
	s_cbranch_scc1 .Lpeel_exit_23
	.p2align 6

; #define PG8_STAGE(bufoff, gbase, voff) do { _Pragma("unroll") for (int _i = 0; _i < 2; ++_i) \
;         __builtin_amdgcn_global_load_lds((const unsigned*)((const char*)(gbase) + (voff)[_i]), (PG8_LAS unsigned*)(lds + (bufoff) + ldsw + _i * 8192), 16, 0, 0); } while (0)
; #define PG8_WAIT_V(n) asm volatile("s_waitcnt vmcnt(" #n ")" ::: "memory")
; #define PG8_BAR __builtin_amdgcn_s_barrier()
; template <class Epi, class Sched, bool ALIGN_EPI = false, bool SP2 = false>
; __device__ __forceinline__ void gemm_phase(PG8_LAS unsigned char* lds, const Gemm g, const Sched& S, const Epi& E) {
;     const int tid = threadIdx.x, wid = __builtin_amdgcn_readfirstlane(tid >> 6), lane = tid & 63, wr = wid >> 2, wc = wid & 3, fr = lane & 15, fq = lane >> 4;
;     const int K = g.K, nt = K / BK;
;     unsigned voffA[2], voffB[2];
; #pragma unroll
;     for (int i = 0; i < 2; ++i) { int R, C; stage_rc(tid * 16 + i * 8192, R, C); const int Rb = Epi::PERM ? ((R & ~31) + perm32(R & 31)) : R;
;         voffA[i] = (unsigned)(R * g.lda + C) * 2u; voffB[i] = (unsigned)(Rb * g.ldb + C) * 2u; }
;     const size_t kstep = (size_t)(BK * 2);
;     const size_t hstepA = (size_t)HALF * g.lda * 2, hstepB = (size_t)HALF * g.ldb * 2;
;     const size_t tstepA = 2 * hstepA, tstepB = 2 * hstepB;
;     const unsigned ldsw = (unsigned)wid * 1024u;
;     const int aoff = lds_byte(wr * 64 + fr, fq * 8), boff = lds_byte(wc * 32 + fr, fq * 8);
;     ...
;         PG8_WAIT_V(2); PG8_BAR;
;         PG8_STAGE(PG8_SB(1, 0), cB + kstep, voffB); PG8_STAGE(PG8_SA(1, 0), cA + kstep, voffA); PG8_STAGE(PG8_SB(1, 1), cB + hstepB + kstep, voffB);
;         PG8_WAIT_V(6); PG8_BAR;
.LBB0_2381:
	s_lshl_b32 s2, s2, 5
	s_and_b32 s12, s2, 0x60
	s_mov_b64 s[2:3], 0x80
	s_add_i32 m0, s19, 0x18000
	v_lshl_add_u64 v[8:9], v[8:9], 0, s[2:3]
	s_lshl_b32 s9, s8, 13
	s_lshl_b32 s13, s12, 7
	s_waitcnt vmcnt(2)
	s_barrier
	global_load_lds_dwordx4 v[8:9], off
	v_lshl_add_u64 v[6:7], v[6:7], 0, s[2:3]
	s_add_i32 m0, s19, 0x1a000
	s_add_i32 s35, s19, 0x8000
	s_add_i32 s36, s19, 0xa000
	global_load_lds_dwordx4 v[6:7], off
	v_lshl_add_u64 v[2:3], v[2:3], 0, s[2:3]
	s_mov_b32 m0, s35
	s_add_u32 s10, s22, 0x80080
	global_load_lds_dwordx4 v[2:3], off
	v_lshl_add_u64 v[2:3], v[4:5], 0, s[2:3]
	s_mov_b32 m0, s36
	s_addc_u32 s11, s23, 0
	global_load_lds_dwordx4 v[2:3], off
	s_add_i32 m0, s19, 0x1c000
	v_lshl_add_u64 v[2:3], s[10:11], 0, v[134:135]
	global_load_lds_dwordx4 v[2:3], off
	v_lshl_add_u64 v[2:3], s[10:11], 0, v[130:131]
	s_add_i32 m0, s19, 0x1e000
	s_sext_i32_i16 s41, s4
	global_load_lds_dwordx4 v[2:3], off
	v_and_b32_e32 v2, 15, v0
	v_lshlrev_b32_e32 v3, 1, v13
	v_lshlrev_b32_e32 v4, 2, v0
	v_lshlrev_b32_e32 v5, 6, v0
	s_movk_i32 s4, 0x3c0
	v_lshl_or_b32 v1, s8, 6, v2
	v_lshl_or_b32 v2, v2, 6, v3
	v_and_b32_e32 v4, 32, v4
	v_and_or_b32 v3, v5, s4, v3
	v_bitop3_b32 v148, s13, v3, v4 bitop3:0xf6
	v_lshlrev_b32_e32 v3, 9, v0
	v_bitop3_b32 v2, v2, s9, v4 bitop3:0xde
	v_and_b32_e32 v3, 0x30000, v3
	v_lshlrev_b32_e32 v4, 12, v14
	v_or3_b32 v3, v11, v3, v4
	v_add_u32_e32 v138, v3, v12
	v_lshlrev_b32_e32 v3, 5, v10
	s_waitcnt vmcnt(0)
	s_cmpk_lt_u32 s5, 0x100
	v_and_b32_e32 v3, 0x70000, v3
	s_cselect_b64 s[8:9], -1, 0
	v_or3_b32 v3, v11, v3, v4
	s_add_i32 s38, 0, 0x10000
	s_add_i32 s39, 0, 0x14000
	s_ashr_i32 s37, s26, 31
	v_or_b32_e32 v149, s12, v13
	v_mov_b32_e32 v139, v135
	v_add_u32_e32 v140, v3, v12
	v_mov_b32_e32 v141, v135
	v_mov_b64_e32 v[142:143], 0x1b80
	v_mov_b64_e32 v[144:145], 0x1b7f
	v_add_u32_e32 v150, s38, v148
	v_add_u32_e32 v151, s39, v148
	v_add_u32_e32 v152, 0, v2
	s_movk_i32 s40, 0x2c00
	s_barrier
	s_branch .LBB0_2384

; #define PG8_STAGE(bufoff, gbase, voff) do { _Pragma("unroll") for (int _i = 0; _i < 2; ++_i) \
;         __builtin_amdgcn_global_load_lds((const unsigned*)((const char*)(gbase) + (voff)[_i]), (PG8_LAS unsigned*)(lds + (bufoff) + ldsw + _i * 8192), 16, 0, 0); } while (0)
; #define PG8_LDA(dst, b, h) do { _Pragma("unroll") for (int m = 0; m < 4; ++m) _Pragma("unroll") for (int k = 0; k < 2; ++k) dst[m][k] = *(const PG8_LAS bf16x8*)(lds + PG8_SA(b, h) + aoff + m * 2048 + k * 1024); } while (0)
; #define PG8_LDB(dst, b, h) do { _Pragma("unroll") for (int n = 0; n < 2; ++n) _Pragma("unroll") for (int k = 0; k < 2; ++k) dst[n][k] = *(const PG8_LAS bf16x8*)(lds + PG8_SB(b, h) + boff + n * 2048 + k * 1024); } while (0)
; #define PG8_WAIT_V(n) asm volatile("s_waitcnt vmcnt(" #n ")" ::: "memory")
; #define PG8_WAIT_L(n) asm volatile("s_waitcnt lgkmcnt(" #n ")" ::: "memory")
; #define PG8_BAR __builtin_amdgcn_s_barrier()
; #define PG8_SCHED __builtin_amdgcn_sched_barrier(0)
; template <class Epi, class Sched, bool ALIGN_EPI = false, bool SP2 = false>
; __device__ __forceinline__ void gemm_phase(PG8_LAS unsigned char* lds, const Gemm g, const Sched& S, const Epi& E) {
;     ...
;         const char* nA = has_next ? (const char*)g.A + (size_t)nxt.pm * tstepA : cA; const char* nB = has_next ? (const char*)g.Bt + (size_t)nxt.pn * tstepB : cB;
;         for (int t = 0; t < nt; t += 2) {
;             const bool last = (t == nt - 2);
;             const char* a1 = cA + (size_t)(t + 1) * kstep;
;             const char* a2 = last ? nA : cA + (size_t)(t + 2) * kstep; const char* b2 = last ? nB : cB + (size_t)(t + 2) * kstep;
;             const char* a3 = a2 + kstep; const char* b3 = b2 + kstep;
;             if (last && has_next) S.a_ready(nxt);
;             if constexpr (SP2) {
;             PG8_LDB(B0, 0, 0); PG8_LDB(B1, 0, 1); PG8_SCHED; PG8_LDA(At, 0, 0); PG8_STAGE(PG8_SA(1, 1), a1 + hstepA, voffA);
;             PG8_WAIT_V(8); PG8_WAIT_L(0); PG8_BAR; PG8_MMA(0, 0, At, B0); PG8_MMA(0, 1, At, B1); PG8_BAR; PG8_SCHED;
;     ...
; #pragma unroll
;         for (int a = 0; a < 2; ++a)
; #pragma unroll
;             for (int b = 0; b < 2; ++b)
; #pragma unroll
;                 for (int m = 0; m < 4; ++m)
; #pragma unroll
;                     for (int n = 0; n < 2; ++n) acc[a][b][m][n] = (f32x4){0.f, 0.f, 0.f, 0.f};
.LBB0_2386:
	s_ashr_i32 s13, s12, 31
	s_lshl_b64 s[14:15], s[12:13], 20
	s_add_u32 s14, s86, s14
	s_addc_u32 s15, s87, s15
	s_and_b64 s[16:17], s[4:5], exec
	s_cselect_b32 s13, s15, s21
	s_cselect_b32 s42, s14, s20
	s_ashr_i32 s11, s10, 31
	s_lshl_b64 s[16:17], s[10:11], 20
	v_readlane_b32 s24, v254, 0
	v_readlane_b32 s25, v254, 1
	s_add_u32 s16, s24, s16
	s_addc_u32 s17, s25, s17
	s_and_b64 s[24:25], s[4:5], exec
	s_cselect_b32 s11, s17, s23
	s_cselect_b32 s43, s16, s22
	s_add_u32 s20, s20, 0x80080
	s_addc_u32 s21, s21, 0
	s_add_u32 s44, s22, 0x100
	v_mov_b32_e32 v2, 0
	s_addc_u32 s45, s23, 0
	s_mov_b32 s46, -2
	v_mov_b32_e32 v3, v2
	v_mov_b32_e32 v4, v2
	v_mov_b32_e32 v5, v2
	v_mov_b32_e32 v6, v2
	v_mov_b32_e32 v7, v2
	v_mov_b32_e32 v8, v2
	v_mov_b32_e32 v9, v2
	v_mov_b32_e32 v18, v2
	v_mov_b32_e32 v19, v2
	v_mov_b32_e32 v20, v2
	v_mov_b32_e32 v21, v2
	v_mov_b32_e32 v22, v2
	v_mov_b32_e32 v23, v2
	v_mov_b32_e32 v24, v2
	v_mov_b32_e32 v25, v2
	v_mov_b32_e32 v34, v2
	v_mov_b32_e32 v35, v2
	v_mov_b32_e32 v36, v2
	v_mov_b32_e32 v37, v2
	v_mov_b32_e32 v38, v2
	v_mov_b32_e32 v39, v2
	v_mov_b32_e32 v40, v2
	v_mov_b32_e32 v41, v2
	v_mov_b32_e32 v50, v2
	v_mov_b32_e32 v51, v2
	v_mov_b32_e32 v52, v2
	v_mov_b32_e32 v53, v2
	v_mov_b32_e32 v54, v2
	v_mov_b32_e32 v55, v2
	v_mov_b32_e32 v56, v2
	v_mov_b32_e32 v57, v2
	v_mov_b32_e32 v10, v2
	v_mov_b32_e32 v11, v2
	v_mov_b32_e32 v12, v2
	v_mov_b32_e32 v13, v2
	v_mov_b32_e32 v14, v2
	v_mov_b32_e32 v15, v2
	v_mov_b32_e32 v16, v2
	v_mov_b32_e32 v17, v2
	v_mov_b32_e32 v26, v2
	v_mov_b32_e32 v27, v2
	v_mov_b32_e32 v28, v2
	v_mov_b32_e32 v29, v2
	v_mov_b32_e32 v30, v2
	v_mov_b32_e32 v31, v2
	v_mov_b32_e32 v32, v2
	v_mov_b32_e32 v33, v2
	v_mov_b32_e32 v42, v2
	v_mov_b32_e32 v43, v2
	v_mov_b32_e32 v44, v2
	v_mov_b32_e32 v45, v2
	v_mov_b32_e32 v46, v2
	v_mov_b32_e32 v47, v2
	v_mov_b32_e32 v48, v2
	v_mov_b32_e32 v49, v2
	v_mov_b32_e32 v58, v2
	v_mov_b32_e32 v59, v2
	v_mov_b32_e32 v60, v2
	v_mov_b32_e32 v61, v2
	v_mov_b32_e32 v62, v2
	v_mov_b32_e32 v63, v2
	v_mov_b32_e32 v64, v2
	v_mov_b32_e32 v65, v2
	v_mov_b32_e32 v66, v2
	v_mov_b32_e32 v67, v2
	v_mov_b32_e32 v68, v2
	v_mov_b32_e32 v69, v2
	v_mov_b32_e32 v70, v2
	v_mov_b32_e32 v71, v2
	v_mov_b32_e32 v72, v2
	v_mov_b32_e32 v73, v2
	v_mov_b32_e32 v82, v2
	v_mov_b32_e32 v83, v2
	v_mov_b32_e32 v84, v2
	v_mov_b32_e32 v85, v2
	v_mov_b32_e32 v86, v2
	v_mov_b32_e32 v87, v2
	v_mov_b32_e32 v88, v2
	v_mov_b32_e32 v89, v2
	v_mov_b32_e32 v98, v2
	v_mov_b32_e32 v99, v2
	v_mov_b32_e32 v100, v2
	v_mov_b32_e32 v101, v2
	v_mov_b32_e32 v102, v2
	v_mov_b32_e32 v103, v2
	v_mov_b32_e32 v104, v2
	v_mov_b32_e32 v105, v2
	v_mov_b32_e32 v114, v2
	v_mov_b32_e32 v115, v2
	v_mov_b32_e32 v116, v2
	v_mov_b32_e32 v117, v2
	v_mov_b32_e32 v118, v2
	v_mov_b32_e32 v119, v2
	v_mov_b32_e32 v120, v2
	v_mov_b32_e32 v121, v2
	v_mov_b32_e32 v74, v2
	v_mov_b32_e32 v75, v2
	v_mov_b32_e32 v76, v2
	v_mov_b32_e32 v77, v2
	v_mov_b32_e32 v78, v2
	v_mov_b32_e32 v79, v2
	v_mov_b32_e32 v80, v2
	v_mov_b32_e32 v81, v2
	v_mov_b32_e32 v90, v2
	v_mov_b32_e32 v91, v2
	v_mov_b32_e32 v92, v2
	v_mov_b32_e32 v93, v2
	v_mov_b32_e32 v94, v2
	v_mov_b32_e32 v95, v2
	v_mov_b32_e32 v96, v2
	v_mov_b32_e32 v97, v2
	v_mov_b32_e32 v106, v2
	v_mov_b32_e32 v107, v2
	v_mov_b32_e32 v108, v2
	v_mov_b32_e32 v109, v2
	v_mov_b32_e32 v110, v2
	v_mov_b32_e32 v111, v2
	v_mov_b32_e32 v112, v2
	v_mov_b32_e32 v113, v2
	v_mov_b32_e32 v122, v2
	v_mov_b32_e32 v123, v2
	v_mov_b32_e32 v124, v2
	v_mov_b32_e32 v125, v2
	v_mov_b32_e32 v126, v2
	v_mov_b32_e32 v127, v2
	v_mov_b32_e32 v128, v2
	v_mov_b32_e32 v129, v2
	ds_read_b128 v[154:157], v150
	ds_read_b128 v[158:161], v150 offset:1024
	ds_read_b128 v[162:165], v150 offset:2048
	ds_read_b128 v[166:169], v150 offset:3072
	ds_read_b128 v[170:173], v151
	ds_read_b128 v[174:177], v151 offset:1024
	ds_read_b128 v[178:181], v151 offset:2048
	ds_read_b128 v[182:185], v151 offset:3072
	s_add_u32 s22, s20, 0xfff80080
	s_addc_u32 s23, s21, -1
	s_cmp_eq_u32 s46, 28
	s_cselect_b32 s25, s13, s23
	s_cselect_b32 s24, s42, s22
	s_cselect_b32 s23, s11, s45
	s_cselect_b32 s22, s43, s44
	v_lshl_add_u64 v[146:147], s[20:21], 0, v[138:139]
	s_add_i32 m0, s19, 0xc000
	ds_read_b128 v[186:189], v152
	ds_read_b128 v[190:193], v152 offset:1024
	ds_read_b128 v[194:197], v152 offset:2048
	ds_read_b128 v[198:201], v152 offset:3072
	ds_read_b128 v[202:205], v152 offset:4096
	ds_read_b128 v[210:213], v152 offset:5120
	ds_read_b128 v[214:217], v152 offset:6144
	ds_read_b128 v[218:221], v152 offset:7168
	global_load_lds_dwordx4 v[146:147], off
	v_lshl_add_u64 v[146:147], s[20:21], 0, v[140:141]
	s_add_i32 m0, s19, 0xe000
	s_nop 0
	global_load_lds_dwordx4 v[146:147], off
	s_waitcnt vmcnt(16)
	s_waitcnt lgkmcnt(0)
	s_barrier
; #define PG8_STAGE(bufoff, gbase, voff) do { _Pragma("unroll") for (int _i = 0; _i < 2; ++_i) \
;         __builtin_amdgcn_global_load_lds((const unsigned*)((const char*)(gbase) + (voff)[_i]), (PG8_LAS unsigned*)(lds + (bufoff) + ldsw + _i * 8192), 16, 0, 0); } while (0)
; #define PG8_LDA(dst, b, h) do { _Pragma("unroll") for (int m = 0; m < 4; ++m) _Pragma("unroll") for (int k = 0; k < 2; ++k) dst[m][k] = *(const PG8_LAS bf16x8*)(lds + PG8_SA(b, h) + aoff + m * 2048 + k * 1024); } while (0)
; #define PG8_MMA(ai, bj, At, Bt) do { __builtin_amdgcn_s_setprio(1); _Pragma("unroll") for (int m = 0; m < 4; ++m) _Pragma("unroll") for (int n = 0; n < 2; ++n) _Pragma("unroll") for (int k = 0; k < 2; ++k) \
;         acc[ai][bj][m][n] = __builtin_amdgcn_mfma_f32_16x16x32_bf16(Bt[n][k], At[m][k], acc[ai][bj][m][n], 0, 0, 0); __builtin_amdgcn_s_setprio(0); } while (0)
; #define PG8_WAIT_V(n) asm volatile("s_waitcnt vmcnt(" #n ")" ::: "memory")
; #define PG8_WAIT_L(n) asm volatile("s_waitcnt lgkmcnt(" #n ")" ::: "memory")
; #define PG8_BAR __builtin_amdgcn_s_barrier()
; #define PG8_SCHED __builtin_amdgcn_sched_barrier(0)
; template <class Epi, class Sched, bool ALIGN_EPI = false, bool SP2 = false>
; __device__ __forceinline__ void gemm_phase(PG8_LAS unsigned char* lds, const Gemm g, const Sched& S, const Epi& E) {
;     ...
;             PG8_WAIT_V(8); PG8_WAIT_L(0); PG8_BAR; PG8_MMA(0, 0, At, B0); PG8_MMA(0, 1, At, B1); PG8_BAR; PG8_SCHED;
;             PG8_LDA(At, 0, 1); PG8_STAGE(PG8_SB(0, 0), b2, voffB); PG8_STAGE(PG8_SB(0, 1), b2 + hstepB, voffB); PG8_STAGE(PG8_SA(0, 0), a2, voffA);
;             PG8_WAIT_V(8); PG8_WAIT_L(0); PG8_BAR; PG8_MMA(1, 0, At, B0); PG8_MMA(1, 1, At, B1); PG8_BAR; PG8_SCHED;
	s_setprio 1
	s_waitcnt lgkmcnt(0)
	v_mfma_f32_16x16x32_bf16 v[126:129], v[154:157], v[186:189], v[126:129]
	v_mfma_f32_16x16x32_bf16 v[122:125], v[162:165], v[186:189], v[122:125]
	v_mfma_f32_16x16x32_bf16 v[110:113], v[154:157], v[194:197], v[110:113]
	v_mfma_f32_16x16x32_bf16 v[106:109], v[162:165], v[194:197], v[106:109]
	v_mfma_f32_16x16x32_bf16 v[94:97], v[154:157], v[202:205], v[94:97]
	v_mfma_f32_16x16x32_bf16 v[90:93], v[162:165], v[202:205], v[90:93]
	v_mfma_f32_16x16x32_bf16 v[78:81], v[154:157], v[214:217], v[78:81]
	v_mfma_f32_16x16x32_bf16 v[74:77], v[162:165], v[214:217], v[74:77]
	v_mfma_f32_16x16x32_bf16 v[126:129], v[158:161], v[190:193], v[126:129]
	v_mfma_f32_16x16x32_bf16 v[122:125], v[166:169], v[190:193], v[122:125]
	v_mfma_f32_16x16x32_bf16 v[110:113], v[158:161], v[198:201], v[110:113]
	v_mfma_f32_16x16x32_bf16 v[106:109], v[166:169], v[198:201], v[106:109]
	v_mfma_f32_16x16x32_bf16 v[94:97], v[158:161], v[210:213], v[94:97]
	v_mfma_f32_16x16x32_bf16 v[90:93], v[166:169], v[210:213], v[90:93]
	v_mfma_f32_16x16x32_bf16 v[78:81], v[158:161], v[218:221], v[78:81]
	v_mfma_f32_16x16x32_bf16 v[74:77], v[166:169], v[218:221], v[74:77]
	s_setprio 0
	s_setprio 1
	v_mfma_f32_16x16x32_bf16 v[118:121], v[170:173], v[186:189], v[118:121]
	v_mfma_f32_16x16x32_bf16 v[114:117], v[178:181], v[186:189], v[114:117]
	v_mfma_f32_16x16x32_bf16 v[102:105], v[170:173], v[194:197], v[102:105]
	v_mfma_f32_16x16x32_bf16 v[98:101], v[178:181], v[194:197], v[98:101]
	v_mfma_f32_16x16x32_bf16 v[86:89], v[170:173], v[202:205], v[86:89]
	v_mfma_f32_16x16x32_bf16 v[82:85], v[178:181], v[202:205], v[82:85]
	v_mfma_f32_16x16x32_bf16 v[70:73], v[170:173], v[214:217], v[70:73]
	v_mfma_f32_16x16x32_bf16 v[66:69], v[178:181], v[214:217], v[66:69]
	v_mfma_f32_16x16x32_bf16 v[118:121], v[174:177], v[190:193], v[118:121]
	v_mfma_f32_16x16x32_bf16 v[114:117], v[182:185], v[190:193], v[114:117]
	v_mfma_f32_16x16x32_bf16 v[102:105], v[174:177], v[198:201], v[102:105]
	v_mfma_f32_16x16x32_bf16 v[98:101], v[182:185], v[198:201], v[98:101]
	v_mfma_f32_16x16x32_bf16 v[86:89], v[174:177], v[210:213], v[86:89]
	v_mfma_f32_16x16x32_bf16 v[82:85], v[182:185], v[210:213], v[82:85]
	v_mfma_f32_16x16x32_bf16 v[70:73], v[174:177], v[218:221], v[70:73]
	v_mfma_f32_16x16x32_bf16 v[66:69], v[182:185], v[218:221], v[66:69]
	s_setprio 0
	s_barrier
	s_add_i32 s47, s38, s27
	v_lshl_add_u64 v[146:147], s[22:23], 0, v[134:135]
	s_mov_b32 m0, s47
	ds_read_b128 v[186:189], v152 offset:16384
	ds_read_b128 v[190:193], v152 offset:17408
	ds_read_b128 v[194:197], v152 offset:18432
	ds_read_b128 v[198:201], v152 offset:19456
	ds_read_b128 v[202:205], v152 offset:20480
	ds_read_b128 v[210:213], v152 offset:21504
	ds_read_b128 v[214:217], v152 offset:22528
	ds_read_b128 v[218:221], v152 offset:23552
	global_load_lds_dwordx4 v[146:147], off
	s_add_i32 m0, s47, 0x2000
	s_add_u32 s48, s22, 0x80000
	v_lshl_add_u64 v[206:207], s[22:23], 0, v[130:131]
	s_addc_u32 s49, s23, 0
	s_add_i32 s47, s39, s27
	global_load_lds_dwordx4 v[206:207], off
	v_lshl_add_u64 v[222:223], s[48:49], 0, v[134:135]
	s_mov_b32 m0, s47
	v_lshl_add_u64 v[224:225], s[24:25], 0, v[132:133]
	global_load_lds_dwordx4 v[222:223], off
	v_lshl_add_u64 v[222:223], s[48:49], 0, v[130:131]
	s_add_i32 m0, s47, 0x2000
	s_nop 0
	global_load_lds_dwordx4 v[222:223], off
	v_lshl_add_u64 v[222:223], s[24:25], 0, v[136:137]
	s_mov_b32 m0, s19
	s_nop 0
	global_load_lds_dwordx4 v[222:223], off
	s_mov_b32 m0, s30
	s_nop 0
	global_load_lds_dwordx4 v[224:225], off
	s_waitcnt vmcnt(16)
	s_waitcnt lgkmcnt(0)
	s_barrier
	s_setprio 1
	s_waitcnt lgkmcnt(0)
	v_mfma_f32_16x16x32_bf16 v[62:65], v[154:157], v[186:189], v[62:65]
	v_mfma_f32_16x16x32_bf16 v[58:61], v[162:165], v[186:189], v[58:61]
	v_mfma_f32_16x16x32_bf16 v[46:49], v[154:157], v[194:197], v[46:49]
	v_mfma_f32_16x16x32_bf16 v[42:45], v[162:165], v[194:197], v[42:45]
	v_mfma_f32_16x16x32_bf16 v[30:33], v[154:157], v[202:205], v[30:33]
	v_mfma_f32_16x16x32_bf16 v[26:29], v[162:165], v[202:205], v[26:29]
	v_mfma_f32_16x16x32_bf16 v[14:17], v[154:157], v[214:217], v[14:17]
	v_mfma_f32_16x16x32_bf16 v[10:13], v[162:165], v[214:217], v[10:13]
	v_mfma_f32_16x16x32_bf16 v[62:65], v[158:161], v[190:193], v[62:65]
	v_mfma_f32_16x16x32_bf16 v[58:61], v[166:169], v[190:193], v[58:61]
	v_mfma_f32_16x16x32_bf16 v[46:49], v[158:161], v[198:201], v[46:49]
	v_mfma_f32_16x16x32_bf16 v[42:45], v[166:169], v[198:201], v[42:45]
	v_mfma_f32_16x16x32_bf16 v[30:33], v[158:161], v[210:213], v[30:33]
	v_mfma_f32_16x16x32_bf16 v[26:29], v[166:169], v[210:213], v[26:29]
	v_mfma_f32_16x16x32_bf16 v[14:17], v[158:161], v[218:221], v[14:17]
	v_mfma_f32_16x16x32_bf16 v[10:13], v[166:169], v[218:221], v[10:13]
	s_setprio 0
	s_setprio 1
	v_mfma_f32_16x16x32_bf16 v[54:57], v[170:173], v[186:189], v[54:57]
	v_mfma_f32_16x16x32_bf16 v[50:53], v[178:181], v[186:189], v[50:53]
	v_mfma_f32_16x16x32_bf16 v[38:41], v[170:173], v[194:197], v[38:41]
	v_mfma_f32_16x16x32_bf16 v[34:37], v[178:181], v[194:197], v[34:37]
	v_mfma_f32_16x16x32_bf16 v[22:25], v[170:173], v[202:205], v[22:25]
	v_mfma_f32_16x16x32_bf16 v[18:21], v[178:181], v[202:205], v[18:21]
	v_mfma_f32_16x16x32_bf16 v[6:9], v[170:173], v[214:217], v[6:9]
	v_mfma_f32_16x16x32_bf16 v[2:5], v[178:181], v[214:217], v[2:5]
	v_mfma_f32_16x16x32_bf16 v[54:57], v[174:177], v[190:193], v[54:57]
	v_mfma_f32_16x16x32_bf16 v[50:53], v[182:185], v[190:193], v[50:53]
	v_mfma_f32_16x16x32_bf16 v[38:41], v[174:177], v[198:201], v[38:41]
	v_mfma_f32_16x16x32_bf16 v[34:37], v[182:185], v[198:201], v[34:37]
	v_mfma_f32_16x16x32_bf16 v[22:25], v[174:177], v[210:213], v[22:25]
	v_mfma_f32_16x16x32_bf16 v[18:21], v[182:185], v[210:213], v[18:21]
	v_mfma_f32_16x16x32_bf16 v[6:9], v[174:177], v[218:221], v[6:9]
	v_mfma_f32_16x16x32_bf16 v[2:5], v[182:185], v[218:221], v[2:5]
	s_setprio 0
	s_barrier
; #define PG8_STAGE(bufoff, gbase, voff) do { _Pragma("unroll") for (int _i = 0; _i < 2; ++_i) \
;         __builtin_amdgcn_global_load_lds((const unsigned*)((const char*)(gbase) + (voff)[_i]), (PG8_LAS unsigned*)(lds + (bufoff) + ldsw + _i * 8192), 16, 0, 0); } while (0)
; #define PG8_LDA(dst, b, h) do { _Pragma("unroll") for (int m = 0; m < 4; ++m) _Pragma("unroll") for (int k = 0; k < 2; ++k) dst[m][k] = *(const PG8_LAS bf16x8*)(lds + PG8_SA(b, h) + aoff + m * 2048 + k * 1024); } while (0)
; #define PG8_LDB(dst, b, h) do { _Pragma("unroll") for (int n = 0; n < 2; ++n) _Pragma("unroll") for (int k = 0; k < 2; ++k) dst[n][k] = *(const PG8_LAS bf16x8*)(lds + PG8_SB(b, h) + boff + n * 2048 + k * 1024); } while (0)
; #define PG8_MMA(ai, bj, At, Bt) do { __builtin_amdgcn_s_setprio(1); _Pragma("unroll") for (int m = 0; m < 4; ++m) _Pragma("unroll") for (int n = 0; n < 2; ++n) _Pragma("unroll") for (int k = 0; k < 2; ++k) \
;         acc[ai][bj][m][n] = __builtin_amdgcn_mfma_f32_16x16x32_bf16(Bt[n][k], At[m][k], acc[ai][bj][m][n], 0, 0, 0); __builtin_amdgcn_s_setprio(0); } while (0)
; #define PG8_WAIT_V(n) asm volatile("s_waitcnt vmcnt(" #n ")" ::: "memory")
; #define PG8_WAIT_L(n) asm volatile("s_waitcnt lgkmcnt(" #n ")" ::: "memory")
; #define PG8_BAR __builtin_amdgcn_s_barrier()
; #define PG8_SCHED __builtin_amdgcn_sched_barrier(0)
; template <class Epi, class Sched, bool ALIGN_EPI = false, bool SP2 = false>
; __device__ __forceinline__ void gemm_phase(PG8_LAS unsigned char* lds, const Gemm g, const Sched& S, const Epi& E) {
;     ...
;             PG8_LDB(B0, 1, 0); PG8_LDB(B1, 1, 1); PG8_SCHED; PG8_LDA(At, 1, 0); PG8_STAGE(PG8_SA(0, 1), a2 + hstepA, voffA);
;             PG8_WAIT_V(8); PG8_WAIT_L(0); PG8_BAR; PG8_MMA(0, 0, At, B0); PG8_MMA(0, 1, At, B1); PG8_BAR; PG8_SCHED;
	s_add_i32 s47, 0, 0x18000
	v_add_u32_e32 v153, s47, v148
	s_add_i32 s48, 0, 0x1c000
	ds_read_b128 v[154:157], v153
	ds_read_b128 v[158:161], v153 offset:1024
	ds_read_b128 v[162:165], v153 offset:2048
	ds_read_b128 v[166:169], v153 offset:3072
	v_add_u32_e32 v153, s48, v148
	ds_read_b128 v[170:173], v153
	ds_read_b128 v[174:177], v153 offset:1024
	ds_read_b128 v[178:181], v153 offset:2048
	ds_read_b128 v[182:185], v153 offset:3072
	s_add_u32 s24, s24, 0x80000
	s_addc_u32 s25, s25, 0
	s_mov_b32 m0, s31
	v_lshl_add_u64 v[226:227], s[24:25], 0, v[136:137]
	ds_read_b128 v[186:189], v152 offset:32768
	ds_read_b128 v[190:193], v152 offset:33792
	ds_read_b128 v[194:197], v152 offset:34816
	ds_read_b128 v[198:201], v152 offset:35840
	ds_read_b128 v[202:205], v152 offset:36864
	ds_read_b128 v[210:213], v152 offset:37888
	ds_read_b128 v[214:217], v152 offset:38912
	ds_read_b128 v[218:221], v152 offset:39936
	global_load_lds_dwordx4 v[226:227], off
	v_lshl_add_u64 v[226:227], s[24:25], 0, v[132:133]
	s_mov_b32 m0, s33
	s_nop 0
	global_load_lds_dwordx4 v[226:227], off
	s_waitcnt vmcnt(8)
	s_waitcnt lgkmcnt(0)
	s_barrier
	s_setprio 1
	s_waitcnt lgkmcnt(0)
	v_mfma_f32_16x16x32_bf16 v[126:129], v[154:157], v[186:189], v[126:129]
	v_mfma_f32_16x16x32_bf16 v[122:125], v[162:165], v[186:189], v[122:125]
	v_mfma_f32_16x16x32_bf16 v[110:113], v[154:157], v[194:197], v[110:113]
	v_mfma_f32_16x16x32_bf16 v[106:109], v[162:165], v[194:197], v[106:109]
	v_mfma_f32_16x16x32_bf16 v[94:97], v[154:157], v[202:205], v[94:97]
	v_mfma_f32_16x16x32_bf16 v[90:93], v[162:165], v[202:205], v[90:93]
	v_mfma_f32_16x16x32_bf16 v[78:81], v[154:157], v[214:217], v[78:81]
	v_mfma_f32_16x16x32_bf16 v[74:77], v[162:165], v[214:217], v[74:77]
	v_mfma_f32_16x16x32_bf16 v[126:129], v[158:161], v[190:193], v[126:129]
	v_mfma_f32_16x16x32_bf16 v[122:125], v[166:169], v[190:193], v[122:125]
	v_mfma_f32_16x16x32_bf16 v[110:113], v[158:161], v[198:201], v[110:113]
	v_mfma_f32_16x16x32_bf16 v[106:109], v[166:169], v[198:201], v[106:109]
	v_mfma_f32_16x16x32_bf16 v[94:97], v[158:161], v[210:213], v[94:97]
	v_mfma_f32_16x16x32_bf16 v[90:93], v[166:169], v[210:213], v[90:93]
	v_mfma_f32_16x16x32_bf16 v[78:81], v[158:161], v[218:221], v[78:81]
	v_mfma_f32_16x16x32_bf16 v[74:77], v[166:169], v[218:221], v[74:77]
	s_setprio 0
	s_setprio 1
	v_mfma_f32_16x16x32_bf16 v[118:121], v[170:173], v[186:189], v[118:121]
	v_mfma_f32_16x16x32_bf16 v[114:117], v[178:181], v[186:189], v[114:117]
	v_mfma_f32_16x16x32_bf16 v[102:105], v[170:173], v[194:197], v[102:105]
	v_mfma_f32_16x16x32_bf16 v[98:101], v[178:181], v[194:197], v[98:101]
	v_mfma_f32_16x16x32_bf16 v[86:89], v[170:173], v[202:205], v[86:89]
	v_mfma_f32_16x16x32_bf16 v[82:85], v[178:181], v[202:205], v[82:85]
	v_mfma_f32_16x16x32_bf16 v[70:73], v[170:173], v[214:217], v[70:73]
	v_mfma_f32_16x16x32_bf16 v[66:69], v[178:181], v[214:217], v[66:69]
	v_mfma_f32_16x16x32_bf16 v[118:121], v[174:177], v[190:193], v[118:121]
	v_mfma_f32_16x16x32_bf16 v[114:117], v[182:185], v[190:193], v[114:117]
	v_mfma_f32_16x16x32_bf16 v[102:105], v[174:177], v[198:201], v[102:105]
	v_mfma_f32_16x16x32_bf16 v[98:101], v[182:185], v[198:201], v[98:101]
	v_mfma_f32_16x16x32_bf16 v[86:89], v[174:177], v[210:213], v[86:89]
	v_mfma_f32_16x16x32_bf16 v[82:85], v[182:185], v[210:213], v[82:85]
	v_mfma_f32_16x16x32_bf16 v[70:73], v[174:177], v[218:221], v[70:73]
	v_mfma_f32_16x16x32_bf16 v[66:69], v[182:185], v[218:221], v[66:69]
	s_setprio 0
	s_barrier
; #define PG8_STAGE(bufoff, gbase, voff) do { _Pragma("unroll") for (int _i = 0; _i < 2; ++_i) \
;         __builtin_amdgcn_global_load_lds((const unsigned*)((const char*)(gbase) + (voff)[_i]), (PG8_LAS unsigned*)(lds + (bufoff) + ldsw + _i * 8192), 16, 0, 0); } while (0)
; #define PG8_LDA(dst, b, h) do { _Pragma("unroll") for (int m = 0; m < 4; ++m) _Pragma("unroll") for (int k = 0; k < 2; ++k) dst[m][k] = *(const PG8_LAS bf16x8*)(lds + PG8_SA(b, h) + aoff + m * 2048 + k * 1024); } while (0)
; #define PG8_MMA(ai, bj, At, Bt) do { __builtin_amdgcn_s_setprio(1); _Pragma("unroll") for (int m = 0; m < 4; ++m) _Pragma("unroll") for (int n = 0; n < 2; ++n) _Pragma("unroll") for (int k = 0; k < 2; ++k) \
;         acc[ai][bj][m][n] = __builtin_amdgcn_mfma_f32_16x16x32_bf16(Bt[n][k], At[m][k], acc[ai][bj][m][n], 0, 0, 0); __builtin_amdgcn_s_setprio(0); } while (0)
; #define PG8_WAIT_V(n) asm volatile("s_waitcnt vmcnt(" #n ")" ::: "memory")
; #define PG8_WAIT_L(n) asm volatile("s_waitcnt lgkmcnt(" #n ")" ::: "memory")
; #define PG8_BAR __builtin_amdgcn_s_barrier()
; #define PG8_SCHED __builtin_amdgcn_sched_barrier(0)
; template <class Epi, class Sched, bool ALIGN_EPI = false, bool SP2 = false>
; __device__ __forceinline__ void gemm_phase(PG8_LAS unsigned char* lds, const Gemm g, const Sched& S, const Epi& E) {
;     ...
;         for (int t = 0; t < nt; t += 2) {
;             const bool last = (t == nt - 2);
;             const char* a1 = cA + (size_t)(t + 1) * kstep;
;             const char* a2 = last ? nA : cA + (size_t)(t + 2) * kstep; const char* b2 = last ? nB : cB + (size_t)(t + 2) * kstep;
;     ...
;             PG8_LDA(At, 1, 1); PG8_STAGE(PG8_SB(1, 0), b3, voffB); PG8_STAGE(PG8_SB(1, 1), b3 + hstepB, voffB); PG8_STAGE(PG8_SA(1, 0), a3, voffA);
;             PG8_WAIT_V(8); PG8_WAIT_L(0); PG8_BAR; PG8_MMA(1, 0, At, B0); PG8_MMA(1, 1, At, B1); PG8_BAR; PG8_SCHED;
	s_add_i32 s24, s47, s27
	v_lshl_add_u64 v[146:147], v[146:147], 0, s[2:3]
	s_mov_b32 m0, s24
	ds_read_b128 v[186:189], v152 offset:49152
	ds_read_b128 v[190:193], v152 offset:50176
	ds_read_b128 v[194:197], v152 offset:51200
	ds_read_b128 v[198:201], v152 offset:52224
	ds_read_b128 v[202:205], v152 offset:53248
	ds_read_b128 v[210:213], v152 offset:54272
	ds_read_b128 v[214:217], v152 offset:55296
	ds_read_b128 v[218:221], v152 offset:56320
	global_load_lds_dwordx4 v[146:147], off
	s_add_i32 m0, s24, 0x2000
	s_add_u32 s22, s22, 0x80080
	v_lshl_add_u64 v[146:147], v[206:207], 0, s[2:3]
	s_addc_u32 s23, s23, 0
	s_add_i32 s24, s48, s27
	global_load_lds_dwordx4 v[146:147], off
	v_lshl_add_u64 v[146:147], s[22:23], 0, v[134:135]
	s_mov_b32 m0, s24
	s_nop 0
	global_load_lds_dwordx4 v[146:147], off
	v_lshl_add_u64 v[146:147], s[22:23], 0, v[130:131]
	s_add_i32 m0, s24, 0x2000
	s_nop 0
	global_load_lds_dwordx4 v[146:147], off
	v_lshl_add_u64 v[146:147], v[222:223], 0, s[2:3]
	s_mov_b32 m0, s35
	s_nop 0
	global_load_lds_dwordx4 v[146:147], off
	v_lshl_add_u64 v[146:147], v[224:225], 0, s[2:3]
	s_mov_b32 m0, s36
	s_nop 0
	global_load_lds_dwordx4 v[146:147], off
	s_waitcnt vmcnt(8)
	s_waitcnt lgkmcnt(0)
	s_barrier
	s_setprio 1
	s_waitcnt lgkmcnt(0)
	v_mfma_f32_16x16x32_bf16 v[62:65], v[154:157], v[186:189], v[62:65]
	v_mfma_f32_16x16x32_bf16 v[58:61], v[162:165], v[186:189], v[58:61]
	v_mfma_f32_16x16x32_bf16 v[46:49], v[154:157], v[194:197], v[46:49]
	v_mfma_f32_16x16x32_bf16 v[42:45], v[162:165], v[194:197], v[42:45]
	v_mfma_f32_16x16x32_bf16 v[30:33], v[154:157], v[202:205], v[30:33]
	v_mfma_f32_16x16x32_bf16 v[26:29], v[162:165], v[202:205], v[26:29]
	v_mfma_f32_16x16x32_bf16 v[14:17], v[154:157], v[214:217], v[14:17]
	v_mfma_f32_16x16x32_bf16 v[10:13], v[162:165], v[214:217], v[10:13]
	v_mfma_f32_16x16x32_bf16 v[62:65], v[158:161], v[190:193], v[62:65]
	v_mfma_f32_16x16x32_bf16 v[58:61], v[166:169], v[190:193], v[58:61]
	v_mfma_f32_16x16x32_bf16 v[46:49], v[158:161], v[198:201], v[46:49]
	v_mfma_f32_16x16x32_bf16 v[42:45], v[166:169], v[198:201], v[42:45]
	v_mfma_f32_16x16x32_bf16 v[30:33], v[158:161], v[210:213], v[30:33]
	v_mfma_f32_16x16x32_bf16 v[26:29], v[166:169], v[210:213], v[26:29]
	v_mfma_f32_16x16x32_bf16 v[14:17], v[158:161], v[218:221], v[14:17]
	v_mfma_f32_16x16x32_bf16 v[10:13], v[166:169], v[218:221], v[10:13]
	s_setprio 0
	s_setprio 1
	v_mfma_f32_16x16x32_bf16 v[54:57], v[170:173], v[186:189], v[54:57]
	v_mfma_f32_16x16x32_bf16 v[50:53], v[178:181], v[186:189], v[50:53]
	v_mfma_f32_16x16x32_bf16 v[38:41], v[170:173], v[194:197], v[38:41]
	v_mfma_f32_16x16x32_bf16 v[34:37], v[178:181], v[194:197], v[34:37]
	v_mfma_f32_16x16x32_bf16 v[22:25], v[170:173], v[202:205], v[22:25]
	v_mfma_f32_16x16x32_bf16 v[18:21], v[178:181], v[202:205], v[18:21]
	v_mfma_f32_16x16x32_bf16 v[6:9], v[170:173], v[214:217], v[6:9]
	v_mfma_f32_16x16x32_bf16 v[2:5], v[178:181], v[214:217], v[2:5]
	v_mfma_f32_16x16x32_bf16 v[54:57], v[174:177], v[190:193], v[54:57]
	v_mfma_f32_16x16x32_bf16 v[50:53], v[182:185], v[190:193], v[50:53]
	v_mfma_f32_16x16x32_bf16 v[38:41], v[174:177], v[198:201], v[38:41]
	v_mfma_f32_16x16x32_bf16 v[34:37], v[182:185], v[198:201], v[34:37]
	v_mfma_f32_16x16x32_bf16 v[22:25], v[174:177], v[210:213], v[22:25]
	v_mfma_f32_16x16x32_bf16 v[18:21], v[182:185], v[210:213], v[18:21]
	v_mfma_f32_16x16x32_bf16 v[6:9], v[174:177], v[218:221], v[6:9]
	v_mfma_f32_16x16x32_bf16 v[2:5], v[182:185], v[218:221], v[2:5]
	s_setprio 0
	s_barrier
	s_add_i32 s46, s46, 2
	s_add_u32 s20, s20, 0x100
	s_addc_u32 s21, s21, 0
	s_add_u32 s44, s44, 0x100
	s_addc_u32 s45, s45, 0
	s_cmp_gt_u32 s46, 29
	s_cbranch_scc1 .Lpeel_exit_25
	.p2align 6

; #define PG8_STAGE(bufoff, gbase, voff) do { _Pragma("unroll") for (int _i = 0; _i < 2; ++_i) \
;         __builtin_amdgcn_global_load_lds((const unsigned*)((const char*)(gbase) + (voff)[_i]), (PG8_LAS unsigned*)(lds + (bufoff) + ldsw + _i * 8192), 16, 0, 0); } while (0)
; #define PG8_WAIT_V(n) asm volatile("s_waitcnt vmcnt(" #n ")" ::: "memory")
; #define PG8_BAR __builtin_amdgcn_s_barrier()
; template <class Epi, class Sched, bool ALIGN_EPI = false, bool SP2 = false>
; __device__ __forceinline__ void gemm_phase(PG8_LAS unsigned char* lds, const Gemm g, const Sched& S, const Epi& E) {
;     const int tid = threadIdx.x, wid = __builtin_amdgcn_readfirstlane(tid >> 6), lane = tid & 63, wr = wid >> 2, wc = wid & 3, fr = lane & 15, fq = lane >> 4;
;     const int K = g.K, nt = K / BK;
;     unsigned voffA[2], voffB[2];
; #pragma unroll
;     for (int i = 0; i < 2; ++i) { int R, C; stage_rc(tid * 16 + i * 8192, R, C); const int Rb = Epi::PERM ? ((R & ~31) + perm32(R & 31)) : R;
;         voffA[i] = (unsigned)(R * g.lda + C) * 2u; voffB[i] = (unsigned)(Rb * g.ldb + C) * 2u; }
;     const size_t kstep = (size_t)(BK * 2);
;     const size_t hstepA = (size_t)HALF * g.lda * 2, hstepB = (size_t)HALF * g.ldb * 2;
;     const size_t tstepA = 2 * hstepA, tstepB = 2 * hstepB;
;     const unsigned ldsw = (unsigned)wid * 1024u;
;     const int aoff = lds_byte(wr * 64 + fr, fq * 8), boff = lds_byte(wc * 32 + fr, fq * 8);
;     ...
;         PG8_WAIT_V(2); PG8_BAR;
;         PG8_STAGE(PG8_SB(1, 0), cB + kstep, voffB); PG8_STAGE(PG8_SA(1, 0), cA + kstep, voffA); PG8_STAGE(PG8_SB(1, 1), cB + hstepB + kstep, voffB);
;         PG8_WAIT_V(6); PG8_BAR;
.LBB0_2477:
	s_lshl_b32 s6, s6, 5
	s_mov_b64 s[8:9], 0x80
	s_and_b32 s6, s6, 0x60
	s_add_i32 m0, s33, 0x18000
	v_lshl_add_u64 v[8:9], v[8:9], 0, s[8:9]
	s_lshl_b32 s12, s5, 13
	s_lshl_b32 s13, s6, 7
	s_waitcnt vmcnt(2)
	s_barrier
	global_load_lds_dwordx4 v[8:9], off
	v_lshl_add_u64 v[6:7], v[6:7], 0, s[8:9]
	s_add_i32 m0, s33, 0x1a000
	s_add_i32 s38, s33, 0x8000
	s_add_i32 s39, s33, 0xa000
	global_load_lds_dwordx4 v[6:7], off
	v_lshl_add_u64 v[2:3], v[2:3], 0, s[8:9]
	s_mov_b32 m0, s38
	s_add_u32 s10, s24, 0x160080
	global_load_lds_dwordx4 v[2:3], off
	v_lshl_add_u64 v[2:3], v[4:5], 0, s[8:9]
	s_mov_b32 m0, s39
	s_addc_u32 s11, s25, 0
	global_load_lds_dwordx4 v[2:3], off
	s_add_i32 m0, s33, 0x1c000
	v_lshl_add_u64 v[2:3], s[10:11], 0, v[134:135]
	global_load_lds_dwordx4 v[2:3], off
	v_lshl_add_u64 v[2:3], s[10:11], 0, v[130:131]
	s_add_i32 m0, s33, 0x1e000
	v_lshlrev_b32_e32 v4, 2, v0
	global_load_lds_dwordx4 v[2:3], off
	v_and_b32_e32 v2, 15, v0
	v_lshl_or_b32 v1, s5, 6, v2
	v_lshlrev_b32_e32 v3, 1, v10
	v_lshlrev_b32_e32 v5, 6, v0
	s_movk_i32 s5, 0x3c0
	v_lshl_or_b32 v2, v2, 6, v3
	v_and_b32_e32 v4, 32, v4
	v_and_or_b32 v3, v5, s5, v3
	v_bitop3_b32 v146, s13, v3, v4 bitop3:0xf6
	s_waitcnt vmcnt(0)
	s_cmpk_lt_u32 s4, 0x100
	v_add_u16_e32 v3, v11, v12
	v_bitop3_b32 v2, v2, s12, v4 bitop3:0xde
	s_cselect_b64 s[10:11], -1, 0
	v_lshrrev_b16_e32 v3, 1, v3
	s_add_i32 s41, 0, 0x10000
	s_add_i32 s42, 0, 0x14000
	s_sext_i32_i8 s50, s7
	s_ashr_i32 s40, s28, 31
	v_or_b32_e32 v147, s6, v10
	v_add_lshl_u32 v138, v14, v3, 1
	v_mov_b32_e32 v139, v135
	v_add_lshl_u32 v140, v13, v3, 1
	v_mov_b32_e32 v141, v135
	v_mov_b64_e32 v[142:143], 0x500
	v_mov_b64_e32 v[144:145], 0x4ff
	v_add_u32_e32 v148, s41, v146
	v_add_u32_e32 v149, s42, v146
	v_add_u32_e32 v150, 0, v2
	s_mov_b64 s[12:13], 0x80000
	s_mov_b32 s43, 0x80000
	s_mov_b64 s[14:15], 0x90000
	s_mov_b32 s44, 0x90000
	s_mov_b64 s[16:17], 0xa0000
	s_mov_b32 s45, 0xa0000
	s_mov_b64 s[18:19], 0xb0000
	s_mov_b32 s46, 0xb0000
	s_barrier
	s_branch .LBB0_2480

; #define PG8_STAGE(bufoff, gbase, voff) do { _Pragma("unroll") for (int _i = 0; _i < 2; ++_i) \
;         __builtin_amdgcn_global_load_lds((const unsigned*)((const char*)(gbase) + (voff)[_i]), (PG8_LAS unsigned*)(lds + (bufoff) + ldsw + _i * 8192), 16, 0, 0); } while (0)
; #define PG8_LDA(dst, b, h) do { _Pragma("unroll") for (int m = 0; m < 4; ++m) _Pragma("unroll") for (int k = 0; k < 2; ++k) dst[m][k] = *(const PG8_LAS bf16x8*)(lds + PG8_SA(b, h) + aoff + m * 2048 + k * 1024); } while (0)
; #define PG8_LDB(dst, b, h) do { _Pragma("unroll") for (int n = 0; n < 2; ++n) _Pragma("unroll") for (int k = 0; k < 2; ++k) dst[n][k] = *(const PG8_LAS bf16x8*)(lds + PG8_SB(b, h) + boff + n * 2048 + k * 1024); } while (0)
; #define PG8_WAIT_V(n) asm volatile("s_waitcnt vmcnt(" #n ")" ::: "memory")
; #define PG8_WAIT_L(n) asm volatile("s_waitcnt lgkmcnt(" #n ")" ::: "memory")
; template <class Epi, class Sched, bool ALIGN_EPI = false, bool SP2 = false>
; __device__ __forceinline__ void gemm_phase(PG8_LAS unsigned char* lds, const Gemm g, const Sched& S, const Epi& E) {
;     ...
;         const char* nA = has_next ? (const char*)g.A + (size_t)nxt.pm * tstepA : cA; const char* nB = has_next ? (const char*)g.Bt + (size_t)nxt.pn * tstepB : cB;
;         for (int t = 0; t < nt; t += 2) {
;             const bool last = (t == nt - 2);
;             const char* a1 = cA + (size_t)(t + 1) * kstep;
;             const char* a2 = last ? nA : cA + (size_t)(t + 2) * kstep; const char* b2 = last ? nB : cB + (size_t)(t + 2) * kstep;
;             const char* a3 = a2 + kstep; const char* b3 = b2 + kstep;
;             if (last && has_next) S.a_ready(nxt);
;             if constexpr (SP2) {
;             PG8_LDB(B0, 0, 0); PG8_LDB(B1, 0, 1); PG8_SCHED; PG8_LDA(At, 0, 0); PG8_STAGE(PG8_SA(1, 1), a1 + hstepA, voffA);
;             PG8_WAIT_V(8); PG8_WAIT_L(0); PG8_BAR; PG8_MMA(0, 0, At, B0); PG8_MMA(0, 1, At, B1); PG8_BAR; PG8_SCHED;
;             PG8_LDA(At, 0, 1); PG8_STAGE(PG8_SB(0, 0), b2, voffB); PG8_STAGE(PG8_SB(0, 1), b2 + hstepB, voffB); PG8_STAGE(PG8_SA(0, 0), a2, voffA);
;     ...
; #pragma unroll
;         for (int a = 0; a < 2; ++a)
; #pragma unroll
;             for (int b = 0; b < 2; ++b)
; #pragma unroll
;                 for (int m = 0; m < 4; ++m)
; #pragma unroll
;                     for (int n = 0; n < 2; ++n) acc[a][b][m][n] = (f32x4){0.f, 0.f, 0.f, 0.f};
.LBB0_2486:
	s_add_u32 s22, s22, 0x160080
	s_addc_u32 s23, s23, 0
	s_add_u32 s51, s24, 0x100
	v_mov_b32_e32 v2, 0
	s_addc_u32 s52, s25, 0
	s_mov_b32 s53, -2
	v_mov_b32_e32 v3, v2
	v_mov_b32_e32 v4, v2
	v_mov_b32_e32 v5, v2
	v_mov_b32_e32 v6, v2
	v_mov_b32_e32 v7, v2
	v_mov_b32_e32 v8, v2
	v_mov_b32_e32 v9, v2
	v_mov_b32_e32 v10, v2
	v_mov_b32_e32 v11, v2
	v_mov_b32_e32 v12, v2
	v_mov_b32_e32 v13, v2
	v_mov_b32_e32 v14, v2
	v_mov_b32_e32 v15, v2
	v_mov_b32_e32 v16, v2
	v_mov_b32_e32 v17, v2
	v_mov_b32_e32 v26, v2
	v_mov_b32_e32 v27, v2
	v_mov_b32_e32 v28, v2
	v_mov_b32_e32 v29, v2
	v_mov_b32_e32 v30, v2
	v_mov_b32_e32 v31, v2
	v_mov_b32_e32 v32, v2
	v_mov_b32_e32 v33, v2
	v_mov_b32_e32 v42, v2
	v_mov_b32_e32 v43, v2
	v_mov_b32_e32 v44, v2
	v_mov_b32_e32 v45, v2
	v_mov_b32_e32 v46, v2
	v_mov_b32_e32 v47, v2
	v_mov_b32_e32 v48, v2
	v_mov_b32_e32 v49, v2
	v_mov_b32_e32 v18, v2
	v_mov_b32_e32 v19, v2
	v_mov_b32_e32 v20, v2
	v_mov_b32_e32 v21, v2
	v_mov_b32_e32 v22, v2
	v_mov_b32_e32 v23, v2
	v_mov_b32_e32 v24, v2
	v_mov_b32_e32 v25, v2
	v_mov_b32_e32 v34, v2
	v_mov_b32_e32 v35, v2
	v_mov_b32_e32 v36, v2
	v_mov_b32_e32 v37, v2
	v_mov_b32_e32 v38, v2
	v_mov_b32_e32 v39, v2
	v_mov_b32_e32 v40, v2
	v_mov_b32_e32 v41, v2
	v_mov_b32_e32 v50, v2
	v_mov_b32_e32 v51, v2
	v_mov_b32_e32 v52, v2
	v_mov_b32_e32 v53, v2
	v_mov_b32_e32 v54, v2
	v_mov_b32_e32 v55, v2
	v_mov_b32_e32 v56, v2
	v_mov_b32_e32 v57, v2
	v_mov_b32_e32 v58, v2
	v_mov_b32_e32 v59, v2
	v_mov_b32_e32 v60, v2
	v_mov_b32_e32 v61, v2
	v_mov_b32_e32 v62, v2
	v_mov_b32_e32 v63, v2
	v_mov_b32_e32 v64, v2
	v_mov_b32_e32 v65, v2
	v_mov_b32_e32 v66, v2
	v_mov_b32_e32 v67, v2
	v_mov_b32_e32 v68, v2
	v_mov_b32_e32 v69, v2
	v_mov_b32_e32 v70, v2
	v_mov_b32_e32 v71, v2
	v_mov_b32_e32 v72, v2
	v_mov_b32_e32 v73, v2
	v_mov_b32_e32 v74, v2
	v_mov_b32_e32 v75, v2
	v_mov_b32_e32 v76, v2
	v_mov_b32_e32 v77, v2
	v_mov_b32_e32 v78, v2
	v_mov_b32_e32 v79, v2
	v_mov_b32_e32 v80, v2
	v_mov_b32_e32 v81, v2
	v_mov_b32_e32 v90, v2
	v_mov_b32_e32 v91, v2
	v_mov_b32_e32 v92, v2
	v_mov_b32_e32 v93, v2
	v_mov_b32_e32 v94, v2
	v_mov_b32_e32 v95, v2
	v_mov_b32_e32 v96, v2
	v_mov_b32_e32 v97, v2
	v_mov_b32_e32 v106, v2
	v_mov_b32_e32 v107, v2
	v_mov_b32_e32 v108, v2
	v_mov_b32_e32 v109, v2
	v_mov_b32_e32 v110, v2
	v_mov_b32_e32 v111, v2
	v_mov_b32_e32 v112, v2
	v_mov_b32_e32 v113, v2
	v_mov_b32_e32 v82, v2
	v_mov_b32_e32 v83, v2
	v_mov_b32_e32 v84, v2
	v_mov_b32_e32 v85, v2
	v_mov_b32_e32 v86, v2
	v_mov_b32_e32 v87, v2
	v_mov_b32_e32 v88, v2
	v_mov_b32_e32 v89, v2
	v_mov_b32_e32 v98, v2
	v_mov_b32_e32 v99, v2
	v_mov_b32_e32 v100, v2
	v_mov_b32_e32 v101, v2
	v_mov_b32_e32 v102, v2
	v_mov_b32_e32 v103, v2
	v_mov_b32_e32 v104, v2
	v_mov_b32_e32 v105, v2
	v_mov_b32_e32 v114, v2
	v_mov_b32_e32 v115, v2
	v_mov_b32_e32 v116, v2
	v_mov_b32_e32 v117, v2
	v_mov_b32_e32 v118, v2
	v_mov_b32_e32 v119, v2
	v_mov_b32_e32 v120, v2
	v_mov_b32_e32 v121, v2
	v_mov_b32_e32 v122, v2
	v_mov_b32_e32 v123, v2
	v_mov_b32_e32 v124, v2
	v_mov_b32_e32 v125, v2
	v_mov_b32_e32 v126, v2
	v_mov_b32_e32 v127, v2
	v_mov_b32_e32 v128, v2
	v_mov_b32_e32 v129, v2
	ds_read_b128 v[152:155], v148
	ds_read_b128 v[156:159], v148 offset:1024
	ds_read_b128 v[160:163], v148 offset:2048
	ds_read_b128 v[164:167], v148 offset:3072
	ds_read_b128 v[168:171], v149
	ds_read_b128 v[172:175], v149 offset:1024
	ds_read_b128 v[176:179], v149 offset:2048
	ds_read_b128 v[180:183], v149 offset:3072
	s_add_u32 s24, s22, 0xffea0080
	s_addc_u32 s25, s23, -1
	s_cmpk_eq_i32 s53, 0x54
	s_cselect_b32 s27, s7, s25
	s_cselect_b32 s26, s6, s24
	s_cselect_b32 s25, s21, s52
	s_cselect_b32 s24, s20, s51
	v_lshl_add_u64 v[218:219], s[22:23], 0, v[138:139]
	s_add_i32 m0, s33, 0xc000
	ds_read_b128 v[184:187], v150
	ds_read_b128 v[188:191], v150 offset:1024
	ds_read_b128 v[192:195], v150 offset:2048
	ds_read_b128 v[196:199], v150 offset:3072
	ds_read_b128 v[200:203], v150 offset:4096
	ds_read_b128 v[204:207], v150 offset:5120
	ds_read_b128 v[210:213], v150 offset:6144
	ds_read_b128 v[214:217], v150 offset:7168
	global_load_lds_dwordx4 v[218:219], off
	v_lshl_add_u64 v[218:219], s[22:23], 0, v[140:141]
	s_add_i32 m0, s33, 0xe000
	s_nop 0
	global_load_lds_dwordx4 v[218:219], off
	s_waitcnt vmcnt(24)
	s_waitcnt lgkmcnt(0)
	s_barrier
	s_setprio 1
	s_waitcnt lgkmcnt(0)
	v_mfma_f32_16x16x32_bf16 v[126:129], v[152:155], v[184:187], v[126:129]
	v_mfma_f32_16x16x32_bf16 v[122:125], v[160:163], v[184:187], v[122:125]
	v_mfma_f32_16x16x32_bf16 v[118:121], v[152:155], v[192:195], v[118:121]
	v_mfma_f32_16x16x32_bf16 v[114:117], v[160:163], v[192:195], v[114:117]
	v_mfma_f32_16x16x32_bf16 v[102:105], v[152:155], v[200:203], v[102:105]
	v_mfma_f32_16x16x32_bf16 v[98:101], v[160:163], v[200:203], v[98:101]
	v_mfma_f32_16x16x32_bf16 v[86:89], v[152:155], v[210:213], v[86:89]
	v_mfma_f32_16x16x32_bf16 v[82:85], v[160:163], v[210:213], v[82:85]
	v_mfma_f32_16x16x32_bf16 v[126:129], v[156:159], v[188:191], v[126:129]
	v_mfma_f32_16x16x32_bf16 v[122:125], v[164:167], v[188:191], v[122:125]
	v_mfma_f32_16x16x32_bf16 v[118:121], v[156:159], v[196:199], v[118:121]
	v_mfma_f32_16x16x32_bf16 v[114:117], v[164:167], v[196:199], v[114:117]
	v_mfma_f32_16x16x32_bf16 v[102:105], v[156:159], v[204:207], v[102:105]
	v_mfma_f32_16x16x32_bf16 v[98:101], v[164:167], v[204:207], v[98:101]
	v_mfma_f32_16x16x32_bf16 v[86:89], v[156:159], v[214:217], v[86:89]
	v_mfma_f32_16x16x32_bf16 v[82:85], v[164:167], v[214:217], v[82:85]
	s_setprio 0
	s_setprio 1
	v_mfma_f32_16x16x32_bf16 v[110:113], v[168:171], v[184:187], v[110:113]
	v_mfma_f32_16x16x32_bf16 v[106:109], v[176:179], v[184:187], v[106:109]
	v_mfma_f32_16x16x32_bf16 v[94:97], v[168:171], v[192:195], v[94:97]
	v_mfma_f32_16x16x32_bf16 v[90:93], v[176:179], v[192:195], v[90:93]
	v_mfma_f32_16x16x32_bf16 v[78:81], v[168:171], v[200:203], v[78:81]
	v_mfma_f32_16x16x32_bf16 v[74:77], v[176:179], v[200:203], v[74:77]
	v_mfma_f32_16x16x32_bf16 v[70:73], v[168:171], v[210:213], v[70:73]
	v_mfma_f32_16x16x32_bf16 v[66:69], v[176:179], v[210:213], v[66:69]
	v_mfma_f32_16x16x32_bf16 v[110:113], v[172:175], v[188:191], v[110:113]
	v_mfma_f32_16x16x32_bf16 v[106:109], v[180:183], v[188:191], v[106:109]
	v_mfma_f32_16x16x32_bf16 v[94:97], v[172:175], v[196:199], v[94:97]
	v_mfma_f32_16x16x32_bf16 v[90:93], v[180:183], v[196:199], v[90:93]
	v_mfma_f32_16x16x32_bf16 v[78:81], v[172:175], v[204:207], v[78:81]
	v_mfma_f32_16x16x32_bf16 v[74:77], v[180:183], v[204:207], v[74:77]
	v_mfma_f32_16x16x32_bf16 v[70:73], v[172:175], v[214:217], v[70:73]
	v_mfma_f32_16x16x32_bf16 v[66:69], v[180:183], v[214:217], v[66:69]
	s_setprio 0
	s_barrier
; #define PG8_STAGE(bufoff, gbase, voff) do { _Pragma("unroll") for (int _i = 0; _i < 2; ++_i) \
;         __builtin_amdgcn_global_load_lds((const unsigned*)((const char*)(gbase) + (voff)[_i]), (PG8_LAS unsigned*)(lds + (bufoff) + ldsw + _i * 8192), 16, 0, 0); } while (0)
; #define PG8_LDA(dst, b, h) do { _Pragma("unroll") for (int m = 0; m < 4; ++m) _Pragma("unroll") for (int k = 0; k < 2; ++k) dst[m][k] = *(const PG8_LAS bf16x8*)(lds + PG8_SA(b, h) + aoff + m * 2048 + k * 1024); } while (0)
; #define PG8_LDB(dst, b, h) do { _Pragma("unroll") for (int n = 0; n < 2; ++n) _Pragma("unroll") for (int k = 0; k < 2; ++k) dst[n][k] = *(const PG8_LAS bf16x8*)(lds + PG8_SB(b, h) + boff + n * 2048 + k * 1024); } while (0)
; #define PG8_MMA(ai, bj, At, Bt) do { __builtin_amdgcn_s_setprio(1); _Pragma("unroll") for (int m = 0; m < 4; ++m) _Pragma("unroll") for (int n = 0; n < 2; ++n) _Pragma("unroll") for (int k = 0; k < 2; ++k) \
;         acc[ai][bj][m][n] = __builtin_amdgcn_mfma_f32_16x16x32_bf16(Bt[n][k], At[m][k], acc[ai][bj][m][n], 0, 0, 0); __builtin_amdgcn_s_setprio(0); } while (0)
; #define PG8_WAIT_V(n) asm volatile("s_waitcnt vmcnt(" #n ")" ::: "memory")
; #define PG8_WAIT_L(n) asm volatile("s_waitcnt lgkmcnt(" #n ")" ::: "memory")
; #define PG8_BAR __builtin_amdgcn_s_barrier()
; #define PG8_SCHED __builtin_amdgcn_sched_barrier(0)
; template <class Epi, class Sched, bool ALIGN_EPI = false, bool SP2 = false>
; __device__ __forceinline__ void gemm_phase(PG8_LAS unsigned char* lds, const Gemm g, const Sched& S, const Epi& E) {
;     ...
;             PG8_LDA(At, 0, 1); PG8_STAGE(PG8_SB(0, 0), b2, voffB); PG8_STAGE(PG8_SB(0, 1), b2 + hstepB, voffB); PG8_STAGE(PG8_SA(0, 0), a2, voffA);
;             PG8_WAIT_V(8); PG8_WAIT_L(0); PG8_BAR; PG8_MMA(1, 0, At, B0); PG8_MMA(1, 1, At, B1); PG8_BAR; PG8_SCHED;
;             PG8_LDB(B0, 1, 0); PG8_LDB(B1, 1, 1); PG8_SCHED; PG8_LDA(At, 1, 0); PG8_STAGE(PG8_SA(0, 1), a2 + hstepA, voffA);
;             PG8_WAIT_V(8); PG8_WAIT_L(0); PG8_BAR; PG8_MMA(0, 0, At, B0); PG8_MMA(0, 1, At, B1); PG8_BAR; PG8_SCHED;
	s_add_i32 s54, s41, s29
	v_lshl_add_u64 v[218:219], s[24:25], 0, v[134:135]
	s_mov_b32 m0, s54
	ds_read_b128 v[184:187], v150 offset:16384
	ds_read_b128 v[188:191], v150 offset:17408
	ds_read_b128 v[192:195], v150 offset:18432
	ds_read_b128 v[196:199], v150 offset:19456
	ds_read_b128 v[200:203], v150 offset:20480
	ds_read_b128 v[204:207], v150 offset:21504
	ds_read_b128 v[210:213], v150 offset:22528
	ds_read_b128 v[214:217], v150 offset:23552
	global_load_lds_dwordx4 v[218:219], off
	s_add_i32 m0, s54, 0x2000
	s_add_u32 s54, s24, 0x160000
	v_lshl_add_u64 v[220:221], s[24:25], 0, v[130:131]
	s_addc_u32 s55, s25, 0
	s_add_i32 s56, s42, s29
	global_load_lds_dwordx4 v[220:221], off
	v_lshl_add_u64 v[222:223], s[54:55], 0, v[134:135]
	s_mov_b32 m0, s56
	v_lshl_add_u64 v[224:225], s[26:27], 0, v[132:133]
	global_load_lds_dwordx4 v[222:223], off
	v_lshl_add_u64 v[222:223], s[54:55], 0, v[130:131]
	s_add_i32 m0, s56, 0x2000
	s_nop 0
	global_load_lds_dwordx4 v[222:223], off
	v_lshl_add_u64 v[222:223], s[26:27], 0, v[136:137]
	s_mov_b32 m0, s33
	s_nop 0
	global_load_lds_dwordx4 v[222:223], off
	s_mov_b32 m0, s34
	s_nop 0
	global_load_lds_dwordx4 v[224:225], off
	s_waitcnt vmcnt(24)
	s_waitcnt lgkmcnt(0)
	s_barrier
	s_setprio 1
	s_waitcnt lgkmcnt(0)
	v_mfma_f32_16x16x32_bf16 v[62:65], v[152:155], v[184:187], v[62:65]
	v_mfma_f32_16x16x32_bf16 v[58:61], v[160:163], v[184:187], v[58:61]
	v_mfma_f32_16x16x32_bf16 v[54:57], v[152:155], v[192:195], v[54:57]
	v_mfma_f32_16x16x32_bf16 v[50:53], v[160:163], v[192:195], v[50:53]
	v_mfma_f32_16x16x32_bf16 v[38:41], v[152:155], v[200:203], v[38:41]
	v_mfma_f32_16x16x32_bf16 v[34:37], v[160:163], v[200:203], v[34:37]
	v_mfma_f32_16x16x32_bf16 v[22:25], v[152:155], v[210:213], v[22:25]
	v_mfma_f32_16x16x32_bf16 v[18:21], v[160:163], v[210:213], v[18:21]
	v_mfma_f32_16x16x32_bf16 v[62:65], v[156:159], v[188:191], v[62:65]
	v_mfma_f32_16x16x32_bf16 v[58:61], v[164:167], v[188:191], v[58:61]
	v_mfma_f32_16x16x32_bf16 v[54:57], v[156:159], v[196:199], v[54:57]
	v_mfma_f32_16x16x32_bf16 v[50:53], v[164:167], v[196:199], v[50:53]
	v_mfma_f32_16x16x32_bf16 v[38:41], v[156:159], v[204:207], v[38:41]
	v_mfma_f32_16x16x32_bf16 v[34:37], v[164:167], v[204:207], v[34:37]
	v_mfma_f32_16x16x32_bf16 v[22:25], v[156:159], v[214:217], v[22:25]
	v_mfma_f32_16x16x32_bf16 v[18:21], v[164:167], v[214:217], v[18:21]
	s_setprio 0
	s_setprio 1
	v_mfma_f32_16x16x32_bf16 v[46:49], v[168:171], v[184:187], v[46:49]
	v_mfma_f32_16x16x32_bf16 v[42:45], v[176:179], v[184:187], v[42:45]
	v_mfma_f32_16x16x32_bf16 v[30:33], v[168:171], v[192:195], v[30:33]
	v_mfma_f32_16x16x32_bf16 v[26:29], v[176:179], v[192:195], v[26:29]
	v_mfma_f32_16x16x32_bf16 v[14:17], v[168:171], v[200:203], v[14:17]
	v_mfma_f32_16x16x32_bf16 v[10:13], v[176:179], v[200:203], v[10:13]
	v_mfma_f32_16x16x32_bf16 v[6:9], v[168:171], v[210:213], v[6:9]
	v_mfma_f32_16x16x32_bf16 v[2:5], v[176:179], v[210:213], v[2:5]
	v_mfma_f32_16x16x32_bf16 v[46:49], v[172:175], v[188:191], v[46:49]
	v_mfma_f32_16x16x32_bf16 v[42:45], v[180:183], v[188:191], v[42:45]
	v_mfma_f32_16x16x32_bf16 v[30:33], v[172:175], v[196:199], v[30:33]
	v_mfma_f32_16x16x32_bf16 v[26:29], v[180:183], v[196:199], v[26:29]
	v_mfma_f32_16x16x32_bf16 v[14:17], v[172:175], v[204:207], v[14:17]
	v_mfma_f32_16x16x32_bf16 v[10:13], v[180:183], v[204:207], v[10:13]
	v_mfma_f32_16x16x32_bf16 v[6:9], v[172:175], v[214:217], v[6:9]
	v_mfma_f32_16x16x32_bf16 v[2:5], v[180:183], v[214:217], v[2:5]
	s_setprio 0
	s_barrier
	s_add_i32 s54, 0, 0x18000
	v_add_u32_e32 v151, s54, v146
	s_add_i32 s55, 0, 0x1c000
	ds_read_b128 v[152:155], v151
	ds_read_b128 v[156:159], v151 offset:1024
	ds_read_b128 v[160:163], v151 offset:2048
	ds_read_b128 v[164:167], v151 offset:3072
	v_add_u32_e32 v151, s55, v146
	ds_read_b128 v[168:171], v151
	ds_read_b128 v[172:175], v151 offset:1024
	ds_read_b128 v[176:179], v151 offset:2048
	ds_read_b128 v[180:183], v151 offset:3072
	s_add_u32 s26, s26, 0x160000
	s_addc_u32 s27, s27, 0
	s_mov_b32 m0, s35
	v_lshl_add_u64 v[226:227], s[26:27], 0, v[136:137]
	ds_read_b128 v[184:187], v150 offset:32768
	ds_read_b128 v[188:191], v150 offset:33792
	ds_read_b128 v[192:195], v150 offset:34816
	ds_read_b128 v[196:199], v150 offset:35840
	ds_read_b128 v[200:203], v150 offset:36864
	ds_read_b128 v[204:207], v150 offset:37888
	ds_read_b128 v[210:213], v150 offset:38912
	ds_read_b128 v[214:217], v150 offset:39936
	global_load_lds_dwordx4 v[226:227], off
	v_lshl_add_u64 v[226:227], s[26:27], 0, v[132:133]
	s_mov_b32 m0, s36
	s_nop 0
	global_load_lds_dwordx4 v[226:227], off
	s_waitcnt vmcnt(8)
	s_waitcnt lgkmcnt(0)
	s_barrier
; #define PG8_STAGE(bufoff, gbase, voff) do { _Pragma("unroll") for (int _i = 0; _i < 2; ++_i) \
;         __builtin_amdgcn_global_load_lds((const unsigned*)((const char*)(gbase) + (voff)[_i]), (PG8_LAS unsigned*)(lds + (bufoff) + ldsw + _i * 8192), 16, 0, 0); } while (0)
; #define PG8_LDA(dst, b, h) do { _Pragma("unroll") for (int m = 0; m < 4; ++m) _Pragma("unroll") for (int k = 0; k < 2; ++k) dst[m][k] = *(const PG8_LAS bf16x8*)(lds + PG8_SA(b, h) + aoff + m * 2048 + k * 1024); } while (0)
; #define PG8_MMA(ai, bj, At, Bt) do { __builtin_amdgcn_s_setprio(1); _Pragma("unroll") for (int m = 0; m < 4; ++m) _Pragma("unroll") for (int n = 0; n < 2; ++n) _Pragma("unroll") for (int k = 0; k < 2; ++k) \
;         acc[ai][bj][m][n] = __builtin_amdgcn_mfma_f32_16x16x32_bf16(Bt[n][k], At[m][k], acc[ai][bj][m][n], 0, 0, 0); __builtin_amdgcn_s_setprio(0); } while (0)
; #define PG8_WAIT_V(n) asm volatile("s_waitcnt vmcnt(" #n ")" ::: "memory")
; #define PG8_WAIT_L(n) asm volatile("s_waitcnt lgkmcnt(" #n ")" ::: "memory")
; #define PG8_BAR __builtin_amdgcn_s_barrier()
; #define PG8_SCHED __builtin_amdgcn_sched_barrier(0)
; template <class Epi, class Sched, bool ALIGN_EPI = false, bool SP2 = false>
; __device__ __forceinline__ void gemm_phase(PG8_LAS unsigned char* lds, const Gemm g, const Sched& S, const Epi& E) {
;     ...
;         for (int t = 0; t < nt; t += 2) {
;             const bool last = (t == nt - 2);
;             const char* a1 = cA + (size_t)(t + 1) * kstep;
;             const char* a2 = last ? nA : cA + (size_t)(t + 2) * kstep; const char* b2 = last ? nB : cB + (size_t)(t + 2) * kstep;
;     ...
;             PG8_WAIT_V(8); PG8_WAIT_L(0); PG8_BAR; PG8_MMA(0, 0, At, B0); PG8_MMA(0, 1, At, B1); PG8_BAR; PG8_SCHED;
;             PG8_LDA(At, 1, 1); PG8_STAGE(PG8_SB(1, 0), b3, voffB); PG8_STAGE(PG8_SB(1, 1), b3 + hstepB, voffB); PG8_STAGE(PG8_SA(1, 0), a3, voffA);
;             PG8_WAIT_V(8); PG8_WAIT_L(0); PG8_BAR; PG8_MMA(1, 0, At, B0); PG8_MMA(1, 1, At, B1); PG8_BAR; PG8_SCHED;
	s_setprio 1
	s_waitcnt lgkmcnt(0)
	v_mfma_f32_16x16x32_bf16 v[126:129], v[152:155], v[184:187], v[126:129]
	v_mfma_f32_16x16x32_bf16 v[122:125], v[160:163], v[184:187], v[122:125]
	v_mfma_f32_16x16x32_bf16 v[118:121], v[152:155], v[192:195], v[118:121]
	v_mfma_f32_16x16x32_bf16 v[114:117], v[160:163], v[192:195], v[114:117]
	v_mfma_f32_16x16x32_bf16 v[102:105], v[152:155], v[200:203], v[102:105]
	v_mfma_f32_16x16x32_bf16 v[98:101], v[160:163], v[200:203], v[98:101]
	v_mfma_f32_16x16x32_bf16 v[86:89], v[152:155], v[210:213], v[86:89]
	v_mfma_f32_16x16x32_bf16 v[82:85], v[160:163], v[210:213], v[82:85]
	v_mfma_f32_16x16x32_bf16 v[126:129], v[156:159], v[188:191], v[126:129]
	v_mfma_f32_16x16x32_bf16 v[122:125], v[164:167], v[188:191], v[122:125]
	v_mfma_f32_16x16x32_bf16 v[118:121], v[156:159], v[196:199], v[118:121]
	v_mfma_f32_16x16x32_bf16 v[114:117], v[164:167], v[196:199], v[114:117]
	v_mfma_f32_16x16x32_bf16 v[102:105], v[156:159], v[204:207], v[102:105]
	v_mfma_f32_16x16x32_bf16 v[98:101], v[164:167], v[204:207], v[98:101]
	v_mfma_f32_16x16x32_bf16 v[86:89], v[156:159], v[214:217], v[86:89]
	v_mfma_f32_16x16x32_bf16 v[82:85], v[164:167], v[214:217], v[82:85]
	s_setprio 0
	s_setprio 1
	v_mfma_f32_16x16x32_bf16 v[110:113], v[168:171], v[184:187], v[110:113]
	v_mfma_f32_16x16x32_bf16 v[106:109], v[176:179], v[184:187], v[106:109]
	v_mfma_f32_16x16x32_bf16 v[94:97], v[168:171], v[192:195], v[94:97]
	v_mfma_f32_16x16x32_bf16 v[90:93], v[176:179], v[192:195], v[90:93]
	v_mfma_f32_16x16x32_bf16 v[78:81], v[168:171], v[200:203], v[78:81]
	v_mfma_f32_16x16x32_bf16 v[74:77], v[176:179], v[200:203], v[74:77]
	v_mfma_f32_16x16x32_bf16 v[70:73], v[168:171], v[210:213], v[70:73]
	v_mfma_f32_16x16x32_bf16 v[66:69], v[176:179], v[210:213], v[66:69]
	v_mfma_f32_16x16x32_bf16 v[110:113], v[172:175], v[188:191], v[110:113]
	v_mfma_f32_16x16x32_bf16 v[106:109], v[180:183], v[188:191], v[106:109]
	v_mfma_f32_16x16x32_bf16 v[94:97], v[172:175], v[196:199], v[94:97]
	v_mfma_f32_16x16x32_bf16 v[90:93], v[180:183], v[196:199], v[90:93]
	v_mfma_f32_16x16x32_bf16 v[78:81], v[172:175], v[204:207], v[78:81]
	v_mfma_f32_16x16x32_bf16 v[74:77], v[180:183], v[204:207], v[74:77]
	v_mfma_f32_16x16x32_bf16 v[70:73], v[172:175], v[214:217], v[70:73]
	v_mfma_f32_16x16x32_bf16 v[66:69], v[180:183], v[214:217], v[66:69]
	s_setprio 0
	s_barrier
	s_add_i32 s26, s54, s29
	v_lshl_add_u64 v[218:219], v[218:219], 0, s[8:9]
	s_mov_b32 m0, s26
	ds_read_b128 v[184:187], v150 offset:49152
	ds_read_b128 v[188:191], v150 offset:50176
	ds_read_b128 v[192:195], v150 offset:51200
	ds_read_b128 v[196:199], v150 offset:52224
	ds_read_b128 v[200:203], v150 offset:53248
	ds_read_b128 v[204:207], v150 offset:54272
	ds_read_b128 v[210:213], v150 offset:55296
	ds_read_b128 v[214:217], v150 offset:56320
	global_load_lds_dwordx4 v[218:219], off
	s_add_i32 m0, s26, 0x2000
	s_add_u32 s24, s24, 0x160080
	v_lshl_add_u64 v[218:219], v[220:221], 0, s[8:9]
	s_addc_u32 s25, s25, 0
	s_add_i32 s26, s55, s29
	global_load_lds_dwordx4 v[218:219], off
	v_lshl_add_u64 v[218:219], s[24:25], 0, v[134:135]
	s_mov_b32 m0, s26
	s_nop 0
	global_load_lds_dwordx4 v[218:219], off
	v_lshl_add_u64 v[218:219], s[24:25], 0, v[130:131]
	s_add_i32 m0, s26, 0x2000
	s_nop 0
	global_load_lds_dwordx4 v[218:219], off
	v_lshl_add_u64 v[218:219], v[222:223], 0, s[8:9]
	s_mov_b32 m0, s38
	s_nop 0
	global_load_lds_dwordx4 v[218:219], off
	v_lshl_add_u64 v[218:219], v[224:225], 0, s[8:9]
	s_mov_b32 m0, s39
	s_nop 0
	global_load_lds_dwordx4 v[218:219], off
	s_waitcnt vmcnt(8)
	s_waitcnt lgkmcnt(0)
	s_barrier
	s_setprio 1
	s_waitcnt lgkmcnt(0)
	v_mfma_f32_16x16x32_bf16 v[62:65], v[152:155], v[184:187], v[62:65]
	v_mfma_f32_16x16x32_bf16 v[58:61], v[160:163], v[184:187], v[58:61]
	v_mfma_f32_16x16x32_bf16 v[54:57], v[152:155], v[192:195], v[54:57]
	v_mfma_f32_16x16x32_bf16 v[50:53], v[160:163], v[192:195], v[50:53]
	v_mfma_f32_16x16x32_bf16 v[38:41], v[152:155], v[200:203], v[38:41]
	v_mfma_f32_16x16x32_bf16 v[34:37], v[160:163], v[200:203], v[34:37]
	v_mfma_f32_16x16x32_bf16 v[22:25], v[152:155], v[210:213], v[22:25]
	v_mfma_f32_16x16x32_bf16 v[18:21], v[160:163], v[210:213], v[18:21]
	v_mfma_f32_16x16x32_bf16 v[62:65], v[156:159], v[188:191], v[62:65]
	v_mfma_f32_16x16x32_bf16 v[58:61], v[164:167], v[188:191], v[58:61]
	v_mfma_f32_16x16x32_bf16 v[54:57], v[156:159], v[196:199], v[54:57]
	v_mfma_f32_16x16x32_bf16 v[50:53], v[164:167], v[196:199], v[50:53]
	v_mfma_f32_16x16x32_bf16 v[38:41], v[156:159], v[204:207], v[38:41]
	v_mfma_f32_16x16x32_bf16 v[34:37], v[164:167], v[204:207], v[34:37]
	v_mfma_f32_16x16x32_bf16 v[22:25], v[156:159], v[214:217], v[22:25]
	v_mfma_f32_16x16x32_bf16 v[18:21], v[164:167], v[214:217], v[18:21]
	s_setprio 0
	s_setprio 1
	v_mfma_f32_16x16x32_bf16 v[46:49], v[168:171], v[184:187], v[46:49]
	v_mfma_f32_16x16x32_bf16 v[42:45], v[176:179], v[184:187], v[42:45]
	v_mfma_f32_16x16x32_bf16 v[30:33], v[168:171], v[192:195], v[30:33]
	v_mfma_f32_16x16x32_bf16 v[26:29], v[176:179], v[192:195], v[26:29]
	v_mfma_f32_16x16x32_bf16 v[14:17], v[168:171], v[200:203], v[14:17]
	v_mfma_f32_16x16x32_bf16 v[10:13], v[176:179], v[200:203], v[10:13]
	v_mfma_f32_16x16x32_bf16 v[6:9], v[168:171], v[210:213], v[6:9]
	v_mfma_f32_16x16x32_bf16 v[2:5], v[176:179], v[210:213], v[2:5]
	v_mfma_f32_16x16x32_bf16 v[46:49], v[172:175], v[188:191], v[46:49]
	v_mfma_f32_16x16x32_bf16 v[42:45], v[180:183], v[188:191], v[42:45]
	v_mfma_f32_16x16x32_bf16 v[30:33], v[172:175], v[196:199], v[30:33]
	v_mfma_f32_16x16x32_bf16 v[26:29], v[180:183], v[196:199], v[26:29]
	v_mfma_f32_16x16x32_bf16 v[14:17], v[172:175], v[204:207], v[14:17]
	v_mfma_f32_16x16x32_bf16 v[10:13], v[180:183], v[204:207], v[10:13]
	v_mfma_f32_16x16x32_bf16 v[6:9], v[172:175], v[214:217], v[6:9]
	v_mfma_f32_16x16x32_bf16 v[2:5], v[180:183], v[214:217], v[2:5]
	s_setprio 0
	s_barrier
	s_add_i32 s53, s53, 2
	s_add_u32 s22, s22, 0x100
	s_addc_u32 s23, s23, 0
	s_add_u32 s51, s51, 0x100
	s_addc_u32 s52, s52, 0
	s_cmpk_gt_u32 s53, 0x55
	s_cbranch_scc1 .Lpeel_exit_26
	.p2align 6

; #define PG8_STAGE(bufoff, gbase, voff) do { _Pragma("unroll") for (int _i = 0; _i < 2; ++_i) \
;         __builtin_amdgcn_global_load_lds((const unsigned*)((const char*)(gbase) + (voff)[_i]), (PG8_LAS unsigned*)(lds + (bufoff) + ldsw + _i * 8192), 16, 0, 0); } while (0)
; #define PG8_WAIT_V(n) asm volatile("s_waitcnt vmcnt(" #n ")" ::: "memory")
; #define PG8_BAR __builtin_amdgcn_s_barrier()
; template <class Epi, class Sched, bool ALIGN_EPI = false, bool SP2 = false>
; __device__ __forceinline__ void gemm_phase(PG8_LAS unsigned char* lds, const Gemm g, const Sched& S, const Epi& E) {
;     const int tid = threadIdx.x, wid = __builtin_amdgcn_readfirstlane(tid >> 6), lane = tid & 63, wr = wid >> 2, wc = wid & 3, fr = lane & 15, fq = lane >> 4;
;     const int K = g.K, nt = K / BK;
;     unsigned voffA[2], voffB[2];
; #pragma unroll
;     for (int i = 0; i < 2; ++i) { int R, C; stage_rc(tid * 16 + i * 8192, R, C); const int Rb = Epi::PERM ? ((R & ~31) + perm32(R & 31)) : R;
;         voffA[i] = (unsigned)(R * g.lda + C) * 2u; voffB[i] = (unsigned)(Rb * g.ldb + C) * 2u; }
;     const size_t kstep = (size_t)(BK * 2);
;     const size_t hstepA = (size_t)HALF * g.lda * 2, hstepB = (size_t)HALF * g.ldb * 2;
;     const size_t tstepA = 2 * hstepA, tstepB = 2 * hstepB;
;     const unsigned ldsw = (unsigned)wid * 1024u;
;     const int aoff = lds_byte(wr * 64 + fr, fq * 8), boff = lds_byte(wc * 32 + fr, fq * 8);
;     ...
;         PG8_WAIT_V(2); PG8_BAR;
;         PG8_STAGE(PG8_SB(1, 0), cB + kstep, voffB); PG8_STAGE(PG8_SA(1, 0), cA + kstep, voffA); PG8_STAGE(PG8_SB(1, 1), cB + hstepB + kstep, voffB);
;         PG8_WAIT_V(6); PG8_BAR;
.LBB0_2609:
	s_lshl_b32 s8, s8, 5
	s_and_b32 s14, s8, 0x60
	s_mov_b64 s[8:9], 0x80
	s_add_i32 m0, s21, 0x18000
	v_lshl_add_u64 v[8:9], v[8:9], 0, s[8:9]
	s_lshl_b32 s11, s10, 13
	s_lshl_b32 s15, s14, 7
	s_waitcnt vmcnt(2)
	s_barrier
	global_load_lds_dwordx4 v[8:9], off
	v_lshl_add_u64 v[6:7], v[6:7], 0, s[8:9]
	s_add_i32 m0, s21, 0x1a000
	s_add_i32 s37, s21, 0x8000
	s_add_i32 s38, s21, 0xa000
	global_load_lds_dwordx4 v[6:7], off
	v_lshl_add_u64 v[2:3], v[2:3], 0, s[8:9]
	s_mov_b32 m0, s37
	s_add_u32 s12, s24, 0x80080
	global_load_lds_dwordx4 v[2:3], off
	v_lshl_add_u64 v[2:3], v[4:5], 0, s[8:9]
	s_mov_b32 m0, s38
	s_addc_u32 s13, s25, 0
	global_load_lds_dwordx4 v[2:3], off
	s_add_i32 m0, s21, 0x1c000
	v_lshl_add_u64 v[2:3], s[12:13], 0, v[150:151]
	global_load_lds_dwordx4 v[2:3], off
	v_lshl_add_u64 v[2:3], s[12:13], 0, v[146:147]
	s_add_i32 m0, s21, 0x1e000
	s_sext_i32_i8 s43, s4
	global_load_lds_dwordx4 v[2:3], off
	v_and_b32_e32 v2, 15, v0
	v_lshlrev_b32_e32 v3, 1, v13
	v_lshlrev_b32_e32 v4, 2, v0
	v_lshlrev_b32_e32 v5, 6, v0
	s_movk_i32 s4, 0x3c0
	v_lshl_or_b32 v1, s10, 6, v2
	v_lshl_or_b32 v2, v2, 6, v3
	v_and_b32_e32 v4, 32, v4
	v_and_or_b32 v3, v5, s4, v3
	v_bitop3_b32 v164, s15, v3, v4 bitop3:0xf6
	v_lshlrev_b32_e32 v3, 9, v0
	v_bitop3_b32 v2, v2, s11, v4 bitop3:0xde
	v_and_b32_e32 v3, 0x30000, v3
	v_lshlrev_b32_e32 v4, 12, v14
	v_or3_b32 v3, v11, v3, v4
	v_add_u32_e32 v154, v3, v12
	v_lshlrev_b32_e32 v3, 5, v10
	s_waitcnt vmcnt(0)
	s_cmpk_lt_u32 s5, 0x100
	v_and_b32_e32 v3, 0x70000, v3
	s_cselect_b64 s[10:11], -1, 0
	v_or3_b32 v3, v11, v3, v4
	s_add_i32 s40, 0, 0x10000
	s_add_i32 s41, 0, 0x14000
	s_waitcnt lgkmcnt(0)
	s_ashr_i32 s39, s28, 31
	v_or_b32_e32 v165, s14, v13
	v_mov_b32_e32 v155, v151
	v_add_u32_e32 v156, v3, v12
	v_mov_b32_e32 v157, v151
	v_mov_b64_e32 v[158:159], 0xf00
	v_mov_b64_e32 v[160:161], 0xeff
	v_add_u32_e32 v166, s40, v164
	v_add_u32_e32 v167, s41, v164
	v_add_u32_e32 v168, 0, v2
	s_movk_i32 s42, 0x3000
	s_barrier
	s_branch .LBB0_2612

; #define PG8_STAGE(bufoff, gbase, voff) do { _Pragma("unroll") for (int _i = 0; _i < 2; ++_i) \
;         __builtin_amdgcn_global_load_lds((const unsigned*)((const char*)(gbase) + (voff)[_i]), (PG8_LAS unsigned*)(lds + (bufoff) + ldsw + _i * 8192), 16, 0, 0); } while (0)
; #define PG8_LDA(dst, b, h) do { _Pragma("unroll") for (int m = 0; m < 4; ++m) _Pragma("unroll") for (int k = 0; k < 2; ++k) dst[m][k] = *(const PG8_LAS bf16x8*)(lds + PG8_SA(b, h) + aoff + m * 2048 + k * 1024); } while (0)
; #define PG8_LDB(dst, b, h) do { _Pragma("unroll") for (int n = 0; n < 2; ++n) _Pragma("unroll") for (int k = 0; k < 2; ++k) dst[n][k] = *(const PG8_LAS bf16x8*)(lds + PG8_SB(b, h) + boff + n * 2048 + k * 1024); } while (0)
; #define PG8_WAIT_V(n) asm volatile("s_waitcnt vmcnt(" #n ")" ::: "memory")
; #define PG8_WAIT_L(n) asm volatile("s_waitcnt lgkmcnt(" #n ")" ::: "memory")
; #define PG8_BAR __builtin_amdgcn_s_barrier()
; #define PG8_SCHED __builtin_amdgcn_sched_barrier(0)
; template <class Epi, class Sched, bool ALIGN_EPI = false, bool SP2 = false>
; __device__ __forceinline__ void gemm_phase(PG8_LAS unsigned char* lds, const Gemm g, const Sched& S, const Epi& E) {
;     ...
;         const char* nA = has_next ? (const char*)g.A + (size_t)nxt.pm * tstepA : cA; const char* nB = has_next ? (const char*)g.Bt + (size_t)nxt.pn * tstepB : cB;
;         for (int t = 0; t < nt; t += 2) {
;             const bool last = (t == nt - 2);
;             const char* a1 = cA + (size_t)(t + 1) * kstep;
;             const char* a2 = last ? nA : cA + (size_t)(t + 2) * kstep; const char* b2 = last ? nB : cB + (size_t)(t + 2) * kstep;
;             const char* a3 = a2 + kstep; const char* b3 = b2 + kstep;
;             if (last && has_next) S.a_ready(nxt);
;             if constexpr (SP2) {
;             PG8_LDB(B0, 0, 0); PG8_LDB(B1, 0, 1); PG8_SCHED; PG8_LDA(At, 0, 0); PG8_STAGE(PG8_SA(1, 1), a1 + hstepA, voffA);
;             PG8_WAIT_V(8); PG8_WAIT_L(0); PG8_BAR; PG8_MMA(0, 0, At, B0); PG8_MMA(0, 1, At, B1); PG8_BAR; PG8_SCHED;
;     ...
; #pragma unroll
;         for (int a = 0; a < 2; ++a)
; #pragma unroll
;             for (int b = 0; b < 2; ++b)
; #pragma unroll
;                 for (int m = 0; m < 4; ++m)
; #pragma unroll
;                     for (int n = 0; n < 2; ++n) acc[a][b][m][n] = (f32x4){0.f, 0.f, 0.f, 0.f};
.LBB0_2614:
	s_ashr_i32 s15, s14, 31
	s_lshl_b64 s[16:17], s[14:15], 20
	s_add_u32 s16, s86, s16
	s_addc_u32 s17, s87, s17
	s_and_b64 s[18:19], s[4:5], exec
	s_cselect_b32 s15, s17, s23
	s_cselect_b32 s44, s16, s22
	s_ashr_i32 s13, s12, 31
	s_lshl_b64 s[18:19], s[12:13], 20
	s_add_u32 s18, s62, s18
	s_addc_u32 s19, s63, s19
	s_and_b64 s[26:27], s[4:5], exec
	s_cselect_b32 s13, s19, s25
	s_cselect_b32 s45, s18, s24
	s_add_u32 s22, s22, 0x80080
	s_addc_u32 s23, s23, 0
	s_add_u32 s46, s24, 0x100
	v_mov_b32_e32 v2, 0
	s_addc_u32 s47, s25, 0
	s_mov_b32 s48, -2
	v_mov_b32_e32 v3, v2
	v_mov_b32_e32 v4, v2
	v_mov_b32_e32 v5, v2
	v_mov_b32_e32 v6, v2
	v_mov_b32_e32 v7, v2
	v_mov_b32_e32 v8, v2
	v_mov_b32_e32 v9, v2
	v_mov_b32_e32 v10, v2
	v_mov_b32_e32 v11, v2
	v_mov_b32_e32 v12, v2
	v_mov_b32_e32 v13, v2
	v_mov_b32_e32 v18, v2
	v_mov_b32_e32 v19, v2
	v_mov_b32_e32 v20, v2
	v_mov_b32_e32 v21, v2
	v_mov_b32_e32 v26, v2
	v_mov_b32_e32 v27, v2
	v_mov_b32_e32 v28, v2
	v_mov_b32_e32 v29, v2
	v_mov_b32_e32 v34, v2
	v_mov_b32_e32 v35, v2
	v_mov_b32_e32 v36, v2
	v_mov_b32_e32 v37, v2
	v_mov_b32_e32 v42, v2
	v_mov_b32_e32 v43, v2
	v_mov_b32_e32 v44, v2
	v_mov_b32_e32 v45, v2
	v_mov_b32_e32 v50, v2
	v_mov_b32_e32 v51, v2
	v_mov_b32_e32 v52, v2
	v_mov_b32_e32 v53, v2
	v_mov_b32_e32 v14, v2
	v_mov_b32_e32 v15, v2
	v_mov_b32_e32 v16, v2
	v_mov_b32_e32 v17, v2
	v_mov_b32_e32 v22, v2
	v_mov_b32_e32 v23, v2
	v_mov_b32_e32 v24, v2
	v_mov_b32_e32 v25, v2
	v_mov_b32_e32 v30, v2
	v_mov_b32_e32 v31, v2
	v_mov_b32_e32 v32, v2
	v_mov_b32_e32 v33, v2
	v_mov_b32_e32 v38, v2
	v_mov_b32_e32 v39, v2
	v_mov_b32_e32 v40, v2
	v_mov_b32_e32 v41, v2
	v_mov_b32_e32 v46, v2
	v_mov_b32_e32 v47, v2
	v_mov_b32_e32 v48, v2
	v_mov_b32_e32 v49, v2
	v_mov_b32_e32 v54, v2
	v_mov_b32_e32 v55, v2
	v_mov_b32_e32 v56, v2
	v_mov_b32_e32 v57, v2
	v_mov_b32_e32 v58, v2
	v_mov_b32_e32 v59, v2
	v_mov_b32_e32 v60, v2
	v_mov_b32_e32 v61, v2
	v_mov_b32_e32 v62, v2
	v_mov_b32_e32 v63, v2
	v_mov_b32_e32 v64, v2
	v_mov_b32_e32 v65, v2
	v_mov_b32_e32 v66, v2
	v_mov_b32_e32 v67, v2
	v_mov_b32_e32 v68, v2
	v_mov_b32_e32 v69, v2
	v_mov_b32_e32 v70, v2
	v_mov_b32_e32 v71, v2
	v_mov_b32_e32 v72, v2
	v_mov_b32_e32 v73, v2
	v_mov_b32_e32 v74, v2
	v_mov_b32_e32 v75, v2
	v_mov_b32_e32 v76, v2
	v_mov_b32_e32 v77, v2
	v_mov_b32_e32 v78, v2
	v_mov_b32_e32 v79, v2
	v_mov_b32_e32 v80, v2
	v_mov_b32_e32 v81, v2
	v_mov_b32_e32 v82, v2
	v_mov_b32_e32 v83, v2
	v_mov_b32_e32 v84, v2
	v_mov_b32_e32 v85, v2
	v_mov_b32_e32 v90, v2
	v_mov_b32_e32 v91, v2
	v_mov_b32_e32 v92, v2
	v_mov_b32_e32 v93, v2
	v_mov_b32_e32 v98, v2
	v_mov_b32_e32 v99, v2
	v_mov_b32_e32 v100, v2
	v_mov_b32_e32 v101, v2
	v_mov_b32_e32 v106, v2
	v_mov_b32_e32 v107, v2
	v_mov_b32_e32 v108, v2
	v_mov_b32_e32 v109, v2
	v_mov_b32_e32 v86, v2
	v_mov_b32_e32 v87, v2
	v_mov_b32_e32 v88, v2
	v_mov_b32_e32 v89, v2
	v_mov_b32_e32 v94, v2
	v_mov_b32_e32 v95, v2
	v_mov_b32_e32 v96, v2
	v_mov_b32_e32 v97, v2
	v_mov_b32_e32 v102, v2
	v_mov_b32_e32 v103, v2
	v_mov_b32_e32 v104, v2
	v_mov_b32_e32 v105, v2
	v_mov_b32_e32 v110, v2
	v_mov_b32_e32 v111, v2
	v_mov_b32_e32 v112, v2
	v_mov_b32_e32 v113, v2
	v_mov_b32_e32 v114, v2
	v_mov_b32_e32 v115, v2
	v_mov_b32_e32 v116, v2
	v_mov_b32_e32 v117, v2
	v_mov_b32_e32 v118, v2
	v_mov_b32_e32 v119, v2
	v_mov_b32_e32 v120, v2
	v_mov_b32_e32 v121, v2
	v_mov_b32_e32 v122, v2
	v_mov_b32_e32 v123, v2
	v_mov_b32_e32 v124, v2
	v_mov_b32_e32 v125, v2
	v_mov_b32_e32 v126, v2
	v_mov_b32_e32 v127, v2
	v_mov_b32_e32 v128, v2
	v_mov_b32_e32 v129, v2
	ds_read_b128 v[130:133], v166
	ds_read_b128 v[134:137], v166 offset:1024
	ds_read_b128 v[138:141], v166 offset:2048
	ds_read_b128 v[142:145], v166 offset:3072
	ds_read_b128 v[170:173], v167
	ds_read_b128 v[174:177], v167 offset:1024
	ds_read_b128 v[178:181], v167 offset:2048
	ds_read_b128 v[182:185], v167 offset:3072
	s_add_u32 s24, s22, 0xfff80080
	s_addc_u32 s25, s23, -1
	s_cmp_eq_u32 s48, 28
	s_cselect_b32 s27, s15, s25
	s_cselect_b32 s26, s44, s24
	s_cselect_b32 s25, s13, s47
	s_cselect_b32 s24, s45, s46
	v_lshl_add_u64 v[162:163], s[22:23], 0, v[154:155]
	s_add_i32 m0, s21, 0xc000
	ds_read_b128 v[186:189], v168
	ds_read_b128 v[190:193], v168 offset:1024
	ds_read_b128 v[194:197], v168 offset:2048
	ds_read_b128 v[198:201], v168 offset:3072
	ds_read_b128 v[202:205], v168 offset:4096
	ds_read_b128 v[210:213], v168 offset:5120
	ds_read_b128 v[214:217], v168 offset:6144
	ds_read_b128 v[218:221], v168 offset:7168
	global_load_lds_dwordx4 v[162:163], off
	v_lshl_add_u64 v[162:163], s[22:23], 0, v[156:157]
	s_add_i32 m0, s21, 0xe000
	s_nop 0
	global_load_lds_dwordx4 v[162:163], off
	s_waitcnt vmcnt(28)
	s_waitcnt lgkmcnt(0)
	s_barrier
; #define PG8_STAGE(bufoff, gbase, voff) do { _Pragma("unroll") for (int _i = 0; _i < 2; ++_i) \
;         __builtin_amdgcn_global_load_lds((const unsigned*)((const char*)(gbase) + (voff)[_i]), (PG8_LAS unsigned*)(lds + (bufoff) + ldsw + _i * 8192), 16, 0, 0); } while (0)
; #define PG8_LDA(dst, b, h) do { _Pragma("unroll") for (int m = 0; m < 4; ++m) _Pragma("unroll") for (int k = 0; k < 2; ++k) dst[m][k] = *(const PG8_LAS bf16x8*)(lds + PG8_SA(b, h) + aoff + m * 2048 + k * 1024); } while (0)
; #define PG8_MMA(ai, bj, At, Bt) do { __builtin_amdgcn_s_setprio(1); _Pragma("unroll") for (int m = 0; m < 4; ++m) _Pragma("unroll") for (int n = 0; n < 2; ++n) _Pragma("unroll") for (int k = 0; k < 2; ++k) \
;         acc[ai][bj][m][n] = __builtin_amdgcn_mfma_f32_16x16x32_bf16(Bt[n][k], At[m][k], acc[ai][bj][m][n], 0, 0, 0); __builtin_amdgcn_s_setprio(0); } while (0)
; #define PG8_WAIT_V(n) asm volatile("s_waitcnt vmcnt(" #n ")" ::: "memory")
; #define PG8_WAIT_L(n) asm volatile("s_waitcnt lgkmcnt(" #n ")" ::: "memory")
; #define PG8_BAR __builtin_amdgcn_s_barrier()
; #define PG8_SCHED __builtin_amdgcn_sched_barrier(0)
; template <class Epi, class Sched, bool ALIGN_EPI = false, bool SP2 = false>
; __device__ __forceinline__ void gemm_phase(PG8_LAS unsigned char* lds, const Gemm g, const Sched& S, const Epi& E) {
;     ...
;             PG8_WAIT_V(8); PG8_WAIT_L(0); PG8_BAR; PG8_MMA(0, 0, At, B0); PG8_MMA(0, 1, At, B1); PG8_BAR; PG8_SCHED;
;             PG8_LDA(At, 0, 1); PG8_STAGE(PG8_SB(0, 0), b2, voffB); PG8_STAGE(PG8_SB(0, 1), b2 + hstepB, voffB); PG8_STAGE(PG8_SA(0, 0), a2, voffA);
;             PG8_WAIT_V(8); PG8_WAIT_L(0); PG8_BAR; PG8_MMA(1, 0, At, B0); PG8_MMA(1, 1, At, B1); PG8_BAR; PG8_SCHED;
	s_setprio 1
	s_waitcnt lgkmcnt(0)
	v_mfma_f32_16x16x32_bf16 v[126:129], v[130:133], v[186:189], v[126:129]
	v_mfma_f32_16x16x32_bf16 v[122:125], v[138:141], v[186:189], v[122:125]
	v_mfma_f32_16x16x32_bf16 v[118:121], v[130:133], v[194:197], v[118:121]
	v_mfma_f32_16x16x32_bf16 v[114:117], v[138:141], v[194:197], v[114:117]
	v_mfma_f32_16x16x32_bf16 v[110:113], v[130:133], v[202:205], v[110:113]
	v_mfma_f32_16x16x32_bf16 v[102:105], v[138:141], v[202:205], v[102:105]
	v_mfma_f32_16x16x32_bf16 v[94:97], v[130:133], v[214:217], v[94:97]
	v_mfma_f32_16x16x32_bf16 v[86:89], v[138:141], v[214:217], v[86:89]
	v_mfma_f32_16x16x32_bf16 v[126:129], v[134:137], v[190:193], v[126:129]
	v_mfma_f32_16x16x32_bf16 v[122:125], v[142:145], v[190:193], v[122:125]
	v_mfma_f32_16x16x32_bf16 v[118:121], v[134:137], v[198:201], v[118:121]
	v_mfma_f32_16x16x32_bf16 v[114:117], v[142:145], v[198:201], v[114:117]
	v_mfma_f32_16x16x32_bf16 v[110:113], v[134:137], v[210:213], v[110:113]
	v_mfma_f32_16x16x32_bf16 v[102:105], v[142:145], v[210:213], v[102:105]
	v_mfma_f32_16x16x32_bf16 v[94:97], v[134:137], v[218:221], v[94:97]
	v_mfma_f32_16x16x32_bf16 v[86:89], v[142:145], v[218:221], v[86:89]
	s_setprio 0
	s_setprio 1
	v_mfma_f32_16x16x32_bf16 v[106:109], v[170:173], v[186:189], v[106:109]
	v_mfma_f32_16x16x32_bf16 v[98:101], v[178:181], v[186:189], v[98:101]
	v_mfma_f32_16x16x32_bf16 v[90:93], v[170:173], v[194:197], v[90:93]
	v_mfma_f32_16x16x32_bf16 v[82:85], v[178:181], v[194:197], v[82:85]
	v_mfma_f32_16x16x32_bf16 v[78:81], v[170:173], v[202:205], v[78:81]
	v_mfma_f32_16x16x32_bf16 v[74:77], v[178:181], v[202:205], v[74:77]
	v_mfma_f32_16x16x32_bf16 v[70:73], v[170:173], v[214:217], v[70:73]
	v_mfma_f32_16x16x32_bf16 v[66:69], v[178:181], v[214:217], v[66:69]
	v_mfma_f32_16x16x32_bf16 v[106:109], v[174:177], v[190:193], v[106:109]
	v_mfma_f32_16x16x32_bf16 v[98:101], v[182:185], v[190:193], v[98:101]
	v_mfma_f32_16x16x32_bf16 v[90:93], v[174:177], v[198:201], v[90:93]
	v_mfma_f32_16x16x32_bf16 v[82:85], v[182:185], v[198:201], v[82:85]
	v_mfma_f32_16x16x32_bf16 v[78:81], v[174:177], v[210:213], v[78:81]
	v_mfma_f32_16x16x32_bf16 v[74:77], v[182:185], v[210:213], v[74:77]
	v_mfma_f32_16x16x32_bf16 v[70:73], v[174:177], v[218:221], v[70:73]
	v_mfma_f32_16x16x32_bf16 v[66:69], v[182:185], v[218:221], v[66:69]
	s_setprio 0
	s_barrier
	s_add_i32 s49, s40, s29
	v_lshl_add_u64 v[162:163], s[24:25], 0, v[150:151]
	s_mov_b32 m0, s49
	ds_read_b128 v[186:189], v168 offset:16384
	ds_read_b128 v[190:193], v168 offset:17408
	ds_read_b128 v[194:197], v168 offset:18432
	ds_read_b128 v[198:201], v168 offset:19456
	ds_read_b128 v[202:205], v168 offset:20480
	ds_read_b128 v[210:213], v168 offset:21504
	ds_read_b128 v[214:217], v168 offset:22528
	ds_read_b128 v[218:221], v168 offset:23552
	global_load_lds_dwordx4 v[162:163], off
	s_add_i32 m0, s49, 0x2000
	s_add_u32 s50, s24, 0x80000
	v_lshl_add_u64 v[206:207], s[24:25], 0, v[146:147]
	s_addc_u32 s51, s25, 0
	s_add_i32 s49, s41, s29
	global_load_lds_dwordx4 v[206:207], off
	v_lshl_add_u64 v[222:223], s[50:51], 0, v[150:151]
	s_mov_b32 m0, s49
	v_lshl_add_u64 v[224:225], s[26:27], 0, v[148:149]
	global_load_lds_dwordx4 v[222:223], off
	v_lshl_add_u64 v[222:223], s[50:51], 0, v[146:147]
	s_add_i32 m0, s49, 0x2000
	s_nop 0
	global_load_lds_dwordx4 v[222:223], off
	v_lshl_add_u64 v[222:223], s[26:27], 0, v[152:153]
	s_mov_b32 m0, s21
	s_nop 0
	global_load_lds_dwordx4 v[222:223], off
	s_mov_b32 m0, s33
	s_nop 0
	global_load_lds_dwordx4 v[224:225], off
	s_waitcnt vmcnt(28)
	s_waitcnt lgkmcnt(0)
	s_barrier
	s_setprio 1
	s_waitcnt lgkmcnt(0)
	v_mfma_f32_16x16x32_bf16 v[62:65], v[130:133], v[186:189], v[62:65]
	v_mfma_f32_16x16x32_bf16 v[58:61], v[138:141], v[186:189], v[58:61]
	v_mfma_f32_16x16x32_bf16 v[54:57], v[130:133], v[194:197], v[54:57]
	v_mfma_f32_16x16x32_bf16 v[46:49], v[138:141], v[194:197], v[46:49]
	v_mfma_f32_16x16x32_bf16 v[38:41], v[130:133], v[202:205], v[38:41]
	v_mfma_f32_16x16x32_bf16 v[30:33], v[138:141], v[202:205], v[30:33]
	v_mfma_f32_16x16x32_bf16 v[22:25], v[130:133], v[214:217], v[22:25]
	v_mfma_f32_16x16x32_bf16 v[14:17], v[138:141], v[214:217], v[14:17]
	v_mfma_f32_16x16x32_bf16 v[62:65], v[134:137], v[190:193], v[62:65]
	v_mfma_f32_16x16x32_bf16 v[58:61], v[142:145], v[190:193], v[58:61]
	v_mfma_f32_16x16x32_bf16 v[54:57], v[134:137], v[198:201], v[54:57]
	v_mfma_f32_16x16x32_bf16 v[46:49], v[142:145], v[198:201], v[46:49]
	v_mfma_f32_16x16x32_bf16 v[38:41], v[134:137], v[210:213], v[38:41]
	v_mfma_f32_16x16x32_bf16 v[30:33], v[142:145], v[210:213], v[30:33]
	v_mfma_f32_16x16x32_bf16 v[22:25], v[134:137], v[218:221], v[22:25]
	v_mfma_f32_16x16x32_bf16 v[14:17], v[142:145], v[218:221], v[14:17]
	s_setprio 0
	s_setprio 1
	v_mfma_f32_16x16x32_bf16 v[50:53], v[170:173], v[186:189], v[50:53]
	v_mfma_f32_16x16x32_bf16 v[42:45], v[178:181], v[186:189], v[42:45]
	v_mfma_f32_16x16x32_bf16 v[34:37], v[170:173], v[194:197], v[34:37]
	v_mfma_f32_16x16x32_bf16 v[26:29], v[178:181], v[194:197], v[26:29]
	v_mfma_f32_16x16x32_bf16 v[18:21], v[170:173], v[202:205], v[18:21]
	v_mfma_f32_16x16x32_bf16 v[10:13], v[178:181], v[202:205], v[10:13]
	v_mfma_f32_16x16x32_bf16 v[6:9], v[170:173], v[214:217], v[6:9]
	v_mfma_f32_16x16x32_bf16 v[2:5], v[178:181], v[214:217], v[2:5]
	v_mfma_f32_16x16x32_bf16 v[50:53], v[174:177], v[190:193], v[50:53]
	v_mfma_f32_16x16x32_bf16 v[42:45], v[182:185], v[190:193], v[42:45]
	v_mfma_f32_16x16x32_bf16 v[34:37], v[174:177], v[198:201], v[34:37]
	v_mfma_f32_16x16x32_bf16 v[26:29], v[182:185], v[198:201], v[26:29]
	v_mfma_f32_16x16x32_bf16 v[18:21], v[174:177], v[210:213], v[18:21]
	v_mfma_f32_16x16x32_bf16 v[10:13], v[182:185], v[210:213], v[10:13]
	v_mfma_f32_16x16x32_bf16 v[6:9], v[174:177], v[218:221], v[6:9]
	v_mfma_f32_16x16x32_bf16 v[2:5], v[182:185], v[218:221], v[2:5]
	s_setprio 0
	s_barrier
; #define PG8_STAGE(bufoff, gbase, voff) do { _Pragma("unroll") for (int _i = 0; _i < 2; ++_i) \
;         __builtin_amdgcn_global_load_lds((const unsigned*)((const char*)(gbase) + (voff)[_i]), (PG8_LAS unsigned*)(lds + (bufoff) + ldsw + _i * 8192), 16, 0, 0); } while (0)
; #define PG8_LDA(dst, b, h) do { _Pragma("unroll") for (int m = 0; m < 4; ++m) _Pragma("unroll") for (int k = 0; k < 2; ++k) dst[m][k] = *(const PG8_LAS bf16x8*)(lds + PG8_SA(b, h) + aoff + m * 2048 + k * 1024); } while (0)
; #define PG8_LDB(dst, b, h) do { _Pragma("unroll") for (int n = 0; n < 2; ++n) _Pragma("unroll") for (int k = 0; k < 2; ++k) dst[n][k] = *(const PG8_LAS bf16x8*)(lds + PG8_SB(b, h) + boff + n * 2048 + k * 1024); } while (0)
; #define PG8_MMA(ai, bj, At, Bt) do { __builtin_amdgcn_s_setprio(1); _Pragma("unroll") for (int m = 0; m < 4; ++m) _Pragma("unroll") for (int n = 0; n < 2; ++n) _Pragma("unroll") for (int k = 0; k < 2; ++k) \
;         acc[ai][bj][m][n] = __builtin_amdgcn_mfma_f32_16x16x32_bf16(Bt[n][k], At[m][k], acc[ai][bj][m][n], 0, 0, 0); __builtin_amdgcn_s_setprio(0); } while (0)
; #define PG8_WAIT_V(n) asm volatile("s_waitcnt vmcnt(" #n ")" ::: "memory")
; #define PG8_WAIT_L(n) asm volatile("s_waitcnt lgkmcnt(" #n ")" ::: "memory")
; #define PG8_BAR __builtin_amdgcn_s_barrier()
; #define PG8_SCHED __builtin_amdgcn_sched_barrier(0)
; template <class Epi, class Sched, bool ALIGN_EPI = false, bool SP2 = false>
; __device__ __forceinline__ void gemm_phase(PG8_LAS unsigned char* lds, const Gemm g, const Sched& S, const Epi& E) {
;     ...
;             PG8_LDB(B0, 1, 0); PG8_LDB(B1, 1, 1); PG8_SCHED; PG8_LDA(At, 1, 0); PG8_STAGE(PG8_SA(0, 1), a2 + hstepA, voffA);
;             PG8_WAIT_V(8); PG8_WAIT_L(0); PG8_BAR; PG8_MMA(0, 0, At, B0); PG8_MMA(0, 1, At, B1); PG8_BAR; PG8_SCHED;
	s_add_i32 s49, 0, 0x18000
	s_add_i32 s50, 0, 0x1c000
	v_add_u32_e32 v142, s49, v164
	v_add_u32_e32 v169, s50, v164
	ds_read_b128 v[130:133], v142
	ds_read_b128 v[134:137], v142 offset:1024
	ds_read_b128 v[138:141], v142 offset:2048
	ds_read_b128 v[142:145], v142 offset:3072
	ds_read_b128 v[170:173], v169
	ds_read_b128 v[174:177], v169 offset:1024
	ds_read_b128 v[178:181], v169 offset:2048
	ds_read_b128 v[182:185], v169 offset:3072
	s_add_u32 s26, s26, 0x80000
	s_addc_u32 s27, s27, 0
	s_mov_b32 m0, s34
	v_lshl_add_u64 v[226:227], s[26:27], 0, v[152:153]
	ds_read_b128 v[186:189], v168 offset:32768
	ds_read_b128 v[190:193], v168 offset:33792
	ds_read_b128 v[194:197], v168 offset:34816
	ds_read_b128 v[198:201], v168 offset:35840
	ds_read_b128 v[202:205], v168 offset:36864
	ds_read_b128 v[210:213], v168 offset:37888
	ds_read_b128 v[214:217], v168 offset:38912
	ds_read_b128 v[218:221], v168 offset:39936
	global_load_lds_dwordx4 v[226:227], off
	v_lshl_add_u64 v[226:227], s[26:27], 0, v[148:149]
	s_mov_b32 m0, s35
	s_nop 0
	global_load_lds_dwordx4 v[226:227], off
	s_waitcnt vmcnt(8)
	s_waitcnt lgkmcnt(0)
	s_barrier
	s_setprio 1
	s_waitcnt lgkmcnt(0)
	v_mfma_f32_16x16x32_bf16 v[126:129], v[130:133], v[186:189], v[126:129]
	v_mfma_f32_16x16x32_bf16 v[122:125], v[138:141], v[186:189], v[122:125]
	v_mfma_f32_16x16x32_bf16 v[118:121], v[130:133], v[194:197], v[118:121]
	v_mfma_f32_16x16x32_bf16 v[114:117], v[138:141], v[194:197], v[114:117]
	v_mfma_f32_16x16x32_bf16 v[110:113], v[130:133], v[202:205], v[110:113]
	v_mfma_f32_16x16x32_bf16 v[102:105], v[138:141], v[202:205], v[102:105]
	v_mfma_f32_16x16x32_bf16 v[94:97], v[130:133], v[214:217], v[94:97]
	v_mfma_f32_16x16x32_bf16 v[86:89], v[138:141], v[214:217], v[86:89]
	v_mfma_f32_16x16x32_bf16 v[126:129], v[134:137], v[190:193], v[126:129]
	v_mfma_f32_16x16x32_bf16 v[122:125], v[142:145], v[190:193], v[122:125]
	v_mfma_f32_16x16x32_bf16 v[118:121], v[134:137], v[198:201], v[118:121]
	v_mfma_f32_16x16x32_bf16 v[114:117], v[142:145], v[198:201], v[114:117]
	v_mfma_f32_16x16x32_bf16 v[110:113], v[134:137], v[210:213], v[110:113]
	v_mfma_f32_16x16x32_bf16 v[102:105], v[142:145], v[210:213], v[102:105]
	v_mfma_f32_16x16x32_bf16 v[94:97], v[134:137], v[218:221], v[94:97]
	v_mfma_f32_16x16x32_bf16 v[86:89], v[142:145], v[218:221], v[86:89]
	s_setprio 0
	s_setprio 1
	v_mfma_f32_16x16x32_bf16 v[106:109], v[170:173], v[186:189], v[106:109]
	v_mfma_f32_16x16x32_bf16 v[98:101], v[178:181], v[186:189], v[98:101]
	v_mfma_f32_16x16x32_bf16 v[90:93], v[170:173], v[194:197], v[90:93]
	v_mfma_f32_16x16x32_bf16 v[82:85], v[178:181], v[194:197], v[82:85]
	v_mfma_f32_16x16x32_bf16 v[78:81], v[170:173], v[202:205], v[78:81]
	v_mfma_f32_16x16x32_bf16 v[74:77], v[178:181], v[202:205], v[74:77]
	v_mfma_f32_16x16x32_bf16 v[70:73], v[170:173], v[214:217], v[70:73]
	v_mfma_f32_16x16x32_bf16 v[66:69], v[178:181], v[214:217], v[66:69]
	v_mfma_f32_16x16x32_bf16 v[106:109], v[174:177], v[190:193], v[106:109]
	v_mfma_f32_16x16x32_bf16 v[98:101], v[182:185], v[190:193], v[98:101]
	v_mfma_f32_16x16x32_bf16 v[90:93], v[174:177], v[198:201], v[90:93]
	v_mfma_f32_16x16x32_bf16 v[82:85], v[182:185], v[198:201], v[82:85]
	v_mfma_f32_16x16x32_bf16 v[78:81], v[174:177], v[210:213], v[78:81]
	v_mfma_f32_16x16x32_bf16 v[74:77], v[182:185], v[210:213], v[74:77]
	v_mfma_f32_16x16x32_bf16 v[70:73], v[174:177], v[218:221], v[70:73]
	v_mfma_f32_16x16x32_bf16 v[66:69], v[182:185], v[218:221], v[66:69]
	s_setprio 0
	s_barrier
; #define PG8_STAGE(bufoff, gbase, voff) do { _Pragma("unroll") for (int _i = 0; _i < 2; ++_i) \
;         __builtin_amdgcn_global_load_lds((const unsigned*)((const char*)(gbase) + (voff)[_i]), (PG8_LAS unsigned*)(lds + (bufoff) + ldsw + _i * 8192), 16, 0, 0); } while (0)
; #define PG8_LDA(dst, b, h) do { _Pragma("unroll") for (int m = 0; m < 4; ++m) _Pragma("unroll") for (int k = 0; k < 2; ++k) dst[m][k] = *(const PG8_LAS bf16x8*)(lds + PG8_SA(b, h) + aoff + m * 2048 + k * 1024); } while (0)
; #define PG8_MMA(ai, bj, At, Bt) do { __builtin_amdgcn_s_setprio(1); _Pragma("unroll") for (int m = 0; m < 4; ++m) _Pragma("unroll") for (int n = 0; n < 2; ++n) _Pragma("unroll") for (int k = 0; k < 2; ++k) \
;         acc[ai][bj][m][n] = __builtin_amdgcn_mfma_f32_16x16x32_bf16(Bt[n][k], At[m][k], acc[ai][bj][m][n], 0, 0, 0); __builtin_amdgcn_s_setprio(0); } while (0)
; #define PG8_WAIT_V(n) asm volatile("s_waitcnt vmcnt(" #n ")" ::: "memory")
; #define PG8_WAIT_L(n) asm volatile("s_waitcnt lgkmcnt(" #n ")" ::: "memory")
; #define PG8_BAR __builtin_amdgcn_s_barrier()
; #define PG8_SCHED __builtin_amdgcn_sched_barrier(0)
; template <class Epi, class Sched, bool ALIGN_EPI = false, bool SP2 = false>
; __device__ __forceinline__ void gemm_phase(PG8_LAS unsigned char* lds, const Gemm g, const Sched& S, const Epi& E) {
;     ...
;         for (int t = 0; t < nt; t += 2) {
;             const bool last = (t == nt - 2);
;             const char* a1 = cA + (size_t)(t + 1) * kstep;
;             const char* a2 = last ? nA : cA + (size_t)(t + 2) * kstep; const char* b2 = last ? nB : cB + (size_t)(t + 2) * kstep;
;             const char* a3 = a2 + kstep; const char* b3 = b2 + kstep;
;     ...
;             PG8_LDA(At, 1, 1); PG8_STAGE(PG8_SB(1, 0), b3, voffB); PG8_STAGE(PG8_SB(1, 1), b3 + hstepB, voffB); PG8_STAGE(PG8_SA(1, 0), a3, voffA);
;             PG8_WAIT_V(8); PG8_WAIT_L(0); PG8_BAR; PG8_MMA(1, 0, At, B0); PG8_MMA(1, 1, At, B1); PG8_BAR; PG8_SCHED;
	s_add_i32 s26, s49, s29
	v_lshl_add_u64 v[162:163], v[162:163], 0, s[8:9]
	s_mov_b32 m0, s26
	ds_read_b128 v[186:189], v168 offset:49152
	ds_read_b128 v[190:193], v168 offset:50176
	ds_read_b128 v[194:197], v168 offset:51200
	ds_read_b128 v[198:201], v168 offset:52224
	ds_read_b128 v[202:205], v168 offset:53248
	ds_read_b128 v[210:213], v168 offset:54272
	ds_read_b128 v[214:217], v168 offset:55296
	ds_read_b128 v[218:221], v168 offset:56320
	global_load_lds_dwordx4 v[162:163], off
	s_add_i32 m0, s26, 0x2000
	s_add_u32 s24, s24, 0x80080
	v_lshl_add_u64 v[162:163], v[206:207], 0, s[8:9]
	s_addc_u32 s25, s25, 0
	s_add_i32 s26, s50, s29
	global_load_lds_dwordx4 v[162:163], off
	v_lshl_add_u64 v[162:163], s[24:25], 0, v[150:151]
	s_mov_b32 m0, s26
	s_nop 0
	global_load_lds_dwordx4 v[162:163], off
	v_lshl_add_u64 v[162:163], s[24:25], 0, v[146:147]
	s_add_i32 m0, s26, 0x2000
	s_nop 0
	global_load_lds_dwordx4 v[162:163], off
	v_lshl_add_u64 v[162:163], v[222:223], 0, s[8:9]
	s_mov_b32 m0, s37
	s_nop 0
	global_load_lds_dwordx4 v[162:163], off
	v_lshl_add_u64 v[162:163], v[224:225], 0, s[8:9]
	s_mov_b32 m0, s38
	s_nop 0
	global_load_lds_dwordx4 v[162:163], off
	s_waitcnt vmcnt(8)
	s_waitcnt lgkmcnt(0)
	s_barrier
	s_setprio 1
	s_waitcnt lgkmcnt(0)
	v_mfma_f32_16x16x32_bf16 v[62:65], v[130:133], v[186:189], v[62:65]
	v_mfma_f32_16x16x32_bf16 v[58:61], v[138:141], v[186:189], v[58:61]
	v_mfma_f32_16x16x32_bf16 v[54:57], v[130:133], v[194:197], v[54:57]
	v_mfma_f32_16x16x32_bf16 v[46:49], v[138:141], v[194:197], v[46:49]
	v_mfma_f32_16x16x32_bf16 v[38:41], v[130:133], v[202:205], v[38:41]
	v_mfma_f32_16x16x32_bf16 v[30:33], v[138:141], v[202:205], v[30:33]
	v_mfma_f32_16x16x32_bf16 v[22:25], v[130:133], v[214:217], v[22:25]
	v_mfma_f32_16x16x32_bf16 v[14:17], v[138:141], v[214:217], v[14:17]
	v_mfma_f32_16x16x32_bf16 v[62:65], v[134:137], v[190:193], v[62:65]
	v_mfma_f32_16x16x32_bf16 v[58:61], v[142:145], v[190:193], v[58:61]
	v_mfma_f32_16x16x32_bf16 v[54:57], v[134:137], v[198:201], v[54:57]
	v_mfma_f32_16x16x32_bf16 v[46:49], v[142:145], v[198:201], v[46:49]
	v_mfma_f32_16x16x32_bf16 v[38:41], v[134:137], v[210:213], v[38:41]
	v_mfma_f32_16x16x32_bf16 v[30:33], v[142:145], v[210:213], v[30:33]
	v_mfma_f32_16x16x32_bf16 v[22:25], v[134:137], v[218:221], v[22:25]
	v_mfma_f32_16x16x32_bf16 v[14:17], v[142:145], v[218:221], v[14:17]
	s_setprio 0
	s_setprio 1
	v_mfma_f32_16x16x32_bf16 v[50:53], v[170:173], v[186:189], v[50:53]
	v_mfma_f32_16x16x32_bf16 v[42:45], v[178:181], v[186:189], v[42:45]
	v_mfma_f32_16x16x32_bf16 v[34:37], v[170:173], v[194:197], v[34:37]
	v_mfma_f32_16x16x32_bf16 v[26:29], v[178:181], v[194:197], v[26:29]
	v_mfma_f32_16x16x32_bf16 v[18:21], v[170:173], v[202:205], v[18:21]
	v_mfma_f32_16x16x32_bf16 v[10:13], v[178:181], v[202:205], v[10:13]
	v_mfma_f32_16x16x32_bf16 v[6:9], v[170:173], v[214:217], v[6:9]
	v_mfma_f32_16x16x32_bf16 v[2:5], v[178:181], v[214:217], v[2:5]
	v_mfma_f32_16x16x32_bf16 v[50:53], v[174:177], v[190:193], v[50:53]
	v_mfma_f32_16x16x32_bf16 v[42:45], v[182:185], v[190:193], v[42:45]
	v_mfma_f32_16x16x32_bf16 v[34:37], v[174:177], v[198:201], v[34:37]
	v_mfma_f32_16x16x32_bf16 v[26:29], v[182:185], v[198:201], v[26:29]
	v_mfma_f32_16x16x32_bf16 v[18:21], v[174:177], v[210:213], v[18:21]
	v_mfma_f32_16x16x32_bf16 v[10:13], v[182:185], v[210:213], v[10:13]
	v_mfma_f32_16x16x32_bf16 v[6:9], v[174:177], v[218:221], v[6:9]
	v_mfma_f32_16x16x32_bf16 v[2:5], v[182:185], v[218:221], v[2:5]
	s_setprio 0
	s_barrier
	s_add_i32 s48, s48, 2
	s_add_u32 s22, s22, 0x100
	s_addc_u32 s23, s23, 0
	s_add_u32 s46, s46, 0x100
	s_addc_u32 s47, s47, 0
	s_cmp_gt_u32 s48, 29
	s_cbranch_scc1 .Lpeel_exit_28
	.p2align 6

; #define PG8_STAGE(bufoff, gbase, voff) do { _Pragma("unroll") for (int _i = 0; _i < 2; ++_i) \
;         __builtin_amdgcn_global_load_lds((const unsigned*)((const char*)(gbase) + (voff)[_i]), (PG8_LAS unsigned*)(lds + (bufoff) + ldsw + _i * 8192), 16, 0, 0); } while (0)
; #define PG8_WAIT_V(n) asm volatile("s_waitcnt vmcnt(" #n ")" ::: "memory")
; #define PG8_BAR __builtin_amdgcn_s_barrier()
; template <class Epi, class Sched, bool ALIGN_EPI = false, bool SP2 = false>
; __device__ __forceinline__ void gemm_phase(PG8_LAS unsigned char* lds, const Gemm g, const Sched& S, const Epi& E) {
;     const int tid = threadIdx.x, wid = __builtin_amdgcn_readfirstlane(tid >> 6), lane = tid & 63, wr = wid >> 2, wc = wid & 3, fr = lane & 15, fq = lane >> 4;
;     const int K = g.K, nt = K / BK;
;     unsigned voffA[2], voffB[2];
; #pragma unroll
;     for (int i = 0; i < 2; ++i) { int R, C; stage_rc(tid * 16 + i * 8192, R, C); const int Rb = Epi::PERM ? ((R & ~31) + perm32(R & 31)) : R;
;         voffA[i] = (unsigned)(R * g.lda + C) * 2u; voffB[i] = (unsigned)(Rb * g.ldb + C) * 2u; }
;     const size_t kstep = (size_t)(BK * 2);
;     const size_t hstepA = (size_t)HALF * g.lda * 2, hstepB = (size_t)HALF * g.ldb * 2;
;     const size_t tstepA = 2 * hstepA, tstepB = 2 * hstepB;
;     const unsigned ldsw = (unsigned)wid * 1024u;
;     const int aoff = lds_byte(wr * 64 + fr, fq * 8), boff = lds_byte(wc * 32 + fr, fq * 8);
;     ...
;         PG8_WAIT_V(2); PG8_BAR;
;         PG8_STAGE(PG8_SB(1, 0), cB + kstep, voffB); PG8_STAGE(PG8_SA(1, 0), cA + kstep, voffA); PG8_STAGE(PG8_SB(1, 1), cB + hstepB + kstep, voffB);
;         PG8_WAIT_V(6); PG8_BAR;
.LBB0_3366:
	s_lshl_b32 s10, s10, 5
	s_and_b32 s16, s10, 0x60
	s_mov_b64 s[10:11], 0x80
	s_add_i32 m0, s29, 0x18000
	v_lshl_add_u64 v[8:9], v[8:9], 0, s[10:11]
	s_lshl_b32 s13, s12, 13
	s_lshl_b32 s17, s16, 7
	s_waitcnt vmcnt(2)
	s_barrier
	global_load_lds_dwordx4 v[8:9], off
	v_lshl_add_u64 v[4:5], v[4:5], 0, s[10:11]
	s_add_i32 m0, s29, 0x1a000
	s_add_i32 s45, s29, 0x8000
	s_add_i32 s46, s29, 0xa000
	global_load_lds_dwordx4 v[4:5], off
	v_lshl_add_u64 v[2:3], v[2:3], 0, s[10:11]
	s_mov_b32 m0, s45
	s_add_u32 s14, s34, 0x80080
	global_load_lds_dwordx4 v[2:3], off
	v_lshl_add_u64 v[2:3], v[6:7], 0, s[10:11]
	s_mov_b32 m0, s46
	s_addc_u32 s15, s35, 0
	global_load_lds_dwordx4 v[2:3], off
	s_add_i32 m0, s29, 0x1c000
	v_lshl_add_u64 v[2:3], s[14:15], 0, v[150:151]
	global_load_lds_dwordx4 v[2:3], off
	v_lshl_add_u64 v[2:3], s[14:15], 0, v[146:147]
	s_add_i32 m0, s29, 0x1e000
	s_sext_i32_i8 s54, s4
	global_load_lds_dwordx4 v[2:3], off
	v_and_b32_e32 v2, 15, v0
	v_lshlrev_b32_e32 v3, 1, v13
	v_lshlrev_b32_e32 v4, 2, v0
	v_lshlrev_b32_e32 v5, 6, v0
	s_movk_i32 s4, 0x3c0
	v_lshl_or_b32 v1, s12, 6, v2
	v_lshl_or_b32 v2, v2, 6, v3
	v_and_b32_e32 v4, 32, v4
	v_and_or_b32 v3, v5, s4, v3
	v_bitop3_b32 v162, s17, v3, v4 bitop3:0xf6
	v_lshlrev_b32_e32 v3, 9, v0
	v_bitop3_b32 v2, v2, s13, v4 bitop3:0xde
	v_and_b32_e32 v3, 0x30000, v3
	v_lshlrev_b32_e32 v4, 12, v14
	v_or3_b32 v3, v11, v3, v4
	v_add_u32_e32 v154, v3, v12
	v_lshlrev_b32_e32 v3, 5, v10
	s_waitcnt vmcnt(0)
	s_cmpk_lt_u32 s5, 0x100
	v_and_b32_e32 v3, 0x70000, v3
	s_cselect_b64 s[12:13], -1, 0
	v_or3_b32 v3, v11, v3, v4
	s_add_i32 s48, 0, 0x10000
	s_add_i32 s49, 0, 0x14000
	s_waitcnt lgkmcnt(0)
	s_ashr_i32 s47, s33, 31
	v_or_b32_e32 v163, s16, v13
	v_mov_b32_e32 v155, v151
	v_add_u32_e32 v156, v3, v12
	v_mov_b32_e32 v157, v151
	v_mov_b64_e32 v[158:159], 0x500
	v_mov_b64_e32 v[160:161], 0x4ff
	v_add_u32_e32 v164, s48, v162
	v_add_u32_e32 v165, s49, v162
	v_add_u32_e32 v166, 0, v2
	s_mov_b32 s50, 0x80000
	s_mov_b64 s[14:15], 0x90000
	s_mov_b32 s51, 0x90000
	s_mov_b64 s[16:17], 0xa0000
	s_mov_b32 s52, 0xa0000
	s_mov_b64 s[18:19], 0xb0000
	s_mov_b32 s53, 0xb0000
	s_barrier
	s_branch .LBB0_3369

; #define PG8_STAGE(bufoff, gbase, voff) do { _Pragma("unroll") for (int _i = 0; _i < 2; ++_i) \
;         __builtin_amdgcn_global_load_lds((const unsigned*)((const char*)(gbase) + (voff)[_i]), (PG8_LAS unsigned*)(lds + (bufoff) + ldsw + _i * 8192), 16, 0, 0); } while (0)
; #define PG8_LDA(dst, b, h) do { _Pragma("unroll") for (int m = 0; m < 4; ++m) _Pragma("unroll") for (int k = 0; k < 2; ++k) dst[m][k] = *(const PG8_LAS bf16x8*)(lds + PG8_SA(b, h) + aoff + m * 2048 + k * 1024); } while (0)
; #define PG8_LDB(dst, b, h) do { _Pragma("unroll") for (int n = 0; n < 2; ++n) _Pragma("unroll") for (int k = 0; k < 2; ++k) dst[n][k] = *(const PG8_LAS bf16x8*)(lds + PG8_SB(b, h) + boff + n * 2048 + k * 1024); } while (0)
; #define PG8_WAIT_V(n) asm volatile("s_waitcnt vmcnt(" #n ")" ::: "memory")
; #define PG8_WAIT_L(n) asm volatile("s_waitcnt lgkmcnt(" #n ")" ::: "memory")
; #define PG8_BAR __builtin_amdgcn_s_barrier()
; #define PG8_SCHED __builtin_amdgcn_sched_barrier(0)
; template <class Epi, class Sched, bool ALIGN_EPI = false, bool SP2 = false>
; __device__ __forceinline__ void gemm_phase(PG8_LAS unsigned char* lds, const Gemm g, const Sched& S, const Epi& E) {
;     ...
;         const bool has_next = S.next(ui + 1, nxt);
;         const char* nA = has_next ? (const char*)g.A + (size_t)nxt.pm * tstepA : cA; const char* nB = has_next ? (const char*)g.Bt + (size_t)nxt.pn * tstepB : cB;
;         for (int t = 0; t < nt; t += 2) {
;             const bool last = (t == nt - 2);
;             const char* a1 = cA + (size_t)(t + 1) * kstep;
;             const char* a2 = last ? nA : cA + (size_t)(t + 2) * kstep; const char* b2 = last ? nB : cB + (size_t)(t + 2) * kstep;
;             const char* a3 = a2 + kstep; const char* b3 = b2 + kstep;
;             if (last && has_next) S.a_ready(nxt);
;             if constexpr (SP2) {
;             PG8_LDB(B0, 0, 0); PG8_LDB(B1, 0, 1); PG8_SCHED; PG8_LDA(At, 0, 0); PG8_STAGE(PG8_SA(1, 1), a1 + hstepA, voffA);
;             PG8_WAIT_V(8); PG8_WAIT_L(0); PG8_BAR; PG8_MMA(0, 0, At, B0); PG8_MMA(0, 1, At, B1); PG8_BAR; PG8_SCHED;
;     ...
;         for (int a = 0; a < 2; ++a)
; #pragma unroll
;             for (int b = 0; b < 2; ++b)
; #pragma unroll
;                 for (int m = 0; m < 4; ++m)
; #pragma unroll
;                     for (int n = 0; n < 2; ++n) acc[a][b][m][n] = (f32x4){0.f, 0.f, 0.f, 0.f};
.LBB0_3371:
	s_ashr_i32 s23, s22, 31
	s_lshl_b64 s[24:25], s[22:23], 20
	s_add_u32 s24, s86, s24
	s_addc_u32 s25, s87, s25
	s_and_b64 s[26:27], s[4:5], exec
	s_cselect_b32 s23, s25, s31
	s_cselect_b32 s55, s24, s30
	s_ashr_i32 s21, s20, 31
	s_lshl_b64 s[26:27], s[20:21], 20
	s_add_u32 s26, s88, s26
	s_addc_u32 s27, s89, s27
	s_and_b64 s[36:37], s[4:5], exec
	s_cselect_b32 s21, s27, s35
	s_cselect_b32 s56, s26, s34
	s_add_u32 s30, s30, 0x80080
	s_addc_u32 s31, s31, 0
	s_add_u32 s57, s34, 0x100
	v_mov_b32_e32 v2, 0
	s_addc_u32 s58, s35, 0
	s_mov_b32 s59, -2
	v_mov_b32_e32 v3, v2
	v_mov_b32_e32 v4, v2
	v_mov_b32_e32 v5, v2
	v_mov_b32_e32 v6, v2
	v_mov_b32_e32 v7, v2
	v_mov_b32_e32 v8, v2
	v_mov_b32_e32 v9, v2
	v_mov_b32_e32 v10, v2
	v_mov_b32_e32 v11, v2
	v_mov_b32_e32 v12, v2
	v_mov_b32_e32 v13, v2
	v_mov_b32_e32 v18, v2
	v_mov_b32_e32 v19, v2
	v_mov_b32_e32 v20, v2
	v_mov_b32_e32 v21, v2
	v_mov_b32_e32 v26, v2
	v_mov_b32_e32 v27, v2
	v_mov_b32_e32 v28, v2
	v_mov_b32_e32 v29, v2
	v_mov_b32_e32 v34, v2
	v_mov_b32_e32 v35, v2
	v_mov_b32_e32 v36, v2
	v_mov_b32_e32 v37, v2
	v_mov_b32_e32 v42, v2
	v_mov_b32_e32 v43, v2
	v_mov_b32_e32 v44, v2
	v_mov_b32_e32 v45, v2
	v_mov_b32_e32 v50, v2
	v_mov_b32_e32 v51, v2
	v_mov_b32_e32 v52, v2
	v_mov_b32_e32 v53, v2
	v_mov_b32_e32 v14, v2
	v_mov_b32_e32 v15, v2
	v_mov_b32_e32 v16, v2
	v_mov_b32_e32 v17, v2
	v_mov_b32_e32 v22, v2
	v_mov_b32_e32 v23, v2
	v_mov_b32_e32 v24, v2
	v_mov_b32_e32 v25, v2
	v_mov_b32_e32 v30, v2
	v_mov_b32_e32 v31, v2
	v_mov_b32_e32 v32, v2
	v_mov_b32_e32 v33, v2
	v_mov_b32_e32 v38, v2
	v_mov_b32_e32 v39, v2
	v_mov_b32_e32 v40, v2
	v_mov_b32_e32 v41, v2
	v_mov_b32_e32 v46, v2
	v_mov_b32_e32 v47, v2
	v_mov_b32_e32 v48, v2
	v_mov_b32_e32 v49, v2
	v_mov_b32_e32 v54, v2
	v_mov_b32_e32 v55, v2
	v_mov_b32_e32 v56, v2
	v_mov_b32_e32 v57, v2
	v_mov_b32_e32 v58, v2
	v_mov_b32_e32 v59, v2
	v_mov_b32_e32 v60, v2
	v_mov_b32_e32 v61, v2
	v_mov_b32_e32 v62, v2
	v_mov_b32_e32 v63, v2
	v_mov_b32_e32 v64, v2
	v_mov_b32_e32 v65, v2
	v_mov_b32_e32 v66, v2
	v_mov_b32_e32 v67, v2
	v_mov_b32_e32 v68, v2
	v_mov_b32_e32 v69, v2
	v_mov_b32_e32 v70, v2
	v_mov_b32_e32 v71, v2
	v_mov_b32_e32 v72, v2
	v_mov_b32_e32 v73, v2
	v_mov_b32_e32 v74, v2
	v_mov_b32_e32 v75, v2
	v_mov_b32_e32 v76, v2
	v_mov_b32_e32 v77, v2
	v_mov_b32_e32 v78, v2
	v_mov_b32_e32 v79, v2
	v_mov_b32_e32 v80, v2
	v_mov_b32_e32 v81, v2
	v_mov_b32_e32 v82, v2
	v_mov_b32_e32 v83, v2
	v_mov_b32_e32 v84, v2
	v_mov_b32_e32 v85, v2
	v_mov_b32_e32 v90, v2
	v_mov_b32_e32 v91, v2
	v_mov_b32_e32 v92, v2
	v_mov_b32_e32 v93, v2
	v_mov_b32_e32 v98, v2
	v_mov_b32_e32 v99, v2
	v_mov_b32_e32 v100, v2
	v_mov_b32_e32 v101, v2
	v_mov_b32_e32 v106, v2
	v_mov_b32_e32 v107, v2
	v_mov_b32_e32 v108, v2
	v_mov_b32_e32 v109, v2
	v_mov_b32_e32 v86, v2
	v_mov_b32_e32 v87, v2
	v_mov_b32_e32 v88, v2
	v_mov_b32_e32 v89, v2
	v_mov_b32_e32 v94, v2
	v_mov_b32_e32 v95, v2
	v_mov_b32_e32 v96, v2
	v_mov_b32_e32 v97, v2
	v_mov_b32_e32 v102, v2
	v_mov_b32_e32 v103, v2
	v_mov_b32_e32 v104, v2
	v_mov_b32_e32 v105, v2
	v_mov_b32_e32 v110, v2
	v_mov_b32_e32 v111, v2
	v_mov_b32_e32 v112, v2
	v_mov_b32_e32 v113, v2
	v_mov_b32_e32 v114, v2
	v_mov_b32_e32 v115, v2
	v_mov_b32_e32 v116, v2
	v_mov_b32_e32 v117, v2
	v_mov_b32_e32 v118, v2
	v_mov_b32_e32 v119, v2
	v_mov_b32_e32 v120, v2
	v_mov_b32_e32 v121, v2
	v_mov_b32_e32 v122, v2
	v_mov_b32_e32 v123, v2
	v_mov_b32_e32 v124, v2
	v_mov_b32_e32 v125, v2
	v_mov_b32_e32 v126, v2
	v_mov_b32_e32 v127, v2
	v_mov_b32_e32 v128, v2
	v_mov_b32_e32 v129, v2
	ds_read_b128 v[130:133], v164
	ds_read_b128 v[134:137], v164 offset:1024
	ds_read_b128 v[138:141], v164 offset:2048
	ds_read_b128 v[142:145], v164 offset:3072
	ds_read_b128 v[168:171], v165
	ds_read_b128 v[172:175], v165 offset:1024
	ds_read_b128 v[176:179], v165 offset:2048
	ds_read_b128 v[180:183], v165 offset:3072
	s_add_u32 s34, s30, 0xfff80080
	s_addc_u32 s35, s31, -1
	s_cmp_eq_u32 s59, 28
	s_cselect_b32 s37, s23, s35
	s_cselect_b32 s36, s55, s34
	s_cselect_b32 s35, s21, s58
	s_cselect_b32 s34, s56, s57
	v_lshl_add_u64 v[218:219], s[30:31], 0, v[154:155]
	s_add_i32 m0, s29, 0xc000
	ds_read_b128 v[184:187], v166
	ds_read_b128 v[188:191], v166 offset:1024
	ds_read_b128 v[192:195], v166 offset:2048
	ds_read_b128 v[196:199], v166 offset:3072
	ds_read_b128 v[200:203], v166 offset:4096
	ds_read_b128 v[204:207], v166 offset:5120
	ds_read_b128 v[210:213], v166 offset:6144
	ds_read_b128 v[214:217], v166 offset:7168
	global_load_lds_dwordx4 v[218:219], off
	v_lshl_add_u64 v[218:219], s[30:31], 0, v[156:157]
	s_add_i32 m0, s29, 0xe000
	s_nop 0
	global_load_lds_dwordx4 v[218:219], off
	s_waitcnt vmcnt(28)
	s_waitcnt lgkmcnt(0)
	s_barrier
; #define PG8_STAGE(bufoff, gbase, voff) do { _Pragma("unroll") for (int _i = 0; _i < 2; ++_i) \
;         __builtin_amdgcn_global_load_lds((const unsigned*)((const char*)(gbase) + (voff)[_i]), (PG8_LAS unsigned*)(lds + (bufoff) + ldsw + _i * 8192), 16, 0, 0); } while (0)
; #define PG8_LDA(dst, b, h) do { _Pragma("unroll") for (int m = 0; m < 4; ++m) _Pragma("unroll") for (int k = 0; k < 2; ++k) dst[m][k] = *(const PG8_LAS bf16x8*)(lds + PG8_SA(b, h) + aoff + m * 2048 + k * 1024); } while (0)
; #define PG8_MMA(ai, bj, At, Bt) do { __builtin_amdgcn_s_setprio(1); _Pragma("unroll") for (int m = 0; m < 4; ++m) _Pragma("unroll") for (int n = 0; n < 2; ++n) _Pragma("unroll") for (int k = 0; k < 2; ++k) \
;         acc[ai][bj][m][n] = __builtin_amdgcn_mfma_f32_16x16x32_bf16(Bt[n][k], At[m][k], acc[ai][bj][m][n], 0, 0, 0); __builtin_amdgcn_s_setprio(0); } while (0)
; #define PG8_WAIT_V(n) asm volatile("s_waitcnt vmcnt(" #n ")" ::: "memory")
; #define PG8_WAIT_L(n) asm volatile("s_waitcnt lgkmcnt(" #n ")" ::: "memory")
; #define PG8_BAR __builtin_amdgcn_s_barrier()
; #define PG8_SCHED __builtin_amdgcn_sched_barrier(0)
; template <class Epi, class Sched, bool ALIGN_EPI = false, bool SP2 = false>
; __device__ __forceinline__ void gemm_phase(PG8_LAS unsigned char* lds, const Gemm g, const Sched& S, const Epi& E) {
;     ...
;             PG8_WAIT_V(8); PG8_WAIT_L(0); PG8_BAR; PG8_MMA(0, 0, At, B0); PG8_MMA(0, 1, At, B1); PG8_BAR; PG8_SCHED;
;             PG8_LDA(At, 0, 1); PG8_STAGE(PG8_SB(0, 0), b2, voffB); PG8_STAGE(PG8_SB(0, 1), b2 + hstepB, voffB); PG8_STAGE(PG8_SA(0, 0), a2, voffA);
;             PG8_WAIT_V(8); PG8_WAIT_L(0); PG8_BAR; PG8_MMA(1, 0, At, B0); PG8_MMA(1, 1, At, B1); PG8_BAR; PG8_SCHED;
	s_setprio 1
	s_waitcnt lgkmcnt(0)
	v_mfma_f32_16x16x32_bf16 v[126:129], v[130:133], v[184:187], v[126:129]
	v_mfma_f32_16x16x32_bf16 v[122:125], v[138:141], v[184:187], v[122:125]
	v_mfma_f32_16x16x32_bf16 v[118:121], v[130:133], v[192:195], v[118:121]
	v_mfma_f32_16x16x32_bf16 v[114:117], v[138:141], v[192:195], v[114:117]
	v_mfma_f32_16x16x32_bf16 v[110:113], v[130:133], v[200:203], v[110:113]
	v_mfma_f32_16x16x32_bf16 v[102:105], v[138:141], v[200:203], v[102:105]
	v_mfma_f32_16x16x32_bf16 v[94:97], v[130:133], v[210:213], v[94:97]
	v_mfma_f32_16x16x32_bf16 v[86:89], v[138:141], v[210:213], v[86:89]
	v_mfma_f32_16x16x32_bf16 v[126:129], v[134:137], v[188:191], v[126:129]
	v_mfma_f32_16x16x32_bf16 v[122:125], v[142:145], v[188:191], v[122:125]
	v_mfma_f32_16x16x32_bf16 v[118:121], v[134:137], v[196:199], v[118:121]
	v_mfma_f32_16x16x32_bf16 v[114:117], v[142:145], v[196:199], v[114:117]
	v_mfma_f32_16x16x32_bf16 v[110:113], v[134:137], v[204:207], v[110:113]
	v_mfma_f32_16x16x32_bf16 v[102:105], v[142:145], v[204:207], v[102:105]
	v_mfma_f32_16x16x32_bf16 v[94:97], v[134:137], v[214:217], v[94:97]
	v_mfma_f32_16x16x32_bf16 v[86:89], v[142:145], v[214:217], v[86:89]
	s_setprio 0
	s_setprio 1
	v_mfma_f32_16x16x32_bf16 v[106:109], v[168:171], v[184:187], v[106:109]
	v_mfma_f32_16x16x32_bf16 v[98:101], v[176:179], v[184:187], v[98:101]
	v_mfma_f32_16x16x32_bf16 v[90:93], v[168:171], v[192:195], v[90:93]
	v_mfma_f32_16x16x32_bf16 v[82:85], v[176:179], v[192:195], v[82:85]
	v_mfma_f32_16x16x32_bf16 v[78:81], v[168:171], v[200:203], v[78:81]
	v_mfma_f32_16x16x32_bf16 v[74:77], v[176:179], v[200:203], v[74:77]
	v_mfma_f32_16x16x32_bf16 v[70:73], v[168:171], v[210:213], v[70:73]
	v_mfma_f32_16x16x32_bf16 v[66:69], v[176:179], v[210:213], v[66:69]
	v_mfma_f32_16x16x32_bf16 v[106:109], v[172:175], v[188:191], v[106:109]
	v_mfma_f32_16x16x32_bf16 v[98:101], v[180:183], v[188:191], v[98:101]
	v_mfma_f32_16x16x32_bf16 v[90:93], v[172:175], v[196:199], v[90:93]
	v_mfma_f32_16x16x32_bf16 v[82:85], v[180:183], v[196:199], v[82:85]
	v_mfma_f32_16x16x32_bf16 v[78:81], v[172:175], v[204:207], v[78:81]
	v_mfma_f32_16x16x32_bf16 v[74:77], v[180:183], v[204:207], v[74:77]
	v_mfma_f32_16x16x32_bf16 v[70:73], v[172:175], v[214:217], v[70:73]
	v_mfma_f32_16x16x32_bf16 v[66:69], v[180:183], v[214:217], v[66:69]
	s_setprio 0
	s_barrier
	s_add_i32 s60, s48, s38
	v_lshl_add_u64 v[218:219], s[34:35], 0, v[150:151]
	s_mov_b32 m0, s60
	ds_read_b128 v[184:187], v166 offset:16384
	ds_read_b128 v[188:191], v166 offset:17408
	ds_read_b128 v[192:195], v166 offset:18432
	ds_read_b128 v[196:199], v166 offset:19456
	ds_read_b128 v[200:203], v166 offset:20480
	ds_read_b128 v[204:207], v166 offset:21504
	ds_read_b128 v[210:213], v166 offset:22528
	ds_read_b128 v[214:217], v166 offset:23552
	global_load_lds_dwordx4 v[218:219], off
	s_add_i32 m0, s60, 0x2000
	s_add_u32 s60, s34, 0x80000
	v_lshl_add_u64 v[220:221], s[34:35], 0, v[146:147]
	s_addc_u32 s61, s35, 0
	s_add_i32 s62, s49, s38
	global_load_lds_dwordx4 v[220:221], off
	v_lshl_add_u64 v[222:223], s[60:61], 0, v[150:151]
	s_mov_b32 m0, s62
	v_lshl_add_u64 v[224:225], s[36:37], 0, v[148:149]
	global_load_lds_dwordx4 v[222:223], off
	v_lshl_add_u64 v[222:223], s[60:61], 0, v[146:147]
	s_add_i32 m0, s62, 0x2000
	s_nop 0
	global_load_lds_dwordx4 v[222:223], off
	v_lshl_add_u64 v[222:223], s[36:37], 0, v[152:153]
	s_mov_b32 m0, s29
	s_nop 0
	global_load_lds_dwordx4 v[222:223], off
	s_mov_b32 m0, s41
	s_nop 0
	global_load_lds_dwordx4 v[224:225], off
	s_waitcnt vmcnt(28)
	s_waitcnt lgkmcnt(0)
	s_barrier
	s_setprio 1
	s_waitcnt lgkmcnt(0)
	v_mfma_f32_16x16x32_bf16 v[62:65], v[130:133], v[184:187], v[62:65]
	v_mfma_f32_16x16x32_bf16 v[58:61], v[138:141], v[184:187], v[58:61]
	v_mfma_f32_16x16x32_bf16 v[54:57], v[130:133], v[192:195], v[54:57]
	v_mfma_f32_16x16x32_bf16 v[46:49], v[138:141], v[192:195], v[46:49]
	v_mfma_f32_16x16x32_bf16 v[38:41], v[130:133], v[200:203], v[38:41]
	v_mfma_f32_16x16x32_bf16 v[30:33], v[138:141], v[200:203], v[30:33]
	v_mfma_f32_16x16x32_bf16 v[22:25], v[130:133], v[210:213], v[22:25]
	v_mfma_f32_16x16x32_bf16 v[14:17], v[138:141], v[210:213], v[14:17]
	v_mfma_f32_16x16x32_bf16 v[62:65], v[134:137], v[188:191], v[62:65]
	v_mfma_f32_16x16x32_bf16 v[58:61], v[142:145], v[188:191], v[58:61]
	v_mfma_f32_16x16x32_bf16 v[54:57], v[134:137], v[196:199], v[54:57]
	v_mfma_f32_16x16x32_bf16 v[46:49], v[142:145], v[196:199], v[46:49]
	v_mfma_f32_16x16x32_bf16 v[38:41], v[134:137], v[204:207], v[38:41]
	v_mfma_f32_16x16x32_bf16 v[30:33], v[142:145], v[204:207], v[30:33]
	v_mfma_f32_16x16x32_bf16 v[22:25], v[134:137], v[214:217], v[22:25]
	v_mfma_f32_16x16x32_bf16 v[14:17], v[142:145], v[214:217], v[14:17]
	s_setprio 0
	s_setprio 1
	v_mfma_f32_16x16x32_bf16 v[50:53], v[168:171], v[184:187], v[50:53]
	v_mfma_f32_16x16x32_bf16 v[42:45], v[176:179], v[184:187], v[42:45]
	v_mfma_f32_16x16x32_bf16 v[34:37], v[168:171], v[192:195], v[34:37]
	v_mfma_f32_16x16x32_bf16 v[26:29], v[176:179], v[192:195], v[26:29]
	v_mfma_f32_16x16x32_bf16 v[18:21], v[168:171], v[200:203], v[18:21]
	v_mfma_f32_16x16x32_bf16 v[10:13], v[176:179], v[200:203], v[10:13]
	v_mfma_f32_16x16x32_bf16 v[6:9], v[168:171], v[210:213], v[6:9]
	v_mfma_f32_16x16x32_bf16 v[2:5], v[176:179], v[210:213], v[2:5]
	v_mfma_f32_16x16x32_bf16 v[50:53], v[172:175], v[188:191], v[50:53]
	v_mfma_f32_16x16x32_bf16 v[42:45], v[180:183], v[188:191], v[42:45]
	v_mfma_f32_16x16x32_bf16 v[34:37], v[172:175], v[196:199], v[34:37]
	v_mfma_f32_16x16x32_bf16 v[26:29], v[180:183], v[196:199], v[26:29]
	v_mfma_f32_16x16x32_bf16 v[18:21], v[172:175], v[204:207], v[18:21]
	v_mfma_f32_16x16x32_bf16 v[10:13], v[180:183], v[204:207], v[10:13]
	v_mfma_f32_16x16x32_bf16 v[6:9], v[172:175], v[214:217], v[6:9]
	v_mfma_f32_16x16x32_bf16 v[2:5], v[180:183], v[214:217], v[2:5]
	s_setprio 0
	s_barrier
; #define PG8_STAGE(bufoff, gbase, voff) do { _Pragma("unroll") for (int _i = 0; _i < 2; ++_i) \
;         __builtin_amdgcn_global_load_lds((const unsigned*)((const char*)(gbase) + (voff)[_i]), (PG8_LAS unsigned*)(lds + (bufoff) + ldsw + _i * 8192), 16, 0, 0); } while (0)
; #define PG8_LDA(dst, b, h) do { _Pragma("unroll") for (int m = 0; m < 4; ++m) _Pragma("unroll") for (int k = 0; k < 2; ++k) dst[m][k] = *(const PG8_LAS bf16x8*)(lds + PG8_SA(b, h) + aoff + m * 2048 + k * 1024); } while (0)
; #define PG8_LDB(dst, b, h) do { _Pragma("unroll") for (int n = 0; n < 2; ++n) _Pragma("unroll") for (int k = 0; k < 2; ++k) dst[n][k] = *(const PG8_LAS bf16x8*)(lds + PG8_SB(b, h) + boff + n * 2048 + k * 1024); } while (0)
; #define PG8_MMA(ai, bj, At, Bt) do { __builtin_amdgcn_s_setprio(1); _Pragma("unroll") for (int m = 0; m < 4; ++m) _Pragma("unroll") for (int n = 0; n < 2; ++n) _Pragma("unroll") for (int k = 0; k < 2; ++k) \
;         acc[ai][bj][m][n] = __builtin_amdgcn_mfma_f32_16x16x32_bf16(Bt[n][k], At[m][k], acc[ai][bj][m][n], 0, 0, 0); __builtin_amdgcn_s_setprio(0); } while (0)
; #define PG8_WAIT_V(n) asm volatile("s_waitcnt vmcnt(" #n ")" ::: "memory")
; #define PG8_WAIT_L(n) asm volatile("s_waitcnt lgkmcnt(" #n ")" ::: "memory")
; #define PG8_BAR __builtin_amdgcn_s_barrier()
; #define PG8_SCHED __builtin_amdgcn_sched_barrier(0)
; template <class Epi, class Sched, bool ALIGN_EPI = false, bool SP2 = false>
; __device__ __forceinline__ void gemm_phase(PG8_LAS unsigned char* lds, const Gemm g, const Sched& S, const Epi& E) {
;     ...
;             PG8_LDB(B0, 1, 0); PG8_LDB(B1, 1, 1); PG8_SCHED; PG8_LDA(At, 1, 0); PG8_STAGE(PG8_SA(0, 1), a2 + hstepA, voffA);
;             PG8_WAIT_V(8); PG8_WAIT_L(0); PG8_BAR; PG8_MMA(0, 0, At, B0); PG8_MMA(0, 1, At, B1); PG8_BAR; PG8_SCHED;
	s_add_i32 s60, 0, 0x18000
	s_add_i32 s61, 0, 0x1c000
	v_add_u32_e32 v142, s60, v162
	v_add_u32_e32 v167, s61, v162
	ds_read_b128 v[130:133], v142
	ds_read_b128 v[134:137], v142 offset:1024
	ds_read_b128 v[138:141], v142 offset:2048
	ds_read_b128 v[142:145], v142 offset:3072
	ds_read_b128 v[168:171], v167
	ds_read_b128 v[172:175], v167 offset:1024
	ds_read_b128 v[176:179], v167 offset:2048
	ds_read_b128 v[180:183], v167 offset:3072
	s_add_u32 s36, s36, 0x80000
	s_addc_u32 s37, s37, 0
	s_mov_b32 m0, s42
	v_lshl_add_u64 v[226:227], s[36:37], 0, v[152:153]
	ds_read_b128 v[184:187], v166 offset:32768
	ds_read_b128 v[188:191], v166 offset:33792
	ds_read_b128 v[192:195], v166 offset:34816
	ds_read_b128 v[196:199], v166 offset:35840
	ds_read_b128 v[200:203], v166 offset:36864
	ds_read_b128 v[204:207], v166 offset:37888
	ds_read_b128 v[210:213], v166 offset:38912
	ds_read_b128 v[214:217], v166 offset:39936
	global_load_lds_dwordx4 v[226:227], off
	v_lshl_add_u64 v[226:227], s[36:37], 0, v[148:149]
	s_mov_b32 m0, s43
	s_nop 0
	global_load_lds_dwordx4 v[226:227], off
	s_waitcnt vmcnt(8)
	s_waitcnt lgkmcnt(0)
	s_barrier
	s_setprio 1
	s_waitcnt lgkmcnt(0)
	v_mfma_f32_16x16x32_bf16 v[126:129], v[130:133], v[184:187], v[126:129]
	v_mfma_f32_16x16x32_bf16 v[122:125], v[138:141], v[184:187], v[122:125]
	v_mfma_f32_16x16x32_bf16 v[118:121], v[130:133], v[192:195], v[118:121]
	v_mfma_f32_16x16x32_bf16 v[114:117], v[138:141], v[192:195], v[114:117]
	v_mfma_f32_16x16x32_bf16 v[110:113], v[130:133], v[200:203], v[110:113]
	v_mfma_f32_16x16x32_bf16 v[102:105], v[138:141], v[200:203], v[102:105]
	v_mfma_f32_16x16x32_bf16 v[94:97], v[130:133], v[210:213], v[94:97]
	v_mfma_f32_16x16x32_bf16 v[86:89], v[138:141], v[210:213], v[86:89]
	v_mfma_f32_16x16x32_bf16 v[126:129], v[134:137], v[188:191], v[126:129]
	v_mfma_f32_16x16x32_bf16 v[122:125], v[142:145], v[188:191], v[122:125]
	v_mfma_f32_16x16x32_bf16 v[118:121], v[134:137], v[196:199], v[118:121]
	v_mfma_f32_16x16x32_bf16 v[114:117], v[142:145], v[196:199], v[114:117]
	v_mfma_f32_16x16x32_bf16 v[110:113], v[134:137], v[204:207], v[110:113]
	v_mfma_f32_16x16x32_bf16 v[102:105], v[142:145], v[204:207], v[102:105]
	v_mfma_f32_16x16x32_bf16 v[94:97], v[134:137], v[214:217], v[94:97]
	v_mfma_f32_16x16x32_bf16 v[86:89], v[142:145], v[214:217], v[86:89]
	s_setprio 0
	s_setprio 1
	v_mfma_f32_16x16x32_bf16 v[106:109], v[168:171], v[184:187], v[106:109]
	v_mfma_f32_16x16x32_bf16 v[98:101], v[176:179], v[184:187], v[98:101]
	v_mfma_f32_16x16x32_bf16 v[90:93], v[168:171], v[192:195], v[90:93]
	v_mfma_f32_16x16x32_bf16 v[82:85], v[176:179], v[192:195], v[82:85]
	v_mfma_f32_16x16x32_bf16 v[78:81], v[168:171], v[200:203], v[78:81]
	v_mfma_f32_16x16x32_bf16 v[74:77], v[176:179], v[200:203], v[74:77]
	v_mfma_f32_16x16x32_bf16 v[70:73], v[168:171], v[210:213], v[70:73]
	v_mfma_f32_16x16x32_bf16 v[66:69], v[176:179], v[210:213], v[66:69]
	v_mfma_f32_16x16x32_bf16 v[106:109], v[172:175], v[188:191], v[106:109]
	v_mfma_f32_16x16x32_bf16 v[98:101], v[180:183], v[188:191], v[98:101]
	v_mfma_f32_16x16x32_bf16 v[90:93], v[172:175], v[196:199], v[90:93]
	v_mfma_f32_16x16x32_bf16 v[82:85], v[180:183], v[196:199], v[82:85]
	v_mfma_f32_16x16x32_bf16 v[78:81], v[172:175], v[204:207], v[78:81]
	v_mfma_f32_16x16x32_bf16 v[74:77], v[180:183], v[204:207], v[74:77]
	v_mfma_f32_16x16x32_bf16 v[70:73], v[172:175], v[214:217], v[70:73]
	v_mfma_f32_16x16x32_bf16 v[66:69], v[180:183], v[214:217], v[66:69]
	s_setprio 0
	s_barrier
; #define PG8_STAGE(bufoff, gbase, voff) do { _Pragma("unroll") for (int _i = 0; _i < 2; ++_i) \
;         __builtin_amdgcn_global_load_lds((const unsigned*)((const char*)(gbase) + (voff)[_i]), (PG8_LAS unsigned*)(lds + (bufoff) + ldsw + _i * 8192), 16, 0, 0); } while (0)
; #define PG8_LDA(dst, b, h) do { _Pragma("unroll") for (int m = 0; m < 4; ++m) _Pragma("unroll") for (int k = 0; k < 2; ++k) dst[m][k] = *(const PG8_LAS bf16x8*)(lds + PG8_SA(b, h) + aoff + m * 2048 + k * 1024); } while (0)
; #define PG8_MMA(ai, bj, At, Bt) do { __builtin_amdgcn_s_setprio(1); _Pragma("unroll") for (int m = 0; m < 4; ++m) _Pragma("unroll") for (int n = 0; n < 2; ++n) _Pragma("unroll") for (int k = 0; k < 2; ++k) \
;         acc[ai][bj][m][n] = __builtin_amdgcn_mfma_f32_16x16x32_bf16(Bt[n][k], At[m][k], acc[ai][bj][m][n], 0, 0, 0); __builtin_amdgcn_s_setprio(0); } while (0)
; #define PG8_WAIT_V(n) asm volatile("s_waitcnt vmcnt(" #n ")" ::: "memory")
; #define PG8_WAIT_L(n) asm volatile("s_waitcnt lgkmcnt(" #n ")" ::: "memory")
; #define PG8_BAR __builtin_amdgcn_s_barrier()
; #define PG8_SCHED __builtin_amdgcn_sched_barrier(0)
; template <class Epi, class Sched, bool ALIGN_EPI = false, bool SP2 = false>
; __device__ __forceinline__ void gemm_phase(PG8_LAS unsigned char* lds, const Gemm g, const Sched& S, const Epi& E) {
;     ...
;         for (int t = 0; t < nt; t += 2) {
;             const bool last = (t == nt - 2);
;             const char* a1 = cA + (size_t)(t + 1) * kstep;
;             const char* a2 = last ? nA : cA + (size_t)(t + 2) * kstep; const char* b2 = last ? nB : cB + (size_t)(t + 2) * kstep;
;             const char* a3 = a2 + kstep; const char* b3 = b2 + kstep;
;     ...
;             PG8_LDA(At, 1, 1); PG8_STAGE(PG8_SB(1, 0), b3, voffB); PG8_STAGE(PG8_SB(1, 1), b3 + hstepB, voffB); PG8_STAGE(PG8_SA(1, 0), a3, voffA);
;             PG8_WAIT_V(8); PG8_WAIT_L(0); PG8_BAR; PG8_MMA(1, 0, At, B0); PG8_MMA(1, 1, At, B1); PG8_BAR; PG8_SCHED;
	s_add_i32 s36, s60, s38
	v_lshl_add_u64 v[218:219], v[218:219], 0, s[10:11]
	s_mov_b32 m0, s36
	ds_read_b128 v[184:187], v166 offset:49152
	ds_read_b128 v[188:191], v166 offset:50176
	ds_read_b128 v[192:195], v166 offset:51200
	ds_read_b128 v[196:199], v166 offset:52224
	ds_read_b128 v[200:203], v166 offset:53248
	ds_read_b128 v[204:207], v166 offset:54272
	ds_read_b128 v[210:213], v166 offset:55296
	ds_read_b128 v[214:217], v166 offset:56320
	global_load_lds_dwordx4 v[218:219], off
	s_add_i32 m0, s36, 0x2000
	s_add_u32 s34, s34, 0x80080
	v_lshl_add_u64 v[218:219], v[220:221], 0, s[10:11]
	s_addc_u32 s35, s35, 0
	s_add_i32 s36, s61, s38
	global_load_lds_dwordx4 v[218:219], off
	v_lshl_add_u64 v[218:219], s[34:35], 0, v[150:151]
	s_mov_b32 m0, s36
	s_nop 0
	global_load_lds_dwordx4 v[218:219], off
	v_lshl_add_u64 v[218:219], s[34:35], 0, v[146:147]
	s_add_i32 m0, s36, 0x2000
	s_nop 0
	global_load_lds_dwordx4 v[218:219], off
	v_lshl_add_u64 v[218:219], v[222:223], 0, s[10:11]
	s_mov_b32 m0, s45
	s_nop 0
	global_load_lds_dwordx4 v[218:219], off
	v_lshl_add_u64 v[218:219], v[224:225], 0, s[10:11]
	s_mov_b32 m0, s46
	s_nop 0
	global_load_lds_dwordx4 v[218:219], off
	s_waitcnt vmcnt(8)
	s_waitcnt lgkmcnt(0)
	s_barrier
	s_setprio 1
	s_waitcnt lgkmcnt(0)
	v_mfma_f32_16x16x32_bf16 v[62:65], v[130:133], v[184:187], v[62:65]
	v_mfma_f32_16x16x32_bf16 v[58:61], v[138:141], v[184:187], v[58:61]
	v_mfma_f32_16x16x32_bf16 v[54:57], v[130:133], v[192:195], v[54:57]
	v_mfma_f32_16x16x32_bf16 v[46:49], v[138:141], v[192:195], v[46:49]
	v_mfma_f32_16x16x32_bf16 v[38:41], v[130:133], v[200:203], v[38:41]
	v_mfma_f32_16x16x32_bf16 v[30:33], v[138:141], v[200:203], v[30:33]
	v_mfma_f32_16x16x32_bf16 v[22:25], v[130:133], v[210:213], v[22:25]
	v_mfma_f32_16x16x32_bf16 v[14:17], v[138:141], v[210:213], v[14:17]
	v_mfma_f32_16x16x32_bf16 v[62:65], v[134:137], v[188:191], v[62:65]
	v_mfma_f32_16x16x32_bf16 v[58:61], v[142:145], v[188:191], v[58:61]
	v_mfma_f32_16x16x32_bf16 v[54:57], v[134:137], v[196:199], v[54:57]
	v_mfma_f32_16x16x32_bf16 v[46:49], v[142:145], v[196:199], v[46:49]
	v_mfma_f32_16x16x32_bf16 v[38:41], v[134:137], v[204:207], v[38:41]
	v_mfma_f32_16x16x32_bf16 v[30:33], v[142:145], v[204:207], v[30:33]
	v_mfma_f32_16x16x32_bf16 v[22:25], v[134:137], v[214:217], v[22:25]
	v_mfma_f32_16x16x32_bf16 v[14:17], v[142:145], v[214:217], v[14:17]
	s_setprio 0
	s_setprio 1
	v_mfma_f32_16x16x32_bf16 v[50:53], v[168:171], v[184:187], v[50:53]
	v_mfma_f32_16x16x32_bf16 v[42:45], v[176:179], v[184:187], v[42:45]
	v_mfma_f32_16x16x32_bf16 v[34:37], v[168:171], v[192:195], v[34:37]
	v_mfma_f32_16x16x32_bf16 v[26:29], v[176:179], v[192:195], v[26:29]
	v_mfma_f32_16x16x32_bf16 v[18:21], v[168:171], v[200:203], v[18:21]
	v_mfma_f32_16x16x32_bf16 v[10:13], v[176:179], v[200:203], v[10:13]
	v_mfma_f32_16x16x32_bf16 v[6:9], v[168:171], v[210:213], v[6:9]
	v_mfma_f32_16x16x32_bf16 v[2:5], v[176:179], v[210:213], v[2:5]
	v_mfma_f32_16x16x32_bf16 v[50:53], v[172:175], v[188:191], v[50:53]
	v_mfma_f32_16x16x32_bf16 v[42:45], v[180:183], v[188:191], v[42:45]
	v_mfma_f32_16x16x32_bf16 v[34:37], v[172:175], v[196:199], v[34:37]
	v_mfma_f32_16x16x32_bf16 v[26:29], v[180:183], v[196:199], v[26:29]
	v_mfma_f32_16x16x32_bf16 v[18:21], v[172:175], v[204:207], v[18:21]
	v_mfma_f32_16x16x32_bf16 v[10:13], v[180:183], v[204:207], v[10:13]
	v_mfma_f32_16x16x32_bf16 v[6:9], v[172:175], v[214:217], v[6:9]
	v_mfma_f32_16x16x32_bf16 v[2:5], v[180:183], v[214:217], v[2:5]
	s_setprio 0
	s_barrier
	s_add_i32 s59, s59, 2
	s_add_u32 s30, s30, 0x100
	s_addc_u32 s31, s31, 0
	s_add_u32 s57, s57, 0x100
	s_addc_u32 s58, s58, 0
	s_cmp_gt_u32 s59, 29
	s_cbranch_scc1 .Lpeel_exit_32
	.p2align 6

; #define PG8_STAGE(bufoff, gbase, voff) do { _Pragma("unroll") for (int _i = 0; _i < 2; ++_i) \
;         __builtin_amdgcn_global_load_lds((const unsigned*)((const char*)(gbase) + (voff)[_i]), (PG8_LAS unsigned*)(lds + (bufoff) + ldsw + _i * 8192), 16, 0, 0); } while (0)
; #define PG8_WAIT_V(n) asm volatile("s_waitcnt vmcnt(" #n ")" ::: "memory")
; #define PG8_BAR __builtin_amdgcn_s_barrier()
; template <class Epi, class Sched, bool ALIGN_EPI = false, bool SP2 = false>
; __device__ __forceinline__ void gemm_phase(PG8_LAS unsigned char* lds, const Gemm g, const Sched& S, const Epi& E) {
;     const int tid = threadIdx.x, wid = __builtin_amdgcn_readfirstlane(tid >> 6), lane = tid & 63, wr = wid >> 2, wc = wid & 3, fr = lane & 15, fq = lane >> 4;
;     const int K = g.K, nt = K / BK;
;     unsigned voffA[2], voffB[2];
; #pragma unroll
;     for (int i = 0; i < 2; ++i) { int R, C; stage_rc(tid * 16 + i * 8192, R, C); const int Rb = Epi::PERM ? ((R & ~31) + perm32(R & 31)) : R;
;         voffA[i] = (unsigned)(R * g.lda + C) * 2u; voffB[i] = (unsigned)(Rb * g.ldb + C) * 2u; }
;     const size_t kstep = (size_t)(BK * 2);
;     const size_t hstepA = (size_t)HALF * g.lda * 2, hstepB = (size_t)HALF * g.ldb * 2;
;     const size_t tstepA = 2 * hstepA, tstepB = 2 * hstepB;
;     const unsigned ldsw = (unsigned)wid * 1024u;
;     const int aoff = lds_byte(wr * 64 + fr, fq * 8), boff = lds_byte(wc * 32 + fr, fq * 8);
;     ...
;         PG8_WAIT_V(2); PG8_BAR;
;         PG8_STAGE(PG8_SB(1, 0), cB + kstep, voffB); PG8_STAGE(PG8_SA(1, 0), cA + kstep, voffA); PG8_STAGE(PG8_SB(1, 1), cB + hstepB + kstep, voffB);
;         PG8_WAIT_V(6); PG8_BAR;
.LBB0_3494:
	s_lshl_b32 s6, s6, 5
	s_and_b32 s12, s6, 0x60
	s_mov_b64 s[6:7], 0x80
	s_add_i32 m0, s19, 0x18000
	v_lshl_add_u64 v[8:9], v[8:9], 0, s[6:7]
	s_lshl_b32 s9, s8, 13
	s_lshl_b32 s13, s12, 7
	s_waitcnt vmcnt(2)
	s_barrier
	global_load_lds_dwordx4 v[8:9], off
	v_lshl_add_u64 v[6:7], v[6:7], 0, s[6:7]
	s_add_i32 m0, s19, 0x1a000
	s_add_i32 s37, s19, 0x8000
	s_add_i32 s38, s19, 0xa000
	global_load_lds_dwordx4 v[6:7], off
	v_lshl_add_u64 v[2:3], v[2:3], 0, s[6:7]
	s_mov_b32 m0, s37
	s_add_u32 s10, s22, 0x80080
	global_load_lds_dwordx4 v[2:3], off
	v_lshl_add_u64 v[2:3], v[4:5], 0, s[6:7]
	s_mov_b32 m0, s38
	s_addc_u32 s11, s23, 0
	global_load_lds_dwordx4 v[2:3], off
	s_add_i32 m0, s19, 0x1c000
	v_lshl_add_u64 v[2:3], s[10:11], 0, v[134:135]
	global_load_lds_dwordx4 v[2:3], off
	v_lshl_add_u64 v[2:3], s[10:11], 0, v[130:131]
	s_add_i32 m0, s19, 0x1e000
	s_sext_i32_i16 s43, s4
	global_load_lds_dwordx4 v[2:3], off
	v_and_b32_e32 v2, 15, v0
	v_lshlrev_b32_e32 v3, 1, v13
	v_lshlrev_b32_e32 v4, 2, v0
	v_lshlrev_b32_e32 v5, 6, v0
	s_movk_i32 s4, 0x3c0
	v_lshl_or_b32 v1, s8, 6, v2
	v_lshl_or_b32 v2, v2, 6, v3
	v_and_b32_e32 v4, 32, v4
	v_and_or_b32 v3, v5, s4, v3
	v_bitop3_b32 v148, s13, v3, v4 bitop3:0xf6
	v_lshlrev_b32_e32 v3, 9, v0
	v_bitop3_b32 v2, v2, s9, v4 bitop3:0xde
	v_and_b32_e32 v3, 0x30000, v3
	v_lshlrev_b32_e32 v4, 12, v14
	v_or3_b32 v3, v11, v3, v4
	v_add_u32_e32 v138, v3, v12
	v_lshlrev_b32_e32 v3, 5, v10
	s_waitcnt vmcnt(0)
	s_cmpk_lt_u32 s5, 0x100
	v_and_b32_e32 v3, 0x70000, v3
	s_cselect_b64 s[8:9], -1, 0
	v_or3_b32 v3, v11, v3, v4
	s_add_i32 s40, 0, 0x10000
	s_add_i32 s41, 0, 0x14000
	s_ashr_i32 s39, s26, 31
	v_or_b32_e32 v149, s12, v13
	v_mov_b32_e32 v139, v135
	v_add_u32_e32 v140, v3, v12
	v_mov_b32_e32 v141, v135
	v_mov_b64_e32 v[142:143], 0x1b80
	v_mov_b64_e32 v[144:145], 0x1b7f
	v_add_u32_e32 v150, s40, v148
	v_add_u32_e32 v151, s41, v148
	v_add_u32_e32 v152, 0, v2
	s_movk_i32 s42, 0x2c00
	s_barrier
	s_branch .LBB0_3497

; #define PG8_STAGE(bufoff, gbase, voff) do { _Pragma("unroll") for (int _i = 0; _i < 2; ++_i) \
;         __builtin_amdgcn_global_load_lds((const unsigned*)((const char*)(gbase) + (voff)[_i]), (PG8_LAS unsigned*)(lds + (bufoff) + ldsw + _i * 8192), 16, 0, 0); } while (0)
; #define PG8_LDA(dst, b, h) do { _Pragma("unroll") for (int m = 0; m < 4; ++m) _Pragma("unroll") for (int k = 0; k < 2; ++k) dst[m][k] = *(const PG8_LAS bf16x8*)(lds + PG8_SA(b, h) + aoff + m * 2048 + k * 1024); } while (0)
; #define PG8_LDB(dst, b, h) do { _Pragma("unroll") for (int n = 0; n < 2; ++n) _Pragma("unroll") for (int k = 0; k < 2; ++k) dst[n][k] = *(const PG8_LAS bf16x8*)(lds + PG8_SB(b, h) + boff + n * 2048 + k * 1024); } while (0)
; #define PG8_WAIT_V(n) asm volatile("s_waitcnt vmcnt(" #n ")" ::: "memory")
; #define PG8_WAIT_L(n) asm volatile("s_waitcnt lgkmcnt(" #n ")" ::: "memory")
; #define PG8_BAR __builtin_amdgcn_s_barrier()
; #define PG8_SCHED __builtin_amdgcn_sched_barrier(0)
; template <class Epi, class Sched, bool ALIGN_EPI = false, bool SP2 = false>
; __device__ __forceinline__ void gemm_phase(PG8_LAS unsigned char* lds, const Gemm g, const Sched& S, const Epi& E) {
;     ...
;         const bool has_next = S.next(ui + 1, nxt);
;         const char* nA = has_next ? (const char*)g.A + (size_t)nxt.pm * tstepA : cA; const char* nB = has_next ? (const char*)g.Bt + (size_t)nxt.pn * tstepB : cB;
;         for (int t = 0; t < nt; t += 2) {
;             const bool last = (t == nt - 2);
;             const char* a1 = cA + (size_t)(t + 1) * kstep;
;             const char* a2 = last ? nA : cA + (size_t)(t + 2) * kstep; const char* b2 = last ? nB : cB + (size_t)(t + 2) * kstep;
;             const char* a3 = a2 + kstep; const char* b3 = b2 + kstep;
;             if (last && has_next) S.a_ready(nxt);
;             if constexpr (SP2) {
;             PG8_LDB(B0, 0, 0); PG8_LDB(B1, 0, 1); PG8_SCHED; PG8_LDA(At, 0, 0); PG8_STAGE(PG8_SA(1, 1), a1 + hstepA, voffA);
;             PG8_WAIT_V(8); PG8_WAIT_L(0); PG8_BAR; PG8_MMA(0, 0, At, B0); PG8_MMA(0, 1, At, B1); PG8_BAR; PG8_SCHED;
;     ...
;         for (int a = 0; a < 2; ++a)
; #pragma unroll
;             for (int b = 0; b < 2; ++b)
; #pragma unroll
;                 for (int m = 0; m < 4; ++m)
; #pragma unroll
;                     for (int n = 0; n < 2; ++n) acc[a][b][m][n] = (f32x4){0.f, 0.f, 0.f, 0.f};
.LBB0_3499:
	s_ashr_i32 s13, s12, 31
	s_lshl_b64 s[14:15], s[12:13], 20
	s_add_u32 s14, s86, s14
	s_addc_u32 s15, s87, s15
	s_and_b64 s[16:17], s[4:5], exec
	s_cselect_b32 s13, s15, s21
	s_cselect_b32 s44, s14, s20
	s_ashr_i32 s11, s10, 31
	s_lshl_b64 s[16:17], s[10:11], 20
	s_add_u32 s16, s27, s16
	s_addc_u32 s17, s28, s17
	s_and_b64 s[24:25], s[4:5], exec
	s_cselect_b32 s11, s17, s23
	s_cselect_b32 s45, s16, s22
	s_add_u32 s20, s20, 0x80080
	s_addc_u32 s21, s21, 0
	s_add_u32 s46, s22, 0x100
	v_mov_b32_e32 v2, 0
	s_addc_u32 s47, s23, 0
	s_mov_b32 s48, -2
	v_mov_b32_e32 v3, v2
	v_mov_b32_e32 v4, v2
	v_mov_b32_e32 v5, v2
	v_mov_b32_e32 v6, v2
	v_mov_b32_e32 v7, v2
	v_mov_b32_e32 v8, v2
	v_mov_b32_e32 v9, v2
	v_mov_b32_e32 v18, v2
	v_mov_b32_e32 v19, v2
	v_mov_b32_e32 v20, v2
	v_mov_b32_e32 v21, v2
	v_mov_b32_e32 v22, v2
	v_mov_b32_e32 v23, v2
	v_mov_b32_e32 v24, v2
	v_mov_b32_e32 v25, v2
	v_mov_b32_e32 v34, v2
	v_mov_b32_e32 v35, v2
	v_mov_b32_e32 v36, v2
	v_mov_b32_e32 v37, v2
	v_mov_b32_e32 v38, v2
	v_mov_b32_e32 v39, v2
	v_mov_b32_e32 v40, v2
	v_mov_b32_e32 v41, v2
	v_mov_b32_e32 v50, v2
	v_mov_b32_e32 v51, v2
	v_mov_b32_e32 v52, v2
	v_mov_b32_e32 v53, v2
	v_mov_b32_e32 v54, v2
	v_mov_b32_e32 v55, v2
	v_mov_b32_e32 v56, v2
	v_mov_b32_e32 v57, v2
	v_mov_b32_e32 v10, v2
	v_mov_b32_e32 v11, v2
	v_mov_b32_e32 v12, v2
	v_mov_b32_e32 v13, v2
	v_mov_b32_e32 v14, v2
	v_mov_b32_e32 v15, v2
	v_mov_b32_e32 v16, v2
	v_mov_b32_e32 v17, v2
	v_mov_b32_e32 v26, v2
	v_mov_b32_e32 v27, v2
	v_mov_b32_e32 v28, v2
	v_mov_b32_e32 v29, v2
	v_mov_b32_e32 v30, v2
	v_mov_b32_e32 v31, v2
	v_mov_b32_e32 v32, v2
	v_mov_b32_e32 v33, v2
	v_mov_b32_e32 v42, v2
	v_mov_b32_e32 v43, v2
	v_mov_b32_e32 v44, v2
	v_mov_b32_e32 v45, v2
	v_mov_b32_e32 v46, v2
	v_mov_b32_e32 v47, v2
	v_mov_b32_e32 v48, v2
	v_mov_b32_e32 v49, v2
	v_mov_b32_e32 v58, v2
	v_mov_b32_e32 v59, v2
	v_mov_b32_e32 v60, v2
	v_mov_b32_e32 v61, v2
	v_mov_b32_e32 v62, v2
	v_mov_b32_e32 v63, v2
	v_mov_b32_e32 v64, v2
	v_mov_b32_e32 v65, v2
	v_mov_b32_e32 v66, v2
	v_mov_b32_e32 v67, v2
	v_mov_b32_e32 v68, v2
	v_mov_b32_e32 v69, v2
	v_mov_b32_e32 v70, v2
	v_mov_b32_e32 v71, v2
	v_mov_b32_e32 v72, v2
	v_mov_b32_e32 v73, v2
	v_mov_b32_e32 v82, v2
	v_mov_b32_e32 v83, v2
	v_mov_b32_e32 v84, v2
	v_mov_b32_e32 v85, v2
	v_mov_b32_e32 v86, v2
	v_mov_b32_e32 v87, v2
	v_mov_b32_e32 v88, v2
	v_mov_b32_e32 v89, v2
	v_mov_b32_e32 v98, v2
	v_mov_b32_e32 v99, v2
	v_mov_b32_e32 v100, v2
	v_mov_b32_e32 v101, v2
	v_mov_b32_e32 v102, v2
	v_mov_b32_e32 v103, v2
	v_mov_b32_e32 v104, v2
	v_mov_b32_e32 v105, v2
	v_mov_b32_e32 v114, v2
	v_mov_b32_e32 v115, v2
	v_mov_b32_e32 v116, v2
	v_mov_b32_e32 v117, v2
	v_mov_b32_e32 v118, v2
	v_mov_b32_e32 v119, v2
	v_mov_b32_e32 v120, v2
	v_mov_b32_e32 v121, v2
	v_mov_b32_e32 v74, v2
	v_mov_b32_e32 v75, v2
	v_mov_b32_e32 v76, v2
	v_mov_b32_e32 v77, v2
	v_mov_b32_e32 v78, v2
	v_mov_b32_e32 v79, v2
	v_mov_b32_e32 v80, v2
	v_mov_b32_e32 v81, v2
	v_mov_b32_e32 v90, v2
	v_mov_b32_e32 v91, v2
	v_mov_b32_e32 v92, v2
	v_mov_b32_e32 v93, v2
	v_mov_b32_e32 v94, v2
	v_mov_b32_e32 v95, v2
	v_mov_b32_e32 v96, v2
	v_mov_b32_e32 v97, v2
	v_mov_b32_e32 v106, v2
	v_mov_b32_e32 v107, v2
	v_mov_b32_e32 v108, v2
	v_mov_b32_e32 v109, v2
	v_mov_b32_e32 v110, v2
	v_mov_b32_e32 v111, v2
	v_mov_b32_e32 v112, v2
	v_mov_b32_e32 v113, v2
	v_mov_b32_e32 v122, v2
	v_mov_b32_e32 v123, v2
	v_mov_b32_e32 v124, v2
	v_mov_b32_e32 v125, v2
	v_mov_b32_e32 v126, v2
	v_mov_b32_e32 v127, v2
	v_mov_b32_e32 v128, v2
	v_mov_b32_e32 v129, v2
	ds_read_b128 v[154:157], v150
	ds_read_b128 v[158:161], v150 offset:1024
	ds_read_b128 v[162:165], v150 offset:2048
	ds_read_b128 v[166:169], v150 offset:3072
	ds_read_b128 v[170:173], v151
	ds_read_b128 v[174:177], v151 offset:1024
	ds_read_b128 v[178:181], v151 offset:2048
	ds_read_b128 v[182:185], v151 offset:3072
	s_add_u32 s22, s20, 0xfff80080
	s_addc_u32 s23, s21, -1
	s_cmp_eq_u32 s48, 28
	s_cselect_b32 s25, s13, s23
	s_cselect_b32 s24, s44, s22
	s_cselect_b32 s23, s11, s47
	s_cselect_b32 s22, s45, s46
	v_lshl_add_u64 v[146:147], s[20:21], 0, v[138:139]
	s_add_i32 m0, s19, 0xc000
	ds_read_b128 v[186:189], v152
	ds_read_b128 v[190:193], v152 offset:1024
	ds_read_b128 v[194:197], v152 offset:2048
	ds_read_b128 v[198:201], v152 offset:3072
	ds_read_b128 v[202:205], v152 offset:4096
	ds_read_b128 v[210:213], v152 offset:5120
	ds_read_b128 v[214:217], v152 offset:6144
	ds_read_b128 v[218:221], v152 offset:7168
	global_load_lds_dwordx4 v[146:147], off
	v_lshl_add_u64 v[146:147], s[20:21], 0, v[140:141]
	s_add_i32 m0, s19, 0xe000
	s_nop 0
	global_load_lds_dwordx4 v[146:147], off
	s_waitcnt vmcnt(16)
	s_waitcnt lgkmcnt(0)
	s_barrier
; #define PG8_STAGE(bufoff, gbase, voff) do { _Pragma("unroll") for (int _i = 0; _i < 2; ++_i) \
;         __builtin_amdgcn_global_load_lds((const unsigned*)((const char*)(gbase) + (voff)[_i]), (PG8_LAS unsigned*)(lds + (bufoff) + ldsw + _i * 8192), 16, 0, 0); } while (0)
; #define PG8_LDA(dst, b, h) do { _Pragma("unroll") for (int m = 0; m < 4; ++m) _Pragma("unroll") for (int k = 0; k < 2; ++k) dst[m][k] = *(const PG8_LAS bf16x8*)(lds + PG8_SA(b, h) + aoff + m * 2048 + k * 1024); } while (0)
; #define PG8_MMA(ai, bj, At, Bt) do { __builtin_amdgcn_s_setprio(1); _Pragma("unroll") for (int m = 0; m < 4; ++m) _Pragma("unroll") for (int n = 0; n < 2; ++n) _Pragma("unroll") for (int k = 0; k < 2; ++k) \
;         acc[ai][bj][m][n] = __builtin_amdgcn_mfma_f32_16x16x32_bf16(Bt[n][k], At[m][k], acc[ai][bj][m][n], 0, 0, 0); __builtin_amdgcn_s_setprio(0); } while (0)
; #define PG8_WAIT_V(n) asm volatile("s_waitcnt vmcnt(" #n ")" ::: "memory")
; #define PG8_WAIT_L(n) asm volatile("s_waitcnt lgkmcnt(" #n ")" ::: "memory")
; #define PG8_BAR __builtin_amdgcn_s_barrier()
; #define PG8_SCHED __builtin_amdgcn_sched_barrier(0)
; template <class Epi, class Sched, bool ALIGN_EPI = false, bool SP2 = false>
; __device__ __forceinline__ void gemm_phase(PG8_LAS unsigned char* lds, const Gemm g, const Sched& S, const Epi& E) {
;     ...
;             PG8_WAIT_V(8); PG8_WAIT_L(0); PG8_BAR; PG8_MMA(0, 0, At, B0); PG8_MMA(0, 1, At, B1); PG8_BAR; PG8_SCHED;
;             PG8_LDA(At, 0, 1); PG8_STAGE(PG8_SB(0, 0), b2, voffB); PG8_STAGE(PG8_SB(0, 1), b2 + hstepB, voffB); PG8_STAGE(PG8_SA(0, 0), a2, voffA);
;             PG8_WAIT_V(8); PG8_WAIT_L(0); PG8_BAR; PG8_MMA(1, 0, At, B0); PG8_MMA(1, 1, At, B1); PG8_BAR; PG8_SCHED;
	s_setprio 1
	s_waitcnt lgkmcnt(0)
	v_mfma_f32_16x16x32_bf16 v[126:129], v[154:157], v[186:189], v[126:129]
	v_mfma_f32_16x16x32_bf16 v[122:125], v[162:165], v[186:189], v[122:125]
	v_mfma_f32_16x16x32_bf16 v[110:113], v[154:157], v[194:197], v[110:113]
	v_mfma_f32_16x16x32_bf16 v[106:109], v[162:165], v[194:197], v[106:109]
	v_mfma_f32_16x16x32_bf16 v[94:97], v[154:157], v[202:205], v[94:97]
	v_mfma_f32_16x16x32_bf16 v[90:93], v[162:165], v[202:205], v[90:93]
	v_mfma_f32_16x16x32_bf16 v[78:81], v[154:157], v[214:217], v[78:81]
	v_mfma_f32_16x16x32_bf16 v[74:77], v[162:165], v[214:217], v[74:77]
	v_mfma_f32_16x16x32_bf16 v[126:129], v[158:161], v[190:193], v[126:129]
	v_mfma_f32_16x16x32_bf16 v[122:125], v[166:169], v[190:193], v[122:125]
	v_mfma_f32_16x16x32_bf16 v[110:113], v[158:161], v[198:201], v[110:113]
	v_mfma_f32_16x16x32_bf16 v[106:109], v[166:169], v[198:201], v[106:109]
	v_mfma_f32_16x16x32_bf16 v[94:97], v[158:161], v[210:213], v[94:97]
	v_mfma_f32_16x16x32_bf16 v[90:93], v[166:169], v[210:213], v[90:93]
	v_mfma_f32_16x16x32_bf16 v[78:81], v[158:161], v[218:221], v[78:81]
	v_mfma_f32_16x16x32_bf16 v[74:77], v[166:169], v[218:221], v[74:77]
	s_setprio 0
	s_setprio 1
	v_mfma_f32_16x16x32_bf16 v[118:121], v[170:173], v[186:189], v[118:121]
	v_mfma_f32_16x16x32_bf16 v[114:117], v[178:181], v[186:189], v[114:117]
	v_mfma_f32_16x16x32_bf16 v[102:105], v[170:173], v[194:197], v[102:105]
	v_mfma_f32_16x16x32_bf16 v[98:101], v[178:181], v[194:197], v[98:101]
	v_mfma_f32_16x16x32_bf16 v[86:89], v[170:173], v[202:205], v[86:89]
	v_mfma_f32_16x16x32_bf16 v[82:85], v[178:181], v[202:205], v[82:85]
	v_mfma_f32_16x16x32_bf16 v[70:73], v[170:173], v[214:217], v[70:73]
	v_mfma_f32_16x16x32_bf16 v[66:69], v[178:181], v[214:217], v[66:69]
	v_mfma_f32_16x16x32_bf16 v[118:121], v[174:177], v[190:193], v[118:121]
	v_mfma_f32_16x16x32_bf16 v[114:117], v[182:185], v[190:193], v[114:117]
	v_mfma_f32_16x16x32_bf16 v[102:105], v[174:177], v[198:201], v[102:105]
	v_mfma_f32_16x16x32_bf16 v[98:101], v[182:185], v[198:201], v[98:101]
	v_mfma_f32_16x16x32_bf16 v[86:89], v[174:177], v[210:213], v[86:89]
	v_mfma_f32_16x16x32_bf16 v[82:85], v[182:185], v[210:213], v[82:85]
	v_mfma_f32_16x16x32_bf16 v[70:73], v[174:177], v[218:221], v[70:73]
	v_mfma_f32_16x16x32_bf16 v[66:69], v[182:185], v[218:221], v[66:69]
	s_setprio 0
	s_barrier
	s_add_i32 s49, s40, s29
	v_lshl_add_u64 v[146:147], s[22:23], 0, v[134:135]
	s_mov_b32 m0, s49
	ds_read_b128 v[186:189], v152 offset:16384
	ds_read_b128 v[190:193], v152 offset:17408
	ds_read_b128 v[194:197], v152 offset:18432
	ds_read_b128 v[198:201], v152 offset:19456
	ds_read_b128 v[202:205], v152 offset:20480
	ds_read_b128 v[210:213], v152 offset:21504
	ds_read_b128 v[214:217], v152 offset:22528
	ds_read_b128 v[218:221], v152 offset:23552
	global_load_lds_dwordx4 v[146:147], off
	s_add_i32 m0, s49, 0x2000
	s_add_u32 s50, s22, 0x80000
	v_lshl_add_u64 v[206:207], s[22:23], 0, v[130:131]
	s_addc_u32 s51, s23, 0
	s_add_i32 s49, s41, s29
	global_load_lds_dwordx4 v[206:207], off
	v_lshl_add_u64 v[222:223], s[50:51], 0, v[134:135]
	s_mov_b32 m0, s49
	v_lshl_add_u64 v[224:225], s[24:25], 0, v[132:133]
	global_load_lds_dwordx4 v[222:223], off
	v_lshl_add_u64 v[222:223], s[50:51], 0, v[130:131]
	s_add_i32 m0, s49, 0x2000
	s_nop 0
	global_load_lds_dwordx4 v[222:223], off
	v_lshl_add_u64 v[222:223], s[24:25], 0, v[136:137]
	s_mov_b32 m0, s19
	s_nop 0
	global_load_lds_dwordx4 v[222:223], off
	s_mov_b32 m0, s33
	s_nop 0
	global_load_lds_dwordx4 v[224:225], off
	s_waitcnt vmcnt(16)
	s_waitcnt lgkmcnt(0)
	s_barrier
	s_setprio 1
	s_waitcnt lgkmcnt(0)
	v_mfma_f32_16x16x32_bf16 v[62:65], v[154:157], v[186:189], v[62:65]
	v_mfma_f32_16x16x32_bf16 v[58:61], v[162:165], v[186:189], v[58:61]
	v_mfma_f32_16x16x32_bf16 v[46:49], v[154:157], v[194:197], v[46:49]
	v_mfma_f32_16x16x32_bf16 v[42:45], v[162:165], v[194:197], v[42:45]
	v_mfma_f32_16x16x32_bf16 v[30:33], v[154:157], v[202:205], v[30:33]
	v_mfma_f32_16x16x32_bf16 v[26:29], v[162:165], v[202:205], v[26:29]
	v_mfma_f32_16x16x32_bf16 v[14:17], v[154:157], v[214:217], v[14:17]
	v_mfma_f32_16x16x32_bf16 v[10:13], v[162:165], v[214:217], v[10:13]
	v_mfma_f32_16x16x32_bf16 v[62:65], v[158:161], v[190:193], v[62:65]
	v_mfma_f32_16x16x32_bf16 v[58:61], v[166:169], v[190:193], v[58:61]
	v_mfma_f32_16x16x32_bf16 v[46:49], v[158:161], v[198:201], v[46:49]
	v_mfma_f32_16x16x32_bf16 v[42:45], v[166:169], v[198:201], v[42:45]
	v_mfma_f32_16x16x32_bf16 v[30:33], v[158:161], v[210:213], v[30:33]
	v_mfma_f32_16x16x32_bf16 v[26:29], v[166:169], v[210:213], v[26:29]
	v_mfma_f32_16x16x32_bf16 v[14:17], v[158:161], v[218:221], v[14:17]
	v_mfma_f32_16x16x32_bf16 v[10:13], v[166:169], v[218:221], v[10:13]
	s_setprio 0
	s_setprio 1
	v_mfma_f32_16x16x32_bf16 v[54:57], v[170:173], v[186:189], v[54:57]
	v_mfma_f32_16x16x32_bf16 v[50:53], v[178:181], v[186:189], v[50:53]
	v_mfma_f32_16x16x32_bf16 v[38:41], v[170:173], v[194:197], v[38:41]
	v_mfma_f32_16x16x32_bf16 v[34:37], v[178:181], v[194:197], v[34:37]
	v_mfma_f32_16x16x32_bf16 v[22:25], v[170:173], v[202:205], v[22:25]
	v_mfma_f32_16x16x32_bf16 v[18:21], v[178:181], v[202:205], v[18:21]
	v_mfma_f32_16x16x32_bf16 v[6:9], v[170:173], v[214:217], v[6:9]
	v_mfma_f32_16x16x32_bf16 v[2:5], v[178:181], v[214:217], v[2:5]
	v_mfma_f32_16x16x32_bf16 v[54:57], v[174:177], v[190:193], v[54:57]
	v_mfma_f32_16x16x32_bf16 v[50:53], v[182:185], v[190:193], v[50:53]
	v_mfma_f32_16x16x32_bf16 v[38:41], v[174:177], v[198:201], v[38:41]
	v_mfma_f32_16x16x32_bf16 v[34:37], v[182:185], v[198:201], v[34:37]
	v_mfma_f32_16x16x32_bf16 v[22:25], v[174:177], v[210:213], v[22:25]
	v_mfma_f32_16x16x32_bf16 v[18:21], v[182:185], v[210:213], v[18:21]
	v_mfma_f32_16x16x32_bf16 v[6:9], v[174:177], v[218:221], v[6:9]
	v_mfma_f32_16x16x32_bf16 v[2:5], v[182:185], v[218:221], v[2:5]
	s_setprio 0
	s_barrier
; #define PG8_STAGE(bufoff, gbase, voff) do { _Pragma("unroll") for (int _i = 0; _i < 2; ++_i) \
;         __builtin_amdgcn_global_load_lds((const unsigned*)((const char*)(gbase) + (voff)[_i]), (PG8_LAS unsigned*)(lds + (bufoff) + ldsw + _i * 8192), 16, 0, 0); } while (0)
; #define PG8_LDA(dst, b, h) do { _Pragma("unroll") for (int m = 0; m < 4; ++m) _Pragma("unroll") for (int k = 0; k < 2; ++k) dst[m][k] = *(const PG8_LAS bf16x8*)(lds + PG8_SA(b, h) + aoff + m * 2048 + k * 1024); } while (0)
; #define PG8_LDB(dst, b, h) do { _Pragma("unroll") for (int n = 0; n < 2; ++n) _Pragma("unroll") for (int k = 0; k < 2; ++k) dst[n][k] = *(const PG8_LAS bf16x8*)(lds + PG8_SB(b, h) + boff + n * 2048 + k * 1024); } while (0)
; #define PG8_MMA(ai, bj, At, Bt) do { __builtin_amdgcn_s_setprio(1); _Pragma("unroll") for (int m = 0; m < 4; ++m) _Pragma("unroll") for (int n = 0; n < 2; ++n) _Pragma("unroll") for (int k = 0; k < 2; ++k) \
;         acc[ai][bj][m][n] = __builtin_amdgcn_mfma_f32_16x16x32_bf16(Bt[n][k], At[m][k], acc[ai][bj][m][n], 0, 0, 0); __builtin_amdgcn_s_setprio(0); } while (0)
; #define PG8_WAIT_V(n) asm volatile("s_waitcnt vmcnt(" #n ")" ::: "memory")
; #define PG8_WAIT_L(n) asm volatile("s_waitcnt lgkmcnt(" #n ")" ::: "memory")
; #define PG8_BAR __builtin_amdgcn_s_barrier()
; #define PG8_SCHED __builtin_amdgcn_sched_barrier(0)
; template <class Epi, class Sched, bool ALIGN_EPI = false, bool SP2 = false>
; __device__ __forceinline__ void gemm_phase(PG8_LAS unsigned char* lds, const Gemm g, const Sched& S, const Epi& E) {
;     ...
;             PG8_LDB(B0, 1, 0); PG8_LDB(B1, 1, 1); PG8_SCHED; PG8_LDA(At, 1, 0); PG8_STAGE(PG8_SA(0, 1), a2 + hstepA, voffA);
;             PG8_WAIT_V(8); PG8_WAIT_L(0); PG8_BAR; PG8_MMA(0, 0, At, B0); PG8_MMA(0, 1, At, B1); PG8_BAR; PG8_SCHED;
	s_add_i32 s49, 0, 0x18000
	v_add_u32_e32 v153, s49, v148
	s_add_i32 s50, 0, 0x1c000
	ds_read_b128 v[154:157], v153
	ds_read_b128 v[158:161], v153 offset:1024
	ds_read_b128 v[162:165], v153 offset:2048
	ds_read_b128 v[166:169], v153 offset:3072
	v_add_u32_e32 v153, s50, v148
	ds_read_b128 v[170:173], v153
	ds_read_b128 v[174:177], v153 offset:1024
	ds_read_b128 v[178:181], v153 offset:2048
	ds_read_b128 v[182:185], v153 offset:3072
	s_add_u32 s24, s24, 0x80000
	s_addc_u32 s25, s25, 0
	s_mov_b32 m0, s34
	v_lshl_add_u64 v[226:227], s[24:25], 0, v[136:137]
	ds_read_b128 v[186:189], v152 offset:32768
	ds_read_b128 v[190:193], v152 offset:33792
	ds_read_b128 v[194:197], v152 offset:34816
	ds_read_b128 v[198:201], v152 offset:35840
	ds_read_b128 v[202:205], v152 offset:36864
	ds_read_b128 v[210:213], v152 offset:37888
	ds_read_b128 v[214:217], v152 offset:38912
	ds_read_b128 v[218:221], v152 offset:39936
	global_load_lds_dwordx4 v[226:227], off
	v_lshl_add_u64 v[226:227], s[24:25], 0, v[132:133]
	s_mov_b32 m0, s35
	s_nop 0
	global_load_lds_dwordx4 v[226:227], off
	s_waitcnt vmcnt(8)
	s_waitcnt lgkmcnt(0)
	s_barrier
	s_setprio 1
	s_waitcnt lgkmcnt(0)
	v_mfma_f32_16x16x32_bf16 v[126:129], v[154:157], v[186:189], v[126:129]
	v_mfma_f32_16x16x32_bf16 v[122:125], v[162:165], v[186:189], v[122:125]
	v_mfma_f32_16x16x32_bf16 v[110:113], v[154:157], v[194:197], v[110:113]
	v_mfma_f32_16x16x32_bf16 v[106:109], v[162:165], v[194:197], v[106:109]
	v_mfma_f32_16x16x32_bf16 v[94:97], v[154:157], v[202:205], v[94:97]
	v_mfma_f32_16x16x32_bf16 v[90:93], v[162:165], v[202:205], v[90:93]
	v_mfma_f32_16x16x32_bf16 v[78:81], v[154:157], v[214:217], v[78:81]
	v_mfma_f32_16x16x32_bf16 v[74:77], v[162:165], v[214:217], v[74:77]
	v_mfma_f32_16x16x32_bf16 v[126:129], v[158:161], v[190:193], v[126:129]
	v_mfma_f32_16x16x32_bf16 v[122:125], v[166:169], v[190:193], v[122:125]
	v_mfma_f32_16x16x32_bf16 v[110:113], v[158:161], v[198:201], v[110:113]
	v_mfma_f32_16x16x32_bf16 v[106:109], v[166:169], v[198:201], v[106:109]
	v_mfma_f32_16x16x32_bf16 v[94:97], v[158:161], v[210:213], v[94:97]
	v_mfma_f32_16x16x32_bf16 v[90:93], v[166:169], v[210:213], v[90:93]
	v_mfma_f32_16x16x32_bf16 v[78:81], v[158:161], v[218:221], v[78:81]
	v_mfma_f32_16x16x32_bf16 v[74:77], v[166:169], v[218:221], v[74:77]
	s_setprio 0
	s_setprio 1
	v_mfma_f32_16x16x32_bf16 v[118:121], v[170:173], v[186:189], v[118:121]
	v_mfma_f32_16x16x32_bf16 v[114:117], v[178:181], v[186:189], v[114:117]
	v_mfma_f32_16x16x32_bf16 v[102:105], v[170:173], v[194:197], v[102:105]
	v_mfma_f32_16x16x32_bf16 v[98:101], v[178:181], v[194:197], v[98:101]
	v_mfma_f32_16x16x32_bf16 v[86:89], v[170:173], v[202:205], v[86:89]
	v_mfma_f32_16x16x32_bf16 v[82:85], v[178:181], v[202:205], v[82:85]
	v_mfma_f32_16x16x32_bf16 v[70:73], v[170:173], v[214:217], v[70:73]
	v_mfma_f32_16x16x32_bf16 v[66:69], v[178:181], v[214:217], v[66:69]
	v_mfma_f32_16x16x32_bf16 v[118:121], v[174:177], v[190:193], v[118:121]
	v_mfma_f32_16x16x32_bf16 v[114:117], v[182:185], v[190:193], v[114:117]
	v_mfma_f32_16x16x32_bf16 v[102:105], v[174:177], v[198:201], v[102:105]
	v_mfma_f32_16x16x32_bf16 v[98:101], v[182:185], v[198:201], v[98:101]
	v_mfma_f32_16x16x32_bf16 v[86:89], v[174:177], v[210:213], v[86:89]
	v_mfma_f32_16x16x32_bf16 v[82:85], v[182:185], v[210:213], v[82:85]
	v_mfma_f32_16x16x32_bf16 v[70:73], v[174:177], v[218:221], v[70:73]
	v_mfma_f32_16x16x32_bf16 v[66:69], v[182:185], v[218:221], v[66:69]
	s_setprio 0
	s_barrier
; #define PG8_STAGE(bufoff, gbase, voff) do { _Pragma("unroll") for (int _i = 0; _i < 2; ++_i) \
;         __builtin_amdgcn_global_load_lds((const unsigned*)((const char*)(gbase) + (voff)[_i]), (PG8_LAS unsigned*)(lds + (bufoff) + ldsw + _i * 8192), 16, 0, 0); } while (0)
; #define PG8_LDA(dst, b, h) do { _Pragma("unroll") for (int m = 0; m < 4; ++m) _Pragma("unroll") for (int k = 0; k < 2; ++k) dst[m][k] = *(const PG8_LAS bf16x8*)(lds + PG8_SA(b, h) + aoff + m * 2048 + k * 1024); } while (0)
; #define PG8_MMA(ai, bj, At, Bt) do { __builtin_amdgcn_s_setprio(1); _Pragma("unroll") for (int m = 0; m < 4; ++m) _Pragma("unroll") for (int n = 0; n < 2; ++n) _Pragma("unroll") for (int k = 0; k < 2; ++k) \
;         acc[ai][bj][m][n] = __builtin_amdgcn_mfma_f32_16x16x32_bf16(Bt[n][k], At[m][k], acc[ai][bj][m][n], 0, 0, 0); __builtin_amdgcn_s_setprio(0); } while (0)
; #define PG8_WAIT_V(n) asm volatile("s_waitcnt vmcnt(" #n ")" ::: "memory")
; #define PG8_WAIT_L(n) asm volatile("s_waitcnt lgkmcnt(" #n ")" ::: "memory")
; #define PG8_BAR __builtin_amdgcn_s_barrier()
; #define PG8_SCHED __builtin_amdgcn_sched_barrier(0)
; template <class Epi, class Sched, bool ALIGN_EPI = false, bool SP2 = false>
; __device__ __forceinline__ void gemm_phase(PG8_LAS unsigned char* lds, const Gemm g, const Sched& S, const Epi& E) {
;     ...
;         for (int t = 0; t < nt; t += 2) {
;             const bool last = (t == nt - 2);
;             const char* a1 = cA + (size_t)(t + 1) * kstep;
;             const char* a2 = last ? nA : cA + (size_t)(t + 2) * kstep; const char* b2 = last ? nB : cB + (size_t)(t + 2) * kstep;
;             const char* a3 = a2 + kstep; const char* b3 = b2 + kstep;
;     ...
;             PG8_LDA(At, 1, 1); PG8_STAGE(PG8_SB(1, 0), b3, voffB); PG8_STAGE(PG8_SB(1, 1), b3 + hstepB, voffB); PG8_STAGE(PG8_SA(1, 0), a3, voffA);
;             PG8_WAIT_V(8); PG8_WAIT_L(0); PG8_BAR; PG8_MMA(1, 0, At, B0); PG8_MMA(1, 1, At, B1); PG8_BAR; PG8_SCHED;
	s_add_i32 s24, s49, s29
	v_lshl_add_u64 v[146:147], v[146:147], 0, s[6:7]
	s_mov_b32 m0, s24
	ds_read_b128 v[186:189], v152 offset:49152
	ds_read_b128 v[190:193], v152 offset:50176
	ds_read_b128 v[194:197], v152 offset:51200
	ds_read_b128 v[198:201], v152 offset:52224
	ds_read_b128 v[202:205], v152 offset:53248
	ds_read_b128 v[210:213], v152 offset:54272
	ds_read_b128 v[214:217], v152 offset:55296
	ds_read_b128 v[218:221], v152 offset:56320
	global_load_lds_dwordx4 v[146:147], off
	s_add_i32 m0, s24, 0x2000
	s_add_u32 s22, s22, 0x80080
	v_lshl_add_u64 v[146:147], v[206:207], 0, s[6:7]
	s_addc_u32 s23, s23, 0
	s_add_i32 s24, s50, s29
	global_load_lds_dwordx4 v[146:147], off
	v_lshl_add_u64 v[146:147], s[22:23], 0, v[134:135]
	s_mov_b32 m0, s24
	s_nop 0
	global_load_lds_dwordx4 v[146:147], off
	v_lshl_add_u64 v[146:147], s[22:23], 0, v[130:131]
	s_add_i32 m0, s24, 0x2000
	s_nop 0
	global_load_lds_dwordx4 v[146:147], off
	v_lshl_add_u64 v[146:147], v[222:223], 0, s[6:7]
	s_mov_b32 m0, s37
	s_nop 0
	global_load_lds_dwordx4 v[146:147], off
	v_lshl_add_u64 v[146:147], v[224:225], 0, s[6:7]
	s_mov_b32 m0, s38
	s_nop 0
	global_load_lds_dwordx4 v[146:147], off
	s_waitcnt vmcnt(8)
	s_waitcnt lgkmcnt(0)
	s_barrier
	s_setprio 1
	s_waitcnt lgkmcnt(0)
	v_mfma_f32_16x16x32_bf16 v[62:65], v[154:157], v[186:189], v[62:65]
	v_mfma_f32_16x16x32_bf16 v[58:61], v[162:165], v[186:189], v[58:61]
	v_mfma_f32_16x16x32_bf16 v[46:49], v[154:157], v[194:197], v[46:49]
	v_mfma_f32_16x16x32_bf16 v[42:45], v[162:165], v[194:197], v[42:45]
	v_mfma_f32_16x16x32_bf16 v[30:33], v[154:157], v[202:205], v[30:33]
	v_mfma_f32_16x16x32_bf16 v[26:29], v[162:165], v[202:205], v[26:29]
	v_mfma_f32_16x16x32_bf16 v[14:17], v[154:157], v[214:217], v[14:17]
	v_mfma_f32_16x16x32_bf16 v[10:13], v[162:165], v[214:217], v[10:13]
	v_mfma_f32_16x16x32_bf16 v[62:65], v[158:161], v[190:193], v[62:65]
	v_mfma_f32_16x16x32_bf16 v[58:61], v[166:169], v[190:193], v[58:61]
	v_mfma_f32_16x16x32_bf16 v[46:49], v[158:161], v[198:201], v[46:49]
	v_mfma_f32_16x16x32_bf16 v[42:45], v[166:169], v[198:201], v[42:45]
	v_mfma_f32_16x16x32_bf16 v[30:33], v[158:161], v[210:213], v[30:33]
	v_mfma_f32_16x16x32_bf16 v[26:29], v[166:169], v[210:213], v[26:29]
	v_mfma_f32_16x16x32_bf16 v[14:17], v[158:161], v[218:221], v[14:17]
	v_mfma_f32_16x16x32_bf16 v[10:13], v[166:169], v[218:221], v[10:13]
	s_setprio 0
	s_setprio 1
	v_mfma_f32_16x16x32_bf16 v[54:57], v[170:173], v[186:189], v[54:57]
	v_mfma_f32_16x16x32_bf16 v[50:53], v[178:181], v[186:189], v[50:53]
	v_mfma_f32_16x16x32_bf16 v[38:41], v[170:173], v[194:197], v[38:41]
	v_mfma_f32_16x16x32_bf16 v[34:37], v[178:181], v[194:197], v[34:37]
	v_mfma_f32_16x16x32_bf16 v[22:25], v[170:173], v[202:205], v[22:25]
	v_mfma_f32_16x16x32_bf16 v[18:21], v[178:181], v[202:205], v[18:21]
	v_mfma_f32_16x16x32_bf16 v[6:9], v[170:173], v[214:217], v[6:9]
	v_mfma_f32_16x16x32_bf16 v[2:5], v[178:181], v[214:217], v[2:5]
	v_mfma_f32_16x16x32_bf16 v[54:57], v[174:177], v[190:193], v[54:57]
	v_mfma_f32_16x16x32_bf16 v[50:53], v[182:185], v[190:193], v[50:53]
	v_mfma_f32_16x16x32_bf16 v[38:41], v[174:177], v[198:201], v[38:41]
	v_mfma_f32_16x16x32_bf16 v[34:37], v[182:185], v[198:201], v[34:37]
	v_mfma_f32_16x16x32_bf16 v[22:25], v[174:177], v[210:213], v[22:25]
	v_mfma_f32_16x16x32_bf16 v[18:21], v[182:185], v[210:213], v[18:21]
	v_mfma_f32_16x16x32_bf16 v[6:9], v[174:177], v[218:221], v[6:9]
	v_mfma_f32_16x16x32_bf16 v[2:5], v[182:185], v[218:221], v[2:5]
	s_setprio 0
	s_barrier
	s_add_i32 s48, s48, 2
	s_add_u32 s20, s20, 0x100
	s_addc_u32 s21, s21, 0
	s_add_u32 s46, s46, 0x100
	s_addc_u32 s47, s47, 0
	s_cmp_gt_u32 s48, 29
	s_cbranch_scc1 .Lpeel_exit_34
	.p2align 6

; #define PG8_STAGE(bufoff, gbase, voff) do { _Pragma("unroll") for (int _i = 0; _i < 2; ++_i) \
;         __builtin_amdgcn_global_load_lds((const unsigned*)((const char*)(gbase) + (voff)[_i]), (PG8_LAS unsigned*)(lds + (bufoff) + ldsw + _i * 8192), 16, 0, 0); } while (0)
; #define PG8_WAIT_V(n) asm volatile("s_waitcnt vmcnt(" #n ")" ::: "memory")
; #define PG8_BAR __builtin_amdgcn_s_barrier()
; template <class Epi, class Sched, bool ALIGN_EPI = false, bool SP2 = false>
; __device__ __forceinline__ void gemm_phase(PG8_LAS unsigned char* lds, const Gemm g, const Sched& S, const Epi& E) {
;     const int tid = threadIdx.x, wid = __builtin_amdgcn_readfirstlane(tid >> 6), lane = tid & 63, wr = wid >> 2, wc = wid & 3, fr = lane & 15, fq = lane >> 4;
;     const int K = g.K, nt = K / BK;
;     unsigned voffA[2], voffB[2];
; #pragma unroll
;     for (int i = 0; i < 2; ++i) { int R, C; stage_rc(tid * 16 + i * 8192, R, C); const int Rb = Epi::PERM ? ((R & ~31) + perm32(R & 31)) : R;
;         voffA[i] = (unsigned)(R * g.lda + C) * 2u; voffB[i] = (unsigned)(Rb * g.ldb + C) * 2u; }
;     const size_t kstep = (size_t)(BK * 2);
;     const size_t hstepA = (size_t)HALF * g.lda * 2, hstepB = (size_t)HALF * g.ldb * 2;
;     const size_t tstepA = 2 * hstepA, tstepB = 2 * hstepB;
;     const unsigned ldsw = (unsigned)wid * 1024u;
;     const int aoff = lds_byte(wr * 64 + fr, fq * 8), boff = lds_byte(wc * 32 + fr, fq * 8);
;     ...
;         PG8_WAIT_V(2); PG8_BAR;
;         PG8_STAGE(PG8_SB(1, 0), cB + kstep, voffB); PG8_STAGE(PG8_SA(1, 0), cA + kstep, voffA); PG8_STAGE(PG8_SB(1, 1), cB + hstepB + kstep, voffB);
;         PG8_WAIT_V(6); PG8_BAR;
.LBB0_3561:
	s_lshl_b32 s6, s6, 5
	s_mov_b64 s[8:9], 0x80
	s_and_b32 s6, s6, 0x60
	s_add_i32 m0, s35, 0x18000
	v_lshl_add_u64 v[8:9], v[8:9], 0, s[8:9]
	s_lshl_b32 s12, s5, 13
	s_lshl_b32 s13, s6, 7
	s_waitcnt vmcnt(2)
	s_barrier
	global_load_lds_dwordx4 v[8:9], off
	v_lshl_add_u64 v[6:7], v[6:7], 0, s[8:9]
	s_add_i32 m0, s35, 0x1a000
	s_add_i32 s40, s35, 0x8000
	s_add_i32 s41, s35, 0xa000
	global_load_lds_dwordx4 v[6:7], off
	v_lshl_add_u64 v[2:3], v[2:3], 0, s[8:9]
	s_mov_b32 m0, s40
	s_add_u32 s10, s24, 0x160080
	global_load_lds_dwordx4 v[2:3], off
	v_lshl_add_u64 v[2:3], v[4:5], 0, s[8:9]
	s_mov_b32 m0, s41
	s_addc_u32 s11, s25, 0
	global_load_lds_dwordx4 v[2:3], off
	s_add_i32 m0, s35, 0x1c000
	v_lshl_add_u64 v[2:3], s[10:11], 0, v[134:135]
	global_load_lds_dwordx4 v[2:3], off
	v_lshl_add_u64 v[2:3], s[10:11], 0, v[130:131]
	s_add_i32 m0, s35, 0x1e000
	v_lshlrev_b32_e32 v4, 2, v0
	global_load_lds_dwordx4 v[2:3], off
	v_and_b32_e32 v2, 15, v0
	v_lshl_or_b32 v1, s5, 6, v2
	v_lshlrev_b32_e32 v3, 1, v10
	v_lshlrev_b32_e32 v5, 6, v0
	s_movk_i32 s5, 0x3c0
	v_lshl_or_b32 v2, v2, 6, v3
	v_and_b32_e32 v4, 32, v4
	v_and_or_b32 v3, v5, s5, v3
	v_bitop3_b32 v146, s13, v3, v4 bitop3:0xf6
	s_waitcnt vmcnt(0)
	s_cmpk_lt_u32 s4, 0x100
	v_add_u16_e32 v3, v11, v12
	v_bitop3_b32 v2, v2, s12, v4 bitop3:0xde
	s_cselect_b64 s[10:11], -1, 0
	v_lshrrev_b16_e32 v3, 1, v3
	s_add_i32 s43, 0, 0x10000
	s_add_i32 s44, 0, 0x14000
	s_sext_i32_i8 s52, s7
	s_ashr_i32 s42, s28, 31
	v_or_b32_e32 v147, s6, v10
	v_add_lshl_u32 v138, v14, v3, 1
	v_mov_b32_e32 v139, v135
	v_add_lshl_u32 v140, v13, v3, 1
	v_mov_b32_e32 v141, v135
	v_mov_b64_e32 v[142:143], 0x500
	v_mov_b64_e32 v[144:145], 0x4ff
	v_add_u32_e32 v148, s43, v146
	v_add_u32_e32 v149, s44, v146
	v_add_u32_e32 v150, 0, v2
	s_mov_b64 s[12:13], 0x80000
	s_mov_b32 s45, 0x80000
	s_mov_b64 s[14:15], 0x90000
	s_mov_b32 s46, 0x90000
	s_mov_b64 s[16:17], 0xa0000
	s_mov_b32 s47, 0xa0000
	s_mov_b64 s[18:19], 0xb0000
	s_mov_b32 s48, 0xb0000
	s_barrier
	s_branch .LBB0_3564

; #define PG8_STAGE(bufoff, gbase, voff) do { _Pragma("unroll") for (int _i = 0; _i < 2; ++_i) \
;         __builtin_amdgcn_global_load_lds((const unsigned*)((const char*)(gbase) + (voff)[_i]), (PG8_LAS unsigned*)(lds + (bufoff) + ldsw + _i * 8192), 16, 0, 0); } while (0)
; #define PG8_LDA(dst, b, h) do { _Pragma("unroll") for (int m = 0; m < 4; ++m) _Pragma("unroll") for (int k = 0; k < 2; ++k) dst[m][k] = *(const PG8_LAS bf16x8*)(lds + PG8_SA(b, h) + aoff + m * 2048 + k * 1024); } while (0)
; #define PG8_LDB(dst, b, h) do { _Pragma("unroll") for (int n = 0; n < 2; ++n) _Pragma("unroll") for (int k = 0; k < 2; ++k) dst[n][k] = *(const PG8_LAS bf16x8*)(lds + PG8_SB(b, h) + boff + n * 2048 + k * 1024); } while (0)
; #define PG8_MMA(ai, bj, At, Bt) do { __builtin_amdgcn_s_setprio(1); _Pragma("unroll") for (int m = 0; m < 4; ++m) _Pragma("unroll") for (int n = 0; n < 2; ++n) _Pragma("unroll") for (int k = 0; k < 2; ++k) \
;         acc[ai][bj][m][n] = __builtin_amdgcn_mfma_f32_16x16x32_bf16(Bt[n][k], At[m][k], acc[ai][bj][m][n], 0, 0, 0); __builtin_amdgcn_s_setprio(0); } while (0)
; #define PG8_WAIT_V(n) asm volatile("s_waitcnt vmcnt(" #n ")" ::: "memory")
; #define PG8_WAIT_L(n) asm volatile("s_waitcnt lgkmcnt(" #n ")" ::: "memory")
; #define PG8_BAR __builtin_amdgcn_s_barrier()
; #define PG8_SCHED __builtin_amdgcn_sched_barrier(0)
; template <class Epi, class Sched, bool ALIGN_EPI = false, bool SP2 = false>
; __device__ __forceinline__ void gemm_phase(PG8_LAS unsigned char* lds, const Gemm g, const Sched& S, const Epi& E) {
;     ...
;             PG8_LDB(B0, 0, 0); PG8_LDB(B1, 0, 1); PG8_SCHED; PG8_LDA(At, 0, 0); PG8_STAGE(PG8_SA(1, 1), a1 + hstepA, voffA);
;             PG8_WAIT_V(8); PG8_WAIT_L(0); PG8_BAR; PG8_MMA(0, 0, At, B0); PG8_MMA(0, 1, At, B1); PG8_BAR; PG8_SCHED;
;     ...
;         for (int a = 0; a < 2; ++a)
; #pragma unroll
;             for (int b = 0; b < 2; ++b)
; #pragma unroll
;                 for (int m = 0; m < 4; ++m)
; #pragma unroll
;                     for (int n = 0; n < 2; ++n) acc[a][b][m][n] = (f32x4){0.f, 0.f, 0.f, 0.f};
.LBB0_3570:
	s_add_u32 s22, s22, 0x160080
	s_addc_u32 s23, s23, 0
	s_add_u32 s53, s24, 0x100
	v_mov_b32_e32 v2, 0
	s_addc_u32 s54, s25, 0
	s_mov_b32 s55, -2
	v_mov_b32_e32 v3, v2
	v_mov_b32_e32 v4, v2
	v_mov_b32_e32 v5, v2
	v_mov_b32_e32 v6, v2
	v_mov_b32_e32 v7, v2
	v_mov_b32_e32 v8, v2
	v_mov_b32_e32 v9, v2
	v_mov_b32_e32 v10, v2
	v_mov_b32_e32 v11, v2
	v_mov_b32_e32 v12, v2
	v_mov_b32_e32 v13, v2
	v_mov_b32_e32 v14, v2
	v_mov_b32_e32 v15, v2
	v_mov_b32_e32 v16, v2
	v_mov_b32_e32 v17, v2
	v_mov_b32_e32 v26, v2
	v_mov_b32_e32 v27, v2
	v_mov_b32_e32 v28, v2
	v_mov_b32_e32 v29, v2
	v_mov_b32_e32 v30, v2
	v_mov_b32_e32 v31, v2
	v_mov_b32_e32 v32, v2
	v_mov_b32_e32 v33, v2
	v_mov_b32_e32 v42, v2
	v_mov_b32_e32 v43, v2
	v_mov_b32_e32 v44, v2
	v_mov_b32_e32 v45, v2
	v_mov_b32_e32 v46, v2
	v_mov_b32_e32 v47, v2
	v_mov_b32_e32 v48, v2
	v_mov_b32_e32 v49, v2
	v_mov_b32_e32 v18, v2
	v_mov_b32_e32 v19, v2
	v_mov_b32_e32 v20, v2
	v_mov_b32_e32 v21, v2
	v_mov_b32_e32 v22, v2
	v_mov_b32_e32 v23, v2
	v_mov_b32_e32 v24, v2
	v_mov_b32_e32 v25, v2
	v_mov_b32_e32 v34, v2
	v_mov_b32_e32 v35, v2
	v_mov_b32_e32 v36, v2
	v_mov_b32_e32 v37, v2
	v_mov_b32_e32 v38, v2
	v_mov_b32_e32 v39, v2
	v_mov_b32_e32 v40, v2
	v_mov_b32_e32 v41, v2
	v_mov_b32_e32 v50, v2
	v_mov_b32_e32 v51, v2
	v_mov_b32_e32 v52, v2
	v_mov_b32_e32 v53, v2
	v_mov_b32_e32 v54, v2
	v_mov_b32_e32 v55, v2
	v_mov_b32_e32 v56, v2
	v_mov_b32_e32 v57, v2
	v_mov_b32_e32 v58, v2
	v_mov_b32_e32 v59, v2
	v_mov_b32_e32 v60, v2
	v_mov_b32_e32 v61, v2
	v_mov_b32_e32 v62, v2
	v_mov_b32_e32 v63, v2
	v_mov_b32_e32 v64, v2
	v_mov_b32_e32 v65, v2
	v_mov_b32_e32 v66, v2
	v_mov_b32_e32 v67, v2
	v_mov_b32_e32 v68, v2
	v_mov_b32_e32 v69, v2
	v_mov_b32_e32 v70, v2
	v_mov_b32_e32 v71, v2
	v_mov_b32_e32 v72, v2
	v_mov_b32_e32 v73, v2
	v_mov_b32_e32 v74, v2
	v_mov_b32_e32 v75, v2
	v_mov_b32_e32 v76, v2
	v_mov_b32_e32 v77, v2
	v_mov_b32_e32 v78, v2
	v_mov_b32_e32 v79, v2
	v_mov_b32_e32 v80, v2
	v_mov_b32_e32 v81, v2
	v_mov_b32_e32 v90, v2
	v_mov_b32_e32 v91, v2
	v_mov_b32_e32 v92, v2
	v_mov_b32_e32 v93, v2
	v_mov_b32_e32 v94, v2
	v_mov_b32_e32 v95, v2
	v_mov_b32_e32 v96, v2
	v_mov_b32_e32 v97, v2
	v_mov_b32_e32 v106, v2
	v_mov_b32_e32 v107, v2
	v_mov_b32_e32 v108, v2
	v_mov_b32_e32 v109, v2
	v_mov_b32_e32 v110, v2
	v_mov_b32_e32 v111, v2
	v_mov_b32_e32 v112, v2
	v_mov_b32_e32 v113, v2
	v_mov_b32_e32 v82, v2
	v_mov_b32_e32 v83, v2
	v_mov_b32_e32 v84, v2
	v_mov_b32_e32 v85, v2
	v_mov_b32_e32 v86, v2
	v_mov_b32_e32 v87, v2
	v_mov_b32_e32 v88, v2
	v_mov_b32_e32 v89, v2
	v_mov_b32_e32 v98, v2
	v_mov_b32_e32 v99, v2
	v_mov_b32_e32 v100, v2
	v_mov_b32_e32 v101, v2
	v_mov_b32_e32 v102, v2
	v_mov_b32_e32 v103, v2
	v_mov_b32_e32 v104, v2
	v_mov_b32_e32 v105, v2
	v_mov_b32_e32 v114, v2
	v_mov_b32_e32 v115, v2
	v_mov_b32_e32 v116, v2
	v_mov_b32_e32 v117, v2
	v_mov_b32_e32 v118, v2
	v_mov_b32_e32 v119, v2
	v_mov_b32_e32 v120, v2
	v_mov_b32_e32 v121, v2
	v_mov_b32_e32 v122, v2
	v_mov_b32_e32 v123, v2
	v_mov_b32_e32 v124, v2
	v_mov_b32_e32 v125, v2
	v_mov_b32_e32 v126, v2
	v_mov_b32_e32 v127, v2
	v_mov_b32_e32 v128, v2
	v_mov_b32_e32 v129, v2
	ds_read_b128 v[152:155], v148
	ds_read_b128 v[156:159], v148 offset:1024
	ds_read_b128 v[160:163], v148 offset:2048
	ds_read_b128 v[164:167], v148 offset:3072
	ds_read_b128 v[168:171], v149
	ds_read_b128 v[172:175], v149 offset:1024
	ds_read_b128 v[176:179], v149 offset:2048
	ds_read_b128 v[180:183], v149 offset:3072
	s_add_u32 s24, s22, 0xffea0080
	s_addc_u32 s25, s23, -1
	s_cmpk_eq_i32 s55, 0x54
	s_cselect_b32 s27, s7, s25
	s_cselect_b32 s26, s6, s24
	s_cselect_b32 s25, s21, s54
	s_cselect_b32 s24, s20, s53
	v_lshl_add_u64 v[218:219], s[22:23], 0, v[138:139]
	s_add_i32 m0, s35, 0xc000
	ds_read_b128 v[184:187], v150
	ds_read_b128 v[188:191], v150 offset:1024
	ds_read_b128 v[192:195], v150 offset:2048
	ds_read_b128 v[196:199], v150 offset:3072
	ds_read_b128 v[200:203], v150 offset:4096
	ds_read_b128 v[204:207], v150 offset:5120
	ds_read_b128 v[210:213], v150 offset:6144
	ds_read_b128 v[214:217], v150 offset:7168
	global_load_lds_dwordx4 v[218:219], off
	v_lshl_add_u64 v[218:219], s[22:23], 0, v[140:141]
	s_add_i32 m0, s35, 0xe000
	s_nop 0
	global_load_lds_dwordx4 v[218:219], off
	s_waitcnt vmcnt(24)
	s_waitcnt lgkmcnt(0)
	s_barrier
	s_setprio 1
	s_waitcnt lgkmcnt(0)
	v_mfma_f32_16x16x32_bf16 v[126:129], v[152:155], v[184:187], v[126:129]
	v_mfma_f32_16x16x32_bf16 v[122:125], v[160:163], v[184:187], v[122:125]
	v_mfma_f32_16x16x32_bf16 v[118:121], v[152:155], v[192:195], v[118:121]
	v_mfma_f32_16x16x32_bf16 v[114:117], v[160:163], v[192:195], v[114:117]
	v_mfma_f32_16x16x32_bf16 v[102:105], v[152:155], v[200:203], v[102:105]
	v_mfma_f32_16x16x32_bf16 v[98:101], v[160:163], v[200:203], v[98:101]
	v_mfma_f32_16x16x32_bf16 v[86:89], v[152:155], v[210:213], v[86:89]
	v_mfma_f32_16x16x32_bf16 v[82:85], v[160:163], v[210:213], v[82:85]
	v_mfma_f32_16x16x32_bf16 v[126:129], v[156:159], v[188:191], v[126:129]
	v_mfma_f32_16x16x32_bf16 v[122:125], v[164:167], v[188:191], v[122:125]
	v_mfma_f32_16x16x32_bf16 v[118:121], v[156:159], v[196:199], v[118:121]
	v_mfma_f32_16x16x32_bf16 v[114:117], v[164:167], v[196:199], v[114:117]
	v_mfma_f32_16x16x32_bf16 v[102:105], v[156:159], v[204:207], v[102:105]
	v_mfma_f32_16x16x32_bf16 v[98:101], v[164:167], v[204:207], v[98:101]
	v_mfma_f32_16x16x32_bf16 v[86:89], v[156:159], v[214:217], v[86:89]
	v_mfma_f32_16x16x32_bf16 v[82:85], v[164:167], v[214:217], v[82:85]
	s_setprio 0
	s_setprio 1
	v_mfma_f32_16x16x32_bf16 v[110:113], v[168:171], v[184:187], v[110:113]
	v_mfma_f32_16x16x32_bf16 v[106:109], v[176:179], v[184:187], v[106:109]
	v_mfma_f32_16x16x32_bf16 v[94:97], v[168:171], v[192:195], v[94:97]
	v_mfma_f32_16x16x32_bf16 v[90:93], v[176:179], v[192:195], v[90:93]
	v_mfma_f32_16x16x32_bf16 v[78:81], v[168:171], v[200:203], v[78:81]
	v_mfma_f32_16x16x32_bf16 v[74:77], v[176:179], v[200:203], v[74:77]
	v_mfma_f32_16x16x32_bf16 v[70:73], v[168:171], v[210:213], v[70:73]
	v_mfma_f32_16x16x32_bf16 v[66:69], v[176:179], v[210:213], v[66:69]
	v_mfma_f32_16x16x32_bf16 v[110:113], v[172:175], v[188:191], v[110:113]
	v_mfma_f32_16x16x32_bf16 v[106:109], v[180:183], v[188:191], v[106:109]
	v_mfma_f32_16x16x32_bf16 v[94:97], v[172:175], v[196:199], v[94:97]
	v_mfma_f32_16x16x32_bf16 v[90:93], v[180:183], v[196:199], v[90:93]
	v_mfma_f32_16x16x32_bf16 v[78:81], v[172:175], v[204:207], v[78:81]
	v_mfma_f32_16x16x32_bf16 v[74:77], v[180:183], v[204:207], v[74:77]
	v_mfma_f32_16x16x32_bf16 v[70:73], v[172:175], v[214:217], v[70:73]
	v_mfma_f32_16x16x32_bf16 v[66:69], v[180:183], v[214:217], v[66:69]
	s_setprio 0
	s_barrier
; #define PG8_STAGE(bufoff, gbase, voff) do { _Pragma("unroll") for (int _i = 0; _i < 2; ++_i) \
;         __builtin_amdgcn_global_load_lds((const unsigned*)((const char*)(gbase) + (voff)[_i]), (PG8_LAS unsigned*)(lds + (bufoff) + ldsw + _i * 8192), 16, 0, 0); } while (0)
; #define PG8_LDA(dst, b, h) do { _Pragma("unroll") for (int m = 0; m < 4; ++m) _Pragma("unroll") for (int k = 0; k < 2; ++k) dst[m][k] = *(const PG8_LAS bf16x8*)(lds + PG8_SA(b, h) + aoff + m * 2048 + k * 1024); } while (0)
; #define PG8_LDB(dst, b, h) do { _Pragma("unroll") for (int n = 0; n < 2; ++n) _Pragma("unroll") for (int k = 0; k < 2; ++k) dst[n][k] = *(const PG8_LAS bf16x8*)(lds + PG8_SB(b, h) + boff + n * 2048 + k * 1024); } while (0)
; #define PG8_MMA(ai, bj, At, Bt) do { __builtin_amdgcn_s_setprio(1); _Pragma("unroll") for (int m = 0; m < 4; ++m) _Pragma("unroll") for (int n = 0; n < 2; ++n) _Pragma("unroll") for (int k = 0; k < 2; ++k) \
;         acc[ai][bj][m][n] = __builtin_amdgcn_mfma_f32_16x16x32_bf16(Bt[n][k], At[m][k], acc[ai][bj][m][n], 0, 0, 0); __builtin_amdgcn_s_setprio(0); } while (0)
; #define PG8_WAIT_V(n) asm volatile("s_waitcnt vmcnt(" #n ")" ::: "memory")
; #define PG8_WAIT_L(n) asm volatile("s_waitcnt lgkmcnt(" #n ")" ::: "memory")
; #define PG8_BAR __builtin_amdgcn_s_barrier()
; #define PG8_SCHED __builtin_amdgcn_sched_barrier(0)
; template <class Epi, class Sched, bool ALIGN_EPI = false, bool SP2 = false>
; __device__ __forceinline__ void gemm_phase(PG8_LAS unsigned char* lds, const Gemm g, const Sched& S, const Epi& E) {
;     ...
;             PG8_LDA(At, 0, 1); PG8_STAGE(PG8_SB(0, 0), b2, voffB); PG8_STAGE(PG8_SB(0, 1), b2 + hstepB, voffB); PG8_STAGE(PG8_SA(0, 0), a2, voffA);
;             PG8_WAIT_V(8); PG8_WAIT_L(0); PG8_BAR; PG8_MMA(1, 0, At, B0); PG8_MMA(1, 1, At, B1); PG8_BAR; PG8_SCHED;
;             PG8_LDB(B0, 1, 0); PG8_LDB(B1, 1, 1); PG8_SCHED; PG8_LDA(At, 1, 0); PG8_STAGE(PG8_SA(0, 1), a2 + hstepA, voffA);
;             PG8_WAIT_V(8); PG8_WAIT_L(0); PG8_BAR; PG8_MMA(0, 0, At, B0); PG8_MMA(0, 1, At, B1); PG8_BAR; PG8_SCHED;
	s_add_i32 s56, s43, s31
	v_lshl_add_u64 v[218:219], s[24:25], 0, v[134:135]
	s_mov_b32 m0, s56
	ds_read_b128 v[184:187], v150 offset:16384
	ds_read_b128 v[188:191], v150 offset:17408
	ds_read_b128 v[192:195], v150 offset:18432
	ds_read_b128 v[196:199], v150 offset:19456
	ds_read_b128 v[200:203], v150 offset:20480
	ds_read_b128 v[204:207], v150 offset:21504
	ds_read_b128 v[210:213], v150 offset:22528
	ds_read_b128 v[214:217], v150 offset:23552
	global_load_lds_dwordx4 v[218:219], off
	s_add_i32 m0, s56, 0x2000
	s_add_u32 s56, s24, 0x160000
	v_lshl_add_u64 v[220:221], s[24:25], 0, v[130:131]
	s_addc_u32 s57, s25, 0
	s_add_i32 s58, s44, s31
	global_load_lds_dwordx4 v[220:221], off
	v_lshl_add_u64 v[222:223], s[56:57], 0, v[134:135]
	s_mov_b32 m0, s58
	v_lshl_add_u64 v[224:225], s[26:27], 0, v[132:133]
	global_load_lds_dwordx4 v[222:223], off
	v_lshl_add_u64 v[222:223], s[56:57], 0, v[130:131]
	s_add_i32 m0, s58, 0x2000
	s_nop 0
	global_load_lds_dwordx4 v[222:223], off
	v_lshl_add_u64 v[222:223], s[26:27], 0, v[136:137]
	s_mov_b32 m0, s35
	s_nop 0
	global_load_lds_dwordx4 v[222:223], off
	s_mov_b32 m0, s36
	s_nop 0
	global_load_lds_dwordx4 v[224:225], off
	s_waitcnt vmcnt(24)
	s_waitcnt lgkmcnt(0)
	s_barrier
	s_setprio 1
	s_waitcnt lgkmcnt(0)
	v_mfma_f32_16x16x32_bf16 v[62:65], v[152:155], v[184:187], v[62:65]
	v_mfma_f32_16x16x32_bf16 v[58:61], v[160:163], v[184:187], v[58:61]
	v_mfma_f32_16x16x32_bf16 v[54:57], v[152:155], v[192:195], v[54:57]
	v_mfma_f32_16x16x32_bf16 v[50:53], v[160:163], v[192:195], v[50:53]
	v_mfma_f32_16x16x32_bf16 v[38:41], v[152:155], v[200:203], v[38:41]
	v_mfma_f32_16x16x32_bf16 v[34:37], v[160:163], v[200:203], v[34:37]
	v_mfma_f32_16x16x32_bf16 v[22:25], v[152:155], v[210:213], v[22:25]
	v_mfma_f32_16x16x32_bf16 v[18:21], v[160:163], v[210:213], v[18:21]
	v_mfma_f32_16x16x32_bf16 v[62:65], v[156:159], v[188:191], v[62:65]
	v_mfma_f32_16x16x32_bf16 v[58:61], v[164:167], v[188:191], v[58:61]
	v_mfma_f32_16x16x32_bf16 v[54:57], v[156:159], v[196:199], v[54:57]
	v_mfma_f32_16x16x32_bf16 v[50:53], v[164:167], v[196:199], v[50:53]
	v_mfma_f32_16x16x32_bf16 v[38:41], v[156:159], v[204:207], v[38:41]
	v_mfma_f32_16x16x32_bf16 v[34:37], v[164:167], v[204:207], v[34:37]
	v_mfma_f32_16x16x32_bf16 v[22:25], v[156:159], v[214:217], v[22:25]
	v_mfma_f32_16x16x32_bf16 v[18:21], v[164:167], v[214:217], v[18:21]
	s_setprio 0
	s_setprio 1
	v_mfma_f32_16x16x32_bf16 v[46:49], v[168:171], v[184:187], v[46:49]
	v_mfma_f32_16x16x32_bf16 v[42:45], v[176:179], v[184:187], v[42:45]
	v_mfma_f32_16x16x32_bf16 v[30:33], v[168:171], v[192:195], v[30:33]
	v_mfma_f32_16x16x32_bf16 v[26:29], v[176:179], v[192:195], v[26:29]
	v_mfma_f32_16x16x32_bf16 v[14:17], v[168:171], v[200:203], v[14:17]
	v_mfma_f32_16x16x32_bf16 v[10:13], v[176:179], v[200:203], v[10:13]
	v_mfma_f32_16x16x32_bf16 v[6:9], v[168:171], v[210:213], v[6:9]
	v_mfma_f32_16x16x32_bf16 v[2:5], v[176:179], v[210:213], v[2:5]
	v_mfma_f32_16x16x32_bf16 v[46:49], v[172:175], v[188:191], v[46:49]
	v_mfma_f32_16x16x32_bf16 v[42:45], v[180:183], v[188:191], v[42:45]
	v_mfma_f32_16x16x32_bf16 v[30:33], v[172:175], v[196:199], v[30:33]
	v_mfma_f32_16x16x32_bf16 v[26:29], v[180:183], v[196:199], v[26:29]
	v_mfma_f32_16x16x32_bf16 v[14:17], v[172:175], v[204:207], v[14:17]
	v_mfma_f32_16x16x32_bf16 v[10:13], v[180:183], v[204:207], v[10:13]
	v_mfma_f32_16x16x32_bf16 v[6:9], v[172:175], v[214:217], v[6:9]
	v_mfma_f32_16x16x32_bf16 v[2:5], v[180:183], v[214:217], v[2:5]
	s_setprio 0
	s_barrier
	s_add_i32 s56, 0, 0x18000
	v_add_u32_e32 v151, s56, v146
	s_add_i32 s57, 0, 0x1c000
	ds_read_b128 v[152:155], v151
	ds_read_b128 v[156:159], v151 offset:1024
	ds_read_b128 v[160:163], v151 offset:2048
	ds_read_b128 v[164:167], v151 offset:3072
	v_add_u32_e32 v151, s57, v146
	ds_read_b128 v[168:171], v151
	ds_read_b128 v[172:175], v151 offset:1024
	ds_read_b128 v[176:179], v151 offset:2048
	ds_read_b128 v[180:183], v151 offset:3072
	s_add_u32 s26, s26, 0x160000
	s_addc_u32 s27, s27, 0
	s_mov_b32 m0, s37
	v_lshl_add_u64 v[226:227], s[26:27], 0, v[136:137]
	ds_read_b128 v[184:187], v150 offset:32768
	ds_read_b128 v[188:191], v150 offset:33792
	ds_read_b128 v[192:195], v150 offset:34816
	ds_read_b128 v[196:199], v150 offset:35840
	ds_read_b128 v[200:203], v150 offset:36864
	ds_read_b128 v[204:207], v150 offset:37888
	ds_read_b128 v[210:213], v150 offset:38912
	ds_read_b128 v[214:217], v150 offset:39936
	global_load_lds_dwordx4 v[226:227], off
	v_lshl_add_u64 v[226:227], s[26:27], 0, v[132:133]
	s_mov_b32 m0, s38
	s_nop 0
	global_load_lds_dwordx4 v[226:227], off
	s_waitcnt vmcnt(8)
	s_waitcnt lgkmcnt(0)
	s_barrier
; #define PG8_STAGE(bufoff, gbase, voff) do { _Pragma("unroll") for (int _i = 0; _i < 2; ++_i) \
;         __builtin_amdgcn_global_load_lds((const unsigned*)((const char*)(gbase) + (voff)[_i]), (PG8_LAS unsigned*)(lds + (bufoff) + ldsw + _i * 8192), 16, 0, 0); } while (0)
; #define PG8_LDA(dst, b, h) do { _Pragma("unroll") for (int m = 0; m < 4; ++m) _Pragma("unroll") for (int k = 0; k < 2; ++k) dst[m][k] = *(const PG8_LAS bf16x8*)(lds + PG8_SA(b, h) + aoff + m * 2048 + k * 1024); } while (0)
; #define PG8_MMA(ai, bj, At, Bt) do { __builtin_amdgcn_s_setprio(1); _Pragma("unroll") for (int m = 0; m < 4; ++m) _Pragma("unroll") for (int n = 0; n < 2; ++n) _Pragma("unroll") for (int k = 0; k < 2; ++k) \
;         acc[ai][bj][m][n] = __builtin_amdgcn_mfma_f32_16x16x32_bf16(Bt[n][k], At[m][k], acc[ai][bj][m][n], 0, 0, 0); __builtin_amdgcn_s_setprio(0); } while (0)
; #define PG8_WAIT_V(n) asm volatile("s_waitcnt vmcnt(" #n ")" ::: "memory")
; #define PG8_WAIT_L(n) asm volatile("s_waitcnt lgkmcnt(" #n ")" ::: "memory")
; #define PG8_BAR __builtin_amdgcn_s_barrier()
; #define PG8_SCHED __builtin_amdgcn_sched_barrier(0)
; template <class Epi, class Sched, bool ALIGN_EPI = false, bool SP2 = false>
; __device__ __forceinline__ void gemm_phase(PG8_LAS unsigned char* lds, const Gemm g, const Sched& S, const Epi& E) {
;     ...
;             PG8_WAIT_V(8); PG8_WAIT_L(0); PG8_BAR; PG8_MMA(0, 0, At, B0); PG8_MMA(0, 1, At, B1); PG8_BAR; PG8_SCHED;
;             PG8_LDA(At, 1, 1); PG8_STAGE(PG8_SB(1, 0), b3, voffB); PG8_STAGE(PG8_SB(1, 1), b3 + hstepB, voffB); PG8_STAGE(PG8_SA(1, 0), a3, voffA);
;             PG8_WAIT_V(8); PG8_WAIT_L(0); PG8_BAR; PG8_MMA(1, 0, At, B0); PG8_MMA(1, 1, At, B1); PG8_BAR; PG8_SCHED;
	s_setprio 1
	s_waitcnt lgkmcnt(0)
	v_mfma_f32_16x16x32_bf16 v[126:129], v[152:155], v[184:187], v[126:129]
	v_mfma_f32_16x16x32_bf16 v[122:125], v[160:163], v[184:187], v[122:125]
	v_mfma_f32_16x16x32_bf16 v[118:121], v[152:155], v[192:195], v[118:121]
	v_mfma_f32_16x16x32_bf16 v[114:117], v[160:163], v[192:195], v[114:117]
	v_mfma_f32_16x16x32_bf16 v[102:105], v[152:155], v[200:203], v[102:105]
	v_mfma_f32_16x16x32_bf16 v[98:101], v[160:163], v[200:203], v[98:101]
	v_mfma_f32_16x16x32_bf16 v[86:89], v[152:155], v[210:213], v[86:89]
	v_mfma_f32_16x16x32_bf16 v[82:85], v[160:163], v[210:213], v[82:85]
	v_mfma_f32_16x16x32_bf16 v[126:129], v[156:159], v[188:191], v[126:129]
	v_mfma_f32_16x16x32_bf16 v[122:125], v[164:167], v[188:191], v[122:125]
	v_mfma_f32_16x16x32_bf16 v[118:121], v[156:159], v[196:199], v[118:121]
	v_mfma_f32_16x16x32_bf16 v[114:117], v[164:167], v[196:199], v[114:117]
	v_mfma_f32_16x16x32_bf16 v[102:105], v[156:159], v[204:207], v[102:105]
	v_mfma_f32_16x16x32_bf16 v[98:101], v[164:167], v[204:207], v[98:101]
	v_mfma_f32_16x16x32_bf16 v[86:89], v[156:159], v[214:217], v[86:89]
	v_mfma_f32_16x16x32_bf16 v[82:85], v[164:167], v[214:217], v[82:85]
	s_setprio 0
	s_setprio 1
	v_mfma_f32_16x16x32_bf16 v[110:113], v[168:171], v[184:187], v[110:113]
	v_mfma_f32_16x16x32_bf16 v[106:109], v[176:179], v[184:187], v[106:109]
	v_mfma_f32_16x16x32_bf16 v[94:97], v[168:171], v[192:195], v[94:97]
	v_mfma_f32_16x16x32_bf16 v[90:93], v[176:179], v[192:195], v[90:93]
	v_mfma_f32_16x16x32_bf16 v[78:81], v[168:171], v[200:203], v[78:81]
	v_mfma_f32_16x16x32_bf16 v[74:77], v[176:179], v[200:203], v[74:77]
	v_mfma_f32_16x16x32_bf16 v[70:73], v[168:171], v[210:213], v[70:73]
	v_mfma_f32_16x16x32_bf16 v[66:69], v[176:179], v[210:213], v[66:69]
	v_mfma_f32_16x16x32_bf16 v[110:113], v[172:175], v[188:191], v[110:113]
	v_mfma_f32_16x16x32_bf16 v[106:109], v[180:183], v[188:191], v[106:109]
	v_mfma_f32_16x16x32_bf16 v[94:97], v[172:175], v[196:199], v[94:97]
	v_mfma_f32_16x16x32_bf16 v[90:93], v[180:183], v[196:199], v[90:93]
	v_mfma_f32_16x16x32_bf16 v[78:81], v[172:175], v[204:207], v[78:81]
	v_mfma_f32_16x16x32_bf16 v[74:77], v[180:183], v[204:207], v[74:77]
	v_mfma_f32_16x16x32_bf16 v[70:73], v[172:175], v[214:217], v[70:73]
	v_mfma_f32_16x16x32_bf16 v[66:69], v[180:183], v[214:217], v[66:69]
	s_setprio 0
	s_barrier
	s_add_i32 s26, s56, s31
	v_lshl_add_u64 v[218:219], v[218:219], 0, s[8:9]
	s_mov_b32 m0, s26
	ds_read_b128 v[184:187], v150 offset:49152
	ds_read_b128 v[188:191], v150 offset:50176
	ds_read_b128 v[192:195], v150 offset:51200
	ds_read_b128 v[196:199], v150 offset:52224
	ds_read_b128 v[200:203], v150 offset:53248
	ds_read_b128 v[204:207], v150 offset:54272
	ds_read_b128 v[210:213], v150 offset:55296
	ds_read_b128 v[214:217], v150 offset:56320
	global_load_lds_dwordx4 v[218:219], off
	s_add_i32 m0, s26, 0x2000
	s_add_u32 s24, s24, 0x160080
	v_lshl_add_u64 v[218:219], v[220:221], 0, s[8:9]
	s_addc_u32 s25, s25, 0
	s_add_i32 s26, s57, s31
	global_load_lds_dwordx4 v[218:219], off
	v_lshl_add_u64 v[218:219], s[24:25], 0, v[134:135]
	s_mov_b32 m0, s26
	s_nop 0
	global_load_lds_dwordx4 v[218:219], off
	v_lshl_add_u64 v[218:219], s[24:25], 0, v[130:131]
	s_add_i32 m0, s26, 0x2000
	s_nop 0
	global_load_lds_dwordx4 v[218:219], off
	v_lshl_add_u64 v[218:219], v[222:223], 0, s[8:9]
	s_mov_b32 m0, s40
	s_nop 0
	global_load_lds_dwordx4 v[218:219], off
	v_lshl_add_u64 v[218:219], v[224:225], 0, s[8:9]
	s_mov_b32 m0, s41
	s_nop 0
	global_load_lds_dwordx4 v[218:219], off
	s_waitcnt vmcnt(8)
	s_waitcnt lgkmcnt(0)
	s_barrier
	s_setprio 1
	s_waitcnt lgkmcnt(0)
	v_mfma_f32_16x16x32_bf16 v[62:65], v[152:155], v[184:187], v[62:65]
	v_mfma_f32_16x16x32_bf16 v[58:61], v[160:163], v[184:187], v[58:61]
	v_mfma_f32_16x16x32_bf16 v[54:57], v[152:155], v[192:195], v[54:57]
	v_mfma_f32_16x16x32_bf16 v[50:53], v[160:163], v[192:195], v[50:53]
	v_mfma_f32_16x16x32_bf16 v[38:41], v[152:155], v[200:203], v[38:41]
	v_mfma_f32_16x16x32_bf16 v[34:37], v[160:163], v[200:203], v[34:37]
	v_mfma_f32_16x16x32_bf16 v[22:25], v[152:155], v[210:213], v[22:25]
	v_mfma_f32_16x16x32_bf16 v[18:21], v[160:163], v[210:213], v[18:21]
	v_mfma_f32_16x16x32_bf16 v[62:65], v[156:159], v[188:191], v[62:65]
	v_mfma_f32_16x16x32_bf16 v[58:61], v[164:167], v[188:191], v[58:61]
	v_mfma_f32_16x16x32_bf16 v[54:57], v[156:159], v[196:199], v[54:57]
	v_mfma_f32_16x16x32_bf16 v[50:53], v[164:167], v[196:199], v[50:53]
	v_mfma_f32_16x16x32_bf16 v[38:41], v[156:159], v[204:207], v[38:41]
	v_mfma_f32_16x16x32_bf16 v[34:37], v[164:167], v[204:207], v[34:37]
	v_mfma_f32_16x16x32_bf16 v[22:25], v[156:159], v[214:217], v[22:25]
	v_mfma_f32_16x16x32_bf16 v[18:21], v[164:167], v[214:217], v[18:21]
	s_setprio 0
	s_setprio 1
	v_mfma_f32_16x16x32_bf16 v[46:49], v[168:171], v[184:187], v[46:49]
	v_mfma_f32_16x16x32_bf16 v[42:45], v[176:179], v[184:187], v[42:45]
	v_mfma_f32_16x16x32_bf16 v[30:33], v[168:171], v[192:195], v[30:33]
	v_mfma_f32_16x16x32_bf16 v[26:29], v[176:179], v[192:195], v[26:29]
	v_mfma_f32_16x16x32_bf16 v[14:17], v[168:171], v[200:203], v[14:17]
	v_mfma_f32_16x16x32_bf16 v[10:13], v[176:179], v[200:203], v[10:13]
	v_mfma_f32_16x16x32_bf16 v[6:9], v[168:171], v[210:213], v[6:9]
	v_mfma_f32_16x16x32_bf16 v[2:5], v[176:179], v[210:213], v[2:5]
	v_mfma_f32_16x16x32_bf16 v[46:49], v[172:175], v[188:191], v[46:49]
	v_mfma_f32_16x16x32_bf16 v[42:45], v[180:183], v[188:191], v[42:45]
	v_mfma_f32_16x16x32_bf16 v[30:33], v[172:175], v[196:199], v[30:33]
	v_mfma_f32_16x16x32_bf16 v[26:29], v[180:183], v[196:199], v[26:29]
	v_mfma_f32_16x16x32_bf16 v[14:17], v[172:175], v[204:207], v[14:17]
	v_mfma_f32_16x16x32_bf16 v[10:13], v[180:183], v[204:207], v[10:13]
	v_mfma_f32_16x16x32_bf16 v[6:9], v[172:175], v[214:217], v[6:9]
	v_mfma_f32_16x16x32_bf16 v[2:5], v[180:183], v[214:217], v[2:5]
	s_setprio 0
	s_barrier
	s_add_i32 s55, s55, 2
	s_add_u32 s22, s22, 0x100
	s_addc_u32 s23, s23, 0
	s_add_u32 s53, s53, 0x100
	s_addc_u32 s54, s54, 0
	s_cmpk_gt_u32 s55, 0x55
	s_cbranch_scc1 .Lpeel_exit_35
	.p2align 6
